# hand-written stage A/B: 60-comparator sort16, key build and key decode through v_bitop3 (7 % fewer VALU)
# speedup vs baseline: 1.0168x; 1.0010x over previous
; __device__ __forceinline__ unsigned f2key(float f) { const unsigned u = __float_as_uint(f); return (u & 0x80000000u) ? ~u : (u | 0x80000000u); }
; __device__ __forceinline__ void peer_tile(const Args& A, LAS unsigned char* lds, int tile) {
;     ...
;         const int tg = w & 3, hg = w >> 2, tl = 16 * tg + l15;
;         const size_t m = (size_t)tile * 64 + tl;
;         unsigned LA[4][2][16];
; #pragma unroll
;         for (int hh = 0; hh < 4; ++hh) {
;             const int h = 4 * hg + hh;
; #pragma unroll
;             for (int p = 0; p < 2; ++p) {
;                 const int hp = 2 * h + p;
;                 unsigned k0[16], k1[16];
;                 { const bf16_t* sp = QRY + m * 2048 + hp * 128 + 32 * g;
;                   const u32x4 s0 = *(const u32x4*)sp, s1 = *(const u32x4*)(sp + 8), s2 = *(const u32x4*)(sp + 16), s3 = *(const u32x4*)(sp + 24);
;                   const unsigned sw[16] = {s0.x, s0.y, s0.z, s0.w, s1.x, s1.y, s1.z, s1.w, s2.x, s2.y, s2.z, s2.w, s3.x, s3.y, s3.z, s3.w};
; #pragma unroll
;                   for (int i = 0; i < 16; ++i) {
;                       const float lo = (float)__builtin_bit_cast(_Float16, (unsigned short)(sw[i] & 0xffffu)), hi = (float)__builtin_bit_cast(_Float16, (unsigned short)(sw[i] >> 16));
;                       const unsigned klo = (f2key(lo) & ~127u) | (unsigned)(127 - (32 * g + 2 * i)), khi = (f2key(hi) & ~127u) | (unsigned)(127 - (32 * g + 2 * i + 1));
;                       if (i < 8) { k0[2 * i] = klo; k0[2 * i + 1] = khi; } else { k1[2 * (i - 8)] = klo; k1[2 * (i - 8) + 1] = khi; } } }
.LBB0_699:
	s_mov_b64 exec, -1
	s_mov_b32 s33, 0x80000000
	s_mov_b32 s40, 0x7fffff80
	s_mov_b32 s41, 0x7fffffff
	v_and_b32_e32 v68, 63, v214
	v_lshrrev_b32_e32 v66, 6, v214
	s_nop 0
	v_readfirstlane_b32 s36, v66
	s_lshl_b32 s0, s2, 18
	s_lshl_b32 s1, s36, 9
	s_add_u32 s34, s54, s0
	s_addc_u32 s35, s55, 0
	s_add_u32 s34, s34, s1
	s_addc_u32 s35, s35, 0
	v_lshrrev_b32_e32 v66, 3, v68
	v_and_b32_e32 v64, 7, v68
	v_lshlrev_b32_e32 v64, 4, v64
	v_mul_u32_u24_e32 v65, 0x90, v66
	v_lshl_add_u32 v66, v66, 12, v64
	s_mul_i32 s0, s36, 0x2400
	s_cmp_eq_u32 s36, 7
	s_cselect_b32 s0, 0x21000, s0
	v_add3_u32 v64, v64, v65, s0
	v_mul_u32_u24_e32 v65, 0x90, v68
	v_add_u32_e32 v65, s0, v65
	v_mul_u32_u24_e32 v67, 0x84, v68
	v_lshlrev_b32_e32 v68, 10, v68
	s_lshl_b32 s1, s36, 7
	s_add_i32 s1, s1, 0x11000
	v_add_u32_e32 v67, s0, v67
	v_add_u32_e32 v68, s1, v68
	s_mov_b64 s[38:39], s[34:35]
	global_load_dwordx4 v[0:3], v66, s[38:39] offset:0
	s_add_u32 s38, s38, 0x8000
	s_addc_u32 s39, s39, 0
	global_load_dwordx4 v[4:7], v66, s[38:39] offset:0
	s_add_u32 s38, s38, 0x8000
	s_addc_u32 s39, s39, 0
	global_load_dwordx4 v[8:11], v66, s[38:39] offset:0
	s_add_u32 s38, s38, 0x8000
	s_addc_u32 s39, s39, 0
	global_load_dwordx4 v[12:15], v66, s[38:39] offset:0
	s_add_u32 s38, s38, 0x8000
	s_addc_u32 s39, s39, 0
	global_load_dwordx4 v[16:19], v66, s[38:39] offset:0
	s_add_u32 s38, s38, 0x8000
	s_addc_u32 s39, s39, 0
	global_load_dwordx4 v[20:23], v66, s[38:39] offset:0
	s_add_u32 s38, s38, 0x8000
	s_addc_u32 s39, s39, 0
	global_load_dwordx4 v[24:27], v66, s[38:39] offset:0
	s_add_u32 s38, s38, 0x8000
	s_addc_u32 s39, s39, 0
	global_load_dwordx4 v[28:31], v66, s[38:39] offset:0
	s_mov_b64 s[38:39], s[34:35]
	global_load_dwordx4 v[32:35], v66, s[38:39] offset:128
	s_add_u32 s38, s38, 0x8000
	s_addc_u32 s39, s39, 0
	global_load_dwordx4 v[36:39], v66, s[38:39] offset:128
	s_add_u32 s38, s38, 0x8000
	s_addc_u32 s39, s39, 0
	global_load_dwordx4 v[40:43], v66, s[38:39] offset:128
	s_add_u32 s38, s38, 0x8000
	s_addc_u32 s39, s39, 0
	global_load_dwordx4 v[44:47], v66, s[38:39] offset:128
	s_add_u32 s38, s38, 0x8000
	s_addc_u32 s39, s39, 0
	global_load_dwordx4 v[48:51], v66, s[38:39] offset:128
	s_add_u32 s38, s38, 0x8000
	s_addc_u32 s39, s39, 0
	global_load_dwordx4 v[52:55], v66, s[38:39] offset:128
	s_add_u32 s38, s38, 0x8000
	s_addc_u32 s39, s39, 0
	global_load_dwordx4 v[56:59], v66, s[38:39] offset:128
	s_add_u32 s38, s38, 0x8000
	s_addc_u32 s39, s39, 0
	global_load_dwordx4 v[60:63], v66, s[38:39] offset:128
	s_waitcnt vmcnt(8)
	ds_write_b128 v64, v[0:3] offset:0
	ds_write_b128 v64, v[4:7] offset:1152
	ds_write_b128 v64, v[8:11] offset:2304
	ds_write_b128 v64, v[12:15] offset:3456
	ds_write_b128 v64, v[16:19] offset:4608
	ds_write_b128 v64, v[20:23] offset:5760
	ds_write_b128 v64, v[24:27] offset:6912
	ds_write_b128 v64, v[28:31] offset:8064
	s_waitcnt lgkmcnt(0)
	ds_read_b128 v[0:3], v65 offset:0
	ds_read_b128 v[4:7], v65 offset:16
	ds_read_b128 v[8:11], v65 offset:32
	ds_read_b128 v[12:15], v65 offset:48
	ds_read_b128 v[16:19], v65 offset:64
	ds_read_b128 v[20:23], v65 offset:80
	ds_read_b128 v[24:27], v65 offset:96
	ds_read_b128 v[28:31], v65 offset:112
	s_waitcnt lgkmcnt(0)
	v_cvt_f32_f16_e32 v70, v0
	v_cvt_f32_f16_sdwa v71, v0 dst_sel:DWORD dst_unused:UNUSED_PAD src0_sel:WORD_1
	v_ashrrev_i32_e32 v72, 31, v70
	v_bitop3_b32 v70, v70, v72, s40 bitop3:0x78
	v_xor_b32_e32 v70, 0x8000007f, v70
	v_ashrrev_i32_e32 v72, 31, v71
	v_bitop3_b32 v71, v71, v72, s40 bitop3:0x78
	v_xor_b32_e32 v71, 0x8000007e, v71
	v_cvt_f32_f16_e32 v72, v1
	v_cvt_f32_f16_sdwa v73, v1 dst_sel:DWORD dst_unused:UNUSED_PAD src0_sel:WORD_1
	v_ashrrev_i32_e32 v74, 31, v72
	v_bitop3_b32 v72, v72, v74, s40 bitop3:0x78
	v_xor_b32_e32 v72, 0x8000007d, v72
	v_ashrrev_i32_e32 v74, 31, v73
	v_bitop3_b32 v73, v73, v74, s40 bitop3:0x78
	v_xor_b32_e32 v73, 0x8000007c, v73
	v_cvt_f32_f16_e32 v74, v2
	v_cvt_f32_f16_sdwa v75, v2 dst_sel:DWORD dst_unused:UNUSED_PAD src0_sel:WORD_1
	v_ashrrev_i32_e32 v76, 31, v74
	v_bitop3_b32 v74, v74, v76, s40 bitop3:0x78
	v_xor_b32_e32 v74, 0x8000007b, v74
	v_ashrrev_i32_e32 v76, 31, v75
	v_bitop3_b32 v75, v75, v76, s40 bitop3:0x78
	v_xor_b32_e32 v75, 0x8000007a, v75
	v_cvt_f32_f16_e32 v76, v3
	v_cvt_f32_f16_sdwa v77, v3 dst_sel:DWORD dst_unused:UNUSED_PAD src0_sel:WORD_1
	v_ashrrev_i32_e32 v78, 31, v76
	v_bitop3_b32 v76, v76, v78, s40 bitop3:0x78
	v_xor_b32_e32 v76, 0x80000079, v76
	v_ashrrev_i32_e32 v78, 31, v77
	v_bitop3_b32 v77, v77, v78, s40 bitop3:0x78
	v_xor_b32_e32 v77, 0x80000078, v77
	v_cvt_f32_f16_e32 v78, v4
	v_cvt_f32_f16_sdwa v79, v4 dst_sel:DWORD dst_unused:UNUSED_PAD src0_sel:WORD_1
	v_ashrrev_i32_e32 v80, 31, v78
	v_bitop3_b32 v78, v78, v80, s40 bitop3:0x78
	v_xor_b32_e32 v78, 0x80000077, v78
	v_ashrrev_i32_e32 v80, 31, v79
	v_bitop3_b32 v79, v79, v80, s40 bitop3:0x78
	v_xor_b32_e32 v79, 0x80000076, v79
	v_cvt_f32_f16_e32 v80, v5
	v_cvt_f32_f16_sdwa v81, v5 dst_sel:DWORD dst_unused:UNUSED_PAD src0_sel:WORD_1
	v_ashrrev_i32_e32 v82, 31, v80
	v_bitop3_b32 v80, v80, v82, s40 bitop3:0x78
	v_xor_b32_e32 v80, 0x80000075, v80
	v_ashrrev_i32_e32 v82, 31, v81
	v_bitop3_b32 v81, v81, v82, s40 bitop3:0x78
	v_xor_b32_e32 v81, 0x80000074, v81
	v_cvt_f32_f16_e32 v82, v6
	v_cvt_f32_f16_sdwa v83, v6 dst_sel:DWORD dst_unused:UNUSED_PAD src0_sel:WORD_1
	v_ashrrev_i32_e32 v84, 31, v82
	v_bitop3_b32 v82, v82, v84, s40 bitop3:0x78
	v_xor_b32_e32 v82, 0x80000073, v82
	v_ashrrev_i32_e32 v84, 31, v83
	v_bitop3_b32 v83, v83, v84, s40 bitop3:0x78
	v_xor_b32_e32 v83, 0x80000072, v83
	v_cvt_f32_f16_e32 v84, v7
	v_cvt_f32_f16_sdwa v85, v7 dst_sel:DWORD dst_unused:UNUSED_PAD src0_sel:WORD_1
; __device__ __forceinline__ unsigned f2key(float f) { const unsigned u = __float_as_uint(f); return (u & 0x80000000u) ? ~u : (u | 0x80000000u); }
; #define CE_DESC(a, b) do { const unsigned _mx = (a) > (b) ? (a) : (b), _mn = (a) > (b) ? (b) : (a); (a) = _mx; (b) = _mn; } while (0)
; __device__ __forceinline__ void sort16_desc(unsigned (&k)[16]) {
; #pragma unroll
;     for (int size = 2; size <= 16; size <<= 1)
; #pragma unroll
;         for (int stride = size >> 1; stride > 0; stride >>= 1)
; #pragma unroll
;             for (int i = 0; i < 16; ++i) { const int j = i ^ stride;
;                 if (j > i) { if ((i & size) == 0) CE_DESC(k[i], k[j]); else CE_DESC(k[j], k[i]); } }
; }
; __device__ __forceinline__ void peer_tile(const Args& A, LAS unsigned char* lds, int tile) {
;     ...
;                   for (int i = 0; i < 16; ++i) {
;                       const float lo = (float)__builtin_bit_cast(_Float16, (unsigned short)(sw[i] & 0xffffu)), hi = (float)__builtin_bit_cast(_Float16, (unsigned short)(sw[i] >> 16));
;                       const unsigned klo = (f2key(lo) & ~127u) | (unsigned)(127 - (32 * g + 2 * i)), khi = (f2key(hi) & ~127u) | (unsigned)(127 - (32 * g + 2 * i + 1));
;                       if (i < 8) { k0[2 * i] = klo; k0[2 * i + 1] = khi; } else { k1[2 * (i - 8)] = klo; k1[2 * (i - 8) + 1] = khi; } } }
	v_ashrrev_i32_e32 v86, 31, v84
	v_bitop3_b32 v84, v84, v86, s40 bitop3:0x78
	v_xor_b32_e32 v84, 0x80000071, v84
	v_ashrrev_i32_e32 v86, 31, v85
	v_bitop3_b32 v85, v85, v86, s40 bitop3:0x78
	v_xor_b32_e32 v85, 0x80000070, v85
	v_max_u32_e32 v86, v70, v83
	v_min_u32_e32 v83, v70, v83
	v_max_u32_e32 v70, v71, v82
	v_min_u32_e32 v82, v71, v82
	v_max_u32_e32 v71, v72, v85
	v_min_u32_e32 v85, v72, v85
	v_max_u32_e32 v72, v73, v84
	v_min_u32_e32 v84, v73, v84
	v_max_u32_e32 v73, v74, v78
	v_min_u32_e32 v78, v74, v78
	v_max_u32_e32 v74, v75, v76
	v_min_u32_e32 v76, v75, v76
	v_max_u32_e32 v75, v77, v81
	v_min_u32_e32 v81, v77, v81
	v_max_u32_e32 v77, v79, v80
	v_min_u32_e32 v80, v79, v80
	v_max_u32_e32 v79, v86, v74
	v_min_u32_e32 v74, v86, v74
	v_max_u32_e32 v86, v70, v75
	v_min_u32_e32 v75, v70, v75
	v_max_u32_e32 v70, v71, v77
	v_min_u32_e32 v77, v71, v77
	v_max_u32_e32 v71, v72, v73
	v_min_u32_e32 v73, v72, v73
	v_max_u32_e32 v72, v76, v83
	v_min_u32_e32 v83, v76, v83
	v_max_u32_e32 v76, v78, v84
	v_min_u32_e32 v84, v78, v84
	v_max_u32_e32 v78, v80, v85
	v_min_u32_e32 v85, v80, v85
	v_max_u32_e32 v80, v81, v82
	v_min_u32_e32 v82, v81, v82
	v_max_u32_e32 v81, v79, v86
	v_min_u32_e32 v86, v79, v86
	v_max_u32_e32 v79, v70, v71
	v_min_u32_e32 v71, v70, v71
	v_max_u32_e32 v70, v73, v74
	v_min_u32_e32 v74, v73, v74
	v_max_u32_e32 v73, v72, v76
	v_min_u32_e32 v76, v72, v76
	v_max_u32_e32 v72, v75, v77
	v_min_u32_e32 v77, v75, v77
	v_max_u32_e32 v75, v78, v80
	v_min_u32_e32 v80, v78, v80
	v_max_u32_e32 v78, v82, v83
	v_min_u32_e32 v83, v82, v83
	v_max_u32_e32 v82, v84, v85
	v_min_u32_e32 v85, v84, v85
	v_max_u32_e32 v84, v81, v79
	v_min_u32_e32 v79, v81, v79
	v_max_u32_e32 v81, v86, v71
	v_min_u32_e32 v71, v86, v71
	v_max_u32_e32 v86, v70, v75
	v_min_u32_e32 v75, v70, v75
	v_max_u32_e32 v70, v74, v80
	v_min_u32_e32 v80, v74, v80
	v_max_u32_e32 v74, v73, v72
	v_min_u32_e32 v72, v73, v72
	v_max_u32_e32 v73, v76, v77
	v_min_u32_e32 v77, v76, v77
	v_max_u32_e32 v76, v78, v82
	v_min_u32_e32 v82, v78, v82
	v_max_u32_e32 v78, v83, v85
	v_min_u32_e32 v85, v83, v85
	v_max_u32_e32 v83, v81, v79
	v_min_u32_e32 v79, v81, v79
	v_max_u32_e32 v81, v71, v76
	v_min_u32_e32 v76, v71, v76
	v_max_u32_e32 v71, v86, v74
	v_min_u32_e32 v74, v86, v74
	v_max_u32_e32 v86, v70, v72
	v_min_u32_e32 v72, v70, v72
	v_max_u32_e32 v70, v73, v75
	v_min_u32_e32 v75, v73, v75
	v_max_u32_e32 v73, v77, v80
	v_min_u32_e32 v80, v77, v80
	v_max_u32_e32 v77, v78, v82
	v_min_u32_e32 v82, v78, v82
	v_max_u32_e32 v78, v83, v71
	v_min_u32_e32 v71, v83, v71
	v_max_u32_e32 v83, v79, v74
	v_min_u32_e32 v74, v79, v74
	v_max_u32_e32 v79, v86, v70
	v_min_u32_e32 v70, v86, v70
	v_max_u32_e32 v86, v72, v75
	v_min_u32_e32 v75, v72, v75
	v_max_u32_e32 v72, v73, v77
	v_min_u32_e32 v77, v73, v77
	v_max_u32_e32 v73, v80, v82
	v_min_u32_e32 v82, v80, v82
	v_max_u32_e32 v80, v83, v71
	v_min_u32_e32 v71, v83, v71
	v_max_u32_e32 v83, v81, v74
	v_min_u32_e32 v74, v81, v74
	v_max_u32_e32 v81, v72, v76
	v_min_u32_e32 v76, v72, v76
	v_max_u32_e32 v72, v73, v77
	v_min_u32_e32 v77, v73, v77
	v_max_u32_e32 v73, v83, v79
	v_min_u32_e32 v79, v83, v79
	v_max_u32_e32 v83, v74, v70
	v_min_u32_e32 v70, v74, v70
	v_max_u32_e32 v74, v86, v81
	v_min_u32_e32 v81, v86, v81
	v_max_u32_e32 v86, v75, v76
	v_min_u32_e32 v76, v75, v76
	v_max_u32_e32 v75, v73, v71
	v_min_u32_e32 v71, v73, v71
	v_max_u32_e32 v73, v79, v83
	v_min_u32_e32 v83, v79, v83
	v_max_u32_e32 v79, v74, v70
	v_min_u32_e32 v70, v74, v70
	v_max_u32_e32 v74, v81, v86
	v_min_u32_e32 v86, v81, v86
	v_max_u32_e32 v81, v72, v76
	v_min_u32_e32 v76, v72, v76
	v_max_u32_e32 v72, v83, v79
	v_min_u32_e32 v79, v83, v79
	v_max_u32_e32 v83, v70, v74
	v_min_u32_e32 v74, v70, v74
	v_cvt_f32_f16_e32 v70, v8
	v_cvt_f32_f16_sdwa v87, v8 dst_sel:DWORD dst_unused:UNUSED_PAD src0_sel:WORD_1
	v_ashrrev_i32_e32 v88, 31, v70
	v_bitop3_b32 v70, v70, v88, s40 bitop3:0x78
	v_xor_b32_e32 v70, 0x8000006f, v70
	v_ashrrev_i32_e32 v88, 31, v87
	v_bitop3_b32 v87, v87, v88, s40 bitop3:0x78
	v_xor_b32_e32 v87, 0x8000006e, v87
	v_cvt_f32_f16_e32 v88, v9
	v_cvt_f32_f16_sdwa v89, v9 dst_sel:DWORD dst_unused:UNUSED_PAD src0_sel:WORD_1
	v_ashrrev_i32_e32 v90, 31, v88
	v_bitop3_b32 v88, v88, v90, s40 bitop3:0x78
	v_xor_b32_e32 v88, 0x8000006d, v88
	v_ashrrev_i32_e32 v90, 31, v89
	v_bitop3_b32 v89, v89, v90, s40 bitop3:0x78
	v_xor_b32_e32 v89, 0x8000006c, v89
	v_cvt_f32_f16_e32 v90, v10
	v_cvt_f32_f16_sdwa v91, v10 dst_sel:DWORD dst_unused:UNUSED_PAD src0_sel:WORD_1
	v_ashrrev_i32_e32 v92, 31, v90
	v_bitop3_b32 v90, v90, v92, s40 bitop3:0x78
	v_xor_b32_e32 v90, 0x8000006b, v90
	v_ashrrev_i32_e32 v92, 31, v91
	v_bitop3_b32 v91, v91, v92, s40 bitop3:0x78
	v_xor_b32_e32 v91, 0x8000006a, v91
	v_cvt_f32_f16_e32 v92, v11
	v_cvt_f32_f16_sdwa v93, v11 dst_sel:DWORD dst_unused:UNUSED_PAD src0_sel:WORD_1
	v_ashrrev_i32_e32 v94, 31, v92
	v_bitop3_b32 v92, v92, v94, s40 bitop3:0x78
	v_xor_b32_e32 v92, 0x80000069, v92
	v_ashrrev_i32_e32 v94, 31, v93
	v_bitop3_b32 v93, v93, v94, s40 bitop3:0x78
	v_xor_b32_e32 v93, 0x80000068, v93
	v_cvt_f32_f16_e32 v94, v12
	v_cvt_f32_f16_sdwa v95, v12 dst_sel:DWORD dst_unused:UNUSED_PAD src0_sel:WORD_1
	v_ashrrev_i32_e32 v96, 31, v94
	v_bitop3_b32 v94, v94, v96, s40 bitop3:0x78
	v_xor_b32_e32 v94, 0x80000067, v94
	v_ashrrev_i32_e32 v96, 31, v95
	v_bitop3_b32 v95, v95, v96, s40 bitop3:0x78
	v_xor_b32_e32 v95, 0x80000066, v95
	v_cvt_f32_f16_e32 v96, v13
	v_cvt_f32_f16_sdwa v97, v13 dst_sel:DWORD dst_unused:UNUSED_PAD src0_sel:WORD_1
	v_ashrrev_i32_e32 v98, 31, v96
	v_bitop3_b32 v96, v96, v98, s40 bitop3:0x78
	v_xor_b32_e32 v96, 0x80000065, v96
	v_ashrrev_i32_e32 v98, 31, v97
; __device__ __forceinline__ unsigned f2key(float f) { const unsigned u = __float_as_uint(f); return (u & 0x80000000u) ? ~u : (u | 0x80000000u); }
; #define CE_DESC(a, b) do { const unsigned _mx = (a) > (b) ? (a) : (b), _mn = (a) > (b) ? (b) : (a); (a) = _mx; (b) = _mn; } while (0)
; __device__ __forceinline__ void sort16_desc(unsigned (&k)[16]) {
; #pragma unroll
;     for (int size = 2; size <= 16; size <<= 1)
; #pragma unroll
;         for (int stride = size >> 1; stride > 0; stride >>= 1)
; #pragma unroll
;             for (int i = 0; i < 16; ++i) { const int j = i ^ stride;
;                 if (j > i) { if ((i & size) == 0) CE_DESC(k[i], k[j]); else CE_DESC(k[j], k[i]); } }
; }
; __device__ __forceinline__ void merge16(unsigned (&a)[16], const unsigned (&b)[16]) {
; #pragma unroll
;     for (int i = 0; i < 16; ++i) a[i] = a[i] > b[15 - i] ? a[i] : b[15 - i];
; #pragma unroll
;     for (int stride = 8; stride > 0; stride >>= 1)
; #pragma unroll
;         for (int i = 0; i < 16; ++i) { const int j = i ^ stride; if (j > i) CE_DESC(a[i], a[j]); }
; }
; __device__ __forceinline__ void peer_tile(const Args& A, LAS unsigned char* lds, int tile) {
;     ...
;                   for (int i = 0; i < 16; ++i) {
;                       const float lo = (float)__builtin_bit_cast(_Float16, (unsigned short)(sw[i] & 0xffffu)), hi = (float)__builtin_bit_cast(_Float16, (unsigned short)(sw[i] >> 16));
;                       const unsigned klo = (f2key(lo) & ~127u) | (unsigned)(127 - (32 * g + 2 * i)), khi = (f2key(hi) & ~127u) | (unsigned)(127 - (32 * g + 2 * i + 1));
;                       if (i < 8) { k0[2 * i] = klo; k0[2 * i + 1] = khi; } else { k1[2 * (i - 8)] = klo; k1[2 * (i - 8) + 1] = khi; } } }
	v_bitop3_b32 v97, v97, v98, s40 bitop3:0x78
	v_xor_b32_e32 v97, 0x80000064, v97
	v_cvt_f32_f16_e32 v98, v14
	v_cvt_f32_f16_sdwa v99, v14 dst_sel:DWORD dst_unused:UNUSED_PAD src0_sel:WORD_1
	v_ashrrev_i32_e32 v100, 31, v98
	v_bitop3_b32 v98, v98, v100, s40 bitop3:0x78
	v_xor_b32_e32 v98, 0x80000063, v98
	v_ashrrev_i32_e32 v100, 31, v99
	v_bitop3_b32 v99, v99, v100, s40 bitop3:0x78
	v_xor_b32_e32 v99, 0x80000062, v99
	v_cvt_f32_f16_e32 v100, v15
	v_cvt_f32_f16_sdwa v101, v15 dst_sel:DWORD dst_unused:UNUSED_PAD src0_sel:WORD_1
	v_ashrrev_i32_e32 v102, 31, v100
	v_bitop3_b32 v100, v100, v102, s40 bitop3:0x78
	v_xor_b32_e32 v100, 0x80000061, v100
	v_ashrrev_i32_e32 v102, 31, v101
	v_bitop3_b32 v101, v101, v102, s40 bitop3:0x78
	v_xor_b32_e32 v101, 0x80000060, v101
	v_max_u32_e32 v102, v70, v99
	v_min_u32_e32 v99, v70, v99
	v_max_u32_e32 v70, v87, v98
	v_min_u32_e32 v98, v87, v98
	v_max_u32_e32 v87, v88, v101
	v_min_u32_e32 v101, v88, v101
	v_max_u32_e32 v88, v89, v100
	v_min_u32_e32 v100, v89, v100
	v_max_u32_e32 v89, v90, v94
	v_min_u32_e32 v94, v90, v94
	v_max_u32_e32 v90, v91, v92
	v_min_u32_e32 v92, v91, v92
	v_max_u32_e32 v91, v93, v97
	v_min_u32_e32 v97, v93, v97
	v_max_u32_e32 v93, v95, v96
	v_min_u32_e32 v96, v95, v96
	v_max_u32_e32 v95, v102, v90
	v_min_u32_e32 v90, v102, v90
	v_max_u32_e32 v102, v70, v91
	v_min_u32_e32 v91, v70, v91
	v_max_u32_e32 v70, v87, v93
	v_min_u32_e32 v93, v87, v93
	v_max_u32_e32 v87, v88, v89
	v_min_u32_e32 v89, v88, v89
	v_max_u32_e32 v88, v92, v99
	v_min_u32_e32 v99, v92, v99
	v_max_u32_e32 v92, v94, v100
	v_min_u32_e32 v100, v94, v100
	v_max_u32_e32 v94, v96, v101
	v_min_u32_e32 v101, v96, v101
	v_max_u32_e32 v96, v97, v98
	v_min_u32_e32 v98, v97, v98
	v_max_u32_e32 v97, v95, v102
	v_min_u32_e32 v102, v95, v102
	v_max_u32_e32 v95, v70, v87
	v_min_u32_e32 v87, v70, v87
	v_max_u32_e32 v70, v89, v90
	v_min_u32_e32 v90, v89, v90
	v_max_u32_e32 v89, v88, v92
	v_min_u32_e32 v92, v88, v92
	v_max_u32_e32 v88, v91, v93
	v_min_u32_e32 v93, v91, v93
	v_max_u32_e32 v91, v94, v96
	v_min_u32_e32 v96, v94, v96
	v_max_u32_e32 v94, v98, v99
	v_min_u32_e32 v99, v98, v99
	v_max_u32_e32 v98, v100, v101
	v_min_u32_e32 v101, v100, v101
	v_max_u32_e32 v100, v97, v95
	v_min_u32_e32 v95, v97, v95
	v_max_u32_e32 v97, v102, v87
	v_min_u32_e32 v87, v102, v87
	v_max_u32_e32 v102, v70, v91
	v_min_u32_e32 v91, v70, v91
	v_max_u32_e32 v70, v90, v96
	v_min_u32_e32 v96, v90, v96
	v_max_u32_e32 v90, v89, v88
	v_min_u32_e32 v88, v89, v88
	v_max_u32_e32 v89, v92, v93
	v_min_u32_e32 v93, v92, v93
	v_max_u32_e32 v92, v94, v98
	v_min_u32_e32 v98, v94, v98
	v_max_u32_e32 v94, v99, v101
	v_min_u32_e32 v101, v99, v101
	v_max_u32_e32 v99, v97, v95
	v_min_u32_e32 v95, v97, v95
	v_max_u32_e32 v97, v87, v92
	v_min_u32_e32 v92, v87, v92
	v_max_u32_e32 v87, v102, v90
	v_min_u32_e32 v90, v102, v90
	v_max_u32_e32 v102, v70, v88
	v_min_u32_e32 v88, v70, v88
	v_max_u32_e32 v70, v89, v91
	v_min_u32_e32 v91, v89, v91
	v_max_u32_e32 v89, v93, v96
	v_min_u32_e32 v96, v93, v96
	v_max_u32_e32 v93, v94, v98
	v_min_u32_e32 v98, v94, v98
	v_max_u32_e32 v94, v99, v87
	v_min_u32_e32 v87, v99, v87
	v_max_u32_e32 v99, v95, v90
	v_min_u32_e32 v90, v95, v90
	v_max_u32_e32 v95, v102, v70
	v_min_u32_e32 v70, v102, v70
	v_max_u32_e32 v102, v88, v91
	v_min_u32_e32 v91, v88, v91
	v_max_u32_e32 v88, v89, v93
	v_min_u32_e32 v93, v89, v93
	v_max_u32_e32 v89, v96, v98
	v_min_u32_e32 v98, v96, v98
	v_max_u32_e32 v96, v99, v87
	v_min_u32_e32 v87, v99, v87
	v_max_u32_e32 v99, v97, v90
	v_min_u32_e32 v90, v97, v90
	v_max_u32_e32 v97, v88, v92
	v_min_u32_e32 v92, v88, v92
	v_max_u32_e32 v88, v89, v93
	v_min_u32_e32 v93, v89, v93
	v_max_u32_e32 v89, v99, v95
	v_min_u32_e32 v95, v99, v95
	v_max_u32_e32 v99, v90, v70
	v_min_u32_e32 v70, v90, v70
	v_max_u32_e32 v90, v102, v97
	v_min_u32_e32 v97, v102, v97
	v_max_u32_e32 v102, v91, v92
	v_min_u32_e32 v92, v91, v92
	v_max_u32_e32 v91, v89, v87
	v_min_u32_e32 v87, v89, v87
	v_max_u32_e32 v89, v95, v99
	v_min_u32_e32 v99, v95, v99
	v_max_u32_e32 v95, v90, v70
	v_min_u32_e32 v70, v90, v70
	v_max_u32_e32 v90, v97, v102
	v_min_u32_e32 v102, v97, v102
	v_max_u32_e32 v97, v88, v92
	v_min_u32_e32 v92, v88, v92
	v_max_u32_e32 v88, v99, v95
	v_min_u32_e32 v95, v99, v95
	v_max_u32_e32 v99, v70, v90
	v_min_u32_e32 v90, v70, v90
	v_max_u32_e32 v84, v84, v101
	v_max_u32_e32 v78, v78, v98
	v_max_u32_e32 v80, v80, v93
	v_max_u32_e32 v75, v75, v92
	v_max_u32_e32 v71, v71, v97
	v_max_u32_e32 v73, v73, v102
	v_max_u32_e32 v72, v72, v90
	v_max_u32_e32 v79, v79, v99
	v_max_u32_e32 v83, v83, v95
	v_max_u32_e32 v74, v74, v88
	v_max_u32_e32 v86, v86, v89
	v_max_u32_e32 v81, v81, v87
	v_max_u32_e32 v76, v76, v91
	v_max_u32_e32 v77, v77, v96
	v_max_u32_e32 v82, v82, v94
	v_max_u32_e32 v85, v85, v100
	v_max_u32_e32 v101, v84, v83
	v_min_u32_e32 v83, v84, v83
	v_max_u32_e32 v84, v78, v74
	v_min_u32_e32 v74, v78, v74
	v_max_u32_e32 v78, v80, v86
	v_min_u32_e32 v86, v80, v86
	v_max_u32_e32 v80, v75, v81
	v_min_u32_e32 v81, v75, v81
	v_max_u32_e32 v75, v71, v76
	v_min_u32_e32 v76, v71, v76
	v_max_u32_e32 v71, v73, v77
	v_min_u32_e32 v77, v73, v77
	v_max_u32_e32 v73, v72, v82
	v_min_u32_e32 v82, v72, v82
	v_max_u32_e32 v72, v79, v85
	v_min_u32_e32 v85, v79, v85
	v_max_u32_e32 v79, v101, v75
	v_min_u32_e32 v75, v101, v75
	v_max_u32_e32 v101, v84, v71
	v_min_u32_e32 v71, v84, v71
	v_max_u32_e32 v84, v78, v73
	v_min_u32_e32 v73, v78, v73
	v_max_u32_e32 v78, v80, v72
	v_min_u32_e32 v72, v80, v72
	v_max_u32_e32 v80, v83, v76
	v_min_u32_e32 v76, v83, v76
	v_max_u32_e32 v83, v74, v77
	v_min_u32_e32 v77, v74, v77
	v_max_u32_e32 v74, v86, v82
	v_min_u32_e32 v82, v86, v82
; __device__ __forceinline__ unsigned f2key(float f) { const unsigned u = __float_as_uint(f); return (u & 0x80000000u) ? ~u : (u | 0x80000000u); }
; #define CE_DESC(a, b) do { const unsigned _mx = (a) > (b) ? (a) : (b), _mn = (a) > (b) ? (b) : (a); (a) = _mx; (b) = _mn; } while (0)
; __device__ __forceinline__ void merge16(unsigned (&a)[16], const unsigned (&b)[16]) {
; #pragma unroll
;     for (int i = 0; i < 16; ++i) a[i] = a[i] > b[15 - i] ? a[i] : b[15 - i];
; #pragma unroll
;     for (int stride = 8; stride > 0; stride >>= 1)
; #pragma unroll
;         for (int i = 0; i < 16; ++i) { const int j = i ^ stride; if (j > i) CE_DESC(a[i], a[j]); }
; }
; __device__ __forceinline__ void peer_tile(const Args& A, LAS unsigned char* lds, int tile) {
;     ...
;                   for (int i = 0; i < 16; ++i) {
;                       const float lo = (float)__builtin_bit_cast(_Float16, (unsigned short)(sw[i] & 0xffffu)), hi = (float)__builtin_bit_cast(_Float16, (unsigned short)(sw[i] >> 16));
;                       const unsigned klo = (f2key(lo) & ~127u) | (unsigned)(127 - (32 * g + 2 * i)), khi = (f2key(hi) & ~127u) | (unsigned)(127 - (32 * g + 2 * i + 1));
;                       if (i < 8) { k0[2 * i] = klo; k0[2 * i + 1] = khi; } else { k1[2 * (i - 8)] = klo; k1[2 * (i - 8) + 1] = khi; } } }
	v_max_u32_e32 v86, v81, v85
	v_min_u32_e32 v85, v81, v85
	v_max_u32_e32 v81, v79, v84
	v_min_u32_e32 v84, v79, v84
	v_max_u32_e32 v79, v101, v78
	v_min_u32_e32 v78, v101, v78
	v_max_u32_e32 v101, v75, v73
	v_min_u32_e32 v73, v75, v73
	v_max_u32_e32 v75, v71, v72
	v_min_u32_e32 v72, v71, v72
	v_max_u32_e32 v71, v80, v74
	v_min_u32_e32 v74, v80, v74
	v_max_u32_e32 v80, v83, v86
	v_min_u32_e32 v86, v83, v86
	v_max_u32_e32 v83, v76, v82
	v_min_u32_e32 v82, v76, v82
	v_max_u32_e32 v76, v77, v85
	v_min_u32_e32 v85, v77, v85
	v_max_u32_e32 v77, v81, v79
	v_min_u32_e32 v79, v81, v79
	v_max_u32_e32 v81, v84, v78
	v_min_u32_e32 v78, v84, v78
	v_max_u32_e32 v84, v101, v75
	v_min_u32_e32 v75, v101, v75
	v_max_u32_e32 v101, v73, v72
	v_min_u32_e32 v72, v73, v72
	v_max_u32_e32 v73, v71, v80
	v_min_u32_e32 v80, v71, v80
	v_max_u32_e32 v71, v74, v86
	v_min_u32_e32 v86, v74, v86
	v_max_u32_e32 v74, v83, v76
	v_min_u32_e32 v76, v83, v76
	v_max_u32_e32 v83, v82, v85
	v_min_u32_e32 v85, v82, v85
	v_cvt_f32_f16_e32 v82, v16
	v_cvt_f32_f16_sdwa v98, v16 dst_sel:DWORD dst_unused:UNUSED_PAD src0_sel:WORD_1
	v_ashrrev_i32_e32 v93, 31, v82
	v_bitop3_b32 v82, v82, v93, s40 bitop3:0x78
	v_xor_b32_e32 v82, 0x8000005f, v82
	v_ashrrev_i32_e32 v93, 31, v98
	v_bitop3_b32 v98, v98, v93, s40 bitop3:0x78
	v_xor_b32_e32 v98, 0x8000005e, v98
	v_cvt_f32_f16_e32 v93, v17
	v_cvt_f32_f16_sdwa v92, v17 dst_sel:DWORD dst_unused:UNUSED_PAD src0_sel:WORD_1
	v_ashrrev_i32_e32 v97, 31, v93
	v_bitop3_b32 v93, v93, v97, s40 bitop3:0x78
	v_xor_b32_e32 v93, 0x8000005d, v93
	v_ashrrev_i32_e32 v97, 31, v92
	v_bitop3_b32 v92, v92, v97, s40 bitop3:0x78
	v_xor_b32_e32 v92, 0x8000005c, v92
	v_cvt_f32_f16_e32 v97, v18
	v_cvt_f32_f16_sdwa v102, v18 dst_sel:DWORD dst_unused:UNUSED_PAD src0_sel:WORD_1
	v_ashrrev_i32_e32 v90, 31, v97
	v_bitop3_b32 v97, v97, v90, s40 bitop3:0x78
	v_xor_b32_e32 v97, 0x8000005b, v97
	v_ashrrev_i32_e32 v90, 31, v102
	v_bitop3_b32 v102, v102, v90, s40 bitop3:0x78
	v_xor_b32_e32 v102, 0x8000005a, v102
	v_cvt_f32_f16_e32 v90, v19
	v_cvt_f32_f16_sdwa v99, v19 dst_sel:DWORD dst_unused:UNUSED_PAD src0_sel:WORD_1
	v_ashrrev_i32_e32 v95, 31, v90
	v_bitop3_b32 v90, v90, v95, s40 bitop3:0x78
	v_xor_b32_e32 v90, 0x80000059, v90
	v_ashrrev_i32_e32 v95, 31, v99
	v_bitop3_b32 v99, v99, v95, s40 bitop3:0x78
	v_xor_b32_e32 v99, 0x80000058, v99
	v_cvt_f32_f16_e32 v95, v20
	v_cvt_f32_f16_sdwa v88, v20 dst_sel:DWORD dst_unused:UNUSED_PAD src0_sel:WORD_1
	v_ashrrev_i32_e32 v89, 31, v95
	v_bitop3_b32 v95, v95, v89, s40 bitop3:0x78
	v_xor_b32_e32 v95, 0x80000057, v95
	v_ashrrev_i32_e32 v89, 31, v88
	v_bitop3_b32 v88, v88, v89, s40 bitop3:0x78
	v_xor_b32_e32 v88, 0x80000056, v88
	v_cvt_f32_f16_e32 v89, v21
	v_cvt_f32_f16_sdwa v87, v21 dst_sel:DWORD dst_unused:UNUSED_PAD src0_sel:WORD_1
	v_ashrrev_i32_e32 v91, 31, v89
	v_bitop3_b32 v89, v89, v91, s40 bitop3:0x78
	v_xor_b32_e32 v89, 0x80000055, v89
	v_ashrrev_i32_e32 v91, 31, v87
	v_bitop3_b32 v87, v87, v91, s40 bitop3:0x78
	v_xor_b32_e32 v87, 0x80000054, v87
	v_cvt_f32_f16_e32 v91, v22
	v_cvt_f32_f16_sdwa v96, v22 dst_sel:DWORD dst_unused:UNUSED_PAD src0_sel:WORD_1
	v_ashrrev_i32_e32 v94, 31, v91
	v_bitop3_b32 v91, v91, v94, s40 bitop3:0x78
	v_xor_b32_e32 v91, 0x80000053, v91
	v_ashrrev_i32_e32 v94, 31, v96
	v_bitop3_b32 v96, v96, v94, s40 bitop3:0x78
	v_xor_b32_e32 v96, 0x80000052, v96
	v_cvt_f32_f16_e32 v94, v23
	v_cvt_f32_f16_sdwa v100, v23 dst_sel:DWORD dst_unused:UNUSED_PAD src0_sel:WORD_1
	v_ashrrev_i32_e32 v70, 31, v94
	v_bitop3_b32 v94, v94, v70, s40 bitop3:0x78
	v_xor_b32_e32 v94, 0x80000051, v94
	v_ashrrev_i32_e32 v70, 31, v100
	v_bitop3_b32 v100, v100, v70, s40 bitop3:0x78
	v_xor_b32_e32 v100, 0x80000050, v100
	v_max_u32_e32 v70, v82, v96
	v_min_u32_e32 v96, v82, v96
	v_max_u32_e32 v82, v98, v91
	v_min_u32_e32 v91, v98, v91
	v_max_u32_e32 v98, v93, v100
	v_min_u32_e32 v100, v93, v100
	v_max_u32_e32 v93, v92, v94
	v_min_u32_e32 v94, v92, v94
	v_max_u32_e32 v92, v97, v95
	v_min_u32_e32 v95, v97, v95
	v_max_u32_e32 v97, v102, v90
	v_min_u32_e32 v90, v102, v90
	v_max_u32_e32 v102, v99, v87
	v_min_u32_e32 v87, v99, v87
	v_max_u32_e32 v99, v88, v89
	v_min_u32_e32 v89, v88, v89
	v_max_u32_e32 v88, v70, v97
	v_min_u32_e32 v97, v70, v97
	v_max_u32_e32 v70, v82, v102
	v_min_u32_e32 v102, v82, v102
	v_max_u32_e32 v82, v98, v99
	v_min_u32_e32 v99, v98, v99
	v_max_u32_e32 v98, v93, v92
	v_min_u32_e32 v92, v93, v92
	v_max_u32_e32 v93, v90, v96
	v_min_u32_e32 v96, v90, v96
	v_max_u32_e32 v90, v95, v94
	v_min_u32_e32 v94, v95, v94
	v_max_u32_e32 v95, v89, v100
	v_min_u32_e32 v100, v89, v100
	v_max_u32_e32 v89, v87, v91
	v_min_u32_e32 v91, v87, v91
	v_max_u32_e32 v87, v88, v70
	v_min_u32_e32 v70, v88, v70
	v_max_u32_e32 v88, v82, v98
	v_min_u32_e32 v98, v82, v98
	v_max_u32_e32 v82, v92, v97
	v_min_u32_e32 v97, v92, v97
	v_max_u32_e32 v92, v93, v90
	v_min_u32_e32 v90, v93, v90
	v_max_u32_e32 v93, v102, v99
	v_min_u32_e32 v99, v102, v99
	v_max_u32_e32 v102, v95, v89
	v_min_u32_e32 v89, v95, v89
	v_max_u32_e32 v95, v91, v96
	v_min_u32_e32 v96, v91, v96
	v_max_u32_e32 v91, v94, v100
	v_min_u32_e32 v100, v94, v100
	v_max_u32_e32 v94, v87, v88
	v_min_u32_e32 v88, v87, v88
	v_max_u32_e32 v87, v70, v98
	v_min_u32_e32 v98, v70, v98
	v_max_u32_e32 v70, v82, v102
	v_min_u32_e32 v102, v82, v102
	v_max_u32_e32 v82, v97, v89
	v_min_u32_e32 v89, v97, v89
	v_max_u32_e32 v97, v92, v93
	v_min_u32_e32 v93, v92, v93
	v_max_u32_e32 v92, v90, v99
	v_min_u32_e32 v99, v90, v99
	v_max_u32_e32 v90, v95, v91
	v_min_u32_e32 v91, v95, v91
	v_max_u32_e32 v95, v96, v100
	v_min_u32_e32 v100, v96, v100
	v_max_u32_e32 v96, v87, v88
	v_min_u32_e32 v88, v87, v88
	v_max_u32_e32 v87, v98, v90
; __device__ __forceinline__ unsigned f2key(float f) { const unsigned u = __float_as_uint(f); return (u & 0x80000000u) ? ~u : (u | 0x80000000u); }
; #define CE_DESC(a, b) do { const unsigned _mx = (a) > (b) ? (a) : (b), _mn = (a) > (b) ? (b) : (a); (a) = _mx; (b) = _mn; } while (0)
; __device__ __forceinline__ void sort16_desc(unsigned (&k)[16]) {
; #pragma unroll
;     for (int size = 2; size <= 16; size <<= 1)
; #pragma unroll
;         for (int stride = size >> 1; stride > 0; stride >>= 1)
; #pragma unroll
;             for (int i = 0; i < 16; ++i) { const int j = i ^ stride;
;                 if (j > i) { if ((i & size) == 0) CE_DESC(k[i], k[j]); else CE_DESC(k[j], k[i]); } }
; }
; __device__ __forceinline__ void merge16(unsigned (&a)[16], const unsigned (&b)[16]) {
; #pragma unroll
;     for (int i = 0; i < 16; ++i) a[i] = a[i] > b[15 - i] ? a[i] : b[15 - i];
; #pragma unroll
;     for (int stride = 8; stride > 0; stride >>= 1)
; #pragma unroll
;         for (int i = 0; i < 16; ++i) { const int j = i ^ stride; if (j > i) CE_DESC(a[i], a[j]); }
; }
; __device__ __forceinline__ void peer_tile(const Args& A, LAS unsigned char* lds, int tile) {
;     ...
;                   for (int i = 0; i < 16; ++i) {
;                       const float lo = (float)__builtin_bit_cast(_Float16, (unsigned short)(sw[i] & 0xffffu)), hi = (float)__builtin_bit_cast(_Float16, (unsigned short)(sw[i] >> 16));
;                       const unsigned klo = (f2key(lo) & ~127u) | (unsigned)(127 - (32 * g + 2 * i)), khi = (f2key(hi) & ~127u) | (unsigned)(127 - (32 * g + 2 * i + 1));
;                       if (i < 8) { k0[2 * i] = klo; k0[2 * i + 1] = khi; } else { k1[2 * (i - 8)] = klo; k1[2 * (i - 8) + 1] = khi; } } }
	v_min_u32_e32 v90, v98, v90
	v_max_u32_e32 v98, v70, v97
	v_min_u32_e32 v97, v70, v97
	v_max_u32_e32 v70, v82, v93
	v_min_u32_e32 v93, v82, v93
	v_max_u32_e32 v82, v92, v102
	v_min_u32_e32 v102, v92, v102
	v_max_u32_e32 v92, v99, v89
	v_min_u32_e32 v89, v99, v89
	v_max_u32_e32 v99, v95, v91
	v_min_u32_e32 v91, v95, v91
	v_max_u32_e32 v95, v96, v98
	v_min_u32_e32 v98, v96, v98
	v_max_u32_e32 v96, v88, v97
	v_min_u32_e32 v97, v88, v97
	v_max_u32_e32 v88, v70, v82
	v_min_u32_e32 v82, v70, v82
	v_max_u32_e32 v70, v93, v102
	v_min_u32_e32 v102, v93, v102
	v_max_u32_e32 v93, v92, v99
	v_min_u32_e32 v99, v92, v99
	v_max_u32_e32 v92, v89, v91
	v_min_u32_e32 v91, v89, v91
	v_max_u32_e32 v89, v96, v98
	v_min_u32_e32 v98, v96, v98
	v_max_u32_e32 v96, v87, v97
	v_min_u32_e32 v97, v87, v97
	v_max_u32_e32 v87, v93, v90
	v_min_u32_e32 v90, v93, v90
	v_max_u32_e32 v93, v92, v99
	v_min_u32_e32 v99, v92, v99
	v_max_u32_e32 v92, v96, v88
	v_min_u32_e32 v88, v96, v88
	v_max_u32_e32 v96, v97, v82
	v_min_u32_e32 v82, v97, v82
	v_max_u32_e32 v97, v70, v87
	v_min_u32_e32 v87, v70, v87
	v_max_u32_e32 v70, v102, v90
	v_min_u32_e32 v90, v102, v90
	v_max_u32_e32 v102, v92, v98
	v_min_u32_e32 v98, v92, v98
	v_max_u32_e32 v92, v88, v96
	v_min_u32_e32 v96, v88, v96
	v_max_u32_e32 v88, v97, v82
	v_min_u32_e32 v82, v97, v82
	v_max_u32_e32 v97, v87, v70
	v_min_u32_e32 v70, v87, v70
	v_max_u32_e32 v87, v93, v90
	v_min_u32_e32 v90, v93, v90
	v_max_u32_e32 v93, v96, v88
	v_min_u32_e32 v88, v96, v88
	v_max_u32_e32 v96, v82, v97
	v_min_u32_e32 v97, v82, v97
	v_max_u32_e32 v77, v77, v100
	v_max_u32_e32 v79, v79, v91
	v_max_u32_e32 v81, v81, v99
	v_max_u32_e32 v78, v78, v90
	v_max_u32_e32 v84, v84, v87
	v_max_u32_e32 v75, v75, v70
	v_max_u32_e32 v101, v101, v97
	v_max_u32_e32 v72, v72, v96
	v_max_u32_e32 v73, v73, v88
	v_max_u32_e32 v80, v80, v93
	v_max_u32_e32 v71, v71, v92
	v_max_u32_e32 v86, v86, v98
	v_max_u32_e32 v74, v74, v102
	v_max_u32_e32 v76, v76, v89
	v_max_u32_e32 v83, v83, v95
	v_max_u32_e32 v85, v85, v94
	v_max_u32_e32 v100, v77, v73
	v_min_u32_e32 v73, v77, v73
	v_max_u32_e32 v77, v79, v80
	v_min_u32_e32 v80, v79, v80
	v_max_u32_e32 v79, v81, v71
	v_min_u32_e32 v71, v81, v71
	v_max_u32_e32 v81, v78, v86
	v_min_u32_e32 v86, v78, v86
	v_max_u32_e32 v78, v84, v74
	v_min_u32_e32 v74, v84, v74
	v_max_u32_e32 v84, v75, v76
	v_min_u32_e32 v76, v75, v76
	v_max_u32_e32 v75, v101, v83
	v_min_u32_e32 v83, v101, v83
	v_max_u32_e32 v101, v72, v85
	v_min_u32_e32 v85, v72, v85
	v_max_u32_e32 v72, v100, v78
	v_min_u32_e32 v78, v100, v78
	v_max_u32_e32 v100, v77, v84
	v_min_u32_e32 v84, v77, v84
	v_max_u32_e32 v77, v79, v75
	v_min_u32_e32 v75, v79, v75
	v_max_u32_e32 v79, v81, v101
	v_min_u32_e32 v101, v81, v101
	v_max_u32_e32 v81, v73, v74
	v_min_u32_e32 v74, v73, v74
	v_max_u32_e32 v73, v80, v76
	v_min_u32_e32 v76, v80, v76
	v_max_u32_e32 v80, v71, v83
	v_min_u32_e32 v83, v71, v83
	v_max_u32_e32 v71, v86, v85
	v_min_u32_e32 v85, v86, v85
	v_max_u32_e32 v86, v72, v77
	v_min_u32_e32 v77, v72, v77
	v_max_u32_e32 v72, v100, v79
	v_min_u32_e32 v79, v100, v79
	v_max_u32_e32 v100, v78, v75
	v_min_u32_e32 v75, v78, v75
	v_max_u32_e32 v78, v84, v101
	v_min_u32_e32 v101, v84, v101
	v_max_u32_e32 v84, v81, v80
	v_min_u32_e32 v80, v81, v80
	v_max_u32_e32 v81, v73, v71
	v_min_u32_e32 v71, v73, v71
	v_max_u32_e32 v73, v74, v83
	v_min_u32_e32 v83, v74, v83
	v_max_u32_e32 v74, v76, v85
	v_min_u32_e32 v85, v76, v85
	v_max_u32_e32 v76, v86, v72
	v_min_u32_e32 v72, v86, v72
	v_max_u32_e32 v86, v77, v79
	v_min_u32_e32 v79, v77, v79
	v_max_u32_e32 v77, v100, v78
	v_min_u32_e32 v78, v100, v78
	v_max_u32_e32 v100, v75, v101
	v_min_u32_e32 v101, v75, v101
	v_max_u32_e32 v75, v84, v81
	v_min_u32_e32 v81, v84, v81
	v_max_u32_e32 v84, v80, v71
	v_min_u32_e32 v71, v80, v71
	v_max_u32_e32 v80, v73, v74
	v_min_u32_e32 v74, v73, v74
	v_max_u32_e32 v73, v83, v85
	v_min_u32_e32 v85, v83, v85
	v_cvt_f32_f16_e32 v83, v24
	v_cvt_f32_f16_sdwa v91, v24 dst_sel:DWORD dst_unused:UNUSED_PAD src0_sel:WORD_1
	v_ashrrev_i32_e32 v99, 31, v83
	v_bitop3_b32 v83, v83, v99, s40 bitop3:0x78
	v_xor_b32_e32 v83, 0x8000004f, v83
	v_ashrrev_i32_e32 v99, 31, v91
	v_bitop3_b32 v91, v91, v99, s40 bitop3:0x78
	v_xor_b32_e32 v91, 0x8000004e, v91
	v_cvt_f32_f16_e32 v99, v25
	v_cvt_f32_f16_sdwa v90, v25 dst_sel:DWORD dst_unused:UNUSED_PAD src0_sel:WORD_1
	v_ashrrev_i32_e32 v87, 31, v99
	v_bitop3_b32 v99, v99, v87, s40 bitop3:0x78
	v_xor_b32_e32 v99, 0x8000004d, v99
	v_ashrrev_i32_e32 v87, 31, v90
	v_bitop3_b32 v90, v90, v87, s40 bitop3:0x78
	v_xor_b32_e32 v90, 0x8000004c, v90
	v_cvt_f32_f16_e32 v87, v26
	v_cvt_f32_f16_sdwa v70, v26 dst_sel:DWORD dst_unused:UNUSED_PAD src0_sel:WORD_1
	v_ashrrev_i32_e32 v97, 31, v87
	v_bitop3_b32 v87, v87, v97, s40 bitop3:0x78
	v_xor_b32_e32 v87, 0x8000004b, v87
	v_ashrrev_i32_e32 v97, 31, v70
	v_bitop3_b32 v70, v70, v97, s40 bitop3:0x78
	v_xor_b32_e32 v70, 0x8000004a, v70
	v_cvt_f32_f16_e32 v97, v27
	v_cvt_f32_f16_sdwa v96, v27 dst_sel:DWORD dst_unused:UNUSED_PAD src0_sel:WORD_1
	v_ashrrev_i32_e32 v88, 31, v97
	v_bitop3_b32 v97, v97, v88, s40 bitop3:0x78
	v_xor_b32_e32 v97, 0x80000049, v97
	v_ashrrev_i32_e32 v88, 31, v96
	v_bitop3_b32 v96, v96, v88, s40 bitop3:0x78
	v_xor_b32_e32 v96, 0x80000048, v96
	v_cvt_f32_f16_e32 v88, v28
	v_cvt_f32_f16_sdwa v93, v28 dst_sel:DWORD dst_unused:UNUSED_PAD src0_sel:WORD_1
	v_ashrrev_i32_e32 v92, 31, v88
	v_bitop3_b32 v88, v88, v92, s40 bitop3:0x78
	v_xor_b32_e32 v88, 0x80000047, v88
	v_ashrrev_i32_e32 v92, 31, v93
	v_bitop3_b32 v93, v93, v92, s40 bitop3:0x78
	v_xor_b32_e32 v93, 0x80000046, v93
	v_cvt_f32_f16_e32 v92, v29
	v_cvt_f32_f16_sdwa v98, v29 dst_sel:DWORD dst_unused:UNUSED_PAD src0_sel:WORD_1
; __device__ __forceinline__ unsigned f2key(float f) { const unsigned u = __float_as_uint(f); return (u & 0x80000000u) ? ~u : (u | 0x80000000u); }
; #define CE_DESC(a, b) do { const unsigned _mx = (a) > (b) ? (a) : (b), _mn = (a) > (b) ? (b) : (a); (a) = _mx; (b) = _mn; } while (0)
; __device__ __forceinline__ void sort16_desc(unsigned (&k)[16]) {
; #pragma unroll
;     for (int size = 2; size <= 16; size <<= 1)
; #pragma unroll
;         for (int stride = size >> 1; stride > 0; stride >>= 1)
; #pragma unroll
;             for (int i = 0; i < 16; ++i) { const int j = i ^ stride;
;                 if (j > i) { if ((i & size) == 0) CE_DESC(k[i], k[j]); else CE_DESC(k[j], k[i]); } }
; }
; __device__ __forceinline__ void merge16(unsigned (&a)[16], const unsigned (&b)[16]) {
; #pragma unroll
;     for (int i = 0; i < 16; ++i) a[i] = a[i] > b[15 - i] ? a[i] : b[15 - i];
; #pragma unroll
;     for (int stride = 8; stride > 0; stride >>= 1)
; #pragma unroll
;         for (int i = 0; i < 16; ++i) { const int j = i ^ stride; if (j > i) CE_DESC(a[i], a[j]); }
; }
; __device__ __forceinline__ void peer_tile(const Args& A, LAS unsigned char* lds, int tile) {
;     ...
;                   for (int i = 0; i < 16; ++i) {
;                       const float lo = (float)__builtin_bit_cast(_Float16, (unsigned short)(sw[i] & 0xffffu)), hi = (float)__builtin_bit_cast(_Float16, (unsigned short)(sw[i] >> 16));
;                       const unsigned klo = (f2key(lo) & ~127u) | (unsigned)(127 - (32 * g + 2 * i)), khi = (f2key(hi) & ~127u) | (unsigned)(127 - (32 * g + 2 * i + 1));
;                       if (i < 8) { k0[2 * i] = klo; k0[2 * i + 1] = khi; } else { k1[2 * (i - 8)] = klo; k1[2 * (i - 8) + 1] = khi; } } }
	v_ashrrev_i32_e32 v102, 31, v92
	v_bitop3_b32 v92, v92, v102, s40 bitop3:0x78
	v_xor_b32_e32 v92, 0x80000045, v92
	v_ashrrev_i32_e32 v102, 31, v98
	v_bitop3_b32 v98, v98, v102, s40 bitop3:0x78
	v_xor_b32_e32 v98, 0x80000044, v98
	v_cvt_f32_f16_e32 v102, v30
	v_cvt_f32_f16_sdwa v89, v30 dst_sel:DWORD dst_unused:UNUSED_PAD src0_sel:WORD_1
	v_ashrrev_i32_e32 v95, 31, v102
	v_bitop3_b32 v102, v102, v95, s40 bitop3:0x78
	v_xor_b32_e32 v102, 0x80000043, v102
	v_ashrrev_i32_e32 v95, 31, v89
	v_bitop3_b32 v89, v89, v95, s40 bitop3:0x78
	v_xor_b32_e32 v89, 0x80000042, v89
	v_cvt_f32_f16_e32 v95, v31
	v_cvt_f32_f16_sdwa v94, v31 dst_sel:DWORD dst_unused:UNUSED_PAD src0_sel:WORD_1
	v_ashrrev_i32_e32 v82, 31, v95
	v_bitop3_b32 v95, v95, v82, s40 bitop3:0x78
	v_xor_b32_e32 v95, 0x80000041, v95
	v_ashrrev_i32_e32 v82, 31, v94
	v_bitop3_b32 v94, v94, v82, s40 bitop3:0x78
	v_xor_b32_e32 v94, 0x80000040, v94
	v_max_u32_e32 v82, v83, v89
	v_min_u32_e32 v89, v83, v89
	v_max_u32_e32 v83, v91, v102
	v_min_u32_e32 v102, v91, v102
	v_max_u32_e32 v91, v99, v94
	v_min_u32_e32 v94, v99, v94
	v_max_u32_e32 v99, v90, v95
	v_min_u32_e32 v95, v90, v95
	v_max_u32_e32 v90, v87, v88
	v_min_u32_e32 v88, v87, v88
	v_max_u32_e32 v87, v70, v97
	v_min_u32_e32 v97, v70, v97
	v_max_u32_e32 v70, v96, v98
	v_min_u32_e32 v98, v96, v98
	v_max_u32_e32 v96, v93, v92
	v_min_u32_e32 v92, v93, v92
	v_max_u32_e32 v93, v82, v87
	v_min_u32_e32 v87, v82, v87
	v_max_u32_e32 v82, v83, v70
	v_min_u32_e32 v70, v83, v70
	v_max_u32_e32 v83, v91, v96
	v_min_u32_e32 v96, v91, v96
	v_max_u32_e32 v91, v99, v90
	v_min_u32_e32 v90, v99, v90
	v_max_u32_e32 v99, v97, v89
	v_min_u32_e32 v89, v97, v89
	v_max_u32_e32 v97, v88, v95
	v_min_u32_e32 v95, v88, v95
	v_max_u32_e32 v88, v92, v94
	v_min_u32_e32 v94, v92, v94
	v_max_u32_e32 v92, v98, v102
	v_min_u32_e32 v102, v98, v102
	v_max_u32_e32 v98, v93, v82
	v_min_u32_e32 v82, v93, v82
	v_max_u32_e32 v93, v83, v91
	v_min_u32_e32 v91, v83, v91
	v_max_u32_e32 v83, v90, v87
	v_min_u32_e32 v87, v90, v87
	v_max_u32_e32 v90, v99, v97
	v_min_u32_e32 v97, v99, v97
	v_max_u32_e32 v99, v70, v96
	v_min_u32_e32 v96, v70, v96
	v_max_u32_e32 v70, v88, v92
	v_min_u32_e32 v92, v88, v92
	v_max_u32_e32 v88, v102, v89
	v_min_u32_e32 v89, v102, v89
	v_max_u32_e32 v102, v95, v94
	v_min_u32_e32 v94, v95, v94
	v_max_u32_e32 v95, v98, v93
	v_min_u32_e32 v93, v98, v93
	v_max_u32_e32 v98, v82, v91
	v_min_u32_e32 v91, v82, v91
	v_max_u32_e32 v82, v83, v70
	v_min_u32_e32 v70, v83, v70
	v_max_u32_e32 v83, v87, v92
	v_min_u32_e32 v92, v87, v92
	v_max_u32_e32 v87, v90, v99
	v_min_u32_e32 v99, v90, v99
	v_max_u32_e32 v90, v97, v96
	v_min_u32_e32 v96, v97, v96
	v_max_u32_e32 v97, v88, v102
	v_min_u32_e32 v102, v88, v102
	v_max_u32_e32 v88, v89, v94
	v_min_u32_e32 v94, v89, v94
	v_max_u32_e32 v89, v98, v93
	v_min_u32_e32 v93, v98, v93
	v_max_u32_e32 v98, v91, v97
	v_min_u32_e32 v97, v91, v97
	v_max_u32_e32 v91, v82, v87
	v_min_u32_e32 v87, v82, v87
	v_max_u32_e32 v82, v83, v99
	v_min_u32_e32 v99, v83, v99
	v_max_u32_e32 v83, v90, v70
	v_min_u32_e32 v70, v90, v70
	v_max_u32_e32 v90, v96, v92
	v_min_u32_e32 v92, v96, v92
	v_max_u32_e32 v96, v88, v102
	v_min_u32_e32 v102, v88, v102
	v_max_u32_e32 v88, v89, v91
	v_min_u32_e32 v91, v89, v91
	v_max_u32_e32 v89, v93, v87
	v_min_u32_e32 v87, v93, v87
	v_max_u32_e32 v93, v82, v83
	v_min_u32_e32 v83, v82, v83
	v_max_u32_e32 v82, v99, v70
	v_min_u32_e32 v70, v99, v70
	v_max_u32_e32 v99, v90, v96
	v_min_u32_e32 v96, v90, v96
	v_max_u32_e32 v90, v92, v102
	v_min_u32_e32 v102, v92, v102
	v_max_u32_e32 v92, v89, v91
	v_min_u32_e32 v91, v89, v91
	v_max_u32_e32 v89, v98, v87
	v_min_u32_e32 v87, v98, v87
	v_max_u32_e32 v98, v99, v97
	v_min_u32_e32 v97, v99, v97
	v_max_u32_e32 v99, v90, v96
	v_min_u32_e32 v96, v90, v96
	v_max_u32_e32 v90, v89, v93
	v_min_u32_e32 v93, v89, v93
	v_max_u32_e32 v89, v87, v83
	v_min_u32_e32 v83, v87, v83
	v_max_u32_e32 v87, v82, v98
	v_min_u32_e32 v98, v82, v98
	v_max_u32_e32 v82, v70, v97
	v_min_u32_e32 v97, v70, v97
	v_max_u32_e32 v70, v90, v91
	v_min_u32_e32 v91, v90, v91
	v_max_u32_e32 v90, v93, v89
	v_min_u32_e32 v89, v93, v89
	v_max_u32_e32 v93, v87, v83
	v_min_u32_e32 v83, v87, v83
	v_max_u32_e32 v87, v98, v82
	v_min_u32_e32 v82, v98, v82
	v_max_u32_e32 v98, v99, v97
	v_min_u32_e32 v97, v99, v97
	v_max_u32_e32 v99, v89, v93
	v_min_u32_e32 v93, v89, v93
	v_max_u32_e32 v89, v83, v87
	v_min_u32_e32 v87, v83, v87
	v_max_u32_e32 v76, v76, v94
	v_max_u32_e32 v72, v72, v102
	v_max_u32_e32 v86, v86, v96
	v_max_u32_e32 v79, v79, v97
	v_max_u32_e32 v77, v77, v98
	v_max_u32_e32 v78, v78, v82
	v_max_u32_e32 v100, v100, v87
	v_max_u32_e32 v101, v101, v89
	v_max_u32_e32 v75, v75, v93
	v_max_u32_e32 v81, v81, v99
	v_max_u32_e32 v84, v84, v90
	v_max_u32_e32 v71, v71, v91
	v_max_u32_e32 v80, v80, v70
	v_max_u32_e32 v74, v74, v92
	v_max_u32_e32 v73, v73, v88
	v_max_u32_e32 v85, v85, v95
	v_max_u32_e32 v94, v76, v75
	v_min_u32_e32 v75, v76, v75
	v_max_u32_e32 v76, v72, v81
	v_min_u32_e32 v81, v72, v81
	v_max_u32_e32 v72, v86, v84
	v_min_u32_e32 v84, v86, v84
	v_max_u32_e32 v86, v79, v71
	v_min_u32_e32 v71, v79, v71
	v_max_u32_e32 v79, v77, v80
	v_min_u32_e32 v80, v77, v80
	v_max_u32_e32 v77, v78, v74
	v_min_u32_e32 v74, v78, v74
	v_max_u32_e32 v78, v100, v73
	v_min_u32_e32 v73, v100, v73
	v_max_u32_e32 v100, v101, v85
	v_min_u32_e32 v85, v101, v85
	v_max_u32_e32 v101, v94, v79
	v_min_u32_e32 v79, v94, v79
	v_max_u32_e32 v94, v76, v77
	v_min_u32_e32 v77, v76, v77
	v_max_u32_e32 v76, v72, v78
	v_min_u32_e32 v78, v72, v78
	v_max_u32_e32 v72, v86, v100
	v_min_u32_e32 v100, v86, v100
	v_max_u32_e32 v86, v75, v80
	v_min_u32_e32 v80, v75, v80
; __device__ __forceinline__ unsigned f2key(float f) { const unsigned u = __float_as_uint(f); return (u & 0x80000000u) ? ~u : (u | 0x80000000u); }
; #define CE_DESC(a, b) do { const unsigned _mx = (a) > (b) ? (a) : (b), _mn = (a) > (b) ? (b) : (a); (a) = _mx; (b) = _mn; } while (0)
; __device__ __forceinline__ void sort16_desc(unsigned (&k)[16]) {
; #pragma unroll
;     for (int size = 2; size <= 16; size <<= 1)
; #pragma unroll
;         for (int stride = size >> 1; stride > 0; stride >>= 1)
; #pragma unroll
;             for (int i = 0; i < 16; ++i) { const int j = i ^ stride;
;                 if (j > i) { if ((i & size) == 0) CE_DESC(k[i], k[j]); else CE_DESC(k[j], k[i]); } }
; }
; __device__ __forceinline__ void merge16(unsigned (&a)[16], const unsigned (&b)[16]) {
; #pragma unroll
;     for (int i = 0; i < 16; ++i) a[i] = a[i] > b[15 - i] ? a[i] : b[15 - i];
; #pragma unroll
;     for (int stride = 8; stride > 0; stride >>= 1)
; #pragma unroll
;         for (int i = 0; i < 16; ++i) { const int j = i ^ stride; if (j > i) CE_DESC(a[i], a[j]); }
; }
; __device__ __forceinline__ void peer_tile(const Args& A, LAS unsigned char* lds, int tile) {
;     ...
;                 { const bf16_t* sp = QRY + m * 2048 + hp * 128 + 32 * g;
;                   const u32x4 s0 = *(const u32x4*)sp, s1 = *(const u32x4*)(sp + 8), s2 = *(const u32x4*)(sp + 16), s3 = *(const u32x4*)(sp + 24);
;                   const unsigned sw[16] = {s0.x, s0.y, s0.z, s0.w, s1.x, s1.y, s1.z, s1.w, s2.x, s2.y, s2.z, s2.w, s3.x, s3.y, s3.z, s3.w};
; #pragma unroll
;                   for (int i = 0; i < 16; ++i) {
;                       const float lo = (float)__builtin_bit_cast(_Float16, (unsigned short)(sw[i] & 0xffffu)), hi = (float)__builtin_bit_cast(_Float16, (unsigned short)(sw[i] >> 16));
;                       const unsigned klo = (f2key(lo) & ~127u) | (unsigned)(127 - (32 * g + 2 * i)), khi = (f2key(hi) & ~127u) | (unsigned)(127 - (32 * g + 2 * i + 1));
;                       if (i < 8) { k0[2 * i] = klo; k0[2 * i + 1] = khi; } else { k1[2 * (i - 8)] = klo; k1[2 * (i - 8) + 1] = khi; } } }
	v_max_u32_e32 v75, v81, v74
	v_min_u32_e32 v74, v81, v74
	v_max_u32_e32 v81, v84, v73
	v_min_u32_e32 v73, v84, v73
	v_max_u32_e32 v84, v71, v85
	v_min_u32_e32 v85, v71, v85
	v_max_u32_e32 v71, v101, v76
	v_min_u32_e32 v76, v101, v76
	v_max_u32_e32 v101, v94, v72
	v_min_u32_e32 v72, v94, v72
	v_max_u32_e32 v94, v79, v78
	v_min_u32_e32 v78, v79, v78
	v_max_u32_e32 v79, v77, v100
	v_min_u32_e32 v100, v77, v100
	v_max_u32_e32 v77, v86, v81
	v_min_u32_e32 v81, v86, v81
	v_max_u32_e32 v86, v75, v84
	v_min_u32_e32 v84, v75, v84
	v_max_u32_e32 v75, v80, v73
	v_min_u32_e32 v73, v80, v73
	v_max_u32_e32 v80, v74, v85
	v_min_u32_e32 v85, v74, v85
	v_max_u32_e32 v74, v71, v101
	v_min_u32_e32 v101, v71, v101
	v_max_u32_e32 v71, v76, v72
	v_min_u32_e32 v72, v76, v72
	v_max_u32_e32 v76, v94, v79
	v_min_u32_e32 v79, v94, v79
	v_max_u32_e32 v94, v78, v100
	v_min_u32_e32 v100, v78, v100
	v_max_u32_e32 v78, v77, v86
	v_min_u32_e32 v86, v77, v86
	v_max_u32_e32 v77, v81, v84
	v_min_u32_e32 v84, v81, v84
	v_max_u32_e32 v81, v75, v80
	v_min_u32_e32 v80, v75, v80
	v_max_u32_e32 v75, v73, v85
	v_min_u32_e32 v85, v73, v85
	s_mov_b64 s[38:39], s[34:35]
	global_load_dwordx4 v[0:3], v66, s[38:39] offset:256
	s_add_u32 s38, s38, 0x8000
	s_addc_u32 s39, s39, 0
	global_load_dwordx4 v[4:7], v66, s[38:39] offset:256
	s_add_u32 s38, s38, 0x8000
	s_addc_u32 s39, s39, 0
	global_load_dwordx4 v[8:11], v66, s[38:39] offset:256
	s_add_u32 s38, s38, 0x8000
	s_addc_u32 s39, s39, 0
	global_load_dwordx4 v[12:15], v66, s[38:39] offset:256
	s_add_u32 s38, s38, 0x8000
	s_addc_u32 s39, s39, 0
	global_load_dwordx4 v[16:19], v66, s[38:39] offset:256
	s_add_u32 s38, s38, 0x8000
	s_addc_u32 s39, s39, 0
	global_load_dwordx4 v[20:23], v66, s[38:39] offset:256
	s_add_u32 s38, s38, 0x8000
	s_addc_u32 s39, s39, 0
	global_load_dwordx4 v[24:27], v66, s[38:39] offset:256
	s_add_u32 s38, s38, 0x8000
	s_addc_u32 s39, s39, 0
	global_load_dwordx4 v[28:31], v66, s[38:39] offset:256
	s_waitcnt vmcnt(8)
	ds_write_b128 v64, v[32:35] offset:0
	ds_write_b128 v64, v[36:39] offset:1152
	ds_write_b128 v64, v[40:43] offset:2304
	ds_write_b128 v64, v[44:47] offset:3456
	ds_write_b128 v64, v[48:51] offset:4608
	ds_write_b128 v64, v[52:55] offset:5760
	ds_write_b128 v64, v[56:59] offset:6912
	ds_write_b128 v64, v[60:63] offset:8064
	s_waitcnt lgkmcnt(0)
	ds_read_b128 v[32:35], v65 offset:0
	ds_read_b128 v[36:39], v65 offset:16
	ds_read_b128 v[40:43], v65 offset:32
	ds_read_b128 v[44:47], v65 offset:48
	ds_read_b128 v[48:51], v65 offset:64
	ds_read_b128 v[52:55], v65 offset:80
	ds_read_b128 v[56:59], v65 offset:96
	ds_read_b128 v[60:63], v65 offset:112
	s_waitcnt lgkmcnt(0)
	v_cvt_f32_f16_e32 v73, v32
	v_cvt_f32_f16_sdwa v102, v32 dst_sel:DWORD dst_unused:UNUSED_PAD src0_sel:WORD_1
	v_ashrrev_i32_e32 v96, 31, v73
	v_bitop3_b32 v73, v73, v96, s40 bitop3:0x78
	v_xor_b32_e32 v73, 0x8000003f, v73
	v_ashrrev_i32_e32 v96, 31, v102
	v_bitop3_b32 v102, v102, v96, s40 bitop3:0x78
	v_xor_b32_e32 v102, 0x8000003e, v102
	v_cvt_f32_f16_e32 v96, v33
	v_cvt_f32_f16_sdwa v97, v33 dst_sel:DWORD dst_unused:UNUSED_PAD src0_sel:WORD_1
	v_ashrrev_i32_e32 v98, 31, v96
	v_bitop3_b32 v96, v96, v98, s40 bitop3:0x78
	v_xor_b32_e32 v96, 0x8000003d, v96
	v_ashrrev_i32_e32 v98, 31, v97
	v_bitop3_b32 v97, v97, v98, s40 bitop3:0x78
	v_xor_b32_e32 v97, 0x8000003c, v97
	v_cvt_f32_f16_e32 v98, v34
	v_cvt_f32_f16_sdwa v82, v34 dst_sel:DWORD dst_unused:UNUSED_PAD src0_sel:WORD_1
	v_ashrrev_i32_e32 v87, 31, v98
	v_bitop3_b32 v98, v98, v87, s40 bitop3:0x78
	v_xor_b32_e32 v98, 0x8000003b, v98
	v_ashrrev_i32_e32 v87, 31, v82
	v_bitop3_b32 v82, v82, v87, s40 bitop3:0x78
	v_xor_b32_e32 v82, 0x8000003a, v82
	v_cvt_f32_f16_e32 v87, v35
	v_cvt_f32_f16_sdwa v89, v35 dst_sel:DWORD dst_unused:UNUSED_PAD src0_sel:WORD_1
	v_ashrrev_i32_e32 v93, 31, v87
	v_bitop3_b32 v87, v87, v93, s40 bitop3:0x78
	v_xor_b32_e32 v87, 0x80000039, v87
	v_ashrrev_i32_e32 v93, 31, v89
	v_bitop3_b32 v89, v89, v93, s40 bitop3:0x78
	v_xor_b32_e32 v89, 0x80000038, v89
	v_cvt_f32_f16_e32 v93, v36
	v_cvt_f32_f16_sdwa v99, v36 dst_sel:DWORD dst_unused:UNUSED_PAD src0_sel:WORD_1
	v_ashrrev_i32_e32 v90, 31, v93
	v_bitop3_b32 v93, v93, v90, s40 bitop3:0x78
	v_xor_b32_e32 v93, 0x80000037, v93
	v_ashrrev_i32_e32 v90, 31, v99
	v_bitop3_b32 v99, v99, v90, s40 bitop3:0x78
	v_xor_b32_e32 v99, 0x80000036, v99
	v_cvt_f32_f16_e32 v90, v37
	v_cvt_f32_f16_sdwa v91, v37 dst_sel:DWORD dst_unused:UNUSED_PAD src0_sel:WORD_1
	v_ashrrev_i32_e32 v70, 31, v90
	v_bitop3_b32 v90, v90, v70, s40 bitop3:0x78
	v_xor_b32_e32 v90, 0x80000035, v90
	v_ashrrev_i32_e32 v70, 31, v91
	v_bitop3_b32 v91, v91, v70, s40 bitop3:0x78
	v_xor_b32_e32 v91, 0x80000034, v91
	v_cvt_f32_f16_e32 v70, v38
	v_cvt_f32_f16_sdwa v92, v38 dst_sel:DWORD dst_unused:UNUSED_PAD src0_sel:WORD_1
	v_ashrrev_i32_e32 v88, 31, v70
	v_bitop3_b32 v70, v70, v88, s40 bitop3:0x78
	v_xor_b32_e32 v70, 0x80000033, v70
	v_ashrrev_i32_e32 v88, 31, v92
	v_bitop3_b32 v92, v92, v88, s40 bitop3:0x78
	v_xor_b32_e32 v92, 0x80000032, v92
	v_cvt_f32_f16_e32 v88, v39
	v_cvt_f32_f16_sdwa v95, v39 dst_sel:DWORD dst_unused:UNUSED_PAD src0_sel:WORD_1
	v_ashrrev_i32_e32 v83, 31, v88
	v_bitop3_b32 v88, v88, v83, s40 bitop3:0x78
	v_xor_b32_e32 v88, 0x80000031, v88
	v_ashrrev_i32_e32 v83, 31, v95
	v_bitop3_b32 v95, v95, v83, s40 bitop3:0x78
	v_xor_b32_e32 v95, 0x80000030, v95
	v_max_u32_e32 v83, v73, v92
	v_min_u32_e32 v92, v73, v92
	v_max_u32_e32 v73, v102, v70
	v_min_u32_e32 v70, v102, v70
	v_max_u32_e32 v102, v96, v95
	v_min_u32_e32 v95, v96, v95
	v_max_u32_e32 v96, v97, v88
	v_min_u32_e32 v88, v97, v88
	v_max_u32_e32 v97, v98, v93
	v_min_u32_e32 v93, v98, v93
	v_max_u32_e32 v98, v82, v87
; #define CE_DESC(a, b) do { const unsigned _mx = (a) > (b) ? (a) : (b), _mn = (a) > (b) ? (b) : (a); (a) = _mx; (b) = _mn; } while (0)
; __device__ __forceinline__ void sort16_desc(unsigned (&k)[16]) {
; #pragma unroll
;     for (int size = 2; size <= 16; size <<= 1)
; #pragma unroll
;         for (int stride = size >> 1; stride > 0; stride >>= 1)
; #pragma unroll
;             for (int i = 0; i < 16; ++i) { const int j = i ^ stride;
;                 if (j > i) { if ((i & size) == 0) CE_DESC(k[i], k[j]); else CE_DESC(k[j], k[i]); } }
; }
; __device__ __forceinline__ void merge16(unsigned (&a)[16], const unsigned (&b)[16]) {
; #pragma unroll
;     for (int i = 0; i < 16; ++i) a[i] = a[i] > b[15 - i] ? a[i] : b[15 - i];
; #pragma unroll
;     for (int stride = 8; stride > 0; stride >>= 1)
; #pragma unroll
;         for (int i = 0; i < 16; ++i) { const int j = i ^ stride; if (j > i) CE_DESC(a[i], a[j]); }
; }
	v_min_u32_e32 v87, v82, v87
	v_max_u32_e32 v82, v89, v91
	v_min_u32_e32 v91, v89, v91
	v_max_u32_e32 v89, v99, v90
	v_min_u32_e32 v90, v99, v90
	v_max_u32_e32 v99, v83, v98
	v_min_u32_e32 v98, v83, v98
	v_max_u32_e32 v83, v73, v82
	v_min_u32_e32 v82, v73, v82
	v_max_u32_e32 v73, v102, v89
	v_min_u32_e32 v89, v102, v89
	v_max_u32_e32 v102, v96, v97
	v_min_u32_e32 v97, v96, v97
	v_max_u32_e32 v96, v87, v92
	v_min_u32_e32 v92, v87, v92
	v_max_u32_e32 v87, v93, v88
	v_min_u32_e32 v88, v93, v88
	v_max_u32_e32 v93, v90, v95
	v_min_u32_e32 v95, v90, v95
	v_max_u32_e32 v90, v91, v70
	v_min_u32_e32 v70, v91, v70
	v_max_u32_e32 v91, v99, v83
	v_min_u32_e32 v83, v99, v83
	v_max_u32_e32 v99, v73, v102
	v_min_u32_e32 v102, v73, v102
	v_max_u32_e32 v73, v97, v98
	v_min_u32_e32 v98, v97, v98
	v_max_u32_e32 v97, v96, v87
	v_min_u32_e32 v87, v96, v87
	v_max_u32_e32 v96, v82, v89
	v_min_u32_e32 v89, v82, v89
	v_max_u32_e32 v82, v93, v90
	v_min_u32_e32 v90, v93, v90
	v_max_u32_e32 v93, v70, v92
	v_min_u32_e32 v92, v70, v92
	v_max_u32_e32 v70, v88, v95
	v_min_u32_e32 v95, v88, v95
	v_max_u32_e32 v88, v91, v99
	v_min_u32_e32 v99, v91, v99
	v_max_u32_e32 v91, v83, v102
	v_min_u32_e32 v102, v83, v102
	v_max_u32_e32 v83, v73, v82
	v_min_u32_e32 v82, v73, v82
	v_max_u32_e32 v73, v98, v90
	v_min_u32_e32 v90, v98, v90
	v_max_u32_e32 v98, v97, v96
	v_min_u32_e32 v96, v97, v96
	v_max_u32_e32 v97, v87, v89
	v_min_u32_e32 v89, v87, v89
	v_max_u32_e32 v87, v93, v70
	v_min_u32_e32 v70, v93, v70
	v_max_u32_e32 v93, v92, v95
	v_min_u32_e32 v95, v92, v95
	v_max_u32_e32 v92, v91, v99
	v_min_u32_e32 v99, v91, v99
	v_max_u32_e32 v91, v102, v87
	v_min_u32_e32 v87, v102, v87
	v_max_u32_e32 v102, v83, v98
	v_min_u32_e32 v98, v83, v98
	v_max_u32_e32 v83, v73, v96
	v_min_u32_e32 v96, v73, v96
	v_max_u32_e32 v73, v97, v82
	v_min_u32_e32 v82, v97, v82
	v_max_u32_e32 v97, v89, v90
	v_min_u32_e32 v90, v89, v90
	v_max_u32_e32 v89, v93, v70
	v_min_u32_e32 v70, v93, v70
	v_max_u32_e32 v93, v92, v102
	v_min_u32_e32 v102, v92, v102
	v_max_u32_e32 v92, v99, v98
	v_min_u32_e32 v98, v99, v98
	v_max_u32_e32 v99, v83, v73
	v_min_u32_e32 v73, v83, v73
	v_max_u32_e32 v83, v96, v82
	v_min_u32_e32 v82, v96, v82
	v_max_u32_e32 v96, v97, v89
	v_min_u32_e32 v89, v97, v89
	v_max_u32_e32 v97, v90, v70
	v_min_u32_e32 v70, v90, v70
	v_max_u32_e32 v90, v92, v102
	v_min_u32_e32 v102, v92, v102
	v_max_u32_e32 v92, v91, v98
	v_min_u32_e32 v98, v91, v98
	v_max_u32_e32 v91, v96, v87
	v_min_u32_e32 v87, v96, v87
	v_max_u32_e32 v96, v97, v89
	v_min_u32_e32 v89, v97, v89
	v_max_u32_e32 v97, v92, v99
	v_min_u32_e32 v99, v92, v99
	v_max_u32_e32 v92, v98, v73
	v_min_u32_e32 v73, v98, v73
	v_max_u32_e32 v98, v83, v91
	v_min_u32_e32 v91, v83, v91
	v_max_u32_e32 v83, v82, v87
	v_min_u32_e32 v87, v82, v87
	v_max_u32_e32 v82, v97, v102
	v_min_u32_e32 v102, v97, v102
	v_max_u32_e32 v97, v99, v92
	v_min_u32_e32 v92, v99, v92
	v_max_u32_e32 v99, v98, v73
	v_min_u32_e32 v73, v98, v73
	v_max_u32_e32 v98, v91, v83
	v_min_u32_e32 v83, v91, v83
	v_max_u32_e32 v91, v96, v87
	v_min_u32_e32 v87, v96, v87
	v_max_u32_e32 v96, v92, v99
	v_min_u32_e32 v99, v92, v99
	v_max_u32_e32 v92, v73, v98
	v_min_u32_e32 v98, v73, v98
	v_max_u32_e32 v74, v74, v95
	v_max_u32_e32 v101, v101, v70
	v_max_u32_e32 v71, v71, v89
	v_max_u32_e32 v72, v72, v87
	v_max_u32_e32 v76, v76, v91
	v_max_u32_e32 v79, v79, v83
	v_max_u32_e32 v94, v94, v98
	v_max_u32_e32 v100, v100, v92
	v_max_u32_e32 v78, v78, v99
	v_max_u32_e32 v86, v86, v96
	v_max_u32_e32 v77, v77, v97
	v_max_u32_e32 v84, v84, v102
	v_max_u32_e32 v81, v81, v82
	v_max_u32_e32 v80, v80, v90
	v_max_u32_e32 v75, v75, v93
	v_max_u32_e32 v85, v85, v88
	v_max_u32_e32 v95, v74, v78
	v_min_u32_e32 v78, v74, v78
	v_max_u32_e32 v74, v101, v86
	v_min_u32_e32 v86, v101, v86
	v_max_u32_e32 v101, v71, v77
	v_min_u32_e32 v77, v71, v77
	v_max_u32_e32 v71, v72, v84
	v_min_u32_e32 v84, v72, v84
	v_max_u32_e32 v72, v76, v81
	v_min_u32_e32 v81, v76, v81
	v_max_u32_e32 v76, v79, v80
	v_min_u32_e32 v80, v79, v80
	v_max_u32_e32 v79, v94, v75
	v_min_u32_e32 v75, v94, v75
	v_max_u32_e32 v94, v100, v85
	v_min_u32_e32 v85, v100, v85
	v_max_u32_e32 v100, v95, v72
	v_min_u32_e32 v72, v95, v72
	v_max_u32_e32 v95, v74, v76
	v_min_u32_e32 v76, v74, v76
	v_max_u32_e32 v74, v101, v79
	v_min_u32_e32 v79, v101, v79
	v_max_u32_e32 v101, v71, v94
	v_min_u32_e32 v94, v71, v94
	v_max_u32_e32 v71, v78, v81
	v_min_u32_e32 v81, v78, v81
	v_max_u32_e32 v78, v86, v80
	v_min_u32_e32 v80, v86, v80
	v_max_u32_e32 v86, v77, v75
	v_min_u32_e32 v75, v77, v75
	v_max_u32_e32 v77, v84, v85
	v_min_u32_e32 v85, v84, v85
	v_max_u32_e32 v84, v100, v74
	v_min_u32_e32 v74, v100, v74
	v_max_u32_e32 v100, v95, v101
	v_min_u32_e32 v101, v95, v101
	v_max_u32_e32 v95, v72, v79
	v_min_u32_e32 v79, v72, v79
	v_max_u32_e32 v72, v76, v94
	v_min_u32_e32 v94, v76, v94
	v_max_u32_e32 v76, v71, v86
	v_min_u32_e32 v86, v71, v86
	v_max_u32_e32 v71, v78, v77
	v_min_u32_e32 v77, v78, v77
	v_max_u32_e32 v78, v81, v75
	v_min_u32_e32 v75, v81, v75
	v_max_u32_e32 v81, v80, v85
	v_min_u32_e32 v85, v80, v85
	v_max_u32_e32 v80, v84, v100
	v_min_u32_e32 v100, v84, v100
	v_max_u32_e32 v84, v74, v101
	v_min_u32_e32 v101, v74, v101
	v_max_u32_e32 v74, v95, v72
	v_min_u32_e32 v72, v95, v72
	v_max_u32_e32 v95, v79, v94
	v_min_u32_e32 v94, v79, v94
	v_max_u32_e32 v79, v76, v71
	v_min_u32_e32 v71, v76, v71
	v_max_u32_e32 v76, v86, v77
	v_min_u32_e32 v77, v86, v77
	v_max_u32_e32 v86, v78, v81
	v_min_u32_e32 v81, v78, v81
	v_max_u32_e32 v78, v75, v85
	v_min_u32_e32 v85, v75, v85
	v_cvt_f32_f16_e32 v75, v40
	v_cvt_f32_f16_sdwa v70, v40 dst_sel:DWORD dst_unused:UNUSED_PAD src0_sel:WORD_1
; __device__ __forceinline__ unsigned f2key(float f) { const unsigned u = __float_as_uint(f); return (u & 0x80000000u) ? ~u : (u | 0x80000000u); }
; #define CE_DESC(a, b) do { const unsigned _mx = (a) > (b) ? (a) : (b), _mn = (a) > (b) ? (b) : (a); (a) = _mx; (b) = _mn; } while (0)
; __device__ __forceinline__ void sort16_desc(unsigned (&k)[16]) {
; #pragma unroll
;     for (int size = 2; size <= 16; size <<= 1)
; #pragma unroll
;         for (int stride = size >> 1; stride > 0; stride >>= 1)
; #pragma unroll
;             for (int i = 0; i < 16; ++i) { const int j = i ^ stride;
;                 if (j > i) { if ((i & size) == 0) CE_DESC(k[i], k[j]); else CE_DESC(k[j], k[i]); } }
; }
; __device__ __forceinline__ void peer_tile(const Args& A, LAS unsigned char* lds, int tile) {
;     ...
;                   for (int i = 0; i < 16; ++i) {
;                       const float lo = (float)__builtin_bit_cast(_Float16, (unsigned short)(sw[i] & 0xffffu)), hi = (float)__builtin_bit_cast(_Float16, (unsigned short)(sw[i] >> 16));
;                       const unsigned klo = (f2key(lo) & ~127u) | (unsigned)(127 - (32 * g + 2 * i)), khi = (f2key(hi) & ~127u) | (unsigned)(127 - (32 * g + 2 * i + 1));
;                       if (i < 8) { k0[2 * i] = klo; k0[2 * i + 1] = khi; } else { k1[2 * (i - 8)] = klo; k1[2 * (i - 8) + 1] = khi; } } }
	v_ashrrev_i32_e32 v89, 31, v75
	v_bitop3_b32 v75, v75, v89, s40 bitop3:0x78
	v_xor_b32_e32 v75, 0x8000002f, v75
	v_ashrrev_i32_e32 v89, 31, v70
	v_bitop3_b32 v70, v70, v89, s40 bitop3:0x78
	v_xor_b32_e32 v70, 0x8000002e, v70
	v_cvt_f32_f16_e32 v89, v41
	v_cvt_f32_f16_sdwa v87, v41 dst_sel:DWORD dst_unused:UNUSED_PAD src0_sel:WORD_1
	v_ashrrev_i32_e32 v91, 31, v89
	v_bitop3_b32 v89, v89, v91, s40 bitop3:0x78
	v_xor_b32_e32 v89, 0x8000002d, v89
	v_ashrrev_i32_e32 v91, 31, v87
	v_bitop3_b32 v87, v87, v91, s40 bitop3:0x78
	v_xor_b32_e32 v87, 0x8000002c, v87
	v_cvt_f32_f16_e32 v91, v42
	v_cvt_f32_f16_sdwa v83, v42 dst_sel:DWORD dst_unused:UNUSED_PAD src0_sel:WORD_1
	v_ashrrev_i32_e32 v98, 31, v91
	v_bitop3_b32 v91, v91, v98, s40 bitop3:0x78
	v_xor_b32_e32 v91, 0x8000002b, v91
	v_ashrrev_i32_e32 v98, 31, v83
	v_bitop3_b32 v83, v83, v98, s40 bitop3:0x78
	v_xor_b32_e32 v83, 0x8000002a, v83
	v_cvt_f32_f16_e32 v98, v43
	v_cvt_f32_f16_sdwa v92, v43 dst_sel:DWORD dst_unused:UNUSED_PAD src0_sel:WORD_1
	v_ashrrev_i32_e32 v99, 31, v98
	v_bitop3_b32 v98, v98, v99, s40 bitop3:0x78
	v_xor_b32_e32 v98, 0x80000029, v98
	v_ashrrev_i32_e32 v99, 31, v92
	v_bitop3_b32 v92, v92, v99, s40 bitop3:0x78
	v_xor_b32_e32 v92, 0x80000028, v92
	v_cvt_f32_f16_e32 v99, v44
	v_cvt_f32_f16_sdwa v96, v44 dst_sel:DWORD dst_unused:UNUSED_PAD src0_sel:WORD_1
	v_ashrrev_i32_e32 v97, 31, v99
	v_bitop3_b32 v99, v99, v97, s40 bitop3:0x78
	v_xor_b32_e32 v99, 0x80000027, v99
	v_ashrrev_i32_e32 v97, 31, v96
	v_bitop3_b32 v96, v96, v97, s40 bitop3:0x78
	v_xor_b32_e32 v96, 0x80000026, v96
	v_cvt_f32_f16_e32 v97, v45
	v_cvt_f32_f16_sdwa v102, v45 dst_sel:DWORD dst_unused:UNUSED_PAD src0_sel:WORD_1
	v_ashrrev_i32_e32 v82, 31, v97
	v_bitop3_b32 v97, v97, v82, s40 bitop3:0x78
	v_xor_b32_e32 v97, 0x80000025, v97
	v_ashrrev_i32_e32 v82, 31, v102
	v_bitop3_b32 v102, v102, v82, s40 bitop3:0x78
	v_xor_b32_e32 v102, 0x80000024, v102
	v_cvt_f32_f16_e32 v82, v46
	v_cvt_f32_f16_sdwa v90, v46 dst_sel:DWORD dst_unused:UNUSED_PAD src0_sel:WORD_1
	v_ashrrev_i32_e32 v93, 31, v82
	v_bitop3_b32 v82, v82, v93, s40 bitop3:0x78
	v_xor_b32_e32 v82, 0x80000023, v82
	v_ashrrev_i32_e32 v93, 31, v90
	v_bitop3_b32 v90, v90, v93, s40 bitop3:0x78
	v_xor_b32_e32 v90, 0x80000022, v90
	v_cvt_f32_f16_e32 v93, v47
	v_cvt_f32_f16_sdwa v88, v47 dst_sel:DWORD dst_unused:UNUSED_PAD src0_sel:WORD_1
	v_ashrrev_i32_e32 v73, 31, v93
	v_bitop3_b32 v93, v93, v73, s40 bitop3:0x78
	v_xor_b32_e32 v93, 0x80000021, v93
	v_ashrrev_i32_e32 v73, 31, v88
	v_bitop3_b32 v88, v88, v73, s40 bitop3:0x78
	v_xor_b32_e32 v88, 0x80000020, v88
	v_max_u32_e32 v73, v75, v90
	v_min_u32_e32 v90, v75, v90
	v_max_u32_e32 v75, v70, v82
	v_min_u32_e32 v82, v70, v82
	v_max_u32_e32 v70, v89, v88
	v_min_u32_e32 v88, v89, v88
	v_max_u32_e32 v89, v87, v93
	v_min_u32_e32 v93, v87, v93
	v_max_u32_e32 v87, v91, v99
	v_min_u32_e32 v99, v91, v99
	v_max_u32_e32 v91, v83, v98
	v_min_u32_e32 v98, v83, v98
	v_max_u32_e32 v83, v92, v102
	v_min_u32_e32 v102, v92, v102
	v_max_u32_e32 v92, v96, v97
	v_min_u32_e32 v97, v96, v97
	v_max_u32_e32 v96, v73, v91
	v_min_u32_e32 v91, v73, v91
	v_max_u32_e32 v73, v75, v83
	v_min_u32_e32 v83, v75, v83
	v_max_u32_e32 v75, v70, v92
	v_min_u32_e32 v92, v70, v92
	v_max_u32_e32 v70, v89, v87
	v_min_u32_e32 v87, v89, v87
	v_max_u32_e32 v89, v98, v90
	v_min_u32_e32 v90, v98, v90
	v_max_u32_e32 v98, v99, v93
	v_min_u32_e32 v93, v99, v93
	v_max_u32_e32 v99, v97, v88
	v_min_u32_e32 v88, v97, v88
	v_max_u32_e32 v97, v102, v82
	v_min_u32_e32 v82, v102, v82
	v_max_u32_e32 v102, v96, v73
	v_min_u32_e32 v73, v96, v73
	v_max_u32_e32 v96, v75, v70
	v_min_u32_e32 v70, v75, v70
	v_max_u32_e32 v75, v87, v91
	v_min_u32_e32 v91, v87, v91
	v_max_u32_e32 v87, v89, v98
	v_min_u32_e32 v98, v89, v98
	v_max_u32_e32 v89, v83, v92
	v_min_u32_e32 v92, v83, v92
	v_max_u32_e32 v83, v99, v97
	v_min_u32_e32 v97, v99, v97
	v_max_u32_e32 v99, v82, v90
	v_min_u32_e32 v90, v82, v90
	v_max_u32_e32 v82, v93, v88
	v_min_u32_e32 v88, v93, v88
	v_max_u32_e32 v93, v102, v96
	v_min_u32_e32 v96, v102, v96
	v_max_u32_e32 v102, v73, v70
	v_min_u32_e32 v70, v73, v70
	v_max_u32_e32 v73, v75, v83
	v_min_u32_e32 v83, v75, v83
	v_max_u32_e32 v75, v91, v97
	v_min_u32_e32 v97, v91, v97
	v_max_u32_e32 v91, v87, v89
	v_min_u32_e32 v89, v87, v89
	v_max_u32_e32 v87, v98, v92
	v_min_u32_e32 v92, v98, v92
	v_max_u32_e32 v98, v99, v82
	v_min_u32_e32 v82, v99, v82
	v_max_u32_e32 v99, v90, v88
	v_min_u32_e32 v88, v90, v88
	v_max_u32_e32 v90, v102, v96
	v_min_u32_e32 v96, v102, v96
	v_max_u32_e32 v102, v70, v98
	v_min_u32_e32 v98, v70, v98
	v_max_u32_e32 v70, v73, v91
	v_min_u32_e32 v91, v73, v91
	v_max_u32_e32 v73, v75, v89
	v_min_u32_e32 v89, v75, v89
	v_max_u32_e32 v75, v87, v83
	v_min_u32_e32 v83, v87, v83
	v_max_u32_e32 v87, v92, v97
	v_min_u32_e32 v97, v92, v97
	v_max_u32_e32 v92, v99, v82
	v_min_u32_e32 v82, v99, v82
	v_max_u32_e32 v99, v90, v70
	v_min_u32_e32 v70, v90, v70
	v_max_u32_e32 v90, v96, v91
	v_min_u32_e32 v91, v96, v91
	v_max_u32_e32 v96, v73, v75
	v_min_u32_e32 v75, v73, v75
	v_max_u32_e32 v73, v89, v83
	v_min_u32_e32 v83, v89, v83
	v_max_u32_e32 v89, v87, v92
	v_min_u32_e32 v92, v87, v92
	v_max_u32_e32 v87, v97, v82
	v_min_u32_e32 v82, v97, v82
	v_max_u32_e32 v97, v90, v70
	v_min_u32_e32 v70, v90, v70
	v_max_u32_e32 v90, v102, v91
	v_min_u32_e32 v91, v102, v91
	v_max_u32_e32 v102, v89, v98
	v_min_u32_e32 v98, v89, v98
	v_max_u32_e32 v89, v87, v92
	v_min_u32_e32 v92, v87, v92
	v_max_u32_e32 v87, v90, v96
	v_min_u32_e32 v96, v90, v96
	v_max_u32_e32 v90, v91, v75
	v_min_u32_e32 v75, v91, v75
	v_max_u32_e32 v91, v73, v102
	v_min_u32_e32 v102, v73, v102
	v_max_u32_e32 v73, v83, v98
; __device__ __forceinline__ unsigned f2key(float f) { const unsigned u = __float_as_uint(f); return (u & 0x80000000u) ? ~u : (u | 0x80000000u); }
; #define CE_DESC(a, b) do { const unsigned _mx = (a) > (b) ? (a) : (b), _mn = (a) > (b) ? (b) : (a); (a) = _mx; (b) = _mn; } while (0)
; __device__ __forceinline__ void sort16_desc(unsigned (&k)[16]) {
; #pragma unroll
;     for (int size = 2; size <= 16; size <<= 1)
; #pragma unroll
;         for (int stride = size >> 1; stride > 0; stride >>= 1)
; #pragma unroll
;             for (int i = 0; i < 16; ++i) { const int j = i ^ stride;
;                 if (j > i) { if ((i & size) == 0) CE_DESC(k[i], k[j]); else CE_DESC(k[j], k[i]); } }
; }
; __device__ __forceinline__ void merge16(unsigned (&a)[16], const unsigned (&b)[16]) {
; #pragma unroll
;     for (int i = 0; i < 16; ++i) a[i] = a[i] > b[15 - i] ? a[i] : b[15 - i];
; #pragma unroll
;     for (int stride = 8; stride > 0; stride >>= 1)
; #pragma unroll
;         for (int i = 0; i < 16; ++i) { const int j = i ^ stride; if (j > i) CE_DESC(a[i], a[j]); }
; }
; __device__ __forceinline__ void peer_tile(const Args& A, LAS unsigned char* lds, int tile) {
;     ...
;                   for (int i = 0; i < 16; ++i) {
;                       const float lo = (float)__builtin_bit_cast(_Float16, (unsigned short)(sw[i] & 0xffffu)), hi = (float)__builtin_bit_cast(_Float16, (unsigned short)(sw[i] >> 16));
;                       const unsigned klo = (f2key(lo) & ~127u) | (unsigned)(127 - (32 * g + 2 * i)), khi = (f2key(hi) & ~127u) | (unsigned)(127 - (32 * g + 2 * i + 1));
;                       if (i < 8) { k0[2 * i] = klo; k0[2 * i + 1] = khi; } else { k1[2 * (i - 8)] = klo; k1[2 * (i - 8) + 1] = khi; } } }
	v_min_u32_e32 v98, v83, v98
	v_max_u32_e32 v83, v87, v70
	v_min_u32_e32 v70, v87, v70
	v_max_u32_e32 v87, v96, v90
	v_min_u32_e32 v90, v96, v90
	v_max_u32_e32 v96, v91, v75
	v_min_u32_e32 v75, v91, v75
	v_max_u32_e32 v91, v102, v73
	v_min_u32_e32 v73, v102, v73
	v_max_u32_e32 v102, v89, v98
	v_min_u32_e32 v98, v89, v98
	v_max_u32_e32 v89, v90, v96
	v_min_u32_e32 v96, v90, v96
	v_max_u32_e32 v90, v75, v91
	v_min_u32_e32 v91, v75, v91
	v_max_u32_e32 v80, v80, v88
	v_max_u32_e32 v100, v100, v82
	v_max_u32_e32 v84, v84, v92
	v_max_u32_e32 v101, v101, v98
	v_max_u32_e32 v74, v74, v102
	v_max_u32_e32 v72, v72, v73
	v_max_u32_e32 v95, v95, v91
	v_max_u32_e32 v94, v94, v90
	v_max_u32_e32 v79, v79, v96
	v_max_u32_e32 v71, v71, v89
	v_max_u32_e32 v76, v76, v87
	v_max_u32_e32 v77, v77, v70
	v_max_u32_e32 v86, v86, v83
	v_max_u32_e32 v81, v81, v97
	v_max_u32_e32 v78, v78, v99
	v_max_u32_e32 v85, v85, v93
	v_max_u32_e32 v88, v80, v79
	v_min_u32_e32 v79, v80, v79
	v_max_u32_e32 v80, v100, v71
	v_min_u32_e32 v71, v100, v71
	v_max_u32_e32 v100, v84, v76
	v_min_u32_e32 v76, v84, v76
	v_max_u32_e32 v84, v101, v77
	v_min_u32_e32 v77, v101, v77
	v_max_u32_e32 v101, v74, v86
	v_min_u32_e32 v86, v74, v86
	v_max_u32_e32 v74, v72, v81
	v_min_u32_e32 v81, v72, v81
	v_max_u32_e32 v72, v95, v78
	v_min_u32_e32 v78, v95, v78
	v_max_u32_e32 v95, v94, v85
	v_min_u32_e32 v85, v94, v85
	v_max_u32_e32 v94, v88, v101
	v_min_u32_e32 v101, v88, v101
	v_max_u32_e32 v88, v80, v74
	v_min_u32_e32 v74, v80, v74
	v_max_u32_e32 v80, v100, v72
	v_min_u32_e32 v72, v100, v72
	v_max_u32_e32 v100, v84, v95
	v_min_u32_e32 v95, v84, v95
	v_max_u32_e32 v84, v79, v86
	v_min_u32_e32 v86, v79, v86
	v_max_u32_e32 v79, v71, v81
	v_min_u32_e32 v81, v71, v81
	v_max_u32_e32 v71, v76, v78
	v_min_u32_e32 v78, v76, v78
	v_max_u32_e32 v76, v77, v85
	v_min_u32_e32 v85, v77, v85
	v_max_u32_e32 v77, v94, v80
	v_min_u32_e32 v80, v94, v80
	v_max_u32_e32 v94, v88, v100
	v_min_u32_e32 v100, v88, v100
	v_max_u32_e32 v88, v101, v72
	v_min_u32_e32 v72, v101, v72
	v_max_u32_e32 v101, v74, v95
	v_min_u32_e32 v95, v74, v95
	v_max_u32_e32 v74, v84, v71
	v_min_u32_e32 v71, v84, v71
	v_max_u32_e32 v84, v79, v76
	v_min_u32_e32 v76, v79, v76
	v_max_u32_e32 v79, v86, v78
	v_min_u32_e32 v78, v86, v78
	v_max_u32_e32 v86, v81, v85
	v_min_u32_e32 v85, v81, v85
	v_max_u32_e32 v81, v77, v94
	v_min_u32_e32 v94, v77, v94
	v_max_u32_e32 v77, v80, v100
	v_min_u32_e32 v100, v80, v100
	v_max_u32_e32 v80, v88, v101
	v_min_u32_e32 v101, v88, v101
	v_max_u32_e32 v88, v72, v95
	v_min_u32_e32 v95, v72, v95
	v_max_u32_e32 v72, v74, v84
	v_min_u32_e32 v84, v74, v84
	v_max_u32_e32 v74, v71, v76
	v_min_u32_e32 v76, v71, v76
	v_max_u32_e32 v71, v79, v86
	v_min_u32_e32 v86, v79, v86
	v_max_u32_e32 v79, v78, v85
	v_min_u32_e32 v85, v78, v85
	v_cvt_f32_f16_e32 v78, v48
	v_cvt_f32_f16_sdwa v82, v48 dst_sel:DWORD dst_unused:UNUSED_PAD src0_sel:WORD_1
	v_ashrrev_i32_e32 v92, 31, v78
	v_bitop3_b32 v78, v78, v92, s40 bitop3:0x78
	v_xor_b32_e32 v78, 0x8000001f, v78
	v_ashrrev_i32_e32 v92, 31, v82
	v_bitop3_b32 v82, v82, v92, s40 bitop3:0x78
	v_xor_b32_e32 v82, 0x8000001e, v82
	v_cvt_f32_f16_e32 v92, v49
	v_cvt_f32_f16_sdwa v98, v49 dst_sel:DWORD dst_unused:UNUSED_PAD src0_sel:WORD_1
	v_ashrrev_i32_e32 v102, 31, v92
	v_bitop3_b32 v92, v92, v102, s40 bitop3:0x78
	v_xor_b32_e32 v92, 0x8000001d, v92
	v_ashrrev_i32_e32 v102, 31, v98
	v_bitop3_b32 v98, v98, v102, s40 bitop3:0x78
	v_xor_b32_e32 v98, 0x8000001c, v98
	v_cvt_f32_f16_e32 v102, v50
	v_cvt_f32_f16_sdwa v73, v50 dst_sel:DWORD dst_unused:UNUSED_PAD src0_sel:WORD_1
	v_ashrrev_i32_e32 v91, 31, v102
	v_bitop3_b32 v102, v102, v91, s40 bitop3:0x78
	v_xor_b32_e32 v102, 0x8000001b, v102
	v_ashrrev_i32_e32 v91, 31, v73
	v_bitop3_b32 v73, v73, v91, s40 bitop3:0x78
	v_xor_b32_e32 v73, 0x8000001a, v73
	v_cvt_f32_f16_e32 v91, v51
	v_cvt_f32_f16_sdwa v90, v51 dst_sel:DWORD dst_unused:UNUSED_PAD src0_sel:WORD_1
	v_ashrrev_i32_e32 v96, 31, v91
	v_bitop3_b32 v91, v91, v96, s40 bitop3:0x78
	v_xor_b32_e32 v91, 0x80000019, v91
	v_ashrrev_i32_e32 v96, 31, v90
	v_bitop3_b32 v90, v90, v96, s40 bitop3:0x78
	v_xor_b32_e32 v90, 0x80000018, v90
	v_cvt_f32_f16_e32 v96, v52
	v_cvt_f32_f16_sdwa v89, v52 dst_sel:DWORD dst_unused:UNUSED_PAD src0_sel:WORD_1
	v_ashrrev_i32_e32 v87, 31, v96
	v_bitop3_b32 v96, v96, v87, s40 bitop3:0x78
	v_xor_b32_e32 v96, 0x80000017, v96
	v_ashrrev_i32_e32 v87, 31, v89
	v_bitop3_b32 v89, v89, v87, s40 bitop3:0x78
	v_xor_b32_e32 v89, 0x80000016, v89
	v_cvt_f32_f16_e32 v87, v53
	v_cvt_f32_f16_sdwa v70, v53 dst_sel:DWORD dst_unused:UNUSED_PAD src0_sel:WORD_1
	v_ashrrev_i32_e32 v83, 31, v87
	v_bitop3_b32 v87, v87, v83, s40 bitop3:0x78
	v_xor_b32_e32 v87, 0x80000015, v87
	v_ashrrev_i32_e32 v83, 31, v70
	v_bitop3_b32 v70, v70, v83, s40 bitop3:0x78
	v_xor_b32_e32 v70, 0x80000014, v70
	v_cvt_f32_f16_e32 v83, v54
	v_cvt_f32_f16_sdwa v97, v54 dst_sel:DWORD dst_unused:UNUSED_PAD src0_sel:WORD_1
	v_ashrrev_i32_e32 v99, 31, v83
	v_bitop3_b32 v83, v83, v99, s40 bitop3:0x78
	v_xor_b32_e32 v83, 0x80000013, v83
	v_ashrrev_i32_e32 v99, 31, v97
	v_bitop3_b32 v97, v97, v99, s40 bitop3:0x78
	v_xor_b32_e32 v97, 0x80000012, v97
	v_cvt_f32_f16_e32 v99, v55
	v_cvt_f32_f16_sdwa v93, v55 dst_sel:DWORD dst_unused:UNUSED_PAD src0_sel:WORD_1
	v_ashrrev_i32_e32 v75, 31, v99
	v_bitop3_b32 v99, v99, v75, s40 bitop3:0x78
	v_xor_b32_e32 v99, 0x80000011, v99
	v_ashrrev_i32_e32 v75, 31, v93
	v_bitop3_b32 v93, v93, v75, s40 bitop3:0x78
	v_xor_b32_e32 v93, 0x80000010, v93
	v_max_u32_e32 v75, v78, v97
	v_min_u32_e32 v97, v78, v97
	v_max_u32_e32 v78, v82, v83
	v_min_u32_e32 v83, v82, v83
	v_max_u32_e32 v82, v92, v93
	v_min_u32_e32 v93, v92, v93
; #define CE_DESC(a, b) do { const unsigned _mx = (a) > (b) ? (a) : (b), _mn = (a) > (b) ? (b) : (a); (a) = _mx; (b) = _mn; } while (0)
; __device__ __forceinline__ void sort16_desc(unsigned (&k)[16]) {
; #pragma unroll
;     for (int size = 2; size <= 16; size <<= 1)
; #pragma unroll
;         for (int stride = size >> 1; stride > 0; stride >>= 1)
; #pragma unroll
;             for (int i = 0; i < 16; ++i) { const int j = i ^ stride;
;                 if (j > i) { if ((i & size) == 0) CE_DESC(k[i], k[j]); else CE_DESC(k[j], k[i]); } }
; }
; __device__ __forceinline__ void merge16(unsigned (&a)[16], const unsigned (&b)[16]) {
; #pragma unroll
;     for (int i = 0; i < 16; ++i) a[i] = a[i] > b[15 - i] ? a[i] : b[15 - i];
; #pragma unroll
;     for (int stride = 8; stride > 0; stride >>= 1)
; #pragma unroll
;         for (int i = 0; i < 16; ++i) { const int j = i ^ stride; if (j > i) CE_DESC(a[i], a[j]); }
; }
	v_max_u32_e32 v92, v98, v99
	v_min_u32_e32 v99, v98, v99
	v_max_u32_e32 v98, v102, v96
	v_min_u32_e32 v96, v102, v96
	v_max_u32_e32 v102, v73, v91
	v_min_u32_e32 v91, v73, v91
	v_max_u32_e32 v73, v90, v70
	v_min_u32_e32 v70, v90, v70
	v_max_u32_e32 v90, v89, v87
	v_min_u32_e32 v87, v89, v87
	v_max_u32_e32 v89, v75, v102
	v_min_u32_e32 v102, v75, v102
	v_max_u32_e32 v75, v78, v73
	v_min_u32_e32 v73, v78, v73
	v_max_u32_e32 v78, v82, v90
	v_min_u32_e32 v90, v82, v90
	v_max_u32_e32 v82, v92, v98
	v_min_u32_e32 v98, v92, v98
	v_max_u32_e32 v92, v91, v97
	v_min_u32_e32 v97, v91, v97
	v_max_u32_e32 v91, v96, v99
	v_min_u32_e32 v99, v96, v99
	v_max_u32_e32 v96, v87, v93
	v_min_u32_e32 v93, v87, v93
	v_max_u32_e32 v87, v70, v83
	v_min_u32_e32 v83, v70, v83
	v_max_u32_e32 v70, v89, v75
	v_min_u32_e32 v75, v89, v75
	v_max_u32_e32 v89, v78, v82
	v_min_u32_e32 v82, v78, v82
	v_max_u32_e32 v78, v98, v102
	v_min_u32_e32 v102, v98, v102
	v_max_u32_e32 v98, v92, v91
	v_min_u32_e32 v91, v92, v91
	v_max_u32_e32 v92, v73, v90
	v_min_u32_e32 v90, v73, v90
	v_max_u32_e32 v73, v96, v87
	v_min_u32_e32 v87, v96, v87
	v_max_u32_e32 v96, v83, v97
	v_min_u32_e32 v97, v83, v97
	v_max_u32_e32 v83, v99, v93
	v_min_u32_e32 v93, v99, v93
	v_max_u32_e32 v99, v70, v89
	v_min_u32_e32 v89, v70, v89
	v_max_u32_e32 v70, v75, v82
	v_min_u32_e32 v82, v75, v82
	v_max_u32_e32 v75, v78, v73
	v_min_u32_e32 v73, v78, v73
	v_max_u32_e32 v78, v102, v87
	v_min_u32_e32 v87, v102, v87
	v_max_u32_e32 v102, v98, v92
	v_min_u32_e32 v92, v98, v92
	v_max_u32_e32 v98, v91, v90
	v_min_u32_e32 v90, v91, v90
	v_max_u32_e32 v91, v96, v83
	v_min_u32_e32 v83, v96, v83
	v_max_u32_e32 v96, v97, v93
	v_min_u32_e32 v93, v97, v93
	v_max_u32_e32 v97, v70, v89
	v_min_u32_e32 v89, v70, v89
	v_max_u32_e32 v70, v82, v91
	v_min_u32_e32 v91, v82, v91
	v_max_u32_e32 v82, v75, v102
	v_min_u32_e32 v102, v75, v102
	v_max_u32_e32 v75, v78, v92
	v_min_u32_e32 v92, v78, v92
	v_max_u32_e32 v78, v98, v73
	v_min_u32_e32 v73, v98, v73
	v_max_u32_e32 v98, v90, v87
	v_min_u32_e32 v87, v90, v87
	v_max_u32_e32 v90, v96, v83
	v_min_u32_e32 v83, v96, v83
	v_max_u32_e32 v96, v97, v82
	v_min_u32_e32 v82, v97, v82
	v_max_u32_e32 v97, v89, v102
	v_min_u32_e32 v102, v89, v102
	v_max_u32_e32 v89, v75, v78
	v_min_u32_e32 v78, v75, v78
	v_max_u32_e32 v75, v92, v73
	v_min_u32_e32 v73, v92, v73
	v_max_u32_e32 v92, v98, v90
	v_min_u32_e32 v90, v98, v90
	v_max_u32_e32 v98, v87, v83
	v_min_u32_e32 v83, v87, v83
	v_max_u32_e32 v87, v97, v82
	v_min_u32_e32 v82, v97, v82
	v_max_u32_e32 v97, v70, v102
	v_min_u32_e32 v102, v70, v102
	v_max_u32_e32 v70, v92, v91
	v_min_u32_e32 v91, v92, v91
	v_max_u32_e32 v92, v98, v90
	v_min_u32_e32 v90, v98, v90
	v_max_u32_e32 v98, v97, v89
	v_min_u32_e32 v89, v97, v89
	v_max_u32_e32 v97, v102, v78
	v_min_u32_e32 v78, v102, v78
	v_max_u32_e32 v102, v75, v70
	v_min_u32_e32 v70, v75, v70
	v_max_u32_e32 v75, v73, v91
	v_min_u32_e32 v91, v73, v91
	v_max_u32_e32 v73, v98, v82
	v_min_u32_e32 v82, v98, v82
	v_max_u32_e32 v98, v89, v97
	v_min_u32_e32 v97, v89, v97
	v_max_u32_e32 v89, v102, v78
	v_min_u32_e32 v78, v102, v78
	v_max_u32_e32 v102, v70, v75
	v_min_u32_e32 v75, v70, v75
	v_max_u32_e32 v70, v92, v91
	v_min_u32_e32 v91, v92, v91
	v_max_u32_e32 v92, v97, v89
	v_min_u32_e32 v89, v97, v89
	v_max_u32_e32 v97, v78, v102
	v_min_u32_e32 v102, v78, v102
	v_max_u32_e32 v81, v81, v93
	v_max_u32_e32 v94, v94, v83
	v_max_u32_e32 v77, v77, v90
	v_max_u32_e32 v100, v100, v91
	v_max_u32_e32 v80, v80, v70
	v_max_u32_e32 v101, v101, v75
	v_max_u32_e32 v88, v88, v102
	v_max_u32_e32 v95, v95, v97
	v_max_u32_e32 v72, v72, v89
	v_max_u32_e32 v84, v84, v92
	v_max_u32_e32 v74, v74, v98
	v_max_u32_e32 v76, v76, v82
	v_max_u32_e32 v71, v71, v73
	v_max_u32_e32 v86, v86, v87
	v_max_u32_e32 v79, v79, v96
	v_max_u32_e32 v85, v85, v99
	v_max_u32_e32 v93, v81, v72
	v_min_u32_e32 v72, v81, v72
	v_max_u32_e32 v81, v94, v84
	v_min_u32_e32 v84, v94, v84
	v_max_u32_e32 v94, v77, v74
	v_min_u32_e32 v74, v77, v74
	v_max_u32_e32 v77, v100, v76
	v_min_u32_e32 v76, v100, v76
	v_max_u32_e32 v100, v80, v71
	v_min_u32_e32 v71, v80, v71
	v_max_u32_e32 v80, v101, v86
	v_min_u32_e32 v86, v101, v86
	v_max_u32_e32 v101, v88, v79
	v_min_u32_e32 v79, v88, v79
	v_max_u32_e32 v88, v95, v85
	v_min_u32_e32 v85, v95, v85
	v_max_u32_e32 v95, v93, v100
	v_min_u32_e32 v100, v93, v100
	v_max_u32_e32 v93, v81, v80
	v_min_u32_e32 v80, v81, v80
	v_max_u32_e32 v81, v94, v101
	v_min_u32_e32 v101, v94, v101
	v_max_u32_e32 v94, v77, v88
	v_min_u32_e32 v88, v77, v88
	v_max_u32_e32 v77, v72, v71
	v_min_u32_e32 v71, v72, v71
	v_max_u32_e32 v72, v84, v86
	v_min_u32_e32 v86, v84, v86
	v_max_u32_e32 v84, v74, v79
	v_min_u32_e32 v79, v74, v79
	v_max_u32_e32 v74, v76, v85
	v_min_u32_e32 v85, v76, v85
	v_max_u32_e32 v76, v95, v81
	v_min_u32_e32 v81, v95, v81
	v_max_u32_e32 v95, v93, v94
	v_min_u32_e32 v94, v93, v94
	v_max_u32_e32 v93, v100, v101
	v_min_u32_e32 v101, v100, v101
	v_max_u32_e32 v100, v80, v88
	v_min_u32_e32 v88, v80, v88
	v_max_u32_e32 v80, v77, v84
	v_min_u32_e32 v84, v77, v84
	v_max_u32_e32 v77, v72, v74
	v_min_u32_e32 v74, v72, v74
	v_max_u32_e32 v72, v71, v79
	v_min_u32_e32 v79, v71, v79
	v_max_u32_e32 v71, v86, v85
	v_min_u32_e32 v85, v86, v85
	v_max_u32_e32 v86, v76, v95
	v_min_u32_e32 v95, v76, v95
	v_max_u32_e32 v76, v81, v94
	v_min_u32_e32 v94, v81, v94
	v_max_u32_e32 v81, v93, v100
	v_min_u32_e32 v100, v93, v100
	v_max_u32_e32 v93, v101, v88
	v_min_u32_e32 v88, v101, v88
	v_max_u32_e32 v101, v80, v77
	v_min_u32_e32 v77, v80, v77
	v_max_u32_e32 v80, v84, v74
	v_min_u32_e32 v74, v84, v74
	v_max_u32_e32 v84, v72, v71
	v_min_u32_e32 v71, v72, v71
; __device__ __forceinline__ unsigned f2key(float f) { const unsigned u = __float_as_uint(f); return (u & 0x80000000u) ? ~u : (u | 0x80000000u); }
; #define CE_DESC(a, b) do { const unsigned _mx = (a) > (b) ? (a) : (b), _mn = (a) > (b) ? (b) : (a); (a) = _mx; (b) = _mn; } while (0)
; __device__ __forceinline__ void sort16_desc(unsigned (&k)[16]) {
; #pragma unroll
;     for (int size = 2; size <= 16; size <<= 1)
; #pragma unroll
;         for (int stride = size >> 1; stride > 0; stride >>= 1)
; #pragma unroll
;             for (int i = 0; i < 16; ++i) { const int j = i ^ stride;
;                 if (j > i) { if ((i & size) == 0) CE_DESC(k[i], k[j]); else CE_DESC(k[j], k[i]); } }
; }
; __device__ __forceinline__ void peer_tile(const Args& A, LAS unsigned char* lds, int tile) {
;     ...
;                   for (int i = 0; i < 16; ++i) {
;                       const float lo = (float)__builtin_bit_cast(_Float16, (unsigned short)(sw[i] & 0xffffu)), hi = (float)__builtin_bit_cast(_Float16, (unsigned short)(sw[i] >> 16));
;                       const unsigned klo = (f2key(lo) & ~127u) | (unsigned)(127 - (32 * g + 2 * i)), khi = (f2key(hi) & ~127u) | (unsigned)(127 - (32 * g + 2 * i + 1));
;                       if (i < 8) { k0[2 * i] = klo; k0[2 * i + 1] = khi; } else { k1[2 * (i - 8)] = klo; k1[2 * (i - 8) + 1] = khi; } } }
	v_max_u32_e32 v72, v79, v85
	v_min_u32_e32 v85, v79, v85
	v_cvt_f32_f16_e32 v79, v56
	v_cvt_f32_f16_sdwa v83, v56 dst_sel:DWORD dst_unused:UNUSED_PAD src0_sel:WORD_1
	v_ashrrev_i32_e32 v90, 31, v79
	v_bitop3_b32 v79, v79, v90, s40 bitop3:0x78
	v_xor_b32_e32 v79, 0x8000000f, v79
	v_ashrrev_i32_e32 v90, 31, v83
	v_bitop3_b32 v83, v83, v90, s40 bitop3:0x78
	v_xor_b32_e32 v83, 0x8000000e, v83
	v_cvt_f32_f16_e32 v90, v57
	v_cvt_f32_f16_sdwa v91, v57 dst_sel:DWORD dst_unused:UNUSED_PAD src0_sel:WORD_1
	v_ashrrev_i32_e32 v70, 31, v90
	v_bitop3_b32 v90, v90, v70, s40 bitop3:0x78
	v_xor_b32_e32 v90, 0x8000000d, v90
	v_ashrrev_i32_e32 v70, 31, v91
	v_bitop3_b32 v91, v91, v70, s40 bitop3:0x78
	v_xor_b32_e32 v91, 0x8000000c, v91
	v_cvt_f32_f16_e32 v70, v58
	v_cvt_f32_f16_sdwa v75, v58 dst_sel:DWORD dst_unused:UNUSED_PAD src0_sel:WORD_1
	v_ashrrev_i32_e32 v102, 31, v70
	v_bitop3_b32 v70, v70, v102, s40 bitop3:0x78
	v_xor_b32_e32 v70, 0x8000000b, v70
	v_ashrrev_i32_e32 v102, 31, v75
	v_bitop3_b32 v75, v75, v102, s40 bitop3:0x78
	v_xor_b32_e32 v75, 0x8000000a, v75
	v_cvt_f32_f16_e32 v102, v59
	v_cvt_f32_f16_sdwa v97, v59 dst_sel:DWORD dst_unused:UNUSED_PAD src0_sel:WORD_1
	v_ashrrev_i32_e32 v89, 31, v102
	v_bitop3_b32 v102, v102, v89, s40 bitop3:0x78
	v_xor_b32_e32 v102, 0x80000009, v102
	v_ashrrev_i32_e32 v89, 31, v97
	v_bitop3_b32 v97, v97, v89, s40 bitop3:0x78
	v_xor_b32_e32 v97, 0x80000008, v97
	v_cvt_f32_f16_e32 v89, v60
	v_cvt_f32_f16_sdwa v92, v60 dst_sel:DWORD dst_unused:UNUSED_PAD src0_sel:WORD_1
	v_ashrrev_i32_e32 v98, 31, v89
	v_bitop3_b32 v89, v89, v98, s40 bitop3:0x78
	v_xor_b32_e32 v89, 0x80000007, v89
	v_ashrrev_i32_e32 v98, 31, v92
	v_bitop3_b32 v92, v92, v98, s40 bitop3:0x78
	v_xor_b32_e32 v92, 0x80000006, v92
	v_cvt_f32_f16_e32 v98, v61
	v_cvt_f32_f16_sdwa v82, v61 dst_sel:DWORD dst_unused:UNUSED_PAD src0_sel:WORD_1
	v_ashrrev_i32_e32 v73, 31, v98
	v_bitop3_b32 v98, v98, v73, s40 bitop3:0x78
	v_xor_b32_e32 v98, 0x80000005, v98
	v_ashrrev_i32_e32 v73, 31, v82
	v_bitop3_b32 v82, v82, v73, s40 bitop3:0x78
	v_xor_b32_e32 v82, 0x80000004, v82
	v_cvt_f32_f16_e32 v73, v62
	v_cvt_f32_f16_sdwa v87, v62 dst_sel:DWORD dst_unused:UNUSED_PAD src0_sel:WORD_1
	v_ashrrev_i32_e32 v96, 31, v73
	v_bitop3_b32 v73, v73, v96, s40 bitop3:0x78
	v_xor_b32_e32 v73, 0x80000003, v73
	v_ashrrev_i32_e32 v96, 31, v87
	v_bitop3_b32 v87, v87, v96, s40 bitop3:0x78
	v_xor_b32_e32 v87, 0x80000002, v87
	v_cvt_f32_f16_e32 v96, v63
	v_cvt_f32_f16_sdwa v99, v63 dst_sel:DWORD dst_unused:UNUSED_PAD src0_sel:WORD_1
	v_ashrrev_i32_e32 v78, 31, v96
	v_bitop3_b32 v96, v96, v78, s40 bitop3:0x78
	v_xor_b32_e32 v96, 0x80000001, v96
	v_ashrrev_i32_e32 v78, 31, v99
	v_bitop3_b32 v99, v99, v78, s40 bitop3:0x78
	v_xor_b32_e32 v99, 0x80000000, v99
	v_max_u32_e32 v78, v79, v87
	v_min_u32_e32 v87, v79, v87
	v_max_u32_e32 v79, v83, v73
	v_min_u32_e32 v73, v83, v73
	v_max_u32_e32 v83, v90, v99
	v_min_u32_e32 v99, v90, v99
	v_max_u32_e32 v90, v91, v96
	v_min_u32_e32 v96, v91, v96
	v_max_u32_e32 v91, v70, v89
	v_min_u32_e32 v89, v70, v89
	v_max_u32_e32 v70, v75, v102
	v_min_u32_e32 v102, v75, v102
	v_max_u32_e32 v75, v97, v82
	v_min_u32_e32 v82, v97, v82
	v_max_u32_e32 v97, v92, v98
	v_min_u32_e32 v98, v92, v98
	v_max_u32_e32 v92, v78, v70
	v_min_u32_e32 v70, v78, v70
	v_max_u32_e32 v78, v79, v75
	v_min_u32_e32 v75, v79, v75
	v_max_u32_e32 v79, v83, v97
	v_min_u32_e32 v97, v83, v97
	v_max_u32_e32 v83, v90, v91
	v_min_u32_e32 v91, v90, v91
	v_max_u32_e32 v90, v102, v87
	v_min_u32_e32 v87, v102, v87
	v_max_u32_e32 v102, v89, v96
	v_min_u32_e32 v96, v89, v96
	v_max_u32_e32 v89, v98, v99
	v_min_u32_e32 v99, v98, v99
	v_max_u32_e32 v98, v82, v73
	v_min_u32_e32 v73, v82, v73
	v_max_u32_e32 v82, v92, v78
	v_min_u32_e32 v78, v92, v78
	v_max_u32_e32 v92, v79, v83
	v_min_u32_e32 v83, v79, v83
	v_max_u32_e32 v79, v91, v70
	v_min_u32_e32 v70, v91, v70
	v_max_u32_e32 v91, v90, v102
	v_min_u32_e32 v102, v90, v102
	v_max_u32_e32 v90, v75, v97
	v_min_u32_e32 v97, v75, v97
	v_max_u32_e32 v75, v89, v98
	v_min_u32_e32 v98, v89, v98
	v_max_u32_e32 v89, v73, v87
	v_min_u32_e32 v87, v73, v87
	v_max_u32_e32 v73, v96, v99
	v_min_u32_e32 v99, v96, v99
	v_max_u32_e32 v96, v82, v92
	v_min_u32_e32 v92, v82, v92
	v_max_u32_e32 v82, v78, v83
	v_min_u32_e32 v83, v78, v83
	v_max_u32_e32 v78, v79, v75
	v_min_u32_e32 v75, v79, v75
	v_max_u32_e32 v79, v70, v98
	v_min_u32_e32 v98, v70, v98
	v_max_u32_e32 v70, v91, v90
	v_min_u32_e32 v90, v91, v90
	v_max_u32_e32 v91, v102, v97
	v_min_u32_e32 v97, v102, v97
	v_max_u32_e32 v102, v89, v73
	v_min_u32_e32 v73, v89, v73
	v_max_u32_e32 v89, v87, v99
	v_min_u32_e32 v99, v87, v99
	v_max_u32_e32 v87, v82, v92
	v_min_u32_e32 v92, v82, v92
	v_max_u32_e32 v82, v83, v102
	v_min_u32_e32 v102, v83, v102
	v_max_u32_e32 v83, v78, v70
	v_min_u32_e32 v70, v78, v70
	v_max_u32_e32 v78, v79, v90
	v_min_u32_e32 v90, v79, v90
	v_max_u32_e32 v79, v91, v75
	v_min_u32_e32 v75, v91, v75
	v_max_u32_e32 v91, v97, v98
	v_min_u32_e32 v98, v97, v98
	v_max_u32_e32 v97, v89, v73
	v_min_u32_e32 v73, v89, v73
	v_max_u32_e32 v89, v87, v83
	v_min_u32_e32 v83, v87, v83
	v_max_u32_e32 v87, v92, v70
	v_min_u32_e32 v70, v92, v70
	v_max_u32_e32 v92, v78, v79
	v_min_u32_e32 v79, v78, v79
	v_max_u32_e32 v78, v90, v75
	v_min_u32_e32 v75, v90, v75
	v_max_u32_e32 v90, v91, v97
	v_min_u32_e32 v97, v91, v97
	v_max_u32_e32 v91, v98, v73
	v_min_u32_e32 v73, v98, v73
	v_max_u32_e32 v98, v87, v83
	v_min_u32_e32 v83, v87, v83
	v_max_u32_e32 v87, v82, v70
	v_min_u32_e32 v70, v82, v70
	v_max_u32_e32 v82, v90, v102
	v_min_u32_e32 v102, v90, v102
	v_max_u32_e32 v90, v91, v97
	v_min_u32_e32 v97, v91, v97
	v_max_u32_e32 v91, v87, v92
; #define CE_DESC(a, b) do { const unsigned _mx = (a) > (b) ? (a) : (b), _mn = (a) > (b) ? (b) : (a); (a) = _mx; (b) = _mn; } while (0)
; __device__ __forceinline__ void merge16(unsigned (&a)[16], const unsigned (&b)[16]) {
; #pragma unroll
;     for (int i = 0; i < 16; ++i) a[i] = a[i] > b[15 - i] ? a[i] : b[15 - i];
; #pragma unroll
;     for (int stride = 8; stride > 0; stride >>= 1)
; #pragma unroll
;         for (int i = 0; i < 16; ++i) { const int j = i ^ stride; if (j > i) CE_DESC(a[i], a[j]); }
; }
; __device__ __forceinline__ void peer_tile(const Args& A, LAS unsigned char* lds, int tile) {
;     ...
;                 { const bf16_t* sp = QRY + m * 2048 + hp * 128 + 32 * g;
;                   const u32x4 s0 = *(const u32x4*)sp, s1 = *(const u32x4*)(sp + 8), s2 = *(const u32x4*)(sp + 16), s3 = *(const u32x4*)(sp + 24);
	v_min_u32_e32 v92, v87, v92
	v_max_u32_e32 v87, v70, v79
	v_min_u32_e32 v79, v70, v79
	v_max_u32_e32 v70, v78, v82
	v_min_u32_e32 v82, v78, v82
	v_max_u32_e32 v78, v75, v102
	v_min_u32_e32 v102, v75, v102
	v_max_u32_e32 v75, v91, v83
	v_min_u32_e32 v83, v91, v83
	v_max_u32_e32 v91, v92, v87
	v_min_u32_e32 v87, v92, v87
	v_max_u32_e32 v92, v70, v79
	v_min_u32_e32 v79, v70, v79
	v_max_u32_e32 v70, v82, v78
	v_min_u32_e32 v78, v82, v78
	v_max_u32_e32 v82, v90, v102
	v_min_u32_e32 v102, v90, v102
	v_max_u32_e32 v90, v87, v92
	v_min_u32_e32 v92, v87, v92
	v_max_u32_e32 v87, v79, v70
	v_min_u32_e32 v70, v79, v70
	v_max_u32_e32 v86, v86, v99
	v_max_u32_e32 v95, v95, v73
	v_max_u32_e32 v76, v76, v97
	v_max_u32_e32 v94, v94, v102
	v_max_u32_e32 v81, v81, v82
	v_max_u32_e32 v100, v100, v78
	v_max_u32_e32 v93, v93, v70
	v_max_u32_e32 v88, v88, v87
	v_max_u32_e32 v101, v101, v92
	v_max_u32_e32 v77, v77, v90
	v_max_u32_e32 v80, v80, v91
	v_max_u32_e32 v74, v74, v83
	v_max_u32_e32 v84, v84, v75
	v_max_u32_e32 v71, v71, v98
	v_max_u32_e32 v72, v72, v89
	v_max_u32_e32 v85, v85, v96
	v_max_u32_e32 v99, v86, v101
	v_min_u32_e32 v101, v86, v101
	v_max_u32_e32 v86, v95, v77
	v_min_u32_e32 v77, v95, v77
	v_max_u32_e32 v95, v76, v80
	v_min_u32_e32 v80, v76, v80
	v_max_u32_e32 v76, v94, v74
	v_min_u32_e32 v74, v94, v74
	v_max_u32_e32 v94, v81, v84
	v_min_u32_e32 v84, v81, v84
	v_max_u32_e32 v81, v100, v71
	v_min_u32_e32 v71, v100, v71
	v_max_u32_e32 v100, v93, v72
	v_min_u32_e32 v72, v93, v72
	v_max_u32_e32 v93, v88, v85
	v_min_u32_e32 v85, v88, v85
	v_max_u32_e32 v88, v99, v94
	v_min_u32_e32 v94, v99, v94
	v_max_u32_e32 v99, v86, v81
	v_min_u32_e32 v81, v86, v81
	v_max_u32_e32 v86, v95, v100
	v_min_u32_e32 v100, v95, v100
	v_max_u32_e32 v95, v76, v93
	v_min_u32_e32 v93, v76, v93
	v_max_u32_e32 v76, v101, v84
	v_min_u32_e32 v84, v101, v84
	v_max_u32_e32 v101, v77, v71
	v_min_u32_e32 v71, v77, v71
	v_max_u32_e32 v77, v80, v72
	v_min_u32_e32 v72, v80, v72
	v_max_u32_e32 v80, v74, v85
	v_min_u32_e32 v85, v74, v85
	v_max_u32_e32 v74, v88, v86
	v_min_u32_e32 v86, v88, v86
	v_max_u32_e32 v88, v99, v95
	v_min_u32_e32 v95, v99, v95
	v_max_u32_e32 v99, v94, v100
	v_min_u32_e32 v100, v94, v100
	v_max_u32_e32 v94, v81, v93
	v_min_u32_e32 v93, v81, v93
	v_max_u32_e32 v81, v76, v77
	v_min_u32_e32 v77, v76, v77
	v_max_u32_e32 v76, v101, v80
	v_min_u32_e32 v80, v101, v80
	v_max_u32_e32 v101, v84, v72
	v_min_u32_e32 v72, v84, v72
	v_max_u32_e32 v84, v71, v85
	v_min_u32_e32 v85, v71, v85
	v_max_u32_e32 v71, v74, v88
	v_min_u32_e32 v88, v74, v88
	v_max_u32_e32 v74, v86, v95
	v_min_u32_e32 v95, v86, v95
	v_max_u32_e32 v86, v99, v94
	v_min_u32_e32 v94, v99, v94
	v_max_u32_e32 v99, v100, v93
	v_min_u32_e32 v93, v100, v93
	v_max_u32_e32 v100, v81, v76
	v_min_u32_e32 v76, v81, v76
	v_max_u32_e32 v81, v77, v80
	v_min_u32_e32 v80, v77, v80
	v_max_u32_e32 v77, v101, v84
	v_min_u32_e32 v84, v101, v84
	v_max_u32_e32 v101, v72, v85
	v_min_u32_e32 v85, v72, v85
	s_mov_b64 s[38:39], s[34:35]
	global_load_dwordx4 v[32:35], v66, s[38:39] offset:384
	s_add_u32 s38, s38, 0x8000
	s_addc_u32 s39, s39, 0
	global_load_dwordx4 v[36:39], v66, s[38:39] offset:384
	s_add_u32 s38, s38, 0x8000
	s_addc_u32 s39, s39, 0
	global_load_dwordx4 v[40:43], v66, s[38:39] offset:384
	s_add_u32 s38, s38, 0x8000
	s_addc_u32 s39, s39, 0
	global_load_dwordx4 v[44:47], v66, s[38:39] offset:384
	s_add_u32 s38, s38, 0x8000
	s_addc_u32 s39, s39, 0
	global_load_dwordx4 v[48:51], v66, s[38:39] offset:384
	s_add_u32 s38, s38, 0x8000
	s_addc_u32 s39, s39, 0
	global_load_dwordx4 v[52:55], v66, s[38:39] offset:384
	s_add_u32 s38, s38, 0x8000
	s_addc_u32 s39, s39, 0
	global_load_dwordx4 v[56:59], v66, s[38:39] offset:384
	s_add_u32 s38, s38, 0x8000
	s_addc_u32 s39, s39, 0
	global_load_dwordx4 v[60:63], v66, s[38:39] offset:384
	s_waitcnt vmcnt(8)
	ds_write_b128 v64, v[0:3] offset:0
	ds_write_b128 v64, v[4:7] offset:1152
	ds_write_b128 v64, v[8:11] offset:2304
	ds_write_b128 v64, v[12:15] offset:3456
	ds_write_b128 v64, v[16:19] offset:4608
	ds_write_b128 v64, v[20:23] offset:5760
	ds_write_b128 v64, v[24:27] offset:6912
	ds_write_b128 v64, v[28:31] offset:8064
	s_waitcnt lgkmcnt(0)
	ds_read_b128 v[0:3], v65 offset:0
	ds_read_b128 v[4:7], v65 offset:16
	ds_read_b128 v[8:11], v65 offset:32
	ds_read_b128 v[12:15], v65 offset:48
	ds_read_b128 v[16:19], v65 offset:64
	ds_read_b128 v[20:23], v65 offset:80
	ds_read_b128 v[24:27], v65 offset:96
	ds_read_b128 v[28:31], v65 offset:112
	s_waitcnt lgkmcnt(0)
; __device__ __forceinline__ unsigned f2key(float f) { const unsigned u = __float_as_uint(f); return (u & 0x80000000u) ? ~u : (u | 0x80000000u); }
; #define CE_DESC(a, b) do { const unsigned _mx = (a) > (b) ? (a) : (b), _mn = (a) > (b) ? (b) : (a); (a) = _mx; (b) = _mn; } while (0)
; __device__ __forceinline__ void sort16_desc(unsigned (&k)[16]) {
; #pragma unroll
;     for (int size = 2; size <= 16; size <<= 1)
; #pragma unroll
;         for (int stride = size >> 1; stride > 0; stride >>= 1)
; #pragma unroll
;             for (int i = 0; i < 16; ++i) { const int j = i ^ stride;
;                 if (j > i) { if ((i & size) == 0) CE_DESC(k[i], k[j]); else CE_DESC(k[j], k[i]); } }
; }
; __device__ __forceinline__ void peer_tile(const Args& A, LAS unsigned char* lds, int tile) {
;     ...
;                   for (int i = 0; i < 16; ++i) {
;                       const float lo = (float)__builtin_bit_cast(_Float16, (unsigned short)(sw[i] & 0xffffu)), hi = (float)__builtin_bit_cast(_Float16, (unsigned short)(sw[i] >> 16));
;                       const unsigned klo = (f2key(lo) & ~127u) | (unsigned)(127 - (32 * g + 2 * i)), khi = (f2key(hi) & ~127u) | (unsigned)(127 - (32 * g + 2 * i + 1));
;                       if (i < 8) { k0[2 * i] = klo; k0[2 * i + 1] = khi; } else { k1[2 * (i - 8)] = klo; k1[2 * (i - 8) + 1] = khi; } } }
	v_cvt_f32_f16_e32 v72, v0
	v_cvt_f32_f16_sdwa v73, v0 dst_sel:DWORD dst_unused:UNUSED_PAD src0_sel:WORD_1
	v_ashrrev_i32_e32 v97, 31, v72
	v_bitop3_b32 v72, v72, v97, s40 bitop3:0x78
	v_xor_b32_e32 v72, 0x8000007f, v72
	v_ashrrev_i32_e32 v97, 31, v73
	v_bitop3_b32 v73, v73, v97, s40 bitop3:0x78
	v_xor_b32_e32 v73, 0x8000007e, v73
	v_cvt_f32_f16_e32 v97, v1
	v_cvt_f32_f16_sdwa v102, v1 dst_sel:DWORD dst_unused:UNUSED_PAD src0_sel:WORD_1
	v_ashrrev_i32_e32 v82, 31, v97
	v_bitop3_b32 v97, v97, v82, s40 bitop3:0x78
	v_xor_b32_e32 v97, 0x8000007d, v97
	v_ashrrev_i32_e32 v82, 31, v102
	v_bitop3_b32 v102, v102, v82, s40 bitop3:0x78
	v_xor_b32_e32 v102, 0x8000007c, v102
	v_cvt_f32_f16_e32 v82, v2
	v_cvt_f32_f16_sdwa v78, v2 dst_sel:DWORD dst_unused:UNUSED_PAD src0_sel:WORD_1
	v_ashrrev_i32_e32 v70, 31, v82
	v_bitop3_b32 v82, v82, v70, s40 bitop3:0x78
	v_xor_b32_e32 v82, 0x8000007b, v82
	v_ashrrev_i32_e32 v70, 31, v78
	v_bitop3_b32 v78, v78, v70, s40 bitop3:0x78
	v_xor_b32_e32 v78, 0x8000007a, v78
	v_cvt_f32_f16_e32 v70, v3
	v_cvt_f32_f16_sdwa v87, v3 dst_sel:DWORD dst_unused:UNUSED_PAD src0_sel:WORD_1
	v_ashrrev_i32_e32 v92, 31, v70
	v_bitop3_b32 v70, v70, v92, s40 bitop3:0x78
	v_xor_b32_e32 v70, 0x80000079, v70
	v_ashrrev_i32_e32 v92, 31, v87
	v_bitop3_b32 v87, v87, v92, s40 bitop3:0x78
	v_xor_b32_e32 v87, 0x80000078, v87
	v_cvt_f32_f16_e32 v92, v4
	v_cvt_f32_f16_sdwa v90, v4 dst_sel:DWORD dst_unused:UNUSED_PAD src0_sel:WORD_1
	v_ashrrev_i32_e32 v91, 31, v92
	v_bitop3_b32 v92, v92, v91, s40 bitop3:0x78
	v_xor_b32_e32 v92, 0x80000077, v92
	v_ashrrev_i32_e32 v91, 31, v90
	v_bitop3_b32 v90, v90, v91, s40 bitop3:0x78
	v_xor_b32_e32 v90, 0x80000076, v90
	v_cvt_f32_f16_e32 v91, v5
	v_cvt_f32_f16_sdwa v83, v5 dst_sel:DWORD dst_unused:UNUSED_PAD src0_sel:WORD_1
	v_ashrrev_i32_e32 v75, 31, v91
	v_bitop3_b32 v91, v91, v75, s40 bitop3:0x78
	v_xor_b32_e32 v91, 0x80000075, v91
	v_ashrrev_i32_e32 v75, 31, v83
	v_bitop3_b32 v83, v83, v75, s40 bitop3:0x78
	v_xor_b32_e32 v83, 0x80000074, v83
	v_cvt_f32_f16_e32 v75, v6
	v_cvt_f32_f16_sdwa v98, v6 dst_sel:DWORD dst_unused:UNUSED_PAD src0_sel:WORD_1
	v_ashrrev_i32_e32 v89, 31, v75
	v_bitop3_b32 v75, v75, v89, s40 bitop3:0x78
	v_xor_b32_e32 v75, 0x80000073, v75
	v_ashrrev_i32_e32 v89, 31, v98
	v_bitop3_b32 v98, v98, v89, s40 bitop3:0x78
	v_xor_b32_e32 v98, 0x80000072, v98
	v_cvt_f32_f16_e32 v89, v7
	v_cvt_f32_f16_sdwa v96, v7 dst_sel:DWORD dst_unused:UNUSED_PAD src0_sel:WORD_1
	v_ashrrev_i32_e32 v79, 31, v89
	v_bitop3_b32 v89, v89, v79, s40 bitop3:0x78
	v_xor_b32_e32 v89, 0x80000071, v89
	v_ashrrev_i32_e32 v79, 31, v96
	v_bitop3_b32 v96, v96, v79, s40 bitop3:0x78
	v_xor_b32_e32 v96, 0x80000070, v96
	v_max_u32_e32 v79, v72, v98
	v_min_u32_e32 v98, v72, v98
	v_max_u32_e32 v72, v73, v75
	v_min_u32_e32 v75, v73, v75
	v_max_u32_e32 v73, v97, v96
	v_min_u32_e32 v96, v97, v96
	v_max_u32_e32 v97, v102, v89
	v_min_u32_e32 v89, v102, v89
	v_max_u32_e32 v102, v82, v92
	v_min_u32_e32 v92, v82, v92
	v_max_u32_e32 v82, v78, v70
	v_min_u32_e32 v70, v78, v70
	v_max_u32_e32 v78, v87, v83
	v_min_u32_e32 v83, v87, v83
	v_max_u32_e32 v87, v90, v91
	v_min_u32_e32 v91, v90, v91
	v_max_u32_e32 v90, v79, v82
	v_min_u32_e32 v82, v79, v82
	v_max_u32_e32 v79, v72, v78
	v_min_u32_e32 v78, v72, v78
	v_max_u32_e32 v72, v73, v87
	v_min_u32_e32 v87, v73, v87
	v_max_u32_e32 v73, v97, v102
	v_min_u32_e32 v102, v97, v102
	v_max_u32_e32 v97, v70, v98
	v_min_u32_e32 v98, v70, v98
	v_max_u32_e32 v70, v92, v89
	v_min_u32_e32 v89, v92, v89
	v_max_u32_e32 v92, v91, v96
	v_min_u32_e32 v96, v91, v96
	v_max_u32_e32 v91, v83, v75
	v_min_u32_e32 v75, v83, v75
	v_max_u32_e32 v83, v90, v79
	v_min_u32_e32 v79, v90, v79
	v_max_u32_e32 v90, v72, v73
	v_min_u32_e32 v73, v72, v73
	v_max_u32_e32 v72, v102, v82
	v_min_u32_e32 v82, v102, v82
	v_max_u32_e32 v102, v97, v70
	v_min_u32_e32 v70, v97, v70
	v_max_u32_e32 v97, v78, v87
	v_min_u32_e32 v87, v78, v87
	v_max_u32_e32 v78, v92, v91
	v_min_u32_e32 v91, v92, v91
	v_max_u32_e32 v92, v75, v98
	v_min_u32_e32 v98, v75, v98
	v_max_u32_e32 v75, v89, v96
	v_min_u32_e32 v96, v89, v96
	v_max_u32_e32 v89, v83, v90
	v_min_u32_e32 v90, v83, v90
	v_max_u32_e32 v83, v79, v73
	v_min_u32_e32 v73, v79, v73
	v_max_u32_e32 v79, v72, v78
	v_min_u32_e32 v78, v72, v78
	v_max_u32_e32 v72, v82, v91
	v_min_u32_e32 v91, v82, v91
	v_max_u32_e32 v82, v102, v97
	v_min_u32_e32 v97, v102, v97
	v_max_u32_e32 v102, v70, v87
	v_min_u32_e32 v87, v70, v87
	v_max_u32_e32 v70, v92, v75
	v_min_u32_e32 v75, v92, v75
	v_max_u32_e32 v92, v98, v96
	v_min_u32_e32 v96, v98, v96
	v_max_u32_e32 v98, v83, v90
	v_min_u32_e32 v90, v83, v90
	v_max_u32_e32 v83, v73, v70
	v_min_u32_e32 v70, v73, v70
	v_max_u32_e32 v73, v79, v82
	v_min_u32_e32 v82, v79, v82
	v_max_u32_e32 v79, v72, v97
	v_min_u32_e32 v97, v72, v97
	v_max_u32_e32 v72, v102, v78
	v_min_u32_e32 v78, v102, v78
	v_max_u32_e32 v102, v87, v91
	v_min_u32_e32 v91, v87, v91
	v_max_u32_e32 v87, v92, v75
	v_min_u32_e32 v75, v92, v75
	v_max_u32_e32 v92, v98, v73
	v_min_u32_e32 v73, v98, v73
	v_max_u32_e32 v98, v90, v82
	v_min_u32_e32 v82, v90, v82
	v_max_u32_e32 v90, v79, v72
	v_min_u32_e32 v72, v79, v72
	v_max_u32_e32 v79, v97, v78
	v_min_u32_e32 v78, v97, v78
	v_max_u32_e32 v97, v102, v87
	v_min_u32_e32 v87, v102, v87
	v_max_u32_e32 v102, v91, v75
	v_min_u32_e32 v75, v91, v75
	v_max_u32_e32 v91, v98, v73
	v_min_u32_e32 v73, v98, v73
	v_max_u32_e32 v98, v83, v82
	v_min_u32_e32 v82, v83, v82
	v_max_u32_e32 v83, v97, v70
	v_min_u32_e32 v70, v97, v70
	v_max_u32_e32 v97, v102, v87
	v_min_u32_e32 v87, v102, v87
	v_max_u32_e32 v102, v98, v90
	v_min_u32_e32 v90, v98, v90
	v_max_u32_e32 v98, v82, v72
	v_min_u32_e32 v72, v82, v72
; __device__ __forceinline__ unsigned f2key(float f) { const unsigned u = __float_as_uint(f); return (u & 0x80000000u) ? ~u : (u | 0x80000000u); }
; #define CE_DESC(a, b) do { const unsigned _mx = (a) > (b) ? (a) : (b), _mn = (a) > (b) ? (b) : (a); (a) = _mx; (b) = _mn; } while (0)
; __device__ __forceinline__ void sort16_desc(unsigned (&k)[16]) {
; #pragma unroll
;     for (int size = 2; size <= 16; size <<= 1)
; #pragma unroll
;         for (int stride = size >> 1; stride > 0; stride >>= 1)
; #pragma unroll
;             for (int i = 0; i < 16; ++i) { const int j = i ^ stride;
;                 if (j > i) { if ((i & size) == 0) CE_DESC(k[i], k[j]); else CE_DESC(k[j], k[i]); } }
; }
; __device__ __forceinline__ void peer_tile(const Args& A, LAS unsigned char* lds, int tile) {
;     ...
;                   for (int i = 0; i < 16; ++i) {
;                       const float lo = (float)__builtin_bit_cast(_Float16, (unsigned short)(sw[i] & 0xffffu)), hi = (float)__builtin_bit_cast(_Float16, (unsigned short)(sw[i] >> 16));
;                       const unsigned klo = (f2key(lo) & ~127u) | (unsigned)(127 - (32 * g + 2 * i)), khi = (f2key(hi) & ~127u) | (unsigned)(127 - (32 * g + 2 * i + 1));
;                       if (i < 8) { k0[2 * i] = klo; k0[2 * i + 1] = khi; } else { k1[2 * (i - 8)] = klo; k1[2 * (i - 8) + 1] = khi; } } }
	v_max_u32_e32 v82, v79, v83
	v_min_u32_e32 v83, v79, v83
	v_max_u32_e32 v79, v78, v70
	v_min_u32_e32 v70, v78, v70
	v_max_u32_e32 v78, v102, v73
	v_min_u32_e32 v73, v102, v73
	v_max_u32_e32 v102, v90, v98
	v_min_u32_e32 v98, v90, v98
	v_max_u32_e32 v90, v82, v72
	v_min_u32_e32 v72, v82, v72
	v_max_u32_e32 v82, v83, v79
	v_min_u32_e32 v79, v83, v79
	v_max_u32_e32 v83, v97, v70
	v_min_u32_e32 v70, v97, v70
	v_max_u32_e32 v97, v98, v90
	v_min_u32_e32 v90, v98, v90
	v_max_u32_e32 v98, v72, v82
	v_min_u32_e32 v82, v72, v82
	v_cvt_f32_f16_e32 v72, v8
	v_cvt_f32_f16_sdwa v103, v8 dst_sel:DWORD dst_unused:UNUSED_PAD src0_sel:WORD_1
	v_ashrrev_i32_e32 v104, 31, v72
	v_bitop3_b32 v72, v72, v104, s40 bitop3:0x78
	v_xor_b32_e32 v72, 0x8000006f, v72
	v_ashrrev_i32_e32 v104, 31, v103
	v_bitop3_b32 v103, v103, v104, s40 bitop3:0x78
	v_xor_b32_e32 v103, 0x8000006e, v103
	v_cvt_f32_f16_e32 v104, v9
	v_cvt_f32_f16_sdwa v105, v9 dst_sel:DWORD dst_unused:UNUSED_PAD src0_sel:WORD_1
	v_ashrrev_i32_e32 v106, 31, v104
	v_bitop3_b32 v104, v104, v106, s40 bitop3:0x78
	v_xor_b32_e32 v104, 0x8000006d, v104
	v_ashrrev_i32_e32 v106, 31, v105
	v_bitop3_b32 v105, v105, v106, s40 bitop3:0x78
	v_xor_b32_e32 v105, 0x8000006c, v105
	v_cvt_f32_f16_e32 v106, v10
	v_cvt_f32_f16_sdwa v107, v10 dst_sel:DWORD dst_unused:UNUSED_PAD src0_sel:WORD_1
	v_ashrrev_i32_e32 v108, 31, v106
	v_bitop3_b32 v106, v106, v108, s40 bitop3:0x78
	v_xor_b32_e32 v106, 0x8000006b, v106
	v_ashrrev_i32_e32 v108, 31, v107
	v_bitop3_b32 v107, v107, v108, s40 bitop3:0x78
	v_xor_b32_e32 v107, 0x8000006a, v107
	v_cvt_f32_f16_e32 v108, v11
	v_cvt_f32_f16_sdwa v109, v11 dst_sel:DWORD dst_unused:UNUSED_PAD src0_sel:WORD_1
	v_ashrrev_i32_e32 v110, 31, v108
	v_bitop3_b32 v108, v108, v110, s40 bitop3:0x78
	v_xor_b32_e32 v108, 0x80000069, v108
	v_ashrrev_i32_e32 v110, 31, v109
	v_bitop3_b32 v109, v109, v110, s40 bitop3:0x78
	v_xor_b32_e32 v109, 0x80000068, v109
	v_cvt_f32_f16_e32 v110, v12
	v_cvt_f32_f16_sdwa v111, v12 dst_sel:DWORD dst_unused:UNUSED_PAD src0_sel:WORD_1
	v_ashrrev_i32_e32 v112, 31, v110
	v_bitop3_b32 v110, v110, v112, s40 bitop3:0x78
	v_xor_b32_e32 v110, 0x80000067, v110
	v_ashrrev_i32_e32 v112, 31, v111
	v_bitop3_b32 v111, v111, v112, s40 bitop3:0x78
	v_xor_b32_e32 v111, 0x80000066, v111
	v_cvt_f32_f16_e32 v112, v13
	v_cvt_f32_f16_sdwa v114, v13 dst_sel:DWORD dst_unused:UNUSED_PAD src0_sel:WORD_1
	v_ashrrev_i32_e32 v115, 31, v112
	v_bitop3_b32 v112, v112, v115, s40 bitop3:0x78
	v_xor_b32_e32 v112, 0x80000065, v112
	v_ashrrev_i32_e32 v115, 31, v114
	v_bitop3_b32 v114, v114, v115, s40 bitop3:0x78
	v_xor_b32_e32 v114, 0x80000064, v114
	v_cvt_f32_f16_e32 v115, v14
	v_cvt_f32_f16_sdwa v116, v14 dst_sel:DWORD dst_unused:UNUSED_PAD src0_sel:WORD_1
	v_ashrrev_i32_e32 v117, 31, v115
	v_bitop3_b32 v115, v115, v117, s40 bitop3:0x78
	v_xor_b32_e32 v115, 0x80000063, v115
	v_ashrrev_i32_e32 v117, 31, v116
	v_bitop3_b32 v116, v116, v117, s40 bitop3:0x78
	v_xor_b32_e32 v116, 0x80000062, v116
	v_cvt_f32_f16_e32 v117, v15
	v_cvt_f32_f16_sdwa v118, v15 dst_sel:DWORD dst_unused:UNUSED_PAD src0_sel:WORD_1
	v_ashrrev_i32_e32 v119, 31, v117
	v_bitop3_b32 v117, v117, v119, s40 bitop3:0x78
	v_xor_b32_e32 v117, 0x80000061, v117
	v_ashrrev_i32_e32 v119, 31, v118
	v_bitop3_b32 v118, v118, v119, s40 bitop3:0x78
	v_xor_b32_e32 v118, 0x80000060, v118
	v_max_u32_e32 v119, v72, v116
	v_min_u32_e32 v116, v72, v116
	v_max_u32_e32 v72, v103, v115
	v_min_u32_e32 v115, v103, v115
	v_max_u32_e32 v103, v104, v118
	v_min_u32_e32 v118, v104, v118
	v_max_u32_e32 v104, v105, v117
	v_min_u32_e32 v117, v105, v117
	v_max_u32_e32 v105, v106, v110
	v_min_u32_e32 v110, v106, v110
	v_max_u32_e32 v106, v107, v108
	v_min_u32_e32 v108, v107, v108
	v_max_u32_e32 v107, v109, v114
	v_min_u32_e32 v114, v109, v114
	v_max_u32_e32 v109, v111, v112
	v_min_u32_e32 v112, v111, v112
	v_max_u32_e32 v111, v119, v106
	v_min_u32_e32 v106, v119, v106
	v_max_u32_e32 v119, v72, v107
	v_min_u32_e32 v107, v72, v107
	v_max_u32_e32 v72, v103, v109
	v_min_u32_e32 v109, v103, v109
	v_max_u32_e32 v103, v104, v105
	v_min_u32_e32 v105, v104, v105
	v_max_u32_e32 v104, v108, v116
	v_min_u32_e32 v116, v108, v116
	v_max_u32_e32 v108, v110, v117
	v_min_u32_e32 v117, v110, v117
	v_max_u32_e32 v110, v112, v118
	v_min_u32_e32 v118, v112, v118
	v_max_u32_e32 v112, v114, v115
	v_min_u32_e32 v115, v114, v115
	v_max_u32_e32 v114, v111, v119
	v_min_u32_e32 v119, v111, v119
	v_max_u32_e32 v111, v72, v103
	v_min_u32_e32 v103, v72, v103
	v_max_u32_e32 v72, v105, v106
	v_min_u32_e32 v106, v105, v106
	v_max_u32_e32 v105, v104, v108
	v_min_u32_e32 v108, v104, v108
	v_max_u32_e32 v104, v107, v109
	v_min_u32_e32 v109, v107, v109
	v_max_u32_e32 v107, v110, v112
	v_min_u32_e32 v112, v110, v112
	v_max_u32_e32 v110, v115, v116
	v_min_u32_e32 v116, v115, v116
	v_max_u32_e32 v115, v117, v118
	v_min_u32_e32 v118, v117, v118
	v_max_u32_e32 v117, v114, v111
	v_min_u32_e32 v111, v114, v111
	v_max_u32_e32 v114, v119, v103
	v_min_u32_e32 v103, v119, v103
	v_max_u32_e32 v119, v72, v107
	v_min_u32_e32 v107, v72, v107
	v_max_u32_e32 v72, v106, v112
	v_min_u32_e32 v112, v106, v112
	v_max_u32_e32 v106, v105, v104
	v_min_u32_e32 v104, v105, v104
	v_max_u32_e32 v105, v108, v109
	v_min_u32_e32 v109, v108, v109
	v_max_u32_e32 v108, v110, v115
	v_min_u32_e32 v115, v110, v115
	v_max_u32_e32 v110, v116, v118
	v_min_u32_e32 v118, v116, v118
	v_max_u32_e32 v116, v114, v111
	v_min_u32_e32 v111, v114, v111
	v_max_u32_e32 v114, v103, v108
	v_min_u32_e32 v108, v103, v108
	v_max_u32_e32 v103, v119, v106
	v_min_u32_e32 v106, v119, v106
	v_max_u32_e32 v119, v72, v104
	v_min_u32_e32 v104, v72, v104
	v_max_u32_e32 v72, v105, v107
; __device__ __forceinline__ unsigned f2key(float f) { const unsigned u = __float_as_uint(f); return (u & 0x80000000u) ? ~u : (u | 0x80000000u); }
; #define CE_DESC(a, b) do { const unsigned _mx = (a) > (b) ? (a) : (b), _mn = (a) > (b) ? (b) : (a); (a) = _mx; (b) = _mn; } while (0)
; __device__ __forceinline__ void merge16(unsigned (&a)[16], const unsigned (&b)[16]) {
; #pragma unroll
;     for (int i = 0; i < 16; ++i) a[i] = a[i] > b[15 - i] ? a[i] : b[15 - i];
; #pragma unroll
;     for (int stride = 8; stride > 0; stride >>= 1)
; #pragma unroll
;         for (int i = 0; i < 16; ++i) { const int j = i ^ stride; if (j > i) CE_DESC(a[i], a[j]); }
; }
; __device__ __forceinline__ void peer_tile(const Args& A, LAS unsigned char* lds, int tile) {
;     ...
;                   for (int i = 0; i < 16; ++i) {
;                       const float lo = (float)__builtin_bit_cast(_Float16, (unsigned short)(sw[i] & 0xffffu)), hi = (float)__builtin_bit_cast(_Float16, (unsigned short)(sw[i] >> 16));
;                       const unsigned klo = (f2key(lo) & ~127u) | (unsigned)(127 - (32 * g + 2 * i)), khi = (f2key(hi) & ~127u) | (unsigned)(127 - (32 * g + 2 * i + 1));
;                       if (i < 8) { k0[2 * i] = klo; k0[2 * i + 1] = khi; } else { k1[2 * (i - 8)] = klo; k1[2 * (i - 8) + 1] = khi; } } }
	v_min_u32_e32 v107, v105, v107
	v_max_u32_e32 v105, v109, v112
	v_min_u32_e32 v112, v109, v112
	v_max_u32_e32 v109, v110, v115
	v_min_u32_e32 v115, v110, v115
	v_max_u32_e32 v110, v116, v103
	v_min_u32_e32 v103, v116, v103
	v_max_u32_e32 v116, v111, v106
	v_min_u32_e32 v106, v111, v106
	v_max_u32_e32 v111, v119, v72
	v_min_u32_e32 v72, v119, v72
	v_max_u32_e32 v119, v104, v107
	v_min_u32_e32 v107, v104, v107
	v_max_u32_e32 v104, v105, v109
	v_min_u32_e32 v109, v105, v109
	v_max_u32_e32 v105, v112, v115
	v_min_u32_e32 v115, v112, v115
	v_max_u32_e32 v112, v116, v103
	v_min_u32_e32 v103, v116, v103
	v_max_u32_e32 v116, v114, v106
	v_min_u32_e32 v106, v114, v106
	v_max_u32_e32 v114, v104, v108
	v_min_u32_e32 v108, v104, v108
	v_max_u32_e32 v104, v105, v109
	v_min_u32_e32 v109, v105, v109
	v_max_u32_e32 v105, v116, v111
	v_min_u32_e32 v111, v116, v111
	v_max_u32_e32 v116, v106, v72
	v_min_u32_e32 v72, v106, v72
	v_max_u32_e32 v106, v119, v114
	v_min_u32_e32 v114, v119, v114
	v_max_u32_e32 v119, v107, v108
	v_min_u32_e32 v108, v107, v108
	v_max_u32_e32 v107, v105, v103
	v_min_u32_e32 v103, v105, v103
	v_max_u32_e32 v105, v111, v116
	v_min_u32_e32 v116, v111, v116
	v_max_u32_e32 v111, v106, v72
	v_min_u32_e32 v72, v106, v72
	v_max_u32_e32 v106, v114, v119
	v_min_u32_e32 v119, v114, v119
	v_max_u32_e32 v114, v104, v108
	v_min_u32_e32 v108, v104, v108
	v_max_u32_e32 v104, v116, v111
	v_min_u32_e32 v111, v116, v111
	v_max_u32_e32 v116, v72, v106
	v_min_u32_e32 v106, v72, v106
	v_max_u32_e32 v89, v89, v118
	v_max_u32_e32 v92, v92, v115
	v_max_u32_e32 v91, v91, v109
	v_max_u32_e32 v78, v78, v108
	v_max_u32_e32 v73, v73, v114
	v_max_u32_e32 v102, v102, v119
	v_max_u32_e32 v97, v97, v106
	v_max_u32_e32 v90, v90, v116
	v_max_u32_e32 v98, v98, v111
	v_max_u32_e32 v82, v82, v104
	v_max_u32_e32 v79, v79, v105
	v_max_u32_e32 v83, v83, v103
	v_max_u32_e32 v70, v70, v107
	v_max_u32_e32 v87, v87, v112
	v_max_u32_e32 v75, v75, v110
	v_max_u32_e32 v96, v96, v117
	v_max_u32_e32 v118, v89, v98
	v_min_u32_e32 v98, v89, v98
	v_max_u32_e32 v89, v92, v82
	v_min_u32_e32 v82, v92, v82
	v_max_u32_e32 v92, v91, v79
	v_min_u32_e32 v79, v91, v79
	v_max_u32_e32 v91, v78, v83
	v_min_u32_e32 v83, v78, v83
	v_max_u32_e32 v78, v73, v70
	v_min_u32_e32 v70, v73, v70
	v_max_u32_e32 v73, v102, v87
	v_min_u32_e32 v87, v102, v87
	v_max_u32_e32 v102, v97, v75
	v_min_u32_e32 v75, v97, v75
	v_max_u32_e32 v97, v90, v96
	v_min_u32_e32 v96, v90, v96
	v_max_u32_e32 v90, v118, v78
	v_min_u32_e32 v78, v118, v78
	v_max_u32_e32 v118, v89, v73
	v_min_u32_e32 v73, v89, v73
	v_max_u32_e32 v89, v92, v102
	v_min_u32_e32 v102, v92, v102
	v_max_u32_e32 v92, v91, v97
	v_min_u32_e32 v97, v91, v97
	v_max_u32_e32 v91, v98, v70
	v_min_u32_e32 v70, v98, v70
	v_max_u32_e32 v98, v82, v87
	v_min_u32_e32 v87, v82, v87
	v_max_u32_e32 v82, v79, v75
	v_min_u32_e32 v75, v79, v75
	v_max_u32_e32 v79, v83, v96
	v_min_u32_e32 v96, v83, v96
	v_max_u32_e32 v83, v90, v89
	v_min_u32_e32 v89, v90, v89
	v_max_u32_e32 v90, v118, v92
	v_min_u32_e32 v92, v118, v92
	v_max_u32_e32 v118, v78, v102
	v_min_u32_e32 v102, v78, v102
	v_max_u32_e32 v78, v73, v97
	v_min_u32_e32 v97, v73, v97
	v_max_u32_e32 v73, v91, v82
	v_min_u32_e32 v82, v91, v82
	v_max_u32_e32 v91, v98, v79
	v_min_u32_e32 v79, v98, v79
	v_max_u32_e32 v98, v70, v75
	v_min_u32_e32 v75, v70, v75
	v_max_u32_e32 v70, v87, v96
	v_min_u32_e32 v96, v87, v96
	v_max_u32_e32 v87, v83, v90
	v_min_u32_e32 v90, v83, v90
	v_max_u32_e32 v83, v89, v92
	v_min_u32_e32 v92, v89, v92
	v_max_u32_e32 v89, v118, v78
	v_min_u32_e32 v78, v118, v78
	v_max_u32_e32 v118, v102, v97
	v_min_u32_e32 v97, v102, v97
	v_max_u32_e32 v102, v73, v91
	v_min_u32_e32 v91, v73, v91
	v_max_u32_e32 v73, v82, v79
	v_min_u32_e32 v79, v82, v79
	v_max_u32_e32 v82, v98, v70
	v_min_u32_e32 v70, v98, v70
	v_max_u32_e32 v98, v75, v96
	v_min_u32_e32 v96, v75, v96
	v_cvt_f32_f16_e32 v75, v16
	v_cvt_f32_f16_sdwa v115, v16 dst_sel:DWORD dst_unused:UNUSED_PAD src0_sel:WORD_1
	v_ashrrev_i32_e32 v109, 31, v75
	v_bitop3_b32 v75, v75, v109, s40 bitop3:0x78
	v_xor_b32_e32 v75, 0x8000005f, v75
	v_ashrrev_i32_e32 v109, 31, v115
	v_bitop3_b32 v115, v115, v109, s40 bitop3:0x78
	v_xor_b32_e32 v115, 0x8000005e, v115
	v_cvt_f32_f16_e32 v109, v17
	v_cvt_f32_f16_sdwa v108, v17 dst_sel:DWORD dst_unused:UNUSED_PAD src0_sel:WORD_1
	v_ashrrev_i32_e32 v114, 31, v109
	v_bitop3_b32 v109, v109, v114, s40 bitop3:0x78
	v_xor_b32_e32 v109, 0x8000005d, v109
	v_ashrrev_i32_e32 v114, 31, v108
	v_bitop3_b32 v108, v108, v114, s40 bitop3:0x78
	v_xor_b32_e32 v108, 0x8000005c, v108
	v_cvt_f32_f16_e32 v114, v18
	v_cvt_f32_f16_sdwa v119, v18 dst_sel:DWORD dst_unused:UNUSED_PAD src0_sel:WORD_1
	v_ashrrev_i32_e32 v106, 31, v114
	v_bitop3_b32 v114, v114, v106, s40 bitop3:0x78
	v_xor_b32_e32 v114, 0x8000005b, v114
	v_ashrrev_i32_e32 v106, 31, v119
	v_bitop3_b32 v119, v119, v106, s40 bitop3:0x78
	v_xor_b32_e32 v119, 0x8000005a, v119
	v_cvt_f32_f16_e32 v106, v19
	v_cvt_f32_f16_sdwa v116, v19 dst_sel:DWORD dst_unused:UNUSED_PAD src0_sel:WORD_1
	v_ashrrev_i32_e32 v111, 31, v106
	v_bitop3_b32 v106, v106, v111, s40 bitop3:0x78
	v_xor_b32_e32 v106, 0x80000059, v106
	v_ashrrev_i32_e32 v111, 31, v116
	v_bitop3_b32 v116, v116, v111, s40 bitop3:0x78
	v_xor_b32_e32 v116, 0x80000058, v116
	v_cvt_f32_f16_e32 v111, v20
	v_cvt_f32_f16_sdwa v104, v20 dst_sel:DWORD dst_unused:UNUSED_PAD src0_sel:WORD_1
	v_ashrrev_i32_e32 v105, 31, v111
	v_bitop3_b32 v111, v111, v105, s40 bitop3:0x78
	v_xor_b32_e32 v111, 0x80000057, v111
	v_ashrrev_i32_e32 v105, 31, v104
	v_bitop3_b32 v104, v104, v105, s40 bitop3:0x78
	v_xor_b32_e32 v104, 0x80000056, v104
	v_cvt_f32_f16_e32 v105, v21
; __device__ __forceinline__ unsigned f2key(float f) { const unsigned u = __float_as_uint(f); return (u & 0x80000000u) ? ~u : (u | 0x80000000u); }
; #define CE_DESC(a, b) do { const unsigned _mx = (a) > (b) ? (a) : (b), _mn = (a) > (b) ? (b) : (a); (a) = _mx; (b) = _mn; } while (0)
; __device__ __forceinline__ void sort16_desc(unsigned (&k)[16]) {
; #pragma unroll
;     for (int size = 2; size <= 16; size <<= 1)
; #pragma unroll
;         for (int stride = size >> 1; stride > 0; stride >>= 1)
; #pragma unroll
;             for (int i = 0; i < 16; ++i) { const int j = i ^ stride;
;                 if (j > i) { if ((i & size) == 0) CE_DESC(k[i], k[j]); else CE_DESC(k[j], k[i]); } }
; }
; __device__ __forceinline__ void merge16(unsigned (&a)[16], const unsigned (&b)[16]) {
; #pragma unroll
;     for (int i = 0; i < 16; ++i) a[i] = a[i] > b[15 - i] ? a[i] : b[15 - i];
; #pragma unroll
;     for (int stride = 8; stride > 0; stride >>= 1)
; #pragma unroll
;         for (int i = 0; i < 16; ++i) { const int j = i ^ stride; if (j > i) CE_DESC(a[i], a[j]); }
; }
; __device__ __forceinline__ void peer_tile(const Args& A, LAS unsigned char* lds, int tile) {
;     ...
;                   for (int i = 0; i < 16; ++i) {
;                       const float lo = (float)__builtin_bit_cast(_Float16, (unsigned short)(sw[i] & 0xffffu)), hi = (float)__builtin_bit_cast(_Float16, (unsigned short)(sw[i] >> 16));
;                       const unsigned klo = (f2key(lo) & ~127u) | (unsigned)(127 - (32 * g + 2 * i)), khi = (f2key(hi) & ~127u) | (unsigned)(127 - (32 * g + 2 * i + 1));
;                       if (i < 8) { k0[2 * i] = klo; k0[2 * i + 1] = khi; } else { k1[2 * (i - 8)] = klo; k1[2 * (i - 8) + 1] = khi; } } }
	v_cvt_f32_f16_sdwa v103, v21 dst_sel:DWORD dst_unused:UNUSED_PAD src0_sel:WORD_1
	v_ashrrev_i32_e32 v107, 31, v105
	v_bitop3_b32 v105, v105, v107, s40 bitop3:0x78
	v_xor_b32_e32 v105, 0x80000055, v105
	v_ashrrev_i32_e32 v107, 31, v103
	v_bitop3_b32 v103, v103, v107, s40 bitop3:0x78
	v_xor_b32_e32 v103, 0x80000054, v103
	v_cvt_f32_f16_e32 v107, v22
	v_cvt_f32_f16_sdwa v112, v22 dst_sel:DWORD dst_unused:UNUSED_PAD src0_sel:WORD_1
	v_ashrrev_i32_e32 v110, 31, v107
	v_bitop3_b32 v107, v107, v110, s40 bitop3:0x78
	v_xor_b32_e32 v107, 0x80000053, v107
	v_ashrrev_i32_e32 v110, 31, v112
	v_bitop3_b32 v112, v112, v110, s40 bitop3:0x78
	v_xor_b32_e32 v112, 0x80000052, v112
	v_cvt_f32_f16_e32 v110, v23
	v_cvt_f32_f16_sdwa v117, v23 dst_sel:DWORD dst_unused:UNUSED_PAD src0_sel:WORD_1
	v_ashrrev_i32_e32 v72, 31, v110
	v_bitop3_b32 v110, v110, v72, s40 bitop3:0x78
	v_xor_b32_e32 v110, 0x80000051, v110
	v_ashrrev_i32_e32 v72, 31, v117
	v_bitop3_b32 v117, v117, v72, s40 bitop3:0x78
	v_xor_b32_e32 v117, 0x80000050, v117
	v_max_u32_e32 v72, v75, v112
	v_min_u32_e32 v112, v75, v112
	v_max_u32_e32 v75, v115, v107
	v_min_u32_e32 v107, v115, v107
	v_max_u32_e32 v115, v109, v117
	v_min_u32_e32 v117, v109, v117
	v_max_u32_e32 v109, v108, v110
	v_min_u32_e32 v110, v108, v110
	v_max_u32_e32 v108, v114, v111
	v_min_u32_e32 v111, v114, v111
	v_max_u32_e32 v114, v119, v106
	v_min_u32_e32 v106, v119, v106
	v_max_u32_e32 v119, v116, v103
	v_min_u32_e32 v103, v116, v103
	v_max_u32_e32 v116, v104, v105
	v_min_u32_e32 v105, v104, v105
	v_max_u32_e32 v104, v72, v114
	v_min_u32_e32 v114, v72, v114
	v_max_u32_e32 v72, v75, v119
	v_min_u32_e32 v119, v75, v119
	v_max_u32_e32 v75, v115, v116
	v_min_u32_e32 v116, v115, v116
	v_max_u32_e32 v115, v109, v108
	v_min_u32_e32 v108, v109, v108
	v_max_u32_e32 v109, v106, v112
	v_min_u32_e32 v112, v106, v112
	v_max_u32_e32 v106, v111, v110
	v_min_u32_e32 v110, v111, v110
	v_max_u32_e32 v111, v105, v117
	v_min_u32_e32 v117, v105, v117
	v_max_u32_e32 v105, v103, v107
	v_min_u32_e32 v107, v103, v107
	v_max_u32_e32 v103, v104, v72
	v_min_u32_e32 v72, v104, v72
	v_max_u32_e32 v104, v75, v115
	v_min_u32_e32 v115, v75, v115
	v_max_u32_e32 v75, v108, v114
	v_min_u32_e32 v114, v108, v114
	v_max_u32_e32 v108, v109, v106
	v_min_u32_e32 v106, v109, v106
	v_max_u32_e32 v109, v119, v116
	v_min_u32_e32 v116, v119, v116
	v_max_u32_e32 v119, v111, v105
	v_min_u32_e32 v105, v111, v105
	v_max_u32_e32 v111, v107, v112
	v_min_u32_e32 v112, v107, v112
	v_max_u32_e32 v107, v110, v117
	v_min_u32_e32 v117, v110, v117
	v_max_u32_e32 v110, v103, v104
	v_min_u32_e32 v104, v103, v104
	v_max_u32_e32 v103, v72, v115
	v_min_u32_e32 v115, v72, v115
	v_max_u32_e32 v72, v75, v119
	v_min_u32_e32 v119, v75, v119
	v_max_u32_e32 v75, v114, v105
	v_min_u32_e32 v105, v114, v105
	v_max_u32_e32 v114, v108, v109
	v_min_u32_e32 v109, v108, v109
	v_max_u32_e32 v108, v106, v116
	v_min_u32_e32 v116, v106, v116
	v_max_u32_e32 v106, v111, v107
	v_min_u32_e32 v107, v111, v107
	v_max_u32_e32 v111, v112, v117
	v_min_u32_e32 v117, v112, v117
	v_max_u32_e32 v112, v103, v104
	v_min_u32_e32 v104, v103, v104
	v_max_u32_e32 v103, v115, v106
	v_min_u32_e32 v106, v115, v106
	v_max_u32_e32 v115, v72, v114
	v_min_u32_e32 v114, v72, v114
	v_max_u32_e32 v72, v75, v109
	v_min_u32_e32 v109, v75, v109
	v_max_u32_e32 v75, v108, v119
	v_min_u32_e32 v119, v108, v119
	v_max_u32_e32 v108, v116, v105
	v_min_u32_e32 v105, v116, v105
	v_max_u32_e32 v116, v111, v107
	v_min_u32_e32 v107, v111, v107
	v_max_u32_e32 v111, v112, v115
	v_min_u32_e32 v115, v112, v115
	v_max_u32_e32 v112, v104, v114
	v_min_u32_e32 v114, v104, v114
	v_max_u32_e32 v104, v72, v75
	v_min_u32_e32 v75, v72, v75
	v_max_u32_e32 v72, v109, v119
	v_min_u32_e32 v119, v109, v119
	v_max_u32_e32 v109, v108, v116
	v_min_u32_e32 v116, v108, v116
	v_max_u32_e32 v108, v105, v107
	v_min_u32_e32 v107, v105, v107
	v_max_u32_e32 v105, v112, v115
	v_min_u32_e32 v115, v112, v115
	v_max_u32_e32 v112, v103, v114
	v_min_u32_e32 v114, v103, v114
	v_max_u32_e32 v103, v109, v106
	v_min_u32_e32 v106, v109, v106
	v_max_u32_e32 v109, v108, v116
	v_min_u32_e32 v116, v108, v116
	v_max_u32_e32 v108, v112, v104
	v_min_u32_e32 v104, v112, v104
	v_max_u32_e32 v112, v114, v75
	v_min_u32_e32 v75, v114, v75
	v_max_u32_e32 v114, v72, v103
	v_min_u32_e32 v103, v72, v103
	v_max_u32_e32 v72, v119, v106
	v_min_u32_e32 v106, v119, v106
	v_max_u32_e32 v119, v108, v115
	v_min_u32_e32 v115, v108, v115
	v_max_u32_e32 v108, v104, v112
	v_min_u32_e32 v112, v104, v112
	v_max_u32_e32 v104, v114, v75
	v_min_u32_e32 v75, v114, v75
	v_max_u32_e32 v114, v103, v72
	v_min_u32_e32 v72, v103, v72
	v_max_u32_e32 v103, v109, v106
	v_min_u32_e32 v106, v109, v106
	v_max_u32_e32 v109, v112, v104
	v_min_u32_e32 v104, v112, v104
	v_max_u32_e32 v112, v75, v114
	v_min_u32_e32 v114, v75, v114
	v_max_u32_e32 v87, v87, v117
	v_max_u32_e32 v90, v90, v107
	v_max_u32_e32 v83, v83, v116
	v_max_u32_e32 v92, v92, v106
	v_max_u32_e32 v89, v89, v103
	v_max_u32_e32 v78, v78, v72
	v_max_u32_e32 v118, v118, v114
	v_max_u32_e32 v97, v97, v112
	v_max_u32_e32 v102, v102, v104
	v_max_u32_e32 v91, v91, v109
	v_max_u32_e32 v73, v73, v108
	v_max_u32_e32 v79, v79, v115
	v_max_u32_e32 v82, v82, v119
	v_max_u32_e32 v70, v70, v105
	v_max_u32_e32 v98, v98, v111
	v_max_u32_e32 v96, v96, v110
	v_max_u32_e32 v117, v87, v102
	v_min_u32_e32 v102, v87, v102
	v_max_u32_e32 v87, v90, v91
	v_min_u32_e32 v91, v90, v91
	v_max_u32_e32 v90, v83, v73
	v_min_u32_e32 v73, v83, v73
	v_max_u32_e32 v83, v92, v79
	v_min_u32_e32 v79, v92, v79
	v_max_u32_e32 v92, v89, v82
	v_min_u32_e32 v82, v89, v82
	v_max_u32_e32 v89, v78, v70
	v_min_u32_e32 v70, v78, v70
; __device__ __forceinline__ unsigned f2key(float f) { const unsigned u = __float_as_uint(f); return (u & 0x80000000u) ? ~u : (u | 0x80000000u); }
; __device__ __forceinline__ void peer_tile(const Args& A, LAS unsigned char* lds, int tile) {
;     ...
;                 { const bf16_t* sp = QRY + m * 2048 + hp * 128 + 32 * g;
;                   const u32x4 s0 = *(const u32x4*)sp, s1 = *(const u32x4*)(sp + 8), s2 = *(const u32x4*)(sp + 16), s3 = *(const u32x4*)(sp + 24);
;                   const unsigned sw[16] = {s0.x, s0.y, s0.z, s0.w, s1.x, s1.y, s1.z, s1.w, s2.x, s2.y, s2.z, s2.w, s3.x, s3.y, s3.z, s3.w};
; #pragma unroll
;                   for (int i = 0; i < 16; ++i) {
;                       const float lo = (float)__builtin_bit_cast(_Float16, (unsigned short)(sw[i] & 0xffffu)), hi = (float)__builtin_bit_cast(_Float16, (unsigned short)(sw[i] >> 16));
;                       const unsigned klo = (f2key(lo) & ~127u) | (unsigned)(127 - (32 * g + 2 * i)), khi = (f2key(hi) & ~127u) | (unsigned)(127 - (32 * g + 2 * i + 1));
;                       if (i < 8) { k0[2 * i] = klo; k0[2 * i + 1] = khi; } else { k1[2 * (i - 8)] = klo; k1[2 * (i - 8) + 1] = khi; } } }
;                 sort16_desc(k0); sort16_desc(k1); merge16(k0, k1);
; #pragma unroll
;                 for (int msk = 16; msk <= 32; msk <<= 1) {
; #pragma unroll
;                     for (int i = 0; i < 16; ++i) k1[i] = (unsigned)__shfl_xor((int)k0[i], msk);
;                     merge16(k0, k1); }
	v_max_u32_e32 v78, v118, v98
	v_min_u32_e32 v98, v118, v98
	v_max_u32_e32 v118, v97, v96
	v_min_u32_e32 v96, v97, v96
	v_max_u32_e32 v97, v117, v92
	v_min_u32_e32 v92, v117, v92
	v_max_u32_e32 v117, v87, v89
	v_min_u32_e32 v89, v87, v89
	v_max_u32_e32 v87, v90, v78
	v_min_u32_e32 v78, v90, v78
	v_max_u32_e32 v90, v83, v118
	v_min_u32_e32 v118, v83, v118
	v_max_u32_e32 v83, v102, v82
	v_min_u32_e32 v82, v102, v82
	v_max_u32_e32 v102, v91, v70
	v_min_u32_e32 v70, v91, v70
	v_max_u32_e32 v91, v73, v98
	v_min_u32_e32 v98, v73, v98
	v_max_u32_e32 v73, v79, v96
	v_min_u32_e32 v96, v79, v96
	v_max_u32_e32 v79, v97, v87
	v_min_u32_e32 v87, v97, v87
	v_max_u32_e32 v97, v117, v90
	v_min_u32_e32 v90, v117, v90
	v_max_u32_e32 v117, v92, v78
	v_min_u32_e32 v78, v92, v78
	v_max_u32_e32 v92, v89, v118
	v_min_u32_e32 v118, v89, v118
	v_max_u32_e32 v89, v83, v91
	v_min_u32_e32 v91, v83, v91
	v_max_u32_e32 v83, v102, v73
	v_min_u32_e32 v73, v102, v73
	v_max_u32_e32 v102, v82, v98
	v_min_u32_e32 v98, v82, v98
	v_max_u32_e32 v82, v70, v96
	v_min_u32_e32 v96, v70, v96
	v_max_u32_e32 v70, v79, v97
	v_min_u32_e32 v97, v79, v97
	v_max_u32_e32 v79, v87, v90
	v_min_u32_e32 v90, v87, v90
	v_max_u32_e32 v87, v117, v92
	v_min_u32_e32 v92, v117, v92
	v_max_u32_e32 v117, v78, v118
	v_min_u32_e32 v118, v78, v118
	v_max_u32_e32 v78, v89, v83
	v_min_u32_e32 v83, v89, v83
	v_max_u32_e32 v89, v91, v73
	v_min_u32_e32 v73, v91, v73
	v_max_u32_e32 v91, v102, v82
	v_min_u32_e32 v82, v102, v82
	v_max_u32_e32 v102, v98, v96
	v_min_u32_e32 v96, v98, v96
	v_cvt_f32_f16_e32 v98, v24
	v_cvt_f32_f16_sdwa v107, v24 dst_sel:DWORD dst_unused:UNUSED_PAD src0_sel:WORD_1
	v_ashrrev_i32_e32 v116, 31, v98
	v_bitop3_b32 v98, v98, v116, s40 bitop3:0x78
	v_xor_b32_e32 v98, 0x8000004f, v98
	v_ashrrev_i32_e32 v116, 31, v107
	v_bitop3_b32 v107, v107, v116, s40 bitop3:0x78
	v_xor_b32_e32 v107, 0x8000004e, v107
	v_cvt_f32_f16_e32 v116, v25
	v_cvt_f32_f16_sdwa v106, v25 dst_sel:DWORD dst_unused:UNUSED_PAD src0_sel:WORD_1
	v_ashrrev_i32_e32 v103, 31, v116
	v_bitop3_b32 v116, v116, v103, s40 bitop3:0x78
	v_xor_b32_e32 v116, 0x8000004d, v116
	v_ashrrev_i32_e32 v103, 31, v106
	v_bitop3_b32 v106, v106, v103, s40 bitop3:0x78
	v_xor_b32_e32 v106, 0x8000004c, v106
	v_cvt_f32_f16_e32 v103, v26
	v_cvt_f32_f16_sdwa v72, v26 dst_sel:DWORD dst_unused:UNUSED_PAD src0_sel:WORD_1
	v_ashrrev_i32_e32 v114, 31, v103
	v_bitop3_b32 v103, v103, v114, s40 bitop3:0x78
	v_xor_b32_e32 v103, 0x8000004b, v103
	v_ashrrev_i32_e32 v114, 31, v72
	v_bitop3_b32 v72, v72, v114, s40 bitop3:0x78
	v_xor_b32_e32 v72, 0x8000004a, v72
	v_cvt_f32_f16_e32 v114, v27
	v_cvt_f32_f16_sdwa v112, v27 dst_sel:DWORD dst_unused:UNUSED_PAD src0_sel:WORD_1
	v_ashrrev_i32_e32 v104, 31, v114
	v_bitop3_b32 v114, v114, v104, s40 bitop3:0x78
	v_xor_b32_e32 v114, 0x80000049, v114
	v_ashrrev_i32_e32 v104, 31, v112
	v_bitop3_b32 v112, v112, v104, s40 bitop3:0x78
	v_xor_b32_e32 v112, 0x80000048, v112
	v_cvt_f32_f16_e32 v104, v28
	v_cvt_f32_f16_sdwa v109, v28 dst_sel:DWORD dst_unused:UNUSED_PAD src0_sel:WORD_1
	v_ashrrev_i32_e32 v108, 31, v104
	v_bitop3_b32 v104, v104, v108, s40 bitop3:0x78
	v_xor_b32_e32 v104, 0x80000047, v104
	v_ashrrev_i32_e32 v108, 31, v109
	v_bitop3_b32 v109, v109, v108, s40 bitop3:0x78
	v_xor_b32_e32 v109, 0x80000046, v109
	v_cvt_f32_f16_e32 v108, v29
	v_cvt_f32_f16_sdwa v115, v29 dst_sel:DWORD dst_unused:UNUSED_PAD src0_sel:WORD_1
	v_ashrrev_i32_e32 v119, 31, v108
	v_bitop3_b32 v108, v108, v119, s40 bitop3:0x78
	v_xor_b32_e32 v108, 0x80000045, v108
	v_ashrrev_i32_e32 v119, 31, v115
	v_bitop3_b32 v115, v115, v119, s40 bitop3:0x78
	v_xor_b32_e32 v115, 0x80000044, v115
	v_cvt_f32_f16_e32 v119, v30
	v_cvt_f32_f16_sdwa v105, v30 dst_sel:DWORD dst_unused:UNUSED_PAD src0_sel:WORD_1
	v_ashrrev_i32_e32 v111, 31, v119
	v_bitop3_b32 v119, v119, v111, s40 bitop3:0x78
	v_xor_b32_e32 v119, 0x80000043, v119
	v_ashrrev_i32_e32 v111, 31, v105
	v_bitop3_b32 v105, v105, v111, s40 bitop3:0x78
	v_xor_b32_e32 v105, 0x80000042, v105
	v_cvt_f32_f16_e32 v111, v31
	v_cvt_f32_f16_sdwa v110, v31 dst_sel:DWORD dst_unused:UNUSED_PAD src0_sel:WORD_1
	v_ashrrev_i32_e32 v75, 31, v111
	v_bitop3_b32 v111, v111, v75, s40 bitop3:0x78
	v_xor_b32_e32 v111, 0x80000041, v111
	v_ashrrev_i32_e32 v75, 31, v110
	v_bitop3_b32 v110, v110, v75, s40 bitop3:0x78
	v_xor_b32_e32 v110, 0x80000040, v110
	v_max_u32_e32 v75, v98, v105
	v_min_u32_e32 v105, v98, v105
	v_max_u32_e32 v98, v107, v119
	v_min_u32_e32 v119, v107, v119
	v_max_u32_e32 v107, v116, v110
	v_min_u32_e32 v110, v116, v110
	v_max_u32_e32 v116, v106, v111
	v_min_u32_e32 v111, v106, v111
	v_max_u32_e32 v106, v103, v104
	v_min_u32_e32 v104, v103, v104
	v_max_u32_e32 v103, v72, v114
	v_min_u32_e32 v114, v72, v114
	v_max_u32_e32 v72, v112, v115
	v_min_u32_e32 v115, v112, v115
	v_max_u32_e32 v112, v109, v108
	v_min_u32_e32 v108, v109, v108
	v_max_u32_e32 v109, v75, v103
	v_min_u32_e32 v103, v75, v103
	v_max_u32_e32 v75, v98, v72
	v_min_u32_e32 v72, v98, v72
	v_max_u32_e32 v98, v107, v112
	v_min_u32_e32 v112, v107, v112
	v_max_u32_e32 v107, v116, v106
	v_min_u32_e32 v106, v116, v106
	v_max_u32_e32 v116, v114, v105
	v_min_u32_e32 v105, v114, v105
	v_max_u32_e32 v114, v104, v111
	v_min_u32_e32 v111, v104, v111
	v_max_u32_e32 v104, v108, v110
	v_min_u32_e32 v110, v108, v110
	v_max_u32_e32 v108, v115, v119
	v_min_u32_e32 v119, v115, v119
	v_max_u32_e32 v115, v109, v75
	v_min_u32_e32 v75, v109, v75
	v_max_u32_e32 v109, v98, v107
	v_min_u32_e32 v107, v98, v107
	v_max_u32_e32 v98, v106, v103
	v_min_u32_e32 v103, v106, v103
	v_max_u32_e32 v106, v116, v114
	v_min_u32_e32 v114, v116, v114
	v_max_u32_e32 v116, v72, v112
	v_min_u32_e32 v112, v72, v112
; __device__ __forceinline__ unsigned f2key(float f) { const unsigned u = __float_as_uint(f); return (u & 0x80000000u) ? ~u : (u | 0x80000000u); }
; __device__ __forceinline__ void peer_tile(const Args& A, LAS unsigned char* lds, int tile) {
;     ...
;                   for (int i = 0; i < 16; ++i) {
;                       const float lo = (float)__builtin_bit_cast(_Float16, (unsigned short)(sw[i] & 0xffffu)), hi = (float)__builtin_bit_cast(_Float16, (unsigned short)(sw[i] >> 16));
;                       const unsigned klo = (f2key(lo) & ~127u) | (unsigned)(127 - (32 * g + 2 * i)), khi = (f2key(hi) & ~127u) | (unsigned)(127 - (32 * g + 2 * i + 1));
;                       if (i < 8) { k0[2 * i] = klo; k0[2 * i + 1] = khi; } else { k1[2 * (i - 8)] = klo; k1[2 * (i - 8) + 1] = khi; } } }
;                 sort16_desc(k0); sort16_desc(k1); merge16(k0, k1);
; #pragma unroll
;                 for (int msk = 16; msk <= 32; msk <<= 1) {
; #pragma unroll
;                     for (int i = 0; i < 16; ++i) k1[i] = (unsigned)__shfl_xor((int)k0[i], msk);
;                     merge16(k0, k1); }
	v_max_u32_e32 v72, v104, v108
	v_min_u32_e32 v108, v104, v108
	v_max_u32_e32 v104, v119, v105
	v_min_u32_e32 v105, v119, v105
	v_max_u32_e32 v119, v111, v110
	v_min_u32_e32 v110, v111, v110
	v_max_u32_e32 v111, v115, v109
	v_min_u32_e32 v109, v115, v109
	v_max_u32_e32 v115, v75, v107
	v_min_u32_e32 v107, v75, v107
	v_max_u32_e32 v75, v98, v72
	v_min_u32_e32 v72, v98, v72
	v_max_u32_e32 v98, v103, v108
	v_min_u32_e32 v108, v103, v108
	v_max_u32_e32 v103, v106, v116
	v_min_u32_e32 v116, v106, v116
	v_max_u32_e32 v106, v114, v112
	v_min_u32_e32 v112, v114, v112
	v_max_u32_e32 v114, v104, v119
	v_min_u32_e32 v119, v104, v119
	v_max_u32_e32 v104, v105, v110
	v_min_u32_e32 v110, v105, v110
	v_max_u32_e32 v105, v115, v109
	v_min_u32_e32 v109, v115, v109
	v_max_u32_e32 v115, v107, v114
	v_min_u32_e32 v114, v107, v114
	v_max_u32_e32 v107, v75, v103
	v_min_u32_e32 v103, v75, v103
	v_max_u32_e32 v75, v98, v116
	v_min_u32_e32 v116, v98, v116
	v_max_u32_e32 v98, v106, v72
	v_min_u32_e32 v72, v106, v72
	v_max_u32_e32 v106, v112, v108
	v_min_u32_e32 v108, v112, v108
	v_max_u32_e32 v112, v104, v119
	v_min_u32_e32 v119, v104, v119
	v_max_u32_e32 v104, v105, v107
	v_min_u32_e32 v107, v105, v107
	v_max_u32_e32 v105, v109, v103
	v_min_u32_e32 v103, v109, v103
	v_max_u32_e32 v109, v75, v98
	v_min_u32_e32 v98, v75, v98
	v_max_u32_e32 v75, v116, v72
	v_min_u32_e32 v72, v116, v72
	v_max_u32_e32 v116, v106, v112
	v_min_u32_e32 v112, v106, v112
	v_max_u32_e32 v106, v108, v119
	v_min_u32_e32 v119, v108, v119
	v_max_u32_e32 v108, v105, v107
	v_min_u32_e32 v107, v105, v107
	v_max_u32_e32 v105, v115, v103
	v_min_u32_e32 v103, v115, v103
	v_max_u32_e32 v115, v116, v114
	v_min_u32_e32 v114, v116, v114
	v_max_u32_e32 v116, v106, v112
	v_min_u32_e32 v112, v106, v112
	v_max_u32_e32 v106, v105, v109
	v_min_u32_e32 v109, v105, v109
	v_max_u32_e32 v105, v103, v98
	v_min_u32_e32 v98, v103, v98
	v_max_u32_e32 v103, v75, v115
	v_min_u32_e32 v115, v75, v115
	v_max_u32_e32 v75, v72, v114
	v_min_u32_e32 v114, v72, v114
	v_max_u32_e32 v72, v106, v107
	v_min_u32_e32 v107, v106, v107
	v_max_u32_e32 v106, v109, v105
	v_min_u32_e32 v105, v109, v105
	v_max_u32_e32 v109, v103, v98
	v_min_u32_e32 v98, v103, v98
	v_max_u32_e32 v103, v115, v75
	v_min_u32_e32 v75, v115, v75
	v_max_u32_e32 v115, v116, v114
	v_min_u32_e32 v114, v116, v114
	v_max_u32_e32 v116, v105, v109
	v_min_u32_e32 v109, v105, v109
	v_max_u32_e32 v105, v98, v103
	v_min_u32_e32 v103, v98, v103
	v_max_u32_e32 v70, v70, v110
	v_max_u32_e32 v97, v97, v119
	v_max_u32_e32 v79, v79, v112
	v_max_u32_e32 v90, v90, v114
	v_max_u32_e32 v87, v87, v115
	v_max_u32_e32 v92, v92, v75
	v_max_u32_e32 v117, v117, v103
	v_max_u32_e32 v118, v118, v105
	v_max_u32_e32 v78, v78, v109
	v_max_u32_e32 v83, v83, v116
	v_max_u32_e32 v89, v89, v106
	v_max_u32_e32 v73, v73, v107
	v_max_u32_e32 v91, v91, v72
	v_max_u32_e32 v82, v82, v108
	v_max_u32_e32 v102, v102, v104
	v_max_u32_e32 v96, v96, v111
	v_max_u32_e32 v110, v70, v78
	v_min_u32_e32 v78, v70, v78
	v_max_u32_e32 v70, v97, v83
	v_min_u32_e32 v83, v97, v83
	v_max_u32_e32 v97, v79, v89
	v_min_u32_e32 v89, v79, v89
	v_max_u32_e32 v79, v90, v73
	v_min_u32_e32 v73, v90, v73
	v_max_u32_e32 v90, v87, v91
	v_min_u32_e32 v91, v87, v91
	v_max_u32_e32 v87, v92, v82
	v_min_u32_e32 v82, v92, v82
	v_max_u32_e32 v92, v117, v102
	v_min_u32_e32 v102, v117, v102
	v_max_u32_e32 v117, v118, v96
	v_min_u32_e32 v96, v118, v96
	v_max_u32_e32 v118, v110, v90
	v_min_u32_e32 v90, v110, v90
	v_max_u32_e32 v110, v70, v87
	v_min_u32_e32 v87, v70, v87
	v_max_u32_e32 v70, v97, v92
	v_min_u32_e32 v92, v97, v92
	v_max_u32_e32 v97, v79, v117
	v_min_u32_e32 v117, v79, v117
	v_max_u32_e32 v79, v78, v91
	v_min_u32_e32 v91, v78, v91
	v_max_u32_e32 v78, v83, v82
	v_min_u32_e32 v82, v83, v82
	v_max_u32_e32 v83, v89, v102
	v_min_u32_e32 v102, v89, v102
	v_max_u32_e32 v89, v73, v96
	v_min_u32_e32 v96, v73, v96
	v_max_u32_e32 v73, v118, v70
	v_min_u32_e32 v70, v118, v70
	v_max_u32_e32 v118, v110, v97
	v_min_u32_e32 v97, v110, v97
	v_max_u32_e32 v110, v90, v92
	v_min_u32_e32 v92, v90, v92
	v_max_u32_e32 v90, v87, v117
	v_min_u32_e32 v117, v87, v117
	v_max_u32_e32 v87, v79, v83
	v_min_u32_e32 v83, v79, v83
	v_max_u32_e32 v79, v78, v89
	v_min_u32_e32 v89, v78, v89
	v_max_u32_e32 v78, v91, v102
	v_min_u32_e32 v102, v91, v102
	v_max_u32_e32 v91, v82, v96
	v_min_u32_e32 v96, v82, v96
	v_max_u32_e32 v82, v73, v118
	v_min_u32_e32 v118, v73, v118
	v_max_u32_e32 v73, v70, v97
	v_min_u32_e32 v97, v70, v97
	v_max_u32_e32 v70, v110, v90
	v_min_u32_e32 v90, v110, v90
	v_max_u32_e32 v110, v92, v117
	v_min_u32_e32 v117, v92, v117
	v_max_u32_e32 v92, v87, v79
	v_min_u32_e32 v79, v87, v79
	v_max_u32_e32 v87, v83, v89
	v_min_u32_e32 v89, v83, v89
	v_max_u32_e32 v83, v78, v91
	v_min_u32_e32 v91, v78, v91
	v_max_u32_e32 v78, v102, v96
	v_min_u32_e32 v96, v102, v96
	s_waitcnt vmcnt(0)
	ds_write_b128 v64, v[32:35] offset:0
	ds_write_b128 v64, v[36:39] offset:1152
	ds_write_b128 v64, v[40:43] offset:2304
	ds_write_b128 v64, v[44:47] offset:3456
	ds_write_b128 v64, v[48:51] offset:4608
	ds_write_b128 v64, v[52:55] offset:5760
	ds_write_b128 v64, v[56:59] offset:6912
	ds_write_b128 v64, v[60:63] offset:8064
	s_waitcnt lgkmcnt(0)
	ds_read_b128 v[32:35], v65 offset:0
	ds_read_b128 v[36:39], v65 offset:16
	ds_read_b128 v[40:43], v65 offset:32
	ds_read_b128 v[44:47], v65 offset:48
	ds_read_b128 v[48:51], v65 offset:64
	ds_read_b128 v[52:55], v65 offset:80
	ds_read_b128 v[56:59], v65 offset:96
	ds_read_b128 v[60:63], v65 offset:112
	s_waitcnt lgkmcnt(0)
; __device__ __forceinline__ unsigned f2key(float f) { const unsigned u = __float_as_uint(f); return (u & 0x80000000u) ? ~u : (u | 0x80000000u); }
; __device__ __forceinline__ void peer_tile(const Args& A, LAS unsigned char* lds, int tile) {
;     ...
;                   for (int i = 0; i < 16; ++i) {
;                       const float lo = (float)__builtin_bit_cast(_Float16, (unsigned short)(sw[i] & 0xffffu)), hi = (float)__builtin_bit_cast(_Float16, (unsigned short)(sw[i] >> 16));
;                       const unsigned klo = (f2key(lo) & ~127u) | (unsigned)(127 - (32 * g + 2 * i)), khi = (f2key(hi) & ~127u) | (unsigned)(127 - (32 * g + 2 * i + 1));
;                       if (i < 8) { k0[2 * i] = klo; k0[2 * i + 1] = khi; } else { k1[2 * (i - 8)] = klo; k1[2 * (i - 8) + 1] = khi; } } }
;                 sort16_desc(k0); sort16_desc(k1); merge16(k0, k1);
	v_cvt_f32_f16_e32 v102, v32
	v_cvt_f32_f16_sdwa v119, v32 dst_sel:DWORD dst_unused:UNUSED_PAD src0_sel:WORD_1
	v_ashrrev_i32_e32 v112, 31, v102
	v_bitop3_b32 v102, v102, v112, s40 bitop3:0x78
	v_xor_b32_e32 v102, 0x8000003f, v102
	v_ashrrev_i32_e32 v112, 31, v119
	v_bitop3_b32 v119, v119, v112, s40 bitop3:0x78
	v_xor_b32_e32 v119, 0x8000003e, v119
	v_cvt_f32_f16_e32 v112, v33
	v_cvt_f32_f16_sdwa v114, v33 dst_sel:DWORD dst_unused:UNUSED_PAD src0_sel:WORD_1
	v_ashrrev_i32_e32 v115, 31, v112
	v_bitop3_b32 v112, v112, v115, s40 bitop3:0x78
	v_xor_b32_e32 v112, 0x8000003d, v112
	v_ashrrev_i32_e32 v115, 31, v114
	v_bitop3_b32 v114, v114, v115, s40 bitop3:0x78
	v_xor_b32_e32 v114, 0x8000003c, v114
	v_cvt_f32_f16_e32 v115, v34
	v_cvt_f32_f16_sdwa v75, v34 dst_sel:DWORD dst_unused:UNUSED_PAD src0_sel:WORD_1
	v_ashrrev_i32_e32 v103, 31, v115
	v_bitop3_b32 v115, v115, v103, s40 bitop3:0x78
	v_xor_b32_e32 v115, 0x8000003b, v115
	v_ashrrev_i32_e32 v103, 31, v75
	v_bitop3_b32 v75, v75, v103, s40 bitop3:0x78
	v_xor_b32_e32 v75, 0x8000003a, v75
	v_cvt_f32_f16_e32 v103, v35
	v_cvt_f32_f16_sdwa v105, v35 dst_sel:DWORD dst_unused:UNUSED_PAD src0_sel:WORD_1
	v_ashrrev_i32_e32 v109, 31, v103
	v_bitop3_b32 v103, v103, v109, s40 bitop3:0x78
	v_xor_b32_e32 v103, 0x80000039, v103
	v_ashrrev_i32_e32 v109, 31, v105
	v_bitop3_b32 v105, v105, v109, s40 bitop3:0x78
	v_xor_b32_e32 v105, 0x80000038, v105
	v_cvt_f32_f16_e32 v109, v36
	v_cvt_f32_f16_sdwa v116, v36 dst_sel:DWORD dst_unused:UNUSED_PAD src0_sel:WORD_1
	v_ashrrev_i32_e32 v106, 31, v109
	v_bitop3_b32 v109, v109, v106, s40 bitop3:0x78
	v_xor_b32_e32 v109, 0x80000037, v109
	v_ashrrev_i32_e32 v106, 31, v116
	v_bitop3_b32 v116, v116, v106, s40 bitop3:0x78
	v_xor_b32_e32 v116, 0x80000036, v116
	v_cvt_f32_f16_e32 v106, v37
	v_cvt_f32_f16_sdwa v107, v37 dst_sel:DWORD dst_unused:UNUSED_PAD src0_sel:WORD_1
	v_ashrrev_i32_e32 v72, 31, v106
	v_bitop3_b32 v106, v106, v72, s40 bitop3:0x78
	v_xor_b32_e32 v106, 0x80000035, v106
	v_ashrrev_i32_e32 v72, 31, v107
	v_bitop3_b32 v107, v107, v72, s40 bitop3:0x78
	v_xor_b32_e32 v107, 0x80000034, v107
	v_cvt_f32_f16_e32 v72, v38
	v_cvt_f32_f16_sdwa v108, v38 dst_sel:DWORD dst_unused:UNUSED_PAD src0_sel:WORD_1
	v_ashrrev_i32_e32 v104, 31, v72
	v_bitop3_b32 v72, v72, v104, s40 bitop3:0x78
	v_xor_b32_e32 v72, 0x80000033, v72
	v_ashrrev_i32_e32 v104, 31, v108
	v_bitop3_b32 v108, v108, v104, s40 bitop3:0x78
	v_xor_b32_e32 v108, 0x80000032, v108
	v_cvt_f32_f16_e32 v104, v39
	v_cvt_f32_f16_sdwa v111, v39 dst_sel:DWORD dst_unused:UNUSED_PAD src0_sel:WORD_1
	v_ashrrev_i32_e32 v98, 31, v104
	v_bitop3_b32 v104, v104, v98, s40 bitop3:0x78
	v_xor_b32_e32 v104, 0x80000031, v104
	v_ashrrev_i32_e32 v98, 31, v111
	v_bitop3_b32 v111, v111, v98, s40 bitop3:0x78
	v_xor_b32_e32 v111, 0x80000030, v111
	v_max_u32_e32 v98, v102, v108
	v_min_u32_e32 v108, v102, v108
	v_max_u32_e32 v102, v119, v72
	v_min_u32_e32 v72, v119, v72
	v_max_u32_e32 v119, v112, v111
	v_min_u32_e32 v111, v112, v111
	v_max_u32_e32 v112, v114, v104
	v_min_u32_e32 v104, v114, v104
	v_max_u32_e32 v114, v115, v109
	v_min_u32_e32 v109, v115, v109
	v_max_u32_e32 v115, v75, v103
	v_min_u32_e32 v103, v75, v103
	v_max_u32_e32 v75, v105, v107
	v_min_u32_e32 v107, v105, v107
	v_max_u32_e32 v105, v116, v106
	v_min_u32_e32 v106, v116, v106
	v_max_u32_e32 v116, v98, v115
	v_min_u32_e32 v115, v98, v115
	v_max_u32_e32 v98, v102, v75
	v_min_u32_e32 v75, v102, v75
	v_max_u32_e32 v102, v119, v105
	v_min_u32_e32 v105, v119, v105
	v_max_u32_e32 v119, v112, v114
	v_min_u32_e32 v114, v112, v114
	v_max_u32_e32 v112, v103, v108
	v_min_u32_e32 v108, v103, v108
	v_max_u32_e32 v103, v109, v104
	v_min_u32_e32 v104, v109, v104
	v_max_u32_e32 v109, v106, v111
	v_min_u32_e32 v111, v106, v111
	v_max_u32_e32 v106, v107, v72
	v_min_u32_e32 v72, v107, v72
	v_max_u32_e32 v107, v116, v98
	v_min_u32_e32 v98, v116, v98
	v_max_u32_e32 v116, v102, v119
	v_min_u32_e32 v119, v102, v119
	v_max_u32_e32 v102, v114, v115
	v_min_u32_e32 v115, v114, v115
	v_max_u32_e32 v114, v112, v103
	v_min_u32_e32 v103, v112, v103
	v_max_u32_e32 v112, v75, v105
	v_min_u32_e32 v105, v75, v105
	v_max_u32_e32 v75, v109, v106
	v_min_u32_e32 v106, v109, v106
	v_max_u32_e32 v109, v72, v108
	v_min_u32_e32 v108, v72, v108
	v_max_u32_e32 v72, v104, v111
	v_min_u32_e32 v111, v104, v111
	v_max_u32_e32 v104, v107, v116
	v_min_u32_e32 v116, v107, v116
	v_max_u32_e32 v107, v98, v119
	v_min_u32_e32 v119, v98, v119
	v_max_u32_e32 v98, v102, v75
	v_min_u32_e32 v75, v102, v75
	v_max_u32_e32 v102, v115, v106
	v_min_u32_e32 v106, v115, v106
	v_max_u32_e32 v115, v114, v112
	v_min_u32_e32 v112, v114, v112
	v_max_u32_e32 v114, v103, v105
	v_min_u32_e32 v105, v103, v105
	v_max_u32_e32 v103, v109, v72
	v_min_u32_e32 v72, v109, v72
	v_max_u32_e32 v109, v108, v111
	v_min_u32_e32 v111, v108, v111
	v_max_u32_e32 v108, v107, v116
	v_min_u32_e32 v116, v107, v116
	v_max_u32_e32 v107, v119, v103
	v_min_u32_e32 v103, v119, v103
	v_max_u32_e32 v119, v98, v115
	v_min_u32_e32 v115, v98, v115
	v_max_u32_e32 v98, v102, v112
	v_min_u32_e32 v112, v102, v112
	v_max_u32_e32 v102, v114, v75
	v_min_u32_e32 v75, v114, v75
	v_max_u32_e32 v114, v105, v106
	v_min_u32_e32 v106, v105, v106
	v_max_u32_e32 v105, v109, v72
	v_min_u32_e32 v72, v109, v72
	v_max_u32_e32 v109, v108, v119
	v_min_u32_e32 v119, v108, v119
	v_max_u32_e32 v108, v116, v115
	v_min_u32_e32 v115, v116, v115
	v_max_u32_e32 v116, v98, v102
	v_min_u32_e32 v102, v98, v102
	v_max_u32_e32 v98, v112, v75
	v_min_u32_e32 v75, v112, v75
	v_max_u32_e32 v112, v114, v105
	v_min_u32_e32 v105, v114, v105
	v_max_u32_e32 v114, v106, v72
	v_min_u32_e32 v72, v106, v72
	v_max_u32_e32 v106, v108, v119
; __device__ __forceinline__ unsigned f2key(float f) { const unsigned u = __float_as_uint(f); return (u & 0x80000000u) ? ~u : (u | 0x80000000u); }
; __device__ __forceinline__ void peer_tile(const Args& A, LAS unsigned char* lds, int tile) {
;     ...
;                   for (int i = 0; i < 16; ++i) {
;                       const float lo = (float)__builtin_bit_cast(_Float16, (unsigned short)(sw[i] & 0xffffu)), hi = (float)__builtin_bit_cast(_Float16, (unsigned short)(sw[i] >> 16));
;                       const unsigned klo = (f2key(lo) & ~127u) | (unsigned)(127 - (32 * g + 2 * i)), khi = (f2key(hi) & ~127u) | (unsigned)(127 - (32 * g + 2 * i + 1));
;                       if (i < 8) { k0[2 * i] = klo; k0[2 * i + 1] = khi; } else { k1[2 * (i - 8)] = klo; k1[2 * (i - 8) + 1] = khi; } } }
;                 sort16_desc(k0); sort16_desc(k1); merge16(k0, k1);
; #pragma unroll
;                 for (int msk = 16; msk <= 32; msk <<= 1) {
; #pragma unroll
;                     for (int i = 0; i < 16; ++i) k1[i] = (unsigned)__shfl_xor((int)k0[i], msk);
;                     merge16(k0, k1); }
	v_min_u32_e32 v119, v108, v119
	v_max_u32_e32 v108, v107, v115
	v_min_u32_e32 v115, v107, v115
	v_max_u32_e32 v107, v112, v103
	v_min_u32_e32 v103, v112, v103
	v_max_u32_e32 v112, v114, v105
	v_min_u32_e32 v105, v114, v105
	v_max_u32_e32 v114, v108, v116
	v_min_u32_e32 v116, v108, v116
	v_max_u32_e32 v108, v115, v102
	v_min_u32_e32 v102, v115, v102
	v_max_u32_e32 v115, v98, v107
	v_min_u32_e32 v107, v98, v107
	v_max_u32_e32 v98, v75, v103
	v_min_u32_e32 v103, v75, v103
	v_max_u32_e32 v75, v114, v119
	v_min_u32_e32 v119, v114, v119
	v_max_u32_e32 v114, v116, v108
	v_min_u32_e32 v108, v116, v108
	v_max_u32_e32 v116, v115, v102
	v_min_u32_e32 v102, v115, v102
	v_max_u32_e32 v115, v107, v98
	v_min_u32_e32 v98, v107, v98
	v_max_u32_e32 v107, v112, v103
	v_min_u32_e32 v103, v112, v103
	v_max_u32_e32 v112, v108, v116
	v_min_u32_e32 v116, v108, v116
	v_max_u32_e32 v108, v102, v115
	v_min_u32_e32 v115, v102, v115
	v_max_u32_e32 v82, v82, v111
	v_max_u32_e32 v118, v118, v72
	v_max_u32_e32 v73, v73, v105
	v_max_u32_e32 v97, v97, v103
	v_max_u32_e32 v70, v70, v107
	v_max_u32_e32 v90, v90, v98
	v_max_u32_e32 v110, v110, v115
	v_max_u32_e32 v117, v117, v108
	v_max_u32_e32 v92, v92, v116
	v_max_u32_e32 v79, v79, v112
	v_max_u32_e32 v87, v87, v114
	v_max_u32_e32 v89, v89, v119
	v_max_u32_e32 v83, v83, v75
	v_max_u32_e32 v91, v91, v106
	v_max_u32_e32 v78, v78, v109
	v_max_u32_e32 v96, v96, v104
	v_max_u32_e32 v111, v82, v92
	v_min_u32_e32 v92, v82, v92
	v_max_u32_e32 v82, v118, v79
	v_min_u32_e32 v79, v118, v79
	v_max_u32_e32 v118, v73, v87
	v_min_u32_e32 v87, v73, v87
	v_max_u32_e32 v73, v97, v89
	v_min_u32_e32 v89, v97, v89
	v_max_u32_e32 v97, v70, v83
	v_min_u32_e32 v83, v70, v83
	v_max_u32_e32 v70, v90, v91
	v_min_u32_e32 v91, v90, v91
	v_max_u32_e32 v90, v110, v78
	v_min_u32_e32 v78, v110, v78
	v_max_u32_e32 v110, v117, v96
	v_min_u32_e32 v96, v117, v96
	v_max_u32_e32 v117, v111, v97
	v_min_u32_e32 v97, v111, v97
	v_max_u32_e32 v111, v82, v70
	v_min_u32_e32 v70, v82, v70
	v_max_u32_e32 v82, v118, v90
	v_min_u32_e32 v90, v118, v90
	v_max_u32_e32 v118, v73, v110
	v_min_u32_e32 v110, v73, v110
	v_max_u32_e32 v73, v92, v83
	v_min_u32_e32 v83, v92, v83
	v_max_u32_e32 v92, v79, v91
	v_min_u32_e32 v91, v79, v91
	v_max_u32_e32 v79, v87, v78
	v_min_u32_e32 v78, v87, v78
	v_max_u32_e32 v87, v89, v96
	v_min_u32_e32 v96, v89, v96
	v_max_u32_e32 v89, v117, v82
	v_min_u32_e32 v82, v117, v82
	v_max_u32_e32 v117, v111, v118
	v_min_u32_e32 v118, v111, v118
	v_max_u32_e32 v111, v97, v90
	v_min_u32_e32 v90, v97, v90
	v_max_u32_e32 v97, v70, v110
	v_min_u32_e32 v110, v70, v110
	v_max_u32_e32 v70, v73, v79
	v_min_u32_e32 v79, v73, v79
	v_max_u32_e32 v73, v92, v87
	v_min_u32_e32 v87, v92, v87
	v_max_u32_e32 v92, v83, v78
	v_min_u32_e32 v78, v83, v78
	v_max_u32_e32 v83, v91, v96
	v_min_u32_e32 v96, v91, v96
	v_max_u32_e32 v91, v89, v117
	v_min_u32_e32 v117, v89, v117
	v_max_u32_e32 v89, v82, v118
	v_min_u32_e32 v118, v82, v118
	v_max_u32_e32 v82, v111, v97
	v_min_u32_e32 v97, v111, v97
	v_max_u32_e32 v111, v90, v110
	v_min_u32_e32 v110, v90, v110
	v_max_u32_e32 v90, v70, v73
	v_min_u32_e32 v73, v70, v73
	v_max_u32_e32 v70, v79, v87
	v_min_u32_e32 v87, v79, v87
	v_max_u32_e32 v79, v92, v83
	v_min_u32_e32 v83, v92, v83
	v_max_u32_e32 v92, v78, v96
	v_min_u32_e32 v96, v78, v96
	v_cvt_f32_f16_e32 v78, v40
	v_cvt_f32_f16_sdwa v72, v40 dst_sel:DWORD dst_unused:UNUSED_PAD src0_sel:WORD_1
	v_ashrrev_i32_e32 v105, 31, v78
	v_bitop3_b32 v78, v78, v105, s40 bitop3:0x78
	v_xor_b32_e32 v78, 0x8000002f, v78
	v_ashrrev_i32_e32 v105, 31, v72
	v_bitop3_b32 v72, v72, v105, s40 bitop3:0x78
	v_xor_b32_e32 v72, 0x8000002e, v72
	v_cvt_f32_f16_e32 v105, v41
	v_cvt_f32_f16_sdwa v103, v41 dst_sel:DWORD dst_unused:UNUSED_PAD src0_sel:WORD_1
	v_ashrrev_i32_e32 v107, 31, v105
	v_bitop3_b32 v105, v105, v107, s40 bitop3:0x78
	v_xor_b32_e32 v105, 0x8000002d, v105
	v_ashrrev_i32_e32 v107, 31, v103
	v_bitop3_b32 v103, v103, v107, s40 bitop3:0x78
	v_xor_b32_e32 v103, 0x8000002c, v103
	v_cvt_f32_f16_e32 v107, v42
	v_cvt_f32_f16_sdwa v98, v42 dst_sel:DWORD dst_unused:UNUSED_PAD src0_sel:WORD_1
	v_ashrrev_i32_e32 v115, 31, v107
	v_bitop3_b32 v107, v107, v115, s40 bitop3:0x78
	v_xor_b32_e32 v107, 0x8000002b, v107
	v_ashrrev_i32_e32 v115, 31, v98
	v_bitop3_b32 v98, v98, v115, s40 bitop3:0x78
	v_xor_b32_e32 v98, 0x8000002a, v98
	v_cvt_f32_f16_e32 v115, v43
	v_cvt_f32_f16_sdwa v108, v43 dst_sel:DWORD dst_unused:UNUSED_PAD src0_sel:WORD_1
	v_ashrrev_i32_e32 v116, 31, v115
	v_bitop3_b32 v115, v115, v116, s40 bitop3:0x78
	v_xor_b32_e32 v115, 0x80000029, v115
	v_ashrrev_i32_e32 v116, 31, v108
	v_bitop3_b32 v108, v108, v116, s40 bitop3:0x78
	v_xor_b32_e32 v108, 0x80000028, v108
	v_cvt_f32_f16_e32 v116, v44
	v_cvt_f32_f16_sdwa v112, v44 dst_sel:DWORD dst_unused:UNUSED_PAD src0_sel:WORD_1
	v_ashrrev_i32_e32 v114, 31, v116
	v_bitop3_b32 v116, v116, v114, s40 bitop3:0x78
	v_xor_b32_e32 v116, 0x80000027, v116
	v_ashrrev_i32_e32 v114, 31, v112
	v_bitop3_b32 v112, v112, v114, s40 bitop3:0x78
	v_xor_b32_e32 v112, 0x80000026, v112
	v_cvt_f32_f16_e32 v114, v45
	v_cvt_f32_f16_sdwa v119, v45 dst_sel:DWORD dst_unused:UNUSED_PAD src0_sel:WORD_1
	v_ashrrev_i32_e32 v75, 31, v114
	v_bitop3_b32 v114, v114, v75, s40 bitop3:0x78
	v_xor_b32_e32 v114, 0x80000025, v114
	v_ashrrev_i32_e32 v75, 31, v119
	v_bitop3_b32 v119, v119, v75, s40 bitop3:0x78
	v_xor_b32_e32 v119, 0x80000024, v119
	v_cvt_f32_f16_e32 v75, v46
	v_cvt_f32_f16_sdwa v106, v46 dst_sel:DWORD dst_unused:UNUSED_PAD src0_sel:WORD_1
	v_ashrrev_i32_e32 v109, 31, v75
	v_bitop3_b32 v75, v75, v109, s40 bitop3:0x78
	v_xor_b32_e32 v75, 0x80000023, v75
	v_ashrrev_i32_e32 v109, 31, v106
; __device__ __forceinline__ unsigned f2key(float f) { const unsigned u = __float_as_uint(f); return (u & 0x80000000u) ? ~u : (u | 0x80000000u); }
; __device__ __forceinline__ void peer_tile(const Args& A, LAS unsigned char* lds, int tile) {
;     ...
;                   for (int i = 0; i < 16; ++i) {
;                       const float lo = (float)__builtin_bit_cast(_Float16, (unsigned short)(sw[i] & 0xffffu)), hi = (float)__builtin_bit_cast(_Float16, (unsigned short)(sw[i] >> 16));
;                       const unsigned klo = (f2key(lo) & ~127u) | (unsigned)(127 - (32 * g + 2 * i)), khi = (f2key(hi) & ~127u) | (unsigned)(127 - (32 * g + 2 * i + 1));
;                       if (i < 8) { k0[2 * i] = klo; k0[2 * i + 1] = khi; } else { k1[2 * (i - 8)] = klo; k1[2 * (i - 8) + 1] = khi; } } }
;                 sort16_desc(k0); sort16_desc(k1); merge16(k0, k1);
; #pragma unroll
;                 for (int msk = 16; msk <= 32; msk <<= 1) {
; #pragma unroll
;                     for (int i = 0; i < 16; ++i) k1[i] = (unsigned)__shfl_xor((int)k0[i], msk);
;                     merge16(k0, k1); }
	v_bitop3_b32 v106, v106, v109, s40 bitop3:0x78
	v_xor_b32_e32 v106, 0x80000022, v106
	v_cvt_f32_f16_e32 v109, v47
	v_cvt_f32_f16_sdwa v104, v47 dst_sel:DWORD dst_unused:UNUSED_PAD src0_sel:WORD_1
	v_ashrrev_i32_e32 v102, 31, v109
	v_bitop3_b32 v109, v109, v102, s40 bitop3:0x78
	v_xor_b32_e32 v109, 0x80000021, v109
	v_ashrrev_i32_e32 v102, 31, v104
	v_bitop3_b32 v104, v104, v102, s40 bitop3:0x78
	v_xor_b32_e32 v104, 0x80000020, v104
	v_max_u32_e32 v102, v78, v106
	v_min_u32_e32 v106, v78, v106
	v_max_u32_e32 v78, v72, v75
	v_min_u32_e32 v75, v72, v75
	v_max_u32_e32 v72, v105, v104
	v_min_u32_e32 v104, v105, v104
	v_max_u32_e32 v105, v103, v109
	v_min_u32_e32 v109, v103, v109
	v_max_u32_e32 v103, v107, v116
	v_min_u32_e32 v116, v107, v116
	v_max_u32_e32 v107, v98, v115
	v_min_u32_e32 v115, v98, v115
	v_max_u32_e32 v98, v108, v119
	v_min_u32_e32 v119, v108, v119
	v_max_u32_e32 v108, v112, v114
	v_min_u32_e32 v114, v112, v114
	v_max_u32_e32 v112, v102, v107
	v_min_u32_e32 v107, v102, v107
	v_max_u32_e32 v102, v78, v98
	v_min_u32_e32 v98, v78, v98
	v_max_u32_e32 v78, v72, v108
	v_min_u32_e32 v108, v72, v108
	v_max_u32_e32 v72, v105, v103
	v_min_u32_e32 v103, v105, v103
	v_max_u32_e32 v105, v115, v106
	v_min_u32_e32 v106, v115, v106
	v_max_u32_e32 v115, v116, v109
	v_min_u32_e32 v109, v116, v109
	v_max_u32_e32 v116, v114, v104
	v_min_u32_e32 v104, v114, v104
	v_max_u32_e32 v114, v119, v75
	v_min_u32_e32 v75, v119, v75
	v_max_u32_e32 v119, v112, v102
	v_min_u32_e32 v102, v112, v102
	v_max_u32_e32 v112, v78, v72
	v_min_u32_e32 v72, v78, v72
	v_max_u32_e32 v78, v103, v107
	v_min_u32_e32 v107, v103, v107
	v_max_u32_e32 v103, v105, v115
	v_min_u32_e32 v115, v105, v115
	v_max_u32_e32 v105, v98, v108
	v_min_u32_e32 v108, v98, v108
	v_max_u32_e32 v98, v116, v114
	v_min_u32_e32 v114, v116, v114
	v_max_u32_e32 v116, v75, v106
	v_min_u32_e32 v106, v75, v106
	v_max_u32_e32 v75, v109, v104
	v_min_u32_e32 v104, v109, v104
	v_max_u32_e32 v109, v119, v112
	v_min_u32_e32 v112, v119, v112
	v_max_u32_e32 v119, v102, v72
	v_min_u32_e32 v72, v102, v72
	v_max_u32_e32 v102, v78, v98
	v_min_u32_e32 v98, v78, v98
	v_max_u32_e32 v78, v107, v114
	v_min_u32_e32 v114, v107, v114
	v_max_u32_e32 v107, v103, v105
	v_min_u32_e32 v105, v103, v105
	v_max_u32_e32 v103, v115, v108
	v_min_u32_e32 v108, v115, v108
	v_max_u32_e32 v115, v116, v75
	v_min_u32_e32 v75, v116, v75
	v_max_u32_e32 v116, v106, v104
	v_min_u32_e32 v104, v106, v104
	v_max_u32_e32 v106, v119, v112
	v_min_u32_e32 v112, v119, v112
	v_max_u32_e32 v119, v72, v115
	v_min_u32_e32 v115, v72, v115
	v_max_u32_e32 v72, v102, v107
	v_min_u32_e32 v107, v102, v107
	v_max_u32_e32 v102, v78, v105
	v_min_u32_e32 v105, v78, v105
	v_max_u32_e32 v78, v103, v98
	v_min_u32_e32 v98, v103, v98
	v_max_u32_e32 v103, v108, v114
	v_min_u32_e32 v114, v108, v114
	v_max_u32_e32 v108, v116, v75
	v_min_u32_e32 v75, v116, v75
	v_max_u32_e32 v116, v106, v72
	v_min_u32_e32 v72, v106, v72
	v_max_u32_e32 v106, v112, v107
	v_min_u32_e32 v107, v112, v107
	v_max_u32_e32 v112, v102, v78
	v_min_u32_e32 v78, v102, v78
	v_max_u32_e32 v102, v105, v98
	v_min_u32_e32 v98, v105, v98
	v_max_u32_e32 v105, v103, v108
	v_min_u32_e32 v108, v103, v108
	v_max_u32_e32 v103, v114, v75
	v_min_u32_e32 v75, v114, v75
	v_max_u32_e32 v114, v106, v72
	v_min_u32_e32 v72, v106, v72
	v_max_u32_e32 v106, v119, v107
	v_min_u32_e32 v107, v119, v107
	v_max_u32_e32 v119, v105, v115
	v_min_u32_e32 v115, v105, v115
	v_max_u32_e32 v105, v103, v108
	v_min_u32_e32 v108, v103, v108
	v_max_u32_e32 v103, v106, v112
	v_min_u32_e32 v112, v106, v112
	v_max_u32_e32 v106, v107, v78
	v_min_u32_e32 v78, v107, v78
	v_max_u32_e32 v107, v102, v119
	v_min_u32_e32 v119, v102, v119
	v_max_u32_e32 v102, v98, v115
	v_min_u32_e32 v115, v98, v115
	v_max_u32_e32 v98, v103, v72
	v_min_u32_e32 v72, v103, v72
	v_max_u32_e32 v103, v112, v106
	v_min_u32_e32 v106, v112, v106
	v_max_u32_e32 v112, v107, v78
	v_min_u32_e32 v78, v107, v78
	v_max_u32_e32 v107, v119, v102
	v_min_u32_e32 v102, v119, v102
	v_max_u32_e32 v119, v105, v115
	v_min_u32_e32 v115, v105, v115
	v_max_u32_e32 v105, v106, v112
	v_min_u32_e32 v112, v106, v112
	v_max_u32_e32 v106, v78, v107
	v_min_u32_e32 v107, v78, v107
	v_max_u32_e32 v91, v91, v104
	v_max_u32_e32 v117, v117, v75
	v_max_u32_e32 v89, v89, v108
	v_max_u32_e32 v118, v118, v115
	v_max_u32_e32 v82, v82, v119
	v_max_u32_e32 v97, v97, v102
	v_max_u32_e32 v111, v111, v107
	v_max_u32_e32 v110, v110, v106
	v_max_u32_e32 v90, v90, v112
	v_max_u32_e32 v73, v73, v105
	v_max_u32_e32 v70, v70, v103
	v_max_u32_e32 v87, v87, v72
	v_max_u32_e32 v79, v79, v98
	v_max_u32_e32 v83, v83, v114
	v_max_u32_e32 v92, v92, v116
	v_max_u32_e32 v96, v96, v109
	v_max_u32_e32 v104, v91, v90
	v_min_u32_e32 v90, v91, v90
	v_max_u32_e32 v91, v117, v73
	v_min_u32_e32 v73, v117, v73
	v_max_u32_e32 v117, v89, v70
	v_min_u32_e32 v70, v89, v70
	v_max_u32_e32 v89, v118, v87
	v_min_u32_e32 v87, v118, v87
	v_max_u32_e32 v118, v82, v79
	v_min_u32_e32 v79, v82, v79
	v_max_u32_e32 v82, v97, v83
	v_min_u32_e32 v83, v97, v83
	v_max_u32_e32 v97, v111, v92
	v_min_u32_e32 v92, v111, v92
	v_max_u32_e32 v111, v110, v96
	v_min_u32_e32 v96, v110, v96
	v_max_u32_e32 v110, v104, v118
	v_min_u32_e32 v118, v104, v118
	v_max_u32_e32 v104, v91, v82
	v_min_u32_e32 v82, v91, v82
	v_max_u32_e32 v91, v117, v97
	v_min_u32_e32 v97, v117, v97
	v_max_u32_e32 v117, v89, v111
	v_min_u32_e32 v111, v89, v111
	v_max_u32_e32 v89, v90, v79
	v_min_u32_e32 v79, v90, v79
	v_max_u32_e32 v90, v73, v83
	v_min_u32_e32 v83, v73, v83
	v_max_u32_e32 v73, v70, v92
	v_min_u32_e32 v92, v70, v92
	v_max_u32_e32 v70, v87, v96
	v_min_u32_e32 v96, v87, v96
; __device__ __forceinline__ unsigned f2key(float f) { const unsigned u = __float_as_uint(f); return (u & 0x80000000u) ? ~u : (u | 0x80000000u); }
; __device__ __forceinline__ void peer_tile(const Args& A, LAS unsigned char* lds, int tile) {
;     ...
;                   for (int i = 0; i < 16; ++i) {
;                       const float lo = (float)__builtin_bit_cast(_Float16, (unsigned short)(sw[i] & 0xffffu)), hi = (float)__builtin_bit_cast(_Float16, (unsigned short)(sw[i] >> 16));
;                       const unsigned klo = (f2key(lo) & ~127u) | (unsigned)(127 - (32 * g + 2 * i)), khi = (f2key(hi) & ~127u) | (unsigned)(127 - (32 * g + 2 * i + 1));
;                       if (i < 8) { k0[2 * i] = klo; k0[2 * i + 1] = khi; } else { k1[2 * (i - 8)] = klo; k1[2 * (i - 8) + 1] = khi; } } }
;                 sort16_desc(k0); sort16_desc(k1); merge16(k0, k1);
; #pragma unroll
;                 for (int msk = 16; msk <= 32; msk <<= 1) {
; #pragma unroll
;                     for (int i = 0; i < 16; ++i) k1[i] = (unsigned)__shfl_xor((int)k0[i], msk);
;                     merge16(k0, k1); }
	v_max_u32_e32 v87, v110, v91
	v_min_u32_e32 v91, v110, v91
	v_max_u32_e32 v110, v104, v117
	v_min_u32_e32 v117, v104, v117
	v_max_u32_e32 v104, v118, v97
	v_min_u32_e32 v97, v118, v97
	v_max_u32_e32 v118, v82, v111
	v_min_u32_e32 v111, v82, v111
	v_max_u32_e32 v82, v89, v73
	v_min_u32_e32 v73, v89, v73
	v_max_u32_e32 v89, v90, v70
	v_min_u32_e32 v70, v90, v70
	v_max_u32_e32 v90, v79, v92
	v_min_u32_e32 v92, v79, v92
	v_max_u32_e32 v79, v83, v96
	v_min_u32_e32 v96, v83, v96
	v_max_u32_e32 v83, v87, v110
	v_min_u32_e32 v110, v87, v110
	v_max_u32_e32 v87, v91, v117
	v_min_u32_e32 v117, v91, v117
	v_max_u32_e32 v91, v104, v118
	v_min_u32_e32 v118, v104, v118
	v_max_u32_e32 v104, v97, v111
	v_min_u32_e32 v111, v97, v111
	v_max_u32_e32 v97, v82, v89
	v_min_u32_e32 v89, v82, v89
	v_max_u32_e32 v82, v73, v70
	v_min_u32_e32 v70, v73, v70
	v_max_u32_e32 v73, v90, v79
	v_min_u32_e32 v79, v90, v79
	v_max_u32_e32 v90, v92, v96
	v_min_u32_e32 v96, v92, v96
	v_cvt_f32_f16_e32 v92, v48
	v_cvt_f32_f16_sdwa v75, v48 dst_sel:DWORD dst_unused:UNUSED_PAD src0_sel:WORD_1
	v_ashrrev_i32_e32 v108, 31, v92
	v_bitop3_b32 v92, v92, v108, s40 bitop3:0x78
	v_xor_b32_e32 v92, 0x8000001f, v92
	v_ashrrev_i32_e32 v108, 31, v75
	v_bitop3_b32 v75, v75, v108, s40 bitop3:0x78
	v_xor_b32_e32 v75, 0x8000001e, v75
	v_cvt_f32_f16_e32 v108, v49
	v_cvt_f32_f16_sdwa v115, v49 dst_sel:DWORD dst_unused:UNUSED_PAD src0_sel:WORD_1
	v_ashrrev_i32_e32 v119, 31, v108
	v_bitop3_b32 v108, v108, v119, s40 bitop3:0x78
	v_xor_b32_e32 v108, 0x8000001d, v108
	v_ashrrev_i32_e32 v119, 31, v115
	v_bitop3_b32 v115, v115, v119, s40 bitop3:0x78
	v_xor_b32_e32 v115, 0x8000001c, v115
	v_cvt_f32_f16_e32 v119, v50
	v_cvt_f32_f16_sdwa v102, v50 dst_sel:DWORD dst_unused:UNUSED_PAD src0_sel:WORD_1
	v_ashrrev_i32_e32 v107, 31, v119
	v_bitop3_b32 v119, v119, v107, s40 bitop3:0x78
	v_xor_b32_e32 v119, 0x8000001b, v119
	v_ashrrev_i32_e32 v107, 31, v102
	v_bitop3_b32 v102, v102, v107, s40 bitop3:0x78
	v_xor_b32_e32 v102, 0x8000001a, v102
	v_cvt_f32_f16_e32 v107, v51
	v_cvt_f32_f16_sdwa v106, v51 dst_sel:DWORD dst_unused:UNUSED_PAD src0_sel:WORD_1
	v_ashrrev_i32_e32 v112, 31, v107
	v_bitop3_b32 v107, v107, v112, s40 bitop3:0x78
	v_xor_b32_e32 v107, 0x80000019, v107
	v_ashrrev_i32_e32 v112, 31, v106
	v_bitop3_b32 v106, v106, v112, s40 bitop3:0x78
	v_xor_b32_e32 v106, 0x80000018, v106
	v_cvt_f32_f16_e32 v112, v52
	v_cvt_f32_f16_sdwa v105, v52 dst_sel:DWORD dst_unused:UNUSED_PAD src0_sel:WORD_1
	v_ashrrev_i32_e32 v103, 31, v112
	v_bitop3_b32 v112, v112, v103, s40 bitop3:0x78
	v_xor_b32_e32 v112, 0x80000017, v112
	v_ashrrev_i32_e32 v103, 31, v105
	v_bitop3_b32 v105, v105, v103, s40 bitop3:0x78
	v_xor_b32_e32 v105, 0x80000016, v105
	v_cvt_f32_f16_e32 v103, v53
	v_cvt_f32_f16_sdwa v72, v53 dst_sel:DWORD dst_unused:UNUSED_PAD src0_sel:WORD_1
	v_ashrrev_i32_e32 v98, 31, v103
	v_bitop3_b32 v103, v103, v98, s40 bitop3:0x78
	v_xor_b32_e32 v103, 0x80000015, v103
	v_ashrrev_i32_e32 v98, 31, v72
	v_bitop3_b32 v72, v72, v98, s40 bitop3:0x78
	v_xor_b32_e32 v72, 0x80000014, v72
	v_cvt_f32_f16_e32 v98, v54
	v_cvt_f32_f16_sdwa v114, v54 dst_sel:DWORD dst_unused:UNUSED_PAD src0_sel:WORD_1
	v_ashrrev_i32_e32 v116, 31, v98
	v_bitop3_b32 v98, v98, v116, s40 bitop3:0x78
	v_xor_b32_e32 v98, 0x80000013, v98
	v_ashrrev_i32_e32 v116, 31, v114
	v_bitop3_b32 v114, v114, v116, s40 bitop3:0x78
	v_xor_b32_e32 v114, 0x80000012, v114
	v_cvt_f32_f16_e32 v116, v55
	v_cvt_f32_f16_sdwa v109, v55 dst_sel:DWORD dst_unused:UNUSED_PAD src0_sel:WORD_1
	v_ashrrev_i32_e32 v78, 31, v116
	v_bitop3_b32 v116, v116, v78, s40 bitop3:0x78
	v_xor_b32_e32 v116, 0x80000011, v116
	v_ashrrev_i32_e32 v78, 31, v109
	v_bitop3_b32 v109, v109, v78, s40 bitop3:0x78
	v_xor_b32_e32 v109, 0x80000010, v109
	v_max_u32_e32 v78, v92, v114
	v_min_u32_e32 v114, v92, v114
	v_max_u32_e32 v92, v75, v98
	v_min_u32_e32 v98, v75, v98
	v_max_u32_e32 v75, v108, v109
	v_min_u32_e32 v109, v108, v109
	v_max_u32_e32 v108, v115, v116
	v_min_u32_e32 v116, v115, v116
	v_max_u32_e32 v115, v119, v112
	v_min_u32_e32 v112, v119, v112
	v_max_u32_e32 v119, v102, v107
	v_min_u32_e32 v107, v102, v107
	v_max_u32_e32 v102, v106, v72
	v_min_u32_e32 v72, v106, v72
	v_max_u32_e32 v106, v105, v103
	v_min_u32_e32 v103, v105, v103
	v_max_u32_e32 v105, v78, v119
	v_min_u32_e32 v119, v78, v119
	v_max_u32_e32 v78, v92, v102
	v_min_u32_e32 v102, v92, v102
	v_max_u32_e32 v92, v75, v106
	v_min_u32_e32 v106, v75, v106
	v_max_u32_e32 v75, v108, v115
	v_min_u32_e32 v115, v108, v115
	v_max_u32_e32 v108, v107, v114
	v_min_u32_e32 v114, v107, v114
	v_max_u32_e32 v107, v112, v116
	v_min_u32_e32 v116, v112, v116
	v_max_u32_e32 v112, v103, v109
	v_min_u32_e32 v109, v103, v109
	v_max_u32_e32 v103, v72, v98
	v_min_u32_e32 v98, v72, v98
	v_max_u32_e32 v72, v105, v78
	v_min_u32_e32 v78, v105, v78
	v_max_u32_e32 v105, v92, v75
	v_min_u32_e32 v75, v92, v75
	v_max_u32_e32 v92, v115, v119
	v_min_u32_e32 v119, v115, v119
	v_max_u32_e32 v115, v108, v107
	v_min_u32_e32 v107, v108, v107
	v_max_u32_e32 v108, v102, v106
	v_min_u32_e32 v106, v102, v106
	v_max_u32_e32 v102, v112, v103
	v_min_u32_e32 v103, v112, v103
	v_max_u32_e32 v112, v98, v114
	v_min_u32_e32 v114, v98, v114
	v_max_u32_e32 v98, v116, v109
	v_min_u32_e32 v109, v116, v109
	v_max_u32_e32 v116, v72, v105
	v_min_u32_e32 v105, v72, v105
	v_max_u32_e32 v72, v78, v75
	v_min_u32_e32 v75, v78, v75
	v_max_u32_e32 v78, v92, v102
	v_min_u32_e32 v102, v92, v102
	v_max_u32_e32 v92, v119, v103
	v_min_u32_e32 v103, v119, v103
	v_max_u32_e32 v119, v115, v108
	v_min_u32_e32 v108, v115, v108
	v_max_u32_e32 v115, v107, v106
	v_min_u32_e32 v106, v107, v106
	v_max_u32_e32 v107, v112, v98
; __device__ __forceinline__ unsigned f2key(float f) { const unsigned u = __float_as_uint(f); return (u & 0x80000000u) ? ~u : (u | 0x80000000u); }
; __device__ __forceinline__ void peer_tile(const Args& A, LAS unsigned char* lds, int tile) {
;     ...
;                   for (int i = 0; i < 16; ++i) {
;                       const float lo = (float)__builtin_bit_cast(_Float16, (unsigned short)(sw[i] & 0xffffu)), hi = (float)__builtin_bit_cast(_Float16, (unsigned short)(sw[i] >> 16));
;                       const unsigned klo = (f2key(lo) & ~127u) | (unsigned)(127 - (32 * g + 2 * i)), khi = (f2key(hi) & ~127u) | (unsigned)(127 - (32 * g + 2 * i + 1));
;                       if (i < 8) { k0[2 * i] = klo; k0[2 * i + 1] = khi; } else { k1[2 * (i - 8)] = klo; k1[2 * (i - 8) + 1] = khi; } } }
;                 sort16_desc(k0); sort16_desc(k1); merge16(k0, k1);
; #pragma unroll
;                 for (int msk = 16; msk <= 32; msk <<= 1) {
; #pragma unroll
;                     for (int i = 0; i < 16; ++i) k1[i] = (unsigned)__shfl_xor((int)k0[i], msk);
;                     merge16(k0, k1); }
	v_min_u32_e32 v98, v112, v98
	v_max_u32_e32 v112, v114, v109
	v_min_u32_e32 v109, v114, v109
	v_max_u32_e32 v114, v72, v105
	v_min_u32_e32 v105, v72, v105
	v_max_u32_e32 v72, v75, v107
	v_min_u32_e32 v107, v75, v107
	v_max_u32_e32 v75, v78, v119
	v_min_u32_e32 v119, v78, v119
	v_max_u32_e32 v78, v92, v108
	v_min_u32_e32 v108, v92, v108
	v_max_u32_e32 v92, v115, v102
	v_min_u32_e32 v102, v115, v102
	v_max_u32_e32 v115, v106, v103
	v_min_u32_e32 v103, v106, v103
	v_max_u32_e32 v106, v112, v98
	v_min_u32_e32 v98, v112, v98
	v_max_u32_e32 v112, v114, v75
	v_min_u32_e32 v75, v114, v75
	v_max_u32_e32 v114, v105, v119
	v_min_u32_e32 v119, v105, v119
	v_max_u32_e32 v105, v78, v92
	v_min_u32_e32 v92, v78, v92
	v_max_u32_e32 v78, v108, v102
	v_min_u32_e32 v102, v108, v102
	v_max_u32_e32 v108, v115, v106
	v_min_u32_e32 v106, v115, v106
	v_max_u32_e32 v115, v103, v98
	v_min_u32_e32 v98, v103, v98
	v_max_u32_e32 v103, v114, v75
	v_min_u32_e32 v75, v114, v75
	v_max_u32_e32 v114, v72, v119
	v_min_u32_e32 v119, v72, v119
	v_max_u32_e32 v72, v108, v107
	v_min_u32_e32 v107, v108, v107
	v_max_u32_e32 v108, v115, v106
	v_min_u32_e32 v106, v115, v106
	v_max_u32_e32 v115, v114, v105
	v_min_u32_e32 v105, v114, v105
	v_max_u32_e32 v114, v119, v92
	v_min_u32_e32 v92, v119, v92
	v_max_u32_e32 v119, v78, v72
	v_min_u32_e32 v72, v78, v72
	v_max_u32_e32 v78, v102, v107
	v_min_u32_e32 v107, v102, v107
	v_max_u32_e32 v102, v115, v75
	v_min_u32_e32 v75, v115, v75
	v_max_u32_e32 v115, v105, v114
	v_min_u32_e32 v114, v105, v114
	v_max_u32_e32 v105, v119, v92
	v_min_u32_e32 v92, v119, v92
	v_max_u32_e32 v119, v72, v78
	v_min_u32_e32 v78, v72, v78
	v_max_u32_e32 v72, v108, v107
	v_min_u32_e32 v107, v108, v107
	v_max_u32_e32 v108, v114, v105
	v_min_u32_e32 v105, v114, v105
	v_max_u32_e32 v114, v92, v119
	v_min_u32_e32 v119, v92, v119
	v_max_u32_e32 v83, v83, v109
	v_max_u32_e32 v110, v110, v98
	v_max_u32_e32 v87, v87, v106
	v_max_u32_e32 v117, v117, v107
	v_max_u32_e32 v91, v91, v72
	v_max_u32_e32 v118, v118, v78
	v_max_u32_e32 v104, v104, v119
	v_max_u32_e32 v111, v111, v114
	v_max_u32_e32 v97, v97, v105
	v_max_u32_e32 v89, v89, v108
	v_max_u32_e32 v82, v82, v115
	v_max_u32_e32 v70, v70, v75
	v_max_u32_e32 v73, v73, v102
	v_max_u32_e32 v79, v79, v103
	v_max_u32_e32 v90, v90, v112
	v_max_u32_e32 v96, v96, v116
	v_max_u32_e32 v109, v83, v97
	v_min_u32_e32 v97, v83, v97
	v_max_u32_e32 v83, v110, v89
	v_min_u32_e32 v89, v110, v89
	v_max_u32_e32 v110, v87, v82
	v_min_u32_e32 v82, v87, v82
	v_max_u32_e32 v87, v117, v70
	v_min_u32_e32 v70, v117, v70
	v_max_u32_e32 v117, v91, v73
	v_min_u32_e32 v73, v91, v73
	v_max_u32_e32 v91, v118, v79
	v_min_u32_e32 v79, v118, v79
	v_max_u32_e32 v118, v104, v90
	v_min_u32_e32 v90, v104, v90
	v_max_u32_e32 v104, v111, v96
	v_min_u32_e32 v96, v111, v96
	v_max_u32_e32 v111, v109, v117
	v_min_u32_e32 v117, v109, v117
	v_max_u32_e32 v109, v83, v91
	v_min_u32_e32 v91, v83, v91
	v_max_u32_e32 v83, v110, v118
	v_min_u32_e32 v118, v110, v118
	v_max_u32_e32 v110, v87, v104
	v_min_u32_e32 v104, v87, v104
	v_max_u32_e32 v87, v97, v73
	v_min_u32_e32 v73, v97, v73
	v_max_u32_e32 v97, v89, v79
	v_min_u32_e32 v79, v89, v79
	v_max_u32_e32 v89, v82, v90
	v_min_u32_e32 v90, v82, v90
	v_max_u32_e32 v82, v70, v96
	v_min_u32_e32 v96, v70, v96
	v_max_u32_e32 v70, v111, v83
	v_min_u32_e32 v83, v111, v83
	v_max_u32_e32 v111, v109, v110
	v_min_u32_e32 v110, v109, v110
	v_max_u32_e32 v109, v117, v118
	v_min_u32_e32 v118, v117, v118
	v_max_u32_e32 v117, v91, v104
	v_min_u32_e32 v104, v91, v104
	v_max_u32_e32 v91, v87, v89
	v_min_u32_e32 v89, v87, v89
	v_max_u32_e32 v87, v97, v82
	v_min_u32_e32 v82, v97, v82
	v_max_u32_e32 v97, v73, v90
	v_min_u32_e32 v90, v73, v90
	v_max_u32_e32 v73, v79, v96
	v_min_u32_e32 v96, v79, v96
	v_max_u32_e32 v79, v70, v111
	v_min_u32_e32 v111, v70, v111
	v_max_u32_e32 v70, v83, v110
	v_min_u32_e32 v110, v83, v110
	v_max_u32_e32 v83, v109, v117
	v_min_u32_e32 v117, v109, v117
	v_max_u32_e32 v109, v118, v104
	v_min_u32_e32 v104, v118, v104
	v_max_u32_e32 v118, v91, v87
	v_min_u32_e32 v87, v91, v87
	v_max_u32_e32 v91, v89, v82
	v_min_u32_e32 v82, v89, v82
	v_max_u32_e32 v89, v97, v73
	v_min_u32_e32 v73, v97, v73
	v_max_u32_e32 v97, v90, v96
	v_min_u32_e32 v96, v90, v96
	v_cvt_f32_f16_e32 v90, v56
	v_cvt_f32_f16_sdwa v98, v56 dst_sel:DWORD dst_unused:UNUSED_PAD src0_sel:WORD_1
	v_ashrrev_i32_e32 v106, 31, v90
	v_bitop3_b32 v90, v90, v106, s40 bitop3:0x78
	v_xor_b32_e32 v90, 0x8000000f, v90
	v_ashrrev_i32_e32 v106, 31, v98
	v_bitop3_b32 v98, v98, v106, s40 bitop3:0x78
	v_xor_b32_e32 v98, 0x8000000e, v98
	v_cvt_f32_f16_e32 v106, v57
	v_cvt_f32_f16_sdwa v107, v57 dst_sel:DWORD dst_unused:UNUSED_PAD src0_sel:WORD_1
	v_ashrrev_i32_e32 v72, 31, v106
	v_bitop3_b32 v106, v106, v72, s40 bitop3:0x78
	v_xor_b32_e32 v106, 0x8000000d, v106
	v_ashrrev_i32_e32 v72, 31, v107
	v_bitop3_b32 v107, v107, v72, s40 bitop3:0x78
	v_xor_b32_e32 v107, 0x8000000c, v107
	v_cvt_f32_f16_e32 v72, v58
	v_cvt_f32_f16_sdwa v78, v58 dst_sel:DWORD dst_unused:UNUSED_PAD src0_sel:WORD_1
	v_ashrrev_i32_e32 v119, 31, v72
	v_bitop3_b32 v72, v72, v119, s40 bitop3:0x78
	v_xor_b32_e32 v72, 0x8000000b, v72
	v_ashrrev_i32_e32 v119, 31, v78
	v_bitop3_b32 v78, v78, v119, s40 bitop3:0x78
	v_xor_b32_e32 v78, 0x8000000a, v78
	v_cvt_f32_f16_e32 v119, v59
	v_cvt_f32_f16_sdwa v114, v59 dst_sel:DWORD dst_unused:UNUSED_PAD src0_sel:WORD_1
	v_ashrrev_i32_e32 v105, 31, v119
	v_bitop3_b32 v119, v119, v105, s40 bitop3:0x78
	v_xor_b32_e32 v119, 0x80000009, v119
	v_ashrrev_i32_e32 v105, 31, v114
	v_bitop3_b32 v114, v114, v105, s40 bitop3:0x78
	v_xor_b32_e32 v114, 0x80000008, v114
	v_cvt_f32_f16_e32 v105, v60
; __device__ __forceinline__ unsigned f2key(float f) { const unsigned u = __float_as_uint(f); return (u & 0x80000000u) ? ~u : (u | 0x80000000u); }
; __device__ __forceinline__ void peer_tile(const Args& A, LAS unsigned char* lds, int tile) {
;     ...
;                   for (int i = 0; i < 16; ++i) {
;                       const float lo = (float)__builtin_bit_cast(_Float16, (unsigned short)(sw[i] & 0xffffu)), hi = (float)__builtin_bit_cast(_Float16, (unsigned short)(sw[i] >> 16));
;                       const unsigned klo = (f2key(lo) & ~127u) | (unsigned)(127 - (32 * g + 2 * i)), khi = (f2key(hi) & ~127u) | (unsigned)(127 - (32 * g + 2 * i + 1));
;                       if (i < 8) { k0[2 * i] = klo; k0[2 * i + 1] = khi; } else { k1[2 * (i - 8)] = klo; k1[2 * (i - 8) + 1] = khi; } } }
;                 sort16_desc(k0); sort16_desc(k1); merge16(k0, k1);
; #pragma unroll
;                 for (int msk = 16; msk <= 32; msk <<= 1) {
; #pragma unroll
;                     for (int i = 0; i < 16; ++i) k1[i] = (unsigned)__shfl_xor((int)k0[i], msk);
;                     merge16(k0, k1); }
	v_cvt_f32_f16_sdwa v108, v60 dst_sel:DWORD dst_unused:UNUSED_PAD src0_sel:WORD_1
	v_ashrrev_i32_e32 v115, 31, v105
	v_bitop3_b32 v105, v105, v115, s40 bitop3:0x78
	v_xor_b32_e32 v105, 0x80000007, v105
	v_ashrrev_i32_e32 v115, 31, v108
	v_bitop3_b32 v108, v108, v115, s40 bitop3:0x78
	v_xor_b32_e32 v108, 0x80000006, v108
	v_cvt_f32_f16_e32 v115, v61
	v_cvt_f32_f16_sdwa v75, v61 dst_sel:DWORD dst_unused:UNUSED_PAD src0_sel:WORD_1
	v_ashrrev_i32_e32 v102, 31, v115
	v_bitop3_b32 v115, v115, v102, s40 bitop3:0x78
	v_xor_b32_e32 v115, 0x80000005, v115
	v_ashrrev_i32_e32 v102, 31, v75
	v_bitop3_b32 v75, v75, v102, s40 bitop3:0x78
	v_xor_b32_e32 v75, 0x80000004, v75
	v_cvt_f32_f16_e32 v102, v62
	v_cvt_f32_f16_sdwa v103, v62 dst_sel:DWORD dst_unused:UNUSED_PAD src0_sel:WORD_1
	v_ashrrev_i32_e32 v112, 31, v102
	v_bitop3_b32 v102, v102, v112, s40 bitop3:0x78
	v_xor_b32_e32 v102, 0x80000003, v102
	v_ashrrev_i32_e32 v112, 31, v103
	v_bitop3_b32 v103, v103, v112, s40 bitop3:0x78
	v_xor_b32_e32 v103, 0x80000002, v103
	v_cvt_f32_f16_e32 v112, v63
	v_cvt_f32_f16_sdwa v116, v63 dst_sel:DWORD dst_unused:UNUSED_PAD src0_sel:WORD_1
	v_ashrrev_i32_e32 v92, 31, v112
	v_bitop3_b32 v112, v112, v92, s40 bitop3:0x78
	v_xor_b32_e32 v112, 0x80000001, v112
	v_ashrrev_i32_e32 v92, 31, v116
	v_bitop3_b32 v116, v116, v92, s40 bitop3:0x78
	v_xor_b32_e32 v116, 0x80000000, v116
	v_max_u32_e32 v92, v90, v103
	v_min_u32_e32 v103, v90, v103
	v_max_u32_e32 v90, v98, v102
	v_min_u32_e32 v102, v98, v102
	v_max_u32_e32 v98, v106, v116
	v_min_u32_e32 v116, v106, v116
	v_max_u32_e32 v106, v107, v112
	v_min_u32_e32 v112, v107, v112
	v_max_u32_e32 v107, v72, v105
	v_min_u32_e32 v105, v72, v105
	v_max_u32_e32 v72, v78, v119
	v_min_u32_e32 v119, v78, v119
	v_max_u32_e32 v78, v114, v75
	v_min_u32_e32 v75, v114, v75
	v_max_u32_e32 v114, v108, v115
	v_min_u32_e32 v115, v108, v115
	v_max_u32_e32 v108, v92, v72
	v_min_u32_e32 v72, v92, v72
	v_max_u32_e32 v92, v90, v78
	v_min_u32_e32 v78, v90, v78
	v_max_u32_e32 v90, v98, v114
	v_min_u32_e32 v114, v98, v114
	v_max_u32_e32 v98, v106, v107
	v_min_u32_e32 v107, v106, v107
	v_max_u32_e32 v106, v119, v103
	v_min_u32_e32 v103, v119, v103
	v_max_u32_e32 v119, v105, v112
	v_min_u32_e32 v112, v105, v112
	v_max_u32_e32 v105, v115, v116
	v_min_u32_e32 v116, v115, v116
	v_max_u32_e32 v115, v75, v102
	v_min_u32_e32 v102, v75, v102
	v_max_u32_e32 v75, v108, v92
	v_min_u32_e32 v92, v108, v92
	v_max_u32_e32 v108, v90, v98
	v_min_u32_e32 v98, v90, v98
	v_max_u32_e32 v90, v107, v72
	v_min_u32_e32 v72, v107, v72
	v_max_u32_e32 v107, v106, v119
	v_min_u32_e32 v119, v106, v119
	v_max_u32_e32 v106, v78, v114
	v_min_u32_e32 v114, v78, v114
	v_max_u32_e32 v78, v105, v115
	v_min_u32_e32 v115, v105, v115
	v_max_u32_e32 v105, v102, v103
	v_min_u32_e32 v103, v102, v103
	v_max_u32_e32 v102, v112, v116
	v_min_u32_e32 v116, v112, v116
	v_max_u32_e32 v112, v75, v108
	v_min_u32_e32 v108, v75, v108
	v_max_u32_e32 v75, v92, v98
	v_min_u32_e32 v98, v92, v98
	v_max_u32_e32 v92, v90, v78
	v_min_u32_e32 v78, v90, v78
	v_max_u32_e32 v90, v72, v115
	v_min_u32_e32 v115, v72, v115
	v_max_u32_e32 v72, v107, v106
	v_min_u32_e32 v106, v107, v106
	v_max_u32_e32 v107, v119, v114
	v_min_u32_e32 v114, v119, v114
	v_max_u32_e32 v119, v105, v102
	v_min_u32_e32 v102, v105, v102
	v_max_u32_e32 v105, v103, v116
	v_min_u32_e32 v116, v103, v116
	v_max_u32_e32 v103, v75, v108
	v_min_u32_e32 v108, v75, v108
	v_max_u32_e32 v75, v98, v119
	v_min_u32_e32 v119, v98, v119
	v_max_u32_e32 v98, v92, v72
	v_min_u32_e32 v72, v92, v72
	v_max_u32_e32 v92, v90, v106
	v_min_u32_e32 v106, v90, v106
	v_max_u32_e32 v90, v107, v78
	v_min_u32_e32 v78, v107, v78
	v_max_u32_e32 v107, v114, v115
	v_min_u32_e32 v115, v114, v115
	v_max_u32_e32 v114, v105, v102
	v_min_u32_e32 v102, v105, v102
	v_max_u32_e32 v105, v103, v98
	v_min_u32_e32 v98, v103, v98
	v_max_u32_e32 v103, v108, v72
	v_min_u32_e32 v72, v108, v72
	v_max_u32_e32 v108, v92, v90
	v_min_u32_e32 v90, v92, v90
	v_max_u32_e32 v92, v106, v78
	v_min_u32_e32 v78, v106, v78
	v_max_u32_e32 v106, v107, v114
	v_min_u32_e32 v114, v107, v114
	v_max_u32_e32 v107, v115, v102
	v_min_u32_e32 v102, v115, v102
	v_max_u32_e32 v115, v103, v98
	v_min_u32_e32 v98, v103, v98
	v_max_u32_e32 v103, v75, v72
	v_min_u32_e32 v72, v75, v72
	v_max_u32_e32 v75, v106, v119
	v_min_u32_e32 v119, v106, v119
	v_max_u32_e32 v106, v107, v114
	v_min_u32_e32 v114, v107, v114
	v_max_u32_e32 v107, v103, v108
	v_min_u32_e32 v108, v103, v108
	v_max_u32_e32 v103, v72, v90
	v_min_u32_e32 v90, v72, v90
	v_max_u32_e32 v72, v92, v75
	v_min_u32_e32 v75, v92, v75
	v_max_u32_e32 v92, v78, v119
	v_min_u32_e32 v119, v78, v119
	v_max_u32_e32 v78, v107, v98
	v_min_u32_e32 v98, v107, v98
	v_max_u32_e32 v107, v108, v103
	v_min_u32_e32 v103, v108, v103
	v_max_u32_e32 v108, v72, v90
	v_min_u32_e32 v90, v72, v90
	v_max_u32_e32 v72, v75, v92
	v_min_u32_e32 v92, v75, v92
	v_max_u32_e32 v75, v106, v119
	v_min_u32_e32 v119, v106, v119
	v_max_u32_e32 v106, v103, v108
	v_min_u32_e32 v108, v103, v108
	v_max_u32_e32 v103, v90, v72
	v_min_u32_e32 v72, v90, v72
	v_max_u32_e32 v79, v79, v116
	v_max_u32_e32 v111, v111, v102
	v_max_u32_e32 v70, v70, v114
	v_max_u32_e32 v110, v110, v119
	v_max_u32_e32 v83, v83, v75
	v_max_u32_e32 v117, v117, v92
	v_max_u32_e32 v109, v109, v72
	v_max_u32_e32 v104, v104, v103
	v_max_u32_e32 v118, v118, v108
	v_max_u32_e32 v87, v87, v106
	v_max_u32_e32 v91, v91, v107
	v_max_u32_e32 v82, v82, v98
	v_max_u32_e32 v89, v89, v78
	v_max_u32_e32 v73, v73, v115
	v_max_u32_e32 v97, v97, v105
	v_max_u32_e32 v96, v96, v112
	v_max_u32_e32 v116, v79, v118
	v_min_u32_e32 v118, v79, v118
	v_max_u32_e32 v79, v111, v87
; __device__ __forceinline__ float key2f(unsigned k) { const unsigned u = (k & 0x80000000u) ? (k & 0x7fffffffu) : ~k; return __uint_as_float(u); }
; __device__ __forceinline__ void peer_tile(const Args& A, LAS unsigned char* lds, int tile) {
;     ...
;                 sort16_desc(k0); sort16_desc(k1); merge16(k0, k1);
; #pragma unroll
;                 for (int msk = 16; msk <= 32; msk <<= 1) {
; #pragma unroll
;                     for (int i = 0; i < 16; ++i) k1[i] = (unsigned)__shfl_xor((int)k0[i], msk);
;                     merge16(k0, k1); }
; #pragma unroll
;                 for (int i = 0; i < 16; ++i) LA[hh][p][i] = k0[i];
;             }
;         }
;         {
;             const int h = 4 * hg + g;
;             unsigned L2[2][16];
; #pragma unroll
;             for (int p = 0; p < 2; ++p)
; #pragma unroll
;                 for (int i = 0; i < 16; ++i) L2[p][i] = (g & 2) ? ((g & 1) ? LA[3][p][i] : LA[2][p][i]) : ((g & 1) ? LA[1][p][i] : LA[0][p][i]);
;             float va[16], vb[16];
; #pragma unroll
;             for (int i = 0; i < 16; ++i) { va[i] = key2f(L2[0][i] & ~127u); vb[i] = key2f(L2[1][i] & ~127u); idx[i] = 127u - (L2[0][i] & 127u); idx[16 + i] = 127u - (L2[1][i] & 127u); }
	v_min_u32_e32 v87, v111, v87
	v_max_u32_e32 v111, v70, v91
	v_min_u32_e32 v91, v70, v91
	v_max_u32_e32 v70, v110, v82
	v_min_u32_e32 v82, v110, v82
	v_max_u32_e32 v110, v83, v89
	v_min_u32_e32 v89, v83, v89
	v_max_u32_e32 v83, v117, v73
	v_min_u32_e32 v73, v117, v73
	v_max_u32_e32 v117, v109, v97
	v_min_u32_e32 v97, v109, v97
	v_max_u32_e32 v109, v104, v96
	v_min_u32_e32 v96, v104, v96
	v_max_u32_e32 v104, v116, v110
	v_min_u32_e32 v110, v116, v110
	v_max_u32_e32 v116, v79, v83
	v_min_u32_e32 v83, v79, v83
	v_max_u32_e32 v79, v111, v117
	v_min_u32_e32 v117, v111, v117
	v_max_u32_e32 v111, v70, v109
	v_min_u32_e32 v109, v70, v109
	v_max_u32_e32 v70, v118, v89
	v_min_u32_e32 v89, v118, v89
	v_max_u32_e32 v118, v87, v73
	v_min_u32_e32 v73, v87, v73
	v_max_u32_e32 v87, v91, v97
	v_min_u32_e32 v97, v91, v97
	v_max_u32_e32 v91, v82, v96
	v_min_u32_e32 v96, v82, v96
	v_max_u32_e32 v82, v104, v79
	v_min_u32_e32 v79, v104, v79
	v_max_u32_e32 v104, v116, v111
	v_min_u32_e32 v111, v116, v111
	v_max_u32_e32 v116, v110, v117
	v_min_u32_e32 v117, v110, v117
	v_max_u32_e32 v110, v83, v109
	v_min_u32_e32 v109, v83, v109
	v_max_u32_e32 v83, v70, v87
	v_min_u32_e32 v87, v70, v87
	v_max_u32_e32 v70, v118, v91
	v_min_u32_e32 v91, v118, v91
	v_max_u32_e32 v118, v89, v97
	v_min_u32_e32 v97, v89, v97
	v_max_u32_e32 v89, v73, v96
	v_min_u32_e32 v96, v73, v96
	v_max_u32_e32 v73, v82, v104
	v_min_u32_e32 v104, v82, v104
	v_max_u32_e32 v82, v79, v111
	v_min_u32_e32 v111, v79, v111
	v_max_u32_e32 v79, v116, v110
	v_min_u32_e32 v110, v116, v110
	v_max_u32_e32 v116, v117, v109
	v_min_u32_e32 v109, v117, v109
	v_max_u32_e32 v117, v83, v70
	v_min_u32_e32 v70, v83, v70
	v_max_u32_e32 v83, v87, v91
	v_min_u32_e32 v91, v87, v91
	v_max_u32_e32 v87, v118, v89
	v_min_u32_e32 v89, v118, v89
	v_max_u32_e32 v118, v97, v96
	v_min_u32_e32 v96, v97, v96
	v_xor_b32_e32 v97, 0x7f, v71
	v_xor_b32_e32 v102, 0x7f, v88
	v_and_b32_e32 v97, 0x7f, v97
	v_and_b32_e32 v102, 0x7f, v102
	ds_write2_b32 v67, v97, v102 offset0:0 offset1:1
	v_xor_b32_e32 v102, 0x7f, v74
	v_xor_b32_e32 v97, 0x7f, v95
	v_and_b32_e32 v102, 0x7f, v102
	v_and_b32_e32 v97, 0x7f, v97
	ds_write2_b32 v67, v102, v97 offset0:2 offset1:3
	v_xor_b32_e32 v97, 0x7f, v86
	v_xor_b32_e32 v102, 0x7f, v94
	v_and_b32_e32 v97, 0x7f, v97
	v_and_b32_e32 v102, 0x7f, v102
	ds_write2_b32 v67, v97, v102 offset0:4 offset1:5
	v_xor_b32_e32 v102, 0x7f, v99
	v_xor_b32_e32 v97, 0x7f, v93
	v_and_b32_e32 v102, 0x7f, v102
	v_and_b32_e32 v97, 0x7f, v97
	ds_write2_b32 v67, v102, v97 offset0:6 offset1:7
	v_xor_b32_e32 v97, 0x7f, v100
	v_xor_b32_e32 v102, 0x7f, v76
	v_and_b32_e32 v97, 0x7f, v97
	v_and_b32_e32 v102, 0x7f, v102
	ds_write2_b32 v67, v97, v102 offset0:8 offset1:9
	v_xor_b32_e32 v102, 0x7f, v81
	v_xor_b32_e32 v97, 0x7f, v80
	v_and_b32_e32 v102, 0x7f, v102
	v_and_b32_e32 v97, 0x7f, v97
	ds_write2_b32 v67, v102, v97 offset0:10 offset1:11
	v_xor_b32_e32 v97, 0x7f, v77
	v_xor_b32_e32 v102, 0x7f, v84
	v_and_b32_e32 v97, 0x7f, v97
	v_and_b32_e32 v102, 0x7f, v102
	ds_write2_b32 v67, v97, v102 offset0:12 offset1:13
	v_xor_b32_e32 v102, 0x7f, v101
	v_xor_b32_e32 v97, 0x7f, v85
	v_and_b32_e32 v102, 0x7f, v102
	v_and_b32_e32 v97, 0x7f, v97
	ds_write2_b32 v67, v102, v97 offset0:14 offset1:15
	v_xor_b32_e32 v97, 0x7f, v73
	v_xor_b32_e32 v102, 0x7f, v104
	v_and_b32_e32 v97, 0x7f, v97
	v_and_b32_e32 v102, 0x7f, v102
	ds_write2_b32 v67, v97, v102 offset0:16 offset1:17
	v_xor_b32_e32 v102, 0x7f, v82
	v_xor_b32_e32 v97, 0x7f, v111
	v_and_b32_e32 v102, 0x7f, v102
	v_and_b32_e32 v97, 0x7f, v97
	ds_write2_b32 v67, v102, v97 offset0:18 offset1:19
	v_xor_b32_e32 v97, 0x7f, v79
	v_xor_b32_e32 v102, 0x7f, v110
	v_and_b32_e32 v97, 0x7f, v97
	v_and_b32_e32 v102, 0x7f, v102
	ds_write2_b32 v67, v97, v102 offset0:20 offset1:21
	v_xor_b32_e32 v102, 0x7f, v116
	v_xor_b32_e32 v97, 0x7f, v109
	v_and_b32_e32 v102, 0x7f, v102
	v_and_b32_e32 v97, 0x7f, v97
	ds_write2_b32 v67, v102, v97 offset0:22 offset1:23
	v_xor_b32_e32 v97, 0x7f, v117
	v_xor_b32_e32 v102, 0x7f, v70
	v_and_b32_e32 v97, 0x7f, v97
	v_and_b32_e32 v102, 0x7f, v102
	ds_write2_b32 v67, v97, v102 offset0:24 offset1:25
	v_xor_b32_e32 v102, 0x7f, v83
	v_xor_b32_e32 v97, 0x7f, v91
	v_and_b32_e32 v102, 0x7f, v102
	v_and_b32_e32 v97, 0x7f, v97
	ds_write2_b32 v67, v102, v97 offset0:26 offset1:27
	v_xor_b32_e32 v97, 0x7f, v87
	v_xor_b32_e32 v102, 0x7f, v89
	v_and_b32_e32 v97, 0x7f, v97
	v_and_b32_e32 v102, 0x7f, v102
	ds_write2_b32 v67, v97, v102 offset0:28 offset1:29
	v_xor_b32_e32 v102, 0x7f, v118
	v_xor_b32_e32 v97, 0x7f, v96
	v_and_b32_e32 v102, 0x7f, v102
	v_and_b32_e32 v97, 0x7f, v97
	ds_write2_b32 v67, v102, v97 offset0:30 offset1:31
	v_ashrrev_i32_e32 v102, 31, v71
	v_and_b32_e32 v97, 0xffffff80, v71
	v_bitop3_b32 v97, v97, v102, s41 bitop3:0x87
	v_ashrrev_i32_e32 v114, 31, v88
	v_and_b32_e32 v102, 0xffffff80, v88
	v_bitop3_b32 v102, v102, v114, s41 bitop3:0x87
	v_ashrrev_i32_e32 v119, 31, v74
	v_and_b32_e32 v114, 0xffffff80, v74
	v_bitop3_b32 v114, v114, v119, s41 bitop3:0x87
	v_ashrrev_i32_e32 v75, 31, v95
	v_and_b32_e32 v119, 0xffffff80, v95
	v_bitop3_b32 v119, v119, v75, s41 bitop3:0x87
	v_ashrrev_i32_e32 v92, 31, v86
	v_and_b32_e32 v75, 0xffffff80, v86
	v_bitop3_b32 v75, v75, v92, s41 bitop3:0x87
	v_ashrrev_i32_e32 v72, 31, v94
	v_and_b32_e32 v92, 0xffffff80, v94
	v_bitop3_b32 v92, v92, v72, s41 bitop3:0x87
	v_ashrrev_i32_e32 v103, 31, v99
	v_and_b32_e32 v72, 0xffffff80, v99
	v_bitop3_b32 v72, v72, v103, s41 bitop3:0x87
	v_ashrrev_i32_e32 v108, 31, v93
	v_and_b32_e32 v103, 0xffffff80, v93
	v_bitop3_b32 v103, v103, v108, s41 bitop3:0x87
	v_ashrrev_i32_e32 v106, 31, v100
	v_and_b32_e32 v108, 0xffffff80, v100
; __device__ __forceinline__ float key2f(unsigned k) { const unsigned u = (k & 0x80000000u) ? (k & 0x7fffffffu) : ~k; return __uint_as_float(u); }
; #define CK(i, j) ((f2key(va[i] + vb[j]) & ~255u) | (unsigned)(255 - (16 * (i) + (j))))
; __device__ __forceinline__ void peer_tile(const Args& A, LAS unsigned char* lds, int tile) {
;     ...
;             for (int i = 0; i < 16; ++i) { va[i] = key2f(L2[0][i] & ~127u); vb[i] = key2f(L2[1][i] & ~127u); idx[i] = 127u - (L2[0][i] & 127u); idx[16 + i] = 127u - (L2[1][i] & 127u); }
;     ...
;             unsigned Lf[16], Bt[16];
; #pragma unroll
;             for (int j = 0; j < 16; ++j) Lf[j] = CK(0, j);
; #pragma unroll
;             for (int j = 0; j < 8; ++j) Bt[j] = CK(1, j);
	v_bitop3_b32 v108, v108, v106, s41 bitop3:0x87
	v_ashrrev_i32_e32 v107, 31, v76
	v_and_b32_e32 v106, 0xffffff80, v76
	v_bitop3_b32 v106, v106, v107, s41 bitop3:0x87
	v_ashrrev_i32_e32 v98, 31, v81
	v_and_b32_e32 v107, 0xffffff80, v81
	v_bitop3_b32 v107, v107, v98, s41 bitop3:0x87
	v_ashrrev_i32_e32 v78, 31, v80
	v_and_b32_e32 v98, 0xffffff80, v80
	v_bitop3_b32 v98, v98, v78, s41 bitop3:0x87
	v_ashrrev_i32_e32 v115, 31, v77
	v_and_b32_e32 v78, 0xffffff80, v77
	v_bitop3_b32 v78, v78, v115, s41 bitop3:0x87
	v_ashrrev_i32_e32 v105, 31, v84
	v_and_b32_e32 v115, 0xffffff80, v84
	v_bitop3_b32 v115, v115, v105, s41 bitop3:0x87
	v_ashrrev_i32_e32 v112, 31, v101
	v_and_b32_e32 v105, 0xffffff80, v101
	v_bitop3_b32 v105, v105, v112, s41 bitop3:0x87
	v_ashrrev_i32_e32 v90, 31, v85
	v_and_b32_e32 v112, 0xffffff80, v85
	v_bitop3_b32 v112, v112, v90, s41 bitop3:0x87
	v_ashrrev_i32_e32 v120, 31, v73
	v_and_b32_e32 v90, 0xffffff80, v73
	v_bitop3_b32 v90, v90, v120, s41 bitop3:0x87
	v_ashrrev_i32_e32 v121, 31, v104
	v_and_b32_e32 v120, 0xffffff80, v104
	v_bitop3_b32 v120, v120, v121, s41 bitop3:0x87
	v_ashrrev_i32_e32 v122, 31, v82
	v_and_b32_e32 v121, 0xffffff80, v82
	v_bitop3_b32 v121, v121, v122, s41 bitop3:0x87
	v_ashrrev_i32_e32 v123, 31, v111
	v_and_b32_e32 v122, 0xffffff80, v111
	v_bitop3_b32 v122, v122, v123, s41 bitop3:0x87
	v_ashrrev_i32_e32 v124, 31, v79
	v_and_b32_e32 v123, 0xffffff80, v79
	v_bitop3_b32 v123, v123, v124, s41 bitop3:0x87
	v_ashrrev_i32_e32 v125, 31, v110
	v_and_b32_e32 v124, 0xffffff80, v110
	v_bitop3_b32 v124, v124, v125, s41 bitop3:0x87
	v_ashrrev_i32_e32 v126, 31, v116
	v_and_b32_e32 v125, 0xffffff80, v116
	v_bitop3_b32 v125, v125, v126, s41 bitop3:0x87
	v_ashrrev_i32_e32 v127, 31, v109
	v_and_b32_e32 v126, 0xffffff80, v109
	v_bitop3_b32 v126, v126, v127, s41 bitop3:0x87
	v_ashrrev_i32_e32 v128, 31, v117
	v_and_b32_e32 v127, 0xffffff80, v117
	v_bitop3_b32 v127, v127, v128, s41 bitop3:0x87
	v_ashrrev_i32_e32 v129, 31, v70
	v_and_b32_e32 v128, 0xffffff80, v70
	v_bitop3_b32 v128, v128, v129, s41 bitop3:0x87
	v_ashrrev_i32_e32 v130, 31, v83
	v_and_b32_e32 v129, 0xffffff80, v83
	v_bitop3_b32 v129, v129, v130, s41 bitop3:0x87
	v_ashrrev_i32_e32 v131, 31, v91
	v_and_b32_e32 v130, 0xffffff80, v91
	v_bitop3_b32 v130, v130, v131, s41 bitop3:0x87
	v_ashrrev_i32_e32 v132, 31, v87
	v_and_b32_e32 v131, 0xffffff80, v87
	v_bitop3_b32 v131, v131, v132, s41 bitop3:0x87
	v_ashrrev_i32_e32 v133, 31, v89
	v_and_b32_e32 v132, 0xffffff80, v89
	v_bitop3_b32 v132, v132, v133, s41 bitop3:0x87
	v_ashrrev_i32_e32 v134, 31, v118
	v_and_b32_e32 v133, 0xffffff80, v118
	v_bitop3_b32 v133, v133, v134, s41 bitop3:0x87
	v_ashrrev_i32_e32 v135, 31, v96
	v_and_b32_e32 v134, 0xffffff80, v96
	v_bitop3_b32 v134, v134, v135, s41 bitop3:0x87
	v_add_f32_e32 v96, v97, v90
	v_ashrrev_i32_e32 v118, 31, v96
	v_and_b32_e32 v96, 0xffffff00, v96
	v_lshl_or_b32 v118, v118, 8, s33
	v_xor_b32_e32 v96, v96, v118
	v_xor_b32_e32 v96, 0xff, v96
	v_add_f32_e32 v118, v97, v120
	v_ashrrev_i32_e32 v89, 31, v118
	v_and_b32_e32 v118, 0xffffff00, v118
	v_lshl_or_b32 v89, v89, 8, s33
	v_xor_b32_e32 v118, v118, v89
	v_xor_b32_e32 v118, 0xfe, v118
	v_add_f32_e32 v89, v97, v121
	v_ashrrev_i32_e32 v87, 31, v89
	v_and_b32_e32 v89, 0xffffff00, v89
	v_lshl_or_b32 v87, v87, 8, s33
	v_xor_b32_e32 v89, v89, v87
	v_xor_b32_e32 v89, 0xfd, v89
	v_add_f32_e32 v87, v97, v122
	v_ashrrev_i32_e32 v91, 31, v87
	v_and_b32_e32 v87, 0xffffff00, v87
	v_lshl_or_b32 v91, v91, 8, s33
	v_xor_b32_e32 v87, v87, v91
	v_xor_b32_e32 v87, 0xfc, v87
	v_add_f32_e32 v91, v97, v123
	v_ashrrev_i32_e32 v83, 31, v91
	v_and_b32_e32 v91, 0xffffff00, v91
	v_lshl_or_b32 v83, v83, 8, s33
	v_xor_b32_e32 v91, v91, v83
	v_xor_b32_e32 v91, 0xfb, v91
	v_add_f32_e32 v83, v97, v124
	v_ashrrev_i32_e32 v70, 31, v83
	v_and_b32_e32 v83, 0xffffff00, v83
	v_lshl_or_b32 v70, v70, 8, s33
	v_xor_b32_e32 v83, v83, v70
	v_xor_b32_e32 v83, 0xfa, v83
	v_add_f32_e32 v70, v97, v125
	v_ashrrev_i32_e32 v117, 31, v70
	v_and_b32_e32 v70, 0xffffff00, v70
	v_lshl_or_b32 v117, v117, 8, s33
	v_xor_b32_e32 v70, v70, v117
	v_xor_b32_e32 v70, 0xf9, v70
	v_add_f32_e32 v117, v97, v126
	v_ashrrev_i32_e32 v109, 31, v117
	v_and_b32_e32 v117, 0xffffff00, v117
	v_lshl_or_b32 v109, v109, 8, s33
	v_xor_b32_e32 v117, v117, v109
	v_xor_b32_e32 v117, 0xf8, v117
	v_add_f32_e32 v109, v97, v127
	v_ashrrev_i32_e32 v116, 31, v109
	v_and_b32_e32 v109, 0xffffff00, v109
	v_lshl_or_b32 v116, v116, 8, s33
	v_xor_b32_e32 v109, v109, v116
	v_xor_b32_e32 v109, 0xf7, v109
	v_add_f32_e32 v116, v97, v128
	v_ashrrev_i32_e32 v110, 31, v116
	v_and_b32_e32 v116, 0xffffff00, v116
	v_lshl_or_b32 v110, v110, 8, s33
	v_xor_b32_e32 v116, v116, v110
	v_xor_b32_e32 v116, 0xf6, v116
	v_add_f32_e32 v110, v97, v129
	v_ashrrev_i32_e32 v79, 31, v110
	v_and_b32_e32 v110, 0xffffff00, v110
	v_lshl_or_b32 v79, v79, 8, s33
	v_xor_b32_e32 v110, v110, v79
	v_xor_b32_e32 v110, 0xf5, v110
	v_add_f32_e32 v79, v97, v130
	v_ashrrev_i32_e32 v111, 31, v79
	v_and_b32_e32 v79, 0xffffff00, v79
	v_lshl_or_b32 v111, v111, 8, s33
	v_xor_b32_e32 v79, v79, v111
	v_xor_b32_e32 v79, 0xf4, v79
	v_add_f32_e32 v111, v97, v131
	v_ashrrev_i32_e32 v82, 31, v111
	v_and_b32_e32 v111, 0xffffff00, v111
	v_lshl_or_b32 v82, v82, 8, s33
	v_xor_b32_e32 v111, v111, v82
	v_xor_b32_e32 v111, 0xf3, v111
	v_add_f32_e32 v82, v97, v132
	v_ashrrev_i32_e32 v104, 31, v82
	v_and_b32_e32 v82, 0xffffff00, v82
	v_lshl_or_b32 v104, v104, 8, s33
	v_xor_b32_e32 v82, v82, v104
	v_xor_b32_e32 v82, 0xf2, v82
	v_add_f32_e32 v104, v97, v133
	v_ashrrev_i32_e32 v73, 31, v104
	v_and_b32_e32 v104, 0xffffff00, v104
	v_lshl_or_b32 v73, v73, 8, s33
	v_xor_b32_e32 v104, v104, v73
; #define CK(i, j) ((f2key(va[i] + vb[j]) & ~255u) | (unsigned)(255 - (16 * (i) + (j))))
; __device__ __forceinline__ void peer_tile(const Args& A, LAS unsigned char* lds, int tile) {
;     ...
;             unsigned Lf[16], Bt[16];
; #pragma unroll
;             for (int j = 0; j < 16; ++j) Lf[j] = CK(0, j);
; #pragma unroll
;             for (int j = 0; j < 8; ++j) Bt[j] = CK(1, j);
; #pragma unroll
;             for (int j = 0; j < 5; ++j) Bt[8 + j] = CK(2, j);
; #pragma unroll
;             for (int j = 0; j < 3; ++j) Bt[13 + j] = CK(4, j);
;             sort16_desc(Bt); merge16(Lf, Bt);
	v_xor_b32_e32 v104, 0xf1, v104
	v_add_f32_e32 v73, v97, v134
	v_ashrrev_i32_e32 v85, 31, v73
	v_and_b32_e32 v73, 0xffffff00, v73
	v_lshl_or_b32 v85, v85, 8, s33
	v_xor_b32_e32 v73, v73, v85
	v_xor_b32_e32 v73, 0xf0, v73
	v_add_f32_e32 v85, v102, v90
	v_ashrrev_i32_e32 v101, 31, v85
	v_and_b32_e32 v85, 0xffffff00, v85
	v_lshl_or_b32 v101, v101, 8, s33
	v_xor_b32_e32 v85, v85, v101
	v_xor_b32_e32 v85, 0xef, v85
	v_add_f32_e32 v101, v102, v120
	v_ashrrev_i32_e32 v84, 31, v101
	v_and_b32_e32 v101, 0xffffff00, v101
	v_lshl_or_b32 v84, v84, 8, s33
	v_xor_b32_e32 v101, v101, v84
	v_xor_b32_e32 v101, 0xee, v101
	v_add_f32_e32 v84, v102, v121
	v_ashrrev_i32_e32 v77, 31, v84
	v_and_b32_e32 v84, 0xffffff00, v84
	v_lshl_or_b32 v77, v77, 8, s33
	v_xor_b32_e32 v84, v84, v77
	v_xor_b32_e32 v84, 0xed, v84
	v_add_f32_e32 v77, v102, v122
	v_ashrrev_i32_e32 v80, 31, v77
	v_and_b32_e32 v77, 0xffffff00, v77
	v_lshl_or_b32 v80, v80, 8, s33
	v_xor_b32_e32 v77, v77, v80
	v_xor_b32_e32 v77, 0xec, v77
	v_add_f32_e32 v80, v102, v123
	v_ashrrev_i32_e32 v81, 31, v80
	v_and_b32_e32 v80, 0xffffff00, v80
	v_lshl_or_b32 v81, v81, 8, s33
	v_xor_b32_e32 v80, v80, v81
	v_xor_b32_e32 v80, 0xeb, v80
	v_add_f32_e32 v81, v102, v124
	v_ashrrev_i32_e32 v76, 31, v81
	v_and_b32_e32 v81, 0xffffff00, v81
	v_lshl_or_b32 v76, v76, 8, s33
	v_xor_b32_e32 v81, v81, v76
	v_xor_b32_e32 v81, 0xea, v81
	v_add_f32_e32 v76, v102, v125
	v_ashrrev_i32_e32 v100, 31, v76
	v_and_b32_e32 v76, 0xffffff00, v76
	v_lshl_or_b32 v100, v100, 8, s33
	v_xor_b32_e32 v76, v76, v100
	v_xor_b32_e32 v76, 0xe9, v76
	v_add_f32_e32 v100, v102, v126
	v_ashrrev_i32_e32 v93, 31, v100
	v_and_b32_e32 v100, 0xffffff00, v100
	v_lshl_or_b32 v93, v93, 8, s33
	v_xor_b32_e32 v100, v100, v93
	v_xor_b32_e32 v100, 0xe8, v100
	v_add_f32_e32 v93, v114, v90
	v_ashrrev_i32_e32 v99, 31, v93
	v_and_b32_e32 v93, 0xffffff00, v93
	v_lshl_or_b32 v99, v99, 8, s33
	v_xor_b32_e32 v93, v93, v99
	v_xor_b32_e32 v93, 0xdf, v93
	v_add_f32_e32 v99, v114, v120
	v_ashrrev_i32_e32 v94, 31, v99
	v_and_b32_e32 v99, 0xffffff00, v99
	v_lshl_or_b32 v94, v94, 8, s33
	v_xor_b32_e32 v99, v99, v94
	v_xor_b32_e32 v99, 0xde, v99
	v_add_f32_e32 v94, v114, v121
	v_ashrrev_i32_e32 v86, 31, v94
	v_and_b32_e32 v94, 0xffffff00, v94
	v_lshl_or_b32 v86, v86, 8, s33
	v_xor_b32_e32 v94, v94, v86
	v_xor_b32_e32 v94, 0xdd, v94
	v_add_f32_e32 v86, v114, v122
	v_ashrrev_i32_e32 v95, 31, v86
	v_and_b32_e32 v86, 0xffffff00, v86
	v_lshl_or_b32 v95, v95, 8, s33
	v_xor_b32_e32 v86, v86, v95
	v_xor_b32_e32 v86, 0xdc, v86
	v_add_f32_e32 v95, v114, v123
	v_ashrrev_i32_e32 v74, 31, v95
	v_and_b32_e32 v95, 0xffffff00, v95
	v_lshl_or_b32 v74, v74, 8, s33
	v_xor_b32_e32 v95, v95, v74
	v_xor_b32_e32 v95, 0xdb, v95
	v_add_f32_e32 v74, v75, v90
	v_ashrrev_i32_e32 v88, 31, v74
	v_and_b32_e32 v74, 0xffffff00, v74
	v_lshl_or_b32 v88, v88, 8, s33
	v_xor_b32_e32 v74, v74, v88
	v_xor_b32_e32 v74, 0xbf, v74
	v_add_f32_e32 v88, v75, v120
	v_ashrrev_i32_e32 v71, 31, v88
	v_and_b32_e32 v88, 0xffffff00, v88
	v_lshl_or_b32 v71, v71, 8, s33
	v_xor_b32_e32 v88, v88, v71
	v_xor_b32_e32 v88, 0xbe, v88
	v_add_f32_e32 v71, v75, v121
	v_ashrrev_i32_e32 v135, 31, v71
	v_and_b32_e32 v71, 0xffffff00, v71
	v_lshl_or_b32 v135, v135, 8, s33
	v_xor_b32_e32 v71, v71, v135
	v_xor_b32_e32 v71, 0xbd, v71
	v_max_u32_e32 v135, v85, v74
	v_min_u32_e32 v74, v85, v74
	v_max_u32_e32 v85, v101, v95
	v_min_u32_e32 v95, v101, v95
	v_max_u32_e32 v101, v84, v71
	v_min_u32_e32 v71, v84, v71
	v_max_u32_e32 v84, v77, v88
	v_min_u32_e32 v88, v77, v88
	v_max_u32_e32 v77, v80, v93
	v_min_u32_e32 v93, v80, v93
	v_max_u32_e32 v80, v81, v76
	v_min_u32_e32 v76, v81, v76
	v_max_u32_e32 v81, v100, v86
	v_min_u32_e32 v86, v100, v86
	v_max_u32_e32 v100, v99, v94
	v_min_u32_e32 v94, v99, v94
	v_max_u32_e32 v99, v135, v80
	v_min_u32_e32 v80, v135, v80
	v_max_u32_e32 v135, v85, v81
	v_min_u32_e32 v81, v85, v81
	v_max_u32_e32 v85, v101, v100
	v_min_u32_e32 v100, v101, v100
	v_max_u32_e32 v101, v84, v77
	v_min_u32_e32 v77, v84, v77
	v_max_u32_e32 v84, v76, v74
	v_min_u32_e32 v74, v76, v74
	v_max_u32_e32 v76, v93, v88
	v_min_u32_e32 v88, v93, v88
	v_max_u32_e32 v93, v94, v71
	v_min_u32_e32 v71, v94, v71
	v_max_u32_e32 v94, v86, v95
	v_min_u32_e32 v95, v86, v95
	v_max_u32_e32 v86, v99, v135
	v_min_u32_e32 v135, v99, v135
	v_max_u32_e32 v99, v85, v101
	v_min_u32_e32 v101, v85, v101
	v_max_u32_e32 v85, v77, v80
	v_min_u32_e32 v80, v77, v80
	v_max_u32_e32 v77, v84, v76
	v_min_u32_e32 v76, v84, v76
	v_max_u32_e32 v84, v81, v100
	v_min_u32_e32 v100, v81, v100
	v_max_u32_e32 v81, v93, v94
	v_min_u32_e32 v94, v93, v94
	v_max_u32_e32 v93, v95, v74
	v_min_u32_e32 v74, v95, v74
	v_max_u32_e32 v95, v88, v71
	v_min_u32_e32 v71, v88, v71
	v_max_u32_e32 v88, v86, v99
	v_min_u32_e32 v99, v86, v99
	v_max_u32_e32 v86, v135, v101
	v_min_u32_e32 v101, v135, v101
	v_max_u32_e32 v135, v85, v81
	v_min_u32_e32 v81, v85, v81
	v_max_u32_e32 v85, v80, v94
	v_min_u32_e32 v94, v80, v94
	v_max_u32_e32 v80, v77, v84
	v_min_u32_e32 v84, v77, v84
	v_max_u32_e32 v77, v76, v100
	v_min_u32_e32 v100, v76, v100
	v_max_u32_e32 v76, v93, v95
	v_min_u32_e32 v95, v93, v95
	v_max_u32_e32 v93, v74, v71
	v_min_u32_e32 v71, v74, v71
	v_max_u32_e32 v74, v86, v99
	v_min_u32_e32 v99, v86, v99
	v_max_u32_e32 v86, v101, v76
	v_min_u32_e32 v76, v101, v76
	v_max_u32_e32 v101, v135, v80
	v_min_u32_e32 v80, v135, v80
	v_max_u32_e32 v135, v85, v84
	v_min_u32_e32 v84, v85, v84
	v_max_u32_e32 v85, v77, v81
	v_min_u32_e32 v81, v77, v81
	v_max_u32_e32 v77, v100, v94
	v_min_u32_e32 v94, v100, v94
	v_max_u32_e32 v100, v93, v95
	v_min_u32_e32 v95, v93, v95
	v_max_u32_e32 v93, v74, v101
	v_min_u32_e32 v101, v74, v101
; #define CK(i, j) ((f2key(va[i] + vb[j]) & ~255u) | (unsigned)(255 - (16 * (i) + (j))))
; __device__ __forceinline__ void peer_tile(const Args& A, LAS unsigned char* lds, int tile) {
;     ...
;             sort16_desc(Bt); merge16(Lf, Bt);
; #pragma unroll
;             for (int j = 0; j < 4; ++j) Bt[j] = CK(3, j);
;             Bt[4] = CK(5, 0); Bt[5] = CK(5, 1); Bt[6] = CK(6, 0); Bt[7] = CK(6, 1); Bt[8] = CK(7, 0); Bt[9] = CK(7, 1);
;             Bt[10] = CK(8, 0); Bt[11] = CK(9, 0); Bt[12] = CK(10, 0); Bt[13] = CK(11, 0); Bt[14] = CK(12, 0); Bt[15] = CK(13, 0);
;             sort16_desc(Bt); merge16(Lf, Bt);
	v_max_u32_e32 v74, v99, v80
	v_min_u32_e32 v80, v99, v80
	v_max_u32_e32 v99, v135, v85
	v_min_u32_e32 v85, v135, v85
	v_max_u32_e32 v135, v84, v81
	v_min_u32_e32 v81, v84, v81
	v_max_u32_e32 v84, v77, v100
	v_min_u32_e32 v100, v77, v100
	v_max_u32_e32 v77, v94, v95
	v_min_u32_e32 v95, v94, v95
	v_max_u32_e32 v94, v74, v101
	v_min_u32_e32 v101, v74, v101
	v_max_u32_e32 v74, v86, v80
	v_min_u32_e32 v80, v86, v80
	v_max_u32_e32 v86, v84, v76
	v_min_u32_e32 v76, v84, v76
	v_max_u32_e32 v84, v77, v100
	v_min_u32_e32 v100, v77, v100
	v_max_u32_e32 v77, v74, v99
	v_min_u32_e32 v99, v74, v99
	v_max_u32_e32 v74, v80, v85
	v_min_u32_e32 v85, v80, v85
	v_max_u32_e32 v80, v135, v86
	v_min_u32_e32 v86, v135, v86
	v_max_u32_e32 v135, v81, v76
	v_min_u32_e32 v76, v81, v76
	v_max_u32_e32 v81, v77, v101
	v_min_u32_e32 v101, v77, v101
	v_max_u32_e32 v77, v99, v74
	v_min_u32_e32 v74, v99, v74
	v_max_u32_e32 v99, v80, v85
	v_min_u32_e32 v85, v80, v85
	v_max_u32_e32 v80, v86, v135
	v_min_u32_e32 v135, v86, v135
	v_max_u32_e32 v86, v84, v76
	v_min_u32_e32 v76, v84, v76
	v_max_u32_e32 v84, v74, v99
	v_min_u32_e32 v99, v74, v99
	v_max_u32_e32 v74, v85, v80
	v_min_u32_e32 v80, v85, v80
	v_max_u32_e32 v96, v96, v71
	v_max_u32_e32 v118, v118, v95
	v_max_u32_e32 v89, v89, v100
	v_max_u32_e32 v87, v87, v76
	v_max_u32_e32 v91, v91, v86
	v_max_u32_e32 v83, v83, v135
	v_max_u32_e32 v70, v70, v80
	v_max_u32_e32 v117, v117, v74
	v_max_u32_e32 v109, v109, v99
	v_max_u32_e32 v116, v116, v84
	v_max_u32_e32 v110, v110, v77
	v_max_u32_e32 v79, v79, v101
	v_max_u32_e32 v111, v111, v81
	v_max_u32_e32 v82, v82, v94
	v_max_u32_e32 v104, v104, v93
	v_max_u32_e32 v73, v73, v88
	v_max_u32_e32 v71, v96, v109
	v_min_u32_e32 v109, v96, v109
	v_max_u32_e32 v96, v118, v116
	v_min_u32_e32 v116, v118, v116
	v_max_u32_e32 v118, v89, v110
	v_min_u32_e32 v110, v89, v110
	v_max_u32_e32 v89, v87, v79
	v_min_u32_e32 v79, v87, v79
	v_max_u32_e32 v87, v91, v111
	v_min_u32_e32 v111, v91, v111
	v_max_u32_e32 v91, v83, v82
	v_min_u32_e32 v82, v83, v82
	v_max_u32_e32 v83, v70, v104
	v_min_u32_e32 v104, v70, v104
	v_max_u32_e32 v70, v117, v73
	v_min_u32_e32 v73, v117, v73
	v_max_u32_e32 v117, v71, v87
	v_min_u32_e32 v87, v71, v87
	v_max_u32_e32 v71, v96, v91
	v_min_u32_e32 v91, v96, v91
	v_max_u32_e32 v96, v118, v83
	v_min_u32_e32 v83, v118, v83
	v_max_u32_e32 v118, v89, v70
	v_min_u32_e32 v70, v89, v70
	v_max_u32_e32 v89, v109, v111
	v_min_u32_e32 v111, v109, v111
	v_max_u32_e32 v109, v116, v82
	v_min_u32_e32 v82, v116, v82
	v_max_u32_e32 v116, v110, v104
	v_min_u32_e32 v104, v110, v104
	v_max_u32_e32 v110, v79, v73
	v_min_u32_e32 v73, v79, v73
	v_max_u32_e32 v79, v117, v96
	v_min_u32_e32 v96, v117, v96
	v_max_u32_e32 v117, v71, v118
	v_min_u32_e32 v118, v71, v118
	v_max_u32_e32 v71, v87, v83
	v_min_u32_e32 v83, v87, v83
	v_max_u32_e32 v87, v91, v70
	v_min_u32_e32 v70, v91, v70
	v_max_u32_e32 v91, v89, v116
	v_min_u32_e32 v116, v89, v116
	v_max_u32_e32 v89, v109, v110
	v_min_u32_e32 v110, v109, v110
	v_max_u32_e32 v109, v111, v104
	v_min_u32_e32 v104, v111, v104
	v_max_u32_e32 v111, v82, v73
	v_min_u32_e32 v73, v82, v73
	v_max_u32_e32 v82, v79, v117
	v_min_u32_e32 v117, v79, v117
	v_max_u32_e32 v79, v96, v118
	v_min_u32_e32 v118, v96, v118
	v_max_u32_e32 v96, v71, v87
	v_min_u32_e32 v87, v71, v87
	v_max_u32_e32 v71, v83, v70
	v_min_u32_e32 v70, v83, v70
	v_max_u32_e32 v83, v91, v89
	v_min_u32_e32 v89, v91, v89
	v_max_u32_e32 v91, v116, v110
	v_min_u32_e32 v110, v116, v110
	v_max_u32_e32 v116, v109, v111
	v_min_u32_e32 v111, v109, v111
	v_max_u32_e32 v109, v104, v73
	v_min_u32_e32 v73, v104, v73
	v_add_f32_e32 v104, v119, v90
	v_ashrrev_i32_e32 v95, 31, v104
	v_and_b32_e32 v104, 0xffffff00, v104
	v_lshl_or_b32 v95, v95, 8, s33
	v_xor_b32_e32 v104, v104, v95
	v_xor_b32_e32 v104, 0xcf, v104
	v_add_f32_e32 v95, v119, v120
	v_ashrrev_i32_e32 v100, 31, v95
	v_and_b32_e32 v95, 0xffffff00, v95
	v_lshl_or_b32 v100, v100, 8, s33
	v_xor_b32_e32 v95, v95, v100
	v_xor_b32_e32 v95, 0xce, v95
	v_add_f32_e32 v100, v119, v121
	v_ashrrev_i32_e32 v76, 31, v100
	v_and_b32_e32 v100, 0xffffff00, v100
	v_lshl_or_b32 v76, v76, 8, s33
	v_xor_b32_e32 v100, v100, v76
	v_xor_b32_e32 v100, 0xcd, v100
	v_add_f32_e32 v76, v119, v122
	v_ashrrev_i32_e32 v86, 31, v76
	v_and_b32_e32 v76, 0xffffff00, v76
	v_lshl_or_b32 v86, v86, 8, s33
	v_xor_b32_e32 v76, v76, v86
	v_xor_b32_e32 v76, 0xcc, v76
	v_add_f32_e32 v86, v92, v90
	v_ashrrev_i32_e32 v135, 31, v86
	v_and_b32_e32 v86, 0xffffff00, v86
	v_lshl_or_b32 v135, v135, 8, s33
	v_xor_b32_e32 v86, v86, v135
	v_xor_b32_e32 v86, 0xaf, v86
	v_add_f32_e32 v135, v92, v120
	v_ashrrev_i32_e32 v80, 31, v135
	v_and_b32_e32 v135, 0xffffff00, v135
	v_lshl_or_b32 v80, v80, 8, s33
	v_xor_b32_e32 v135, v135, v80
	v_xor_b32_e32 v135, 0xae, v135
	v_add_f32_e32 v80, v72, v90
	v_ashrrev_i32_e32 v74, 31, v80
	v_and_b32_e32 v80, 0xffffff00, v80
	v_lshl_or_b32 v74, v74, 8, s33
	v_xor_b32_e32 v80, v80, v74
	v_xor_b32_e32 v80, 0x9f, v80
	v_add_f32_e32 v74, v72, v120
	v_ashrrev_i32_e32 v99, 31, v74
	v_and_b32_e32 v74, 0xffffff00, v74
	v_lshl_or_b32 v99, v99, 8, s33
	v_xor_b32_e32 v74, v74, v99
	v_xor_b32_e32 v74, 0x9e, v74
	v_add_f32_e32 v99, v103, v90
	v_ashrrev_i32_e32 v84, 31, v99
	v_and_b32_e32 v99, 0xffffff00, v99
	v_lshl_or_b32 v84, v84, 8, s33
	v_xor_b32_e32 v99, v99, v84
	v_xor_b32_e32 v99, 0x8f, v99
	v_add_f32_e32 v84, v103, v120
	v_ashrrev_i32_e32 v77, 31, v84
	v_and_b32_e32 v84, 0xffffff00, v84
	v_lshl_or_b32 v77, v77, 8, s33
	v_xor_b32_e32 v84, v84, v77
	v_xor_b32_e32 v84, 0x8e, v84
	v_add_f32_e32 v77, v108, v90
	v_ashrrev_i32_e32 v101, 31, v77
	v_and_b32_e32 v77, 0xffffff00, v77
	v_lshl_or_b32 v101, v101, 8, s33
; #define CK(i, j) ((f2key(va[i] + vb[j]) & ~255u) | (unsigned)(255 - (16 * (i) + (j))))
; __device__ __forceinline__ void peer_tile(const Args& A, LAS unsigned char* lds, int tile) {
;     ...
;             for (int j = 0; j < 4; ++j) Bt[j] = CK(3, j);
;             Bt[4] = CK(5, 0); Bt[5] = CK(5, 1); Bt[6] = CK(6, 0); Bt[7] = CK(6, 1); Bt[8] = CK(7, 0); Bt[9] = CK(7, 1);
;             Bt[10] = CK(8, 0); Bt[11] = CK(9, 0); Bt[12] = CK(10, 0); Bt[13] = CK(11, 0); Bt[14] = CK(12, 0); Bt[15] = CK(13, 0);
;             sort16_desc(Bt); merge16(Lf, Bt);
	v_xor_b32_e32 v77, v77, v101
	v_xor_b32_e32 v77, 0x7f, v77
	v_add_f32_e32 v101, v106, v90
	v_ashrrev_i32_e32 v81, 31, v101
	v_and_b32_e32 v101, 0xffffff00, v101
	v_lshl_or_b32 v81, v81, 8, s33
	v_xor_b32_e32 v101, v101, v81
	v_xor_b32_e32 v101, 0x6f, v101
	v_add_f32_e32 v81, v107, v90
	v_ashrrev_i32_e32 v94, 31, v81
	v_and_b32_e32 v81, 0xffffff00, v81
	v_lshl_or_b32 v94, v94, 8, s33
	v_xor_b32_e32 v81, v81, v94
	v_xor_b32_e32 v81, 0x5f, v81
	v_add_f32_e32 v94, v98, v90
	v_ashrrev_i32_e32 v93, 31, v94
	v_and_b32_e32 v94, 0xffffff00, v94
	v_lshl_or_b32 v93, v93, 8, s33
	v_xor_b32_e32 v94, v94, v93
	v_xor_b32_e32 v94, 0x4f, v94
	v_add_f32_e32 v93, v78, v90
	v_ashrrev_i32_e32 v88, 31, v93
	v_and_b32_e32 v93, 0xffffff00, v93
	v_lshl_or_b32 v88, v88, 8, s33
	v_xor_b32_e32 v93, v93, v88
	v_xor_b32_e32 v93, 63, v93
	v_add_f32_e32 v88, v115, v90
	v_ashrrev_i32_e32 v85, 31, v88
	v_and_b32_e32 v88, 0xffffff00, v88
	v_lshl_or_b32 v85, v85, 8, s33
	v_xor_b32_e32 v88, v88, v85
	v_xor_b32_e32 v88, 47, v88
	v_max_u32_e32 v85, v104, v94
	v_min_u32_e32 v94, v104, v94
	v_max_u32_e32 v104, v95, v81
	v_min_u32_e32 v81, v95, v81
	v_max_u32_e32 v95, v100, v88
	v_min_u32_e32 v88, v100, v88
	v_max_u32_e32 v100, v76, v93
	v_min_u32_e32 v93, v76, v93
	v_max_u32_e32 v76, v86, v99
	v_min_u32_e32 v99, v86, v99
	v_max_u32_e32 v86, v135, v80
	v_min_u32_e32 v80, v135, v80
	v_max_u32_e32 v135, v74, v101
	v_min_u32_e32 v101, v74, v101
	v_max_u32_e32 v74, v84, v77
	v_min_u32_e32 v77, v84, v77
	v_max_u32_e32 v84, v85, v86
	v_min_u32_e32 v86, v85, v86
	v_max_u32_e32 v85, v104, v135
	v_min_u32_e32 v135, v104, v135
	v_max_u32_e32 v104, v95, v74
	v_min_u32_e32 v74, v95, v74
	v_max_u32_e32 v95, v100, v76
	v_min_u32_e32 v76, v100, v76
	v_max_u32_e32 v100, v80, v94
	v_min_u32_e32 v94, v80, v94
	v_max_u32_e32 v80, v99, v93
	v_min_u32_e32 v93, v99, v93
	v_max_u32_e32 v99, v77, v88
	v_min_u32_e32 v88, v77, v88
	v_max_u32_e32 v77, v101, v81
	v_min_u32_e32 v81, v101, v81
	v_max_u32_e32 v101, v84, v85
	v_min_u32_e32 v85, v84, v85
	v_max_u32_e32 v84, v104, v95
	v_min_u32_e32 v95, v104, v95
	v_max_u32_e32 v104, v76, v86
	v_min_u32_e32 v86, v76, v86
	v_max_u32_e32 v76, v100, v80
	v_min_u32_e32 v80, v100, v80
	v_max_u32_e32 v100, v135, v74
	v_min_u32_e32 v74, v135, v74
	v_max_u32_e32 v135, v99, v77
	v_min_u32_e32 v77, v99, v77
	v_max_u32_e32 v99, v81, v94
	v_min_u32_e32 v94, v81, v94
	v_max_u32_e32 v81, v93, v88
	v_min_u32_e32 v88, v93, v88
	v_max_u32_e32 v93, v101, v84
	v_min_u32_e32 v84, v101, v84
	v_max_u32_e32 v101, v85, v95
	v_min_u32_e32 v95, v85, v95
	v_max_u32_e32 v85, v104, v135
	v_min_u32_e32 v135, v104, v135
	v_max_u32_e32 v104, v86, v77
	v_min_u32_e32 v77, v86, v77
	v_max_u32_e32 v86, v76, v100
	v_min_u32_e32 v100, v76, v100
	v_max_u32_e32 v76, v80, v74
	v_min_u32_e32 v74, v80, v74
	v_max_u32_e32 v80, v99, v81
	v_min_u32_e32 v81, v99, v81
	v_max_u32_e32 v99, v94, v88
	v_min_u32_e32 v88, v94, v88
	v_max_u32_e32 v94, v101, v84
	v_min_u32_e32 v84, v101, v84
	v_max_u32_e32 v101, v95, v80
	v_min_u32_e32 v80, v95, v80
	v_max_u32_e32 v95, v85, v86
	v_min_u32_e32 v86, v85, v86
	v_max_u32_e32 v85, v104, v100
	v_min_u32_e32 v100, v104, v100
	v_max_u32_e32 v104, v76, v135
	v_min_u32_e32 v135, v76, v135
	v_max_u32_e32 v76, v74, v77
	v_min_u32_e32 v77, v74, v77
	v_max_u32_e32 v74, v99, v81
	v_min_u32_e32 v81, v99, v81
	v_max_u32_e32 v99, v94, v95
	v_min_u32_e32 v95, v94, v95
	v_max_u32_e32 v94, v84, v86
	v_min_u32_e32 v86, v84, v86
	v_max_u32_e32 v84, v85, v104
	v_min_u32_e32 v104, v85, v104
	v_max_u32_e32 v85, v100, v135
	v_min_u32_e32 v135, v100, v135
	v_max_u32_e32 v100, v76, v74
	v_min_u32_e32 v74, v76, v74
	v_max_u32_e32 v76, v77, v81
	v_min_u32_e32 v81, v77, v81
	v_max_u32_e32 v77, v94, v95
	v_min_u32_e32 v95, v94, v95
	v_max_u32_e32 v94, v101, v86
	v_min_u32_e32 v86, v101, v86
	v_max_u32_e32 v101, v100, v80
	v_min_u32_e32 v80, v100, v80
	v_max_u32_e32 v100, v76, v74
	v_min_u32_e32 v74, v76, v74
	v_max_u32_e32 v76, v94, v84
	v_min_u32_e32 v84, v94, v84
	v_max_u32_e32 v94, v86, v104
	v_min_u32_e32 v104, v86, v104
	v_max_u32_e32 v86, v85, v101
	v_min_u32_e32 v101, v85, v101
	v_max_u32_e32 v85, v135, v80
	v_min_u32_e32 v80, v135, v80
	v_max_u32_e32 v135, v76, v95
	v_min_u32_e32 v95, v76, v95
	v_max_u32_e32 v76, v84, v94
	v_min_u32_e32 v94, v84, v94
	v_max_u32_e32 v84, v86, v104
	v_min_u32_e32 v104, v86, v104
	v_max_u32_e32 v86, v101, v85
	v_min_u32_e32 v85, v101, v85
	v_max_u32_e32 v101, v100, v80
	v_min_u32_e32 v80, v100, v80
	v_max_u32_e32 v100, v94, v84
	v_min_u32_e32 v84, v94, v84
	v_max_u32_e32 v94, v104, v86
	v_min_u32_e32 v86, v104, v86
	v_max_u32_e32 v82, v82, v88
	v_max_u32_e32 v117, v117, v81
	v_max_u32_e32 v79, v79, v74
	v_max_u32_e32 v118, v118, v80
	v_max_u32_e32 v96, v96, v101
	v_max_u32_e32 v87, v87, v85
	v_max_u32_e32 v71, v71, v86
	v_max_u32_e32 v70, v70, v94
	v_max_u32_e32 v83, v83, v84
	v_max_u32_e32 v89, v89, v100
	v_max_u32_e32 v91, v91, v76
	v_max_u32_e32 v110, v110, v95
	v_max_u32_e32 v116, v116, v135
	v_max_u32_e32 v111, v111, v77
	v_max_u32_e32 v109, v109, v99
	v_max_u32_e32 v73, v73, v93
	v_max_u32_e32 v88, v82, v83
	v_min_u32_e32 v83, v82, v83
	v_max_u32_e32 v82, v117, v89
	v_min_u32_e32 v89, v117, v89
	v_max_u32_e32 v117, v79, v91
	v_min_u32_e32 v91, v79, v91
	v_max_u32_e32 v79, v118, v110
	v_min_u32_e32 v110, v118, v110
	v_max_u32_e32 v118, v96, v116
	v_min_u32_e32 v116, v96, v116
	v_max_u32_e32 v96, v87, v111
	v_min_u32_e32 v111, v87, v111
	v_max_u32_e32 v87, v71, v109
	v_min_u32_e32 v109, v71, v109
	v_max_u32_e32 v71, v70, v73
	v_min_u32_e32 v73, v70, v73
	v_max_u32_e32 v70, v88, v118
	v_min_u32_e32 v118, v88, v118
	v_max_u32_e32 v88, v82, v96
; __device__ __forceinline__ float key2f(unsigned k) { const unsigned u = (k & 0x80000000u) ? (k & 0x7fffffffu) : ~k; return __uint_as_float(u); }
; #define CE_DESC(a, b) do { const unsigned _mx = (a) > (b) ? (a) : (b), _mn = (a) > (b) ? (b) : (a); (a) = _mx; (b) = _mn; } while (0)
; #define CK(i, j) ((f2key(va[i] + vb[j]) & ~255u) | (unsigned)(255 - (16 * (i) + (j))))
; __device__ __forceinline__ void peer_tile(const Args& A, LAS unsigned char* lds, int tile) {
;     ...
;             sort16_desc(Bt); merge16(Lf, Bt);
;             { unsigned x0 = CK(14, 0), x1 = CK(15, 0);
; #pragma unroll
;               for (int i = 0; i < 16; ++i) CE_DESC(Lf[i], x0);
; #pragma unroll
;               for (int i = 0; i < 16; ++i) CE_DESC(Lf[i], x1); }
;     ...
;             float fv[16], den = 0.f; const float f0 = key2f(Lf[0] & ~255u);
; #pragma unroll
;             for (int k = 0; k < 16; ++k) { fv[k] = __expf(key2f(Lf[k] & ~255u) - f0); den += fv[k]; }
	v_min_u32_e32 v96, v82, v96
	v_max_u32_e32 v82, v117, v87
	v_min_u32_e32 v87, v117, v87
	v_max_u32_e32 v117, v79, v71
	v_min_u32_e32 v71, v79, v71
	v_max_u32_e32 v79, v83, v116
	v_min_u32_e32 v116, v83, v116
	v_max_u32_e32 v83, v89, v111
	v_min_u32_e32 v111, v89, v111
	v_max_u32_e32 v89, v91, v109
	v_min_u32_e32 v109, v91, v109
	v_max_u32_e32 v91, v110, v73
	v_min_u32_e32 v73, v110, v73
	v_max_u32_e32 v110, v70, v82
	v_min_u32_e32 v82, v70, v82
	v_max_u32_e32 v70, v88, v117
	v_min_u32_e32 v117, v88, v117
	v_max_u32_e32 v88, v118, v87
	v_min_u32_e32 v87, v118, v87
	v_max_u32_e32 v118, v96, v71
	v_min_u32_e32 v71, v96, v71
	v_max_u32_e32 v96, v79, v89
	v_min_u32_e32 v89, v79, v89
	v_max_u32_e32 v79, v83, v91
	v_min_u32_e32 v91, v83, v91
	v_max_u32_e32 v83, v116, v109
	v_min_u32_e32 v109, v116, v109
	v_max_u32_e32 v116, v111, v73
	v_min_u32_e32 v73, v111, v73
	v_max_u32_e32 v111, v110, v70
	v_min_u32_e32 v70, v110, v70
	v_max_u32_e32 v110, v82, v117
	v_min_u32_e32 v117, v82, v117
	v_max_u32_e32 v82, v88, v118
	v_min_u32_e32 v118, v88, v118
	v_max_u32_e32 v88, v87, v71
	v_min_u32_e32 v71, v87, v71
	v_max_u32_e32 v87, v96, v79
	v_min_u32_e32 v79, v96, v79
	v_max_u32_e32 v96, v89, v91
	v_min_u32_e32 v91, v89, v91
	v_max_u32_e32 v89, v83, v116
	v_min_u32_e32 v116, v83, v116
	v_max_u32_e32 v83, v109, v73
	v_min_u32_e32 v73, v109, v73
	v_add_f32_e32 v109, v105, v90
	v_ashrrev_i32_e32 v81, 31, v109
	v_and_b32_e32 v109, 0xffffff00, v109
	v_lshl_or_b32 v81, v81, 8, s33
	v_xor_b32_e32 v109, v109, v81
	v_xor_b32_e32 v109, 31, v109
	v_max_u32_e32 v81, v111, v109
	v_min_u32_e32 v109, v111, v109
	v_max_u32_e32 v111, v70, v109
	v_min_u32_e32 v109, v70, v109
	v_max_u32_e32 v70, v110, v109
	v_min_u32_e32 v109, v110, v109
	v_max_u32_e32 v110, v117, v109
	v_min_u32_e32 v109, v117, v109
	v_max_u32_e32 v117, v82, v109
	v_min_u32_e32 v109, v82, v109
	v_max_u32_e32 v82, v118, v109
	v_min_u32_e32 v109, v118, v109
	v_max_u32_e32 v118, v88, v109
	v_min_u32_e32 v109, v88, v109
	v_max_u32_e32 v88, v71, v109
	v_min_u32_e32 v109, v71, v109
	v_max_u32_e32 v71, v87, v109
	v_min_u32_e32 v109, v87, v109
	v_max_u32_e32 v87, v79, v109
	v_min_u32_e32 v109, v79, v109
	v_max_u32_e32 v79, v96, v109
	v_min_u32_e32 v109, v96, v109
	v_max_u32_e32 v96, v91, v109
	v_min_u32_e32 v109, v91, v109
	v_max_u32_e32 v91, v89, v109
	v_min_u32_e32 v109, v89, v109
	v_max_u32_e32 v89, v116, v109
	v_min_u32_e32 v109, v116, v109
	v_max_u32_e32 v116, v83, v109
	v_min_u32_e32 v109, v83, v109
	v_max_u32_e32 v83, v73, v109
	v_min_u32_e32 v109, v73, v109
	v_add_f32_e32 v109, v112, v90
	v_ashrrev_i32_e32 v73, 31, v109
	v_and_b32_e32 v109, 0xffffff00, v109
	v_lshl_or_b32 v73, v73, 8, s33
	v_xor_b32_e32 v109, v109, v73
	v_xor_b32_e32 v109, 15, v109
	v_max_u32_e32 v73, v81, v109
	v_min_u32_e32 v109, v81, v109
	v_max_u32_e32 v81, v111, v109
	v_min_u32_e32 v109, v111, v109
	v_max_u32_e32 v111, v70, v109
	v_min_u32_e32 v109, v70, v109
	v_max_u32_e32 v70, v110, v109
	v_min_u32_e32 v109, v110, v109
	v_max_u32_e32 v110, v117, v109
	v_min_u32_e32 v109, v117, v109
	v_max_u32_e32 v117, v82, v109
	v_min_u32_e32 v109, v82, v109
	v_max_u32_e32 v82, v118, v109
	v_min_u32_e32 v109, v118, v109
	v_max_u32_e32 v118, v88, v109
	v_min_u32_e32 v109, v88, v109
	v_max_u32_e32 v88, v71, v109
	v_min_u32_e32 v109, v71, v109
	v_max_u32_e32 v71, v87, v109
	v_min_u32_e32 v109, v87, v109
	v_max_u32_e32 v87, v79, v109
	v_min_u32_e32 v109, v79, v109
	v_max_u32_e32 v79, v96, v109
	v_min_u32_e32 v109, v96, v109
	v_max_u32_e32 v96, v91, v109
	v_min_u32_e32 v109, v91, v109
	v_max_u32_e32 v91, v89, v109
	v_min_u32_e32 v109, v89, v109
	v_max_u32_e32 v89, v116, v109
	v_min_u32_e32 v109, v116, v109
	v_max_u32_e32 v116, v83, v109
	v_min_u32_e32 v109, v83, v109
	v_ashrrev_i32_e32 v133, 31, v73
	v_and_b32_e32 v134, 0xffffff00, v73
	v_bitop3_b32 v134, v134, v133, s41 bitop3:0x87
	v_ashrrev_i32_e32 v131, 31, v73
	v_and_b32_e32 v132, 0xffffff00, v73
	v_bitop3_b32 v132, v132, v131, s41 bitop3:0x87
	v_sub_f32_e32 v132, v132, v134
	v_mul_f32_e32 v132, 0x3fb8aa3b, v132
	v_exp_f32_e32 v132, v132
	v_ashrrev_i32_e32 v130, 31, v81
	v_and_b32_e32 v131, 0xffffff00, v81
	v_bitop3_b32 v131, v131, v130, s41 bitop3:0x87
	v_sub_f32_e32 v131, v131, v134
	v_mul_f32_e32 v131, 0x3fb8aa3b, v131
	v_exp_f32_e32 v131, v131
	v_ashrrev_i32_e32 v129, 31, v111
	v_and_b32_e32 v130, 0xffffff00, v111
	v_bitop3_b32 v130, v130, v129, s41 bitop3:0x87
	v_sub_f32_e32 v130, v130, v134
	v_mul_f32_e32 v130, 0x3fb8aa3b, v130
	v_exp_f32_e32 v130, v130
	v_ashrrev_i32_e32 v128, 31, v70
	v_and_b32_e32 v129, 0xffffff00, v70
	v_bitop3_b32 v129, v129, v128, s41 bitop3:0x87
	v_sub_f32_e32 v129, v129, v134
	v_mul_f32_e32 v129, 0x3fb8aa3b, v129
	v_exp_f32_e32 v129, v129
	v_ashrrev_i32_e32 v127, 31, v110
	v_and_b32_e32 v128, 0xffffff00, v110
	v_bitop3_b32 v128, v128, v127, s41 bitop3:0x87
	v_sub_f32_e32 v128, v128, v134
	v_mul_f32_e32 v128, 0x3fb8aa3b, v128
	v_exp_f32_e32 v128, v128
	v_ashrrev_i32_e32 v126, 31, v117
	v_and_b32_e32 v127, 0xffffff00, v117
	v_bitop3_b32 v127, v127, v126, s41 bitop3:0x87
	v_sub_f32_e32 v127, v127, v134
	v_mul_f32_e32 v127, 0x3fb8aa3b, v127
	v_exp_f32_e32 v127, v127
	v_ashrrev_i32_e32 v125, 31, v82
	v_and_b32_e32 v126, 0xffffff00, v82
	v_bitop3_b32 v126, v126, v125, s41 bitop3:0x87
	v_sub_f32_e32 v126, v126, v134
	v_mul_f32_e32 v126, 0x3fb8aa3b, v126
	v_exp_f32_e32 v126, v126
	v_ashrrev_i32_e32 v124, 31, v118
	v_and_b32_e32 v125, 0xffffff00, v118
	v_bitop3_b32 v125, v125, v124, s41 bitop3:0x87
	v_sub_f32_e32 v125, v125, v134
	v_mul_f32_e32 v125, 0x3fb8aa3b, v125
	v_exp_f32_e32 v125, v125
	v_ashrrev_i32_e32 v123, 31, v88
	v_and_b32_e32 v124, 0xffffff00, v88
; __device__ __forceinline__ float key2f(unsigned k) { const unsigned u = (k & 0x80000000u) ? (k & 0x7fffffffu) : ~k; return __uint_as_float(u); }
; __device__ __forceinline__ void peer_tile(const Args& A, LAS unsigned char* lds, int tile) {
;     ...
;             float fv[16], den = 0.f; const float f0 = key2f(Lf[0] & ~255u);
; #pragma unroll
;             for (int k = 0; k < 16; ++k) { fv[k] = __expf(key2f(Lf[k] & ~255u) - f0); den += fv[k]; }
;             const float rden = 1.f / den;
	v_bitop3_b32 v124, v124, v123, s41 bitop3:0x87
	v_sub_f32_e32 v124, v124, v134
	v_mul_f32_e32 v124, 0x3fb8aa3b, v124
	v_exp_f32_e32 v124, v124
	v_ashrrev_i32_e32 v122, 31, v71
	v_and_b32_e32 v123, 0xffffff00, v71
	v_bitop3_b32 v123, v123, v122, s41 bitop3:0x87
	v_sub_f32_e32 v123, v123, v134
	v_mul_f32_e32 v123, 0x3fb8aa3b, v123
	v_exp_f32_e32 v123, v123
	v_ashrrev_i32_e32 v121, 31, v87
	v_and_b32_e32 v122, 0xffffff00, v87
	v_bitop3_b32 v122, v122, v121, s41 bitop3:0x87
	v_sub_f32_e32 v122, v122, v134
	v_mul_f32_e32 v122, 0x3fb8aa3b, v122
	v_exp_f32_e32 v122, v122
	v_ashrrev_i32_e32 v120, 31, v79
	v_and_b32_e32 v121, 0xffffff00, v79
	v_bitop3_b32 v121, v121, v120, s41 bitop3:0x87
	v_sub_f32_e32 v121, v121, v134
	v_mul_f32_e32 v121, 0x3fb8aa3b, v121
	v_exp_f32_e32 v121, v121
	v_ashrrev_i32_e32 v90, 31, v96
	v_and_b32_e32 v120, 0xffffff00, v96
	v_bitop3_b32 v120, v120, v90, s41 bitop3:0x87
	v_sub_f32_e32 v120, v120, v134
	v_mul_f32_e32 v120, 0x3fb8aa3b, v120
	v_exp_f32_e32 v120, v120
	v_ashrrev_i32_e32 v112, 31, v91
	v_and_b32_e32 v90, 0xffffff00, v91
	v_bitop3_b32 v90, v90, v112, s41 bitop3:0x87
	v_sub_f32_e32 v90, v90, v134
	v_mul_f32_e32 v90, 0x3fb8aa3b, v90
	v_exp_f32_e32 v90, v90
	v_ashrrev_i32_e32 v105, 31, v89
	v_and_b32_e32 v112, 0xffffff00, v89
	v_bitop3_b32 v112, v112, v105, s41 bitop3:0x87
	v_sub_f32_e32 v112, v112, v134
	v_mul_f32_e32 v112, 0x3fb8aa3b, v112
	v_exp_f32_e32 v112, v112
	v_ashrrev_i32_e32 v115, 31, v116
	v_and_b32_e32 v105, 0xffffff00, v116
	v_bitop3_b32 v105, v105, v115, s41 bitop3:0x87
	v_sub_f32_e32 v105, v105, v134
	v_mul_f32_e32 v105, 0x3fb8aa3b, v105
	v_exp_f32_e32 v105, v105
	v_add_f32_e32 v133, 0, v132
	v_add_f32_e32 v133, v133, v131
	v_add_f32_e32 v133, v133, v130
	v_add_f32_e32 v133, v133, v129
	v_add_f32_e32 v133, v133, v128
	v_add_f32_e32 v133, v133, v127
	v_add_f32_e32 v133, v133, v126
	v_add_f32_e32 v133, v133, v125
	v_add_f32_e32 v133, v133, v124
	v_add_f32_e32 v133, v133, v123
	v_add_f32_e32 v133, v133, v122
	v_add_f32_e32 v133, v133, v121
	v_add_f32_e32 v133, v133, v120
	v_add_f32_e32 v133, v133, v90
	v_add_f32_e32 v133, v133, v112
	v_add_f32_e32 v133, v133, v105
	v_div_scale_f32 v115, s[0:1], v133, v133, 1.0
	v_rcp_f32_e32 v78, v115
	s_nop 0
	v_fma_f32 v98, -v115, v78, 1.0
	v_fmac_f32_e32 v78, v98, v78
	v_div_scale_f32 v98, vcc, 1.0, v133, 1.0
	v_mul_f32_e32 v107, v98, v78
	v_fma_f32 v106, -v115, v107, v98
	v_fmac_f32_e32 v107, v106, v78
	v_fma_f32 v115, -v115, v107, v98
	s_nop 1
	v_div_fmas_f32 v115, v115, v78, v107
	v_div_fixup_f32 v115, v115, v133, 1.0
	s_waitcnt lgkmcnt(0)
; #define LDS_WAIT() asm volatile("s_waitcnt lgkmcnt(0)" ::: "memory")
; __device__ __forceinline__ void peer_tile(const Args& A, LAS unsigned char* lds, int tile) {
;     ...
;             LDS_WAIT();
; #pragma unroll
;             for (int k = 0; k < 16; ++k) { const unsigned code = 255u - (Lf[k] & 255u); const unsigned e = idx[code >> 4] * 128u + idx[16 + (code & 15u)];
;                 u32x2 sv; sv.x = e; sv.y = __float_as_uint(fv[k] * rden); SEL[(tl * 8 + h) * 16 + k] = sv; }
	v_xor_b32_e32 v106, 0xff, v73
	v_bfe_u32 v107, v106, 4, 4
	v_and_b32_e32 v106, 15, v106
	v_lshl_add_u32 v107, v107, 2, v67
	v_lshl_add_u32 v106, v106, 2, v67
	ds_read_b32 v107, v107
	ds_read_b32 v106, v106 offset:64
	v_xor_b32_e32 v98, 0xff, v81
	v_bfe_u32 v78, v98, 4, 4
	v_and_b32_e32 v98, 15, v98
	v_lshl_add_u32 v78, v78, 2, v67
	v_lshl_add_u32 v98, v98, 2, v67
	ds_read_b32 v78, v78
	ds_read_b32 v98, v98 offset:64
	v_xor_b32_e32 v108, 0xff, v111
	v_bfe_u32 v103, v108, 4, 4
	v_and_b32_e32 v108, 15, v108
	v_lshl_add_u32 v103, v103, 2, v67
	v_lshl_add_u32 v108, v108, 2, v67
	ds_read_b32 v103, v103
	ds_read_b32 v108, v108 offset:64
	v_xor_b32_e32 v72, 0xff, v70
	v_bfe_u32 v92, v72, 4, 4
	v_and_b32_e32 v72, 15, v72
	v_lshl_add_u32 v92, v92, 2, v67
	v_lshl_add_u32 v72, v72, 2, v67
	ds_read_b32 v92, v92
	ds_read_b32 v72, v72 offset:64
	v_xor_b32_e32 v75, 0xff, v110
	v_bfe_u32 v119, v75, 4, 4
	v_and_b32_e32 v75, 15, v75
	v_lshl_add_u32 v119, v119, 2, v67
	v_lshl_add_u32 v75, v75, 2, v67
	ds_read_b32 v119, v119
	ds_read_b32 v75, v75 offset:64
	v_xor_b32_e32 v114, 0xff, v117
	v_bfe_u32 v102, v114, 4, 4
	v_and_b32_e32 v114, 15, v114
	v_lshl_add_u32 v102, v102, 2, v67
	v_lshl_add_u32 v114, v114, 2, v67
	ds_read_b32 v102, v102
	ds_read_b32 v114, v114 offset:64
	v_xor_b32_e32 v97, 0xff, v82
	v_bfe_u32 v109, v97, 4, 4
	v_and_b32_e32 v97, 15, v97
	v_lshl_add_u32 v109, v109, 2, v67
	v_lshl_add_u32 v97, v97, 2, v67
	ds_read_b32 v109, v109
	ds_read_b32 v97, v97 offset:64
	v_xor_b32_e32 v83, 0xff, v118
	v_bfe_u32 v74, v83, 4, 4
	v_and_b32_e32 v83, 15, v83
	v_lshl_add_u32 v74, v74, 2, v67
	v_lshl_add_u32 v83, v83, 2, v67
	ds_read_b32 v74, v74
	ds_read_b32 v83, v83 offset:64
	v_xor_b32_e32 v80, 0xff, v88
	v_bfe_u32 v101, v80, 4, 4
	v_and_b32_e32 v80, 15, v80
	v_lshl_add_u32 v101, v101, 2, v67
	v_lshl_add_u32 v80, v80, 2, v67
	ds_read_b32 v101, v101
	ds_read_b32 v80, v80 offset:64
	v_xor_b32_e32 v85, 0xff, v71
	v_bfe_u32 v86, v85, 4, 4
	v_and_b32_e32 v85, 15, v85
	v_lshl_add_u32 v86, v86, 2, v67
	v_lshl_add_u32 v85, v85, 2, v67
	ds_read_b32 v86, v86
	ds_read_b32 v85, v85 offset:64
	v_xor_b32_e32 v94, 0xff, v87
	v_bfe_u32 v84, v94, 4, 4
	v_and_b32_e32 v94, 15, v94
	v_lshl_add_u32 v84, v84, 2, v67
	v_lshl_add_u32 v94, v94, 2, v67
	ds_read_b32 v84, v84
	ds_read_b32 v94, v94 offset:64
	v_xor_b32_e32 v100, 0xff, v79
	v_bfe_u32 v76, v100, 4, 4
	v_and_b32_e32 v100, 15, v100
	v_lshl_add_u32 v76, v76, 2, v67
	v_lshl_add_u32 v100, v100, 2, v67
	ds_read_b32 v76, v76
	ds_read_b32 v100, v100 offset:64
	v_xor_b32_e32 v95, 0xff, v96
	v_bfe_u32 v135, v95, 4, 4
	v_and_b32_e32 v95, 15, v95
	v_lshl_add_u32 v135, v135, 2, v67
	v_lshl_add_u32 v95, v95, 2, v67
	ds_read_b32 v135, v135
	ds_read_b32 v95, v95 offset:64
	v_xor_b32_e32 v77, 0xff, v91
	v_bfe_u32 v99, v77, 4, 4
	v_and_b32_e32 v77, 15, v77
	v_lshl_add_u32 v99, v99, 2, v67
	v_lshl_add_u32 v77, v77, 2, v67
	ds_read_b32 v99, v99
	ds_read_b32 v77, v77 offset:64
	v_xor_b32_e32 v93, 0xff, v89
	v_bfe_u32 v104, v93, 4, 4
	v_and_b32_e32 v93, 15, v93
	v_lshl_add_u32 v104, v104, 2, v67
	v_lshl_add_u32 v93, v93, 2, v67
	ds_read_b32 v104, v104
	ds_read_b32 v93, v93 offset:64
	v_xor_b32_e32 v136, 0xff, v116
	v_bfe_u32 v137, v136, 4, 4
	v_and_b32_e32 v136, 15, v136
	v_lshl_add_u32 v137, v137, 2, v67
	v_lshl_add_u32 v136, v136, 2, v67
	ds_read_b32 v137, v137
	ds_read_b32 v136, v136 offset:64
	s_waitcnt lgkmcnt(0)
	v_lshl_add_u32 v138, v107, 7, v106
	v_mul_f32_e32 v139, v132, v115
	v_lshl_add_u32 v140, v78, 7, v98
	v_mul_f32_e32 v141, v131, v115
	ds_write_b128 v68, v[138:141] offset:0
	v_lshl_add_u32 v138, v103, 7, v108
	v_mul_f32_e32 v139, v130, v115
	v_lshl_add_u32 v140, v92, 7, v72
	v_mul_f32_e32 v141, v129, v115
	ds_write_b128 v68, v[138:141] offset:16
	v_lshl_add_u32 v138, v119, 7, v75
	v_mul_f32_e32 v139, v128, v115
	v_lshl_add_u32 v140, v102, 7, v114
	v_mul_f32_e32 v141, v127, v115
	ds_write_b128 v68, v[138:141] offset:32
	v_lshl_add_u32 v138, v109, 7, v97
	v_mul_f32_e32 v139, v126, v115
	v_lshl_add_u32 v140, v74, 7, v83
	v_mul_f32_e32 v141, v125, v115
	ds_write_b128 v68, v[138:141] offset:48
	v_lshl_add_u32 v138, v101, 7, v80
	v_mul_f32_e32 v139, v124, v115
	v_lshl_add_u32 v140, v86, 7, v85
	v_mul_f32_e32 v141, v123, v115
	ds_write_b128 v68, v[138:141] offset:64
	v_lshl_add_u32 v138, v84, 7, v94
	v_mul_f32_e32 v139, v122, v115
	v_lshl_add_u32 v140, v76, 7, v100
	v_mul_f32_e32 v141, v121, v115
	ds_write_b128 v68, v[138:141] offset:80
	v_lshl_add_u32 v138, v135, 7, v95
	v_mul_f32_e32 v139, v120, v115
	v_lshl_add_u32 v140, v99, 7, v77
	v_mul_f32_e32 v141, v90, v115
	ds_write_b128 v68, v[138:141] offset:96
	v_lshl_add_u32 v138, v104, 7, v93
	v_mul_f32_e32 v139, v112, v115
	v_lshl_add_u32 v140, v137, 7, v136
	v_mul_f32_e32 v141, v105, v115
	ds_write_b128 v68, v[138:141] offset:112

; __device__ __forceinline__ unsigned pk2(float lo, float hi) { const f32x2 v = {lo, hi}; const bf16x2_t b = __builtin_convertvector(v, bf16x2_t); return __builtin_bit_cast(unsigned, b); }
; __device__ __forceinline__ float bflo(unsigned u) { return __uint_as_float(u << 16); }
; __device__ __forceinline__ float bfhi(unsigned u) { return __uint_as_float(u & 0xffff0000u); }
; __device__ __forceinline__ void peer_tile(const Args& A, LAS unsigned char* lds, int tile) {
;     ...
;     for (int pass = 0; pass < 2; ++pass) {
;         const int tb = 8 * w + 4 * pass;
;         u32x4 xpa[4], xpb[4]; f32x2 oacc[4][8];
; #pragma unroll
;         for (int tk = 0; tk < 4; ++tk) { const size_t m = (size_t)tile * 64 + tb + tk;
;             { const u32x4 ra = *(const u32x4*)(A3 + m * 1024 + 16 * lane), rb = *(const u32x4*)(A3 + m * 1024 + 16 * lane + 8);
;               float xr_; { const f32x4 p0 = *(const f32x4*)(RSq + m * 16), p1 = *(const f32x4*)(RSq + m * 16 + 4), p2 = *(const f32x4*)(RSq + m * 16 + 8), p3 = *(const f32x4*)(RSq + m * 16 + 12);
;                 const f32x4 ps = (p0 + p1) + (p2 + p3); xr_ = rsqrtf(((ps[0] + ps[1]) + (ps[2] + ps[3])) * (1.f / 1024.f) + 1e-6f); }
;               const unsigned rr[8] = {ra.x, ra.y, ra.z, ra.w, rb.x, rb.y, rb.z, rb.w}; unsigned hh[8];
;               const float* sp = MOD + (int)(m >> 11) * 6144 + 3072 + 16 * lane;
; #pragma unroll
;               for (int q = 0; q < 8; ++q) { const f32x2 sh = *(const f32x2*)(sp + 2 * q); hh[q] = pk2(bflo(rr[q]) * xr_ + sh[0], bfhi(rr[q]) * xr_ + sh[1]); }
;               xpa[tk] = (u32x4){hh[0], hh[1], hh[2], hh[3]}; xpb[tk] = (u32x4){hh[4], hh[5], hh[6], hh[7]}; }
; #pragma unroll
;             for (int q = 0; q < 8; ++q) oacc[tk][q] = (f32x2){0.f, 0.f}; }
	s_mov_b64 exec, -1
	v_and_b32_e32 v240, 63, v214
	v_lshrrev_b32_e32 v242, 6, v214
	v_lshlrev_b32_e32 v240, 4, v240
	v_readfirstlane_b32 s16, v242
	v_lshlrev_b32_e32 v245, 1, v240
	v_lshlrev_b32_e32 v246, 2, v240
	v_lshrrev_b32_e32 v247, 4, v240
	v_and_b32_e32 v247, 48, v247
	v_mov_b32_e32 v244, 0
	v_mov_b32_e32 v243, 0x358637bd
	v_mov_b32_e32 v242, 0xbf3a00e3
	s_add_u32 s4, s50, 0x1000000
	s_addc_u32 s5, s51, 0
	s_add_u32 s6, s50, 0x2000000
	s_addc_u32 s7, s51, 0
	s_add_u32 s8, s50, 0x3000000
	s_addc_u32 s9, s51, 0
	s_add_u32 s52, s50, 0x3010000
	s_addc_u32 s53, s51, 0
	s_add_u32 s12, s50, 0xb000000
	s_addc_u32 s13, s51, 0
	s_add_u32 s14, s50, 0xd000000
	s_addc_u32 s15, s51, 0
	s_lshr_b32 s0, s2, 5
	s_mul_i32 s0, s0, 0x6000
	s_add_u32 s10, s50, s0
	s_addc_u32 s11, s51, 0
	s_add_u32 s80, s10, 0x4000
	s_addc_u32 s81, s11, 0
	s_add_u32 s82, s10, 0x6000
	s_addc_u32 s83, s11, 0
	s_mul_i32 s22, s16, 9920
	s_cmp_eq_u32 s16, 7
	s_cselect_b32 s22, 0x21000, s22
	s_mov_b32 s85, 0xffffffff
	s_mov_b32 s72, 0x3e6d3388
	s_mov_b32 s56, s4
	s_and_b32 s57, s5, 0xffff
	s_or_b32 s57, s57, 0x04000000
	s_mov_b32 s58, 16384
	s_mov_b32 s59, 0x00027000
	s_mov_b32 s60, s6
	s_and_b32 s61, s7, 0xffff
	s_or_b32 s61, s61, 0x04000000
	s_mov_b32 s62, 16384
	s_mov_b32 s63, 0x00027000
	s_lshl_b32 s76, s16, 3
	s_lshl_b32 s0, s2, 6
	s_add_i32 s77, s0, s76
	global_load_dwordx4 v[192:195], v246, s[80:81] offset:0
	global_load_dwordx4 v[196:199], v246, s[80:81] offset:16
	global_load_dwordx4 v[200:203], v246, s[80:81] offset:32
	global_load_dwordx4 v[204:207], v246, s[80:81] offset:48
	s_add_i32 s0, s77, 0
	s_lshl_b32 s1, s0, 11
	s_add_u32 s78, s12, s1
	s_addc_u32 s79, s13, 0
	global_load_dwordx4 v[128:131], v245, s[78:79]
	global_load_dwordx4 v[132:135], v245, s[78:79] offset:16
	global_load_dwordx4 v[136:139], v245, s[78:79] offset:2048
	global_load_dwordx4 v[140:143], v245, s[78:79] offset:2064
	s_lshl_b32 s1, s0, 6
	s_add_u32 s78, s14, s1
	s_addc_u32 s79, s15, 0
	global_load_dwordx4 v[144:147], v244, s[78:79] offset:0
	global_load_dwordx4 v[148:151], v244, s[78:79] offset:16
	global_load_dwordx4 v[152:155], v244, s[78:79] offset:32
	global_load_dwordx4 v[156:159], v244, s[78:79] offset:48
	global_load_dwordx4 v[160:163], v244, s[78:79] offset:64
	global_load_dwordx4 v[164:167], v244, s[78:79] offset:80
	global_load_dwordx4 v[168:171], v244, s[78:79] offset:96
	global_load_dwordx4 v[172:175], v244, s[78:79] offset:112
	s_waitcnt lgkmcnt(0)
	s_barrier
	s_add_i32 s0, s77, 2
	s_lshl_b32 s1, s0, 11
	s_add_u32 s78, s12, s1
	s_addc_u32 s79, s13, 0
	global_load_dwordx4 v[176:179], v245, s[78:79]
	global_load_dwordx4 v[180:183], v245, s[78:79] offset:16
	global_load_dwordx4 v[184:187], v245, s[78:79] offset:2048
	global_load_dwordx4 v[188:191], v245, s[78:79] offset:2064
	s_lshl_b32 s1, s0, 6
	s_add_u32 s78, s14, s1
	s_addc_u32 s79, s15, 0
	global_load_dwordx4 v[216:219], v244, s[78:79] offset:0
	global_load_dwordx4 v[220:223], v244, s[78:79] offset:16
	global_load_dwordx4 v[224:227], v244, s[78:79] offset:32
	global_load_dwordx4 v[228:231], v244, s[78:79] offset:48
	global_load_dwordx4 v[232:235], v244, s[78:79] offset:64
	global_load_dwordx4 v[236:239], v244, s[78:79] offset:80
	global_load_dwordx4 v[248:251], v244, s[78:79] offset:96
	global_load_dwordx4 v[252:255], v244, s[78:79] offset:112
	s_waitcnt vmcnt(12)
	v_pk_add_f32 v[144:145], v[144:145], v[148:149]
	v_pk_add_f32 v[146:147], v[146:147], v[150:151]
	v_pk_add_f32 v[152:153], v[152:153], v[156:157]
	v_pk_add_f32 v[154:155], v[154:155], v[158:159]
	v_pk_add_f32 v[144:145], v[144:145], v[152:153]
	v_pk_add_f32 v[146:147], v[146:147], v[154:155]
	v_add_f32_e32 v144, v144, v145
	v_add_f32_e32 v146, v146, v147
	v_add_f32_e32 v144, v144, v146
	v_fmamk_f32 v144, v144, 0x3a800000, v243
	v_rsq_f32_e32 v144, v144
	v_pk_add_f32 v[160:161], v[160:161], v[164:165]
	v_pk_add_f32 v[162:163], v[162:163], v[166:167]
	v_pk_add_f32 v[168:169], v[168:169], v[172:173]
	v_pk_add_f32 v[170:171], v[170:171], v[174:175]
	v_pk_add_f32 v[160:161], v[160:161], v[168:169]
	v_pk_add_f32 v[162:163], v[162:163], v[170:171]
	v_add_f32_e32 v160, v160, v161
	v_add_f32_e32 v162, v162, v163
	v_add_f32_e32 v160, v160, v162
	v_fmamk_f32 v160, v160, 0x3a800000, v243
	v_rsq_f32_e32 v160, v160
	v_lshlrev_b32_e32 v208, 16, v128
	v_and_b32_e32 v209, 0xffff0000, v128
	v_fma_f32 v208, v208, v144, v192
	v_fma_f32 v209, v209, v144, v193
	v_cvt_pk_bf16_f32 v210, v208, v209
	v_lshlrev_b32_e32 v0, 16, v210
	v_and_b32_e32 v1, 0xffff0000, v210
	v_lshlrev_b32_e32 v208, 16, v129
	v_and_b32_e32 v209, 0xffff0000, v129
	v_fma_f32 v208, v208, v144, v194
	v_fma_f32 v209, v209, v144, v195
	v_cvt_pk_bf16_f32 v210, v208, v209
	v_lshlrev_b32_e32 v2, 16, v210
	v_and_b32_e32 v3, 0xffff0000, v210
	v_lshlrev_b32_e32 v208, 16, v130
	v_and_b32_e32 v209, 0xffff0000, v130
	v_fma_f32 v208, v208, v144, v196
	v_fma_f32 v209, v209, v144, v197
	v_cvt_pk_bf16_f32 v210, v208, v209
	v_lshlrev_b32_e32 v4, 16, v210
	v_and_b32_e32 v5, 0xffff0000, v210
	v_lshlrev_b32_e32 v208, 16, v131
	v_and_b32_e32 v209, 0xffff0000, v131
	v_fma_f32 v208, v208, v144, v198
	v_fma_f32 v209, v209, v144, v199
	v_cvt_pk_bf16_f32 v210, v208, v209
	v_lshlrev_b32_e32 v6, 16, v210
	v_and_b32_e32 v7, 0xffff0000, v210
	v_lshlrev_b32_e32 v208, 16, v132
	v_and_b32_e32 v209, 0xffff0000, v132
	v_fma_f32 v208, v208, v144, v200
	v_fma_f32 v209, v209, v144, v201
	v_cvt_pk_bf16_f32 v210, v208, v209
	v_lshlrev_b32_e32 v8, 16, v210
	v_and_b32_e32 v9, 0xffff0000, v210
	v_lshlrev_b32_e32 v208, 16, v133
	v_and_b32_e32 v209, 0xffff0000, v133
	v_fma_f32 v208, v208, v144, v202
	v_fma_f32 v209, v209, v144, v203
	v_cvt_pk_bf16_f32 v210, v208, v209
; __device__ __forceinline__ unsigned pk2(float lo, float hi) { const f32x2 v = {lo, hi}; const bf16x2_t b = __builtin_convertvector(v, bf16x2_t); return __builtin_bit_cast(unsigned, b); }
; __device__ __forceinline__ float bflo(unsigned u) { return __uint_as_float(u << 16); }
; __device__ __forceinline__ float bfhi(unsigned u) { return __uint_as_float(u & 0xffff0000u); }
; __device__ __forceinline__ void peer_tile(const Args& A, LAS unsigned char* lds, int tile) {
;     ...
;         for (int tk = 0; tk < 4; ++tk) { const size_t m = (size_t)tile * 64 + tb + tk;
;             { const u32x4 ra = *(const u32x4*)(A3 + m * 1024 + 16 * lane), rb = *(const u32x4*)(A3 + m * 1024 + 16 * lane + 8);
;               float xr_; { const f32x4 p0 = *(const f32x4*)(RSq + m * 16), p1 = *(const f32x4*)(RSq + m * 16 + 4), p2 = *(const f32x4*)(RSq + m * 16 + 8), p3 = *(const f32x4*)(RSq + m * 16 + 12);
;                 const f32x4 ps = (p0 + p1) + (p2 + p3); xr_ = rsqrtf(((ps[0] + ps[1]) + (ps[2] + ps[3])) * (1.f / 1024.f) + 1e-6f); }
;               const unsigned rr[8] = {ra.x, ra.y, ra.z, ra.w, rb.x, rb.y, rb.z, rb.w}; unsigned hh[8];
;               const float* sp = MOD + (int)(m >> 11) * 6144 + 3072 + 16 * lane;
; #pragma unroll
;               for (int q = 0; q < 8; ++q) { const f32x2 sh = *(const f32x2*)(sp + 2 * q); hh[q] = pk2(bflo(rr[q]) * xr_ + sh[0], bfhi(rr[q]) * xr_ + sh[1]); }
;               xpa[tk] = (u32x4){hh[0], hh[1], hh[2], hh[3]}; xpb[tk] = (u32x4){hh[4], hh[5], hh[6], hh[7]}; }
; #pragma unroll
;             for (int q = 0; q < 8; ++q) oacc[tk][q] = (f32x2){0.f, 0.f}; }
	v_lshlrev_b32_e32 v10, 16, v210
	v_and_b32_e32 v11, 0xffff0000, v210
	v_lshlrev_b32_e32 v208, 16, v134
	v_and_b32_e32 v209, 0xffff0000, v134
	v_fma_f32 v208, v208, v144, v204
	v_fma_f32 v209, v209, v144, v205
	v_cvt_pk_bf16_f32 v210, v208, v209
	v_lshlrev_b32_e32 v12, 16, v210
	v_and_b32_e32 v13, 0xffff0000, v210
	v_lshlrev_b32_e32 v208, 16, v135
	v_and_b32_e32 v209, 0xffff0000, v135
	v_fma_f32 v208, v208, v144, v206
	v_fma_f32 v209, v209, v144, v207
	v_cvt_pk_bf16_f32 v210, v208, v209
	v_lshlrev_b32_e32 v14, 16, v210
	v_and_b32_e32 v15, 0xffff0000, v210
	v_lshlrev_b32_e32 v208, 16, v136
	v_and_b32_e32 v209, 0xffff0000, v136
	v_fma_f32 v208, v208, v160, v192
	v_fma_f32 v209, v209, v160, v193
	v_cvt_pk_bf16_f32 v210, v208, v209
	v_lshlrev_b32_e32 v16, 16, v210
	v_and_b32_e32 v17, 0xffff0000, v210
	v_lshlrev_b32_e32 v208, 16, v137
	v_and_b32_e32 v209, 0xffff0000, v137
	v_fma_f32 v208, v208, v160, v194
	v_fma_f32 v209, v209, v160, v195
	v_cvt_pk_bf16_f32 v210, v208, v209
	v_lshlrev_b32_e32 v18, 16, v210
	v_and_b32_e32 v19, 0xffff0000, v210
	v_lshlrev_b32_e32 v208, 16, v138
	v_and_b32_e32 v209, 0xffff0000, v138
	v_fma_f32 v208, v208, v160, v196
	v_fma_f32 v209, v209, v160, v197
	v_cvt_pk_bf16_f32 v210, v208, v209
	v_lshlrev_b32_e32 v20, 16, v210
	v_and_b32_e32 v21, 0xffff0000, v210
	v_lshlrev_b32_e32 v208, 16, v139
	v_and_b32_e32 v209, 0xffff0000, v139
	v_fma_f32 v208, v208, v160, v198
	v_fma_f32 v209, v209, v160, v199
	v_cvt_pk_bf16_f32 v210, v208, v209
	v_lshlrev_b32_e32 v22, 16, v210
	v_and_b32_e32 v23, 0xffff0000, v210
	v_lshlrev_b32_e32 v208, 16, v140
	v_and_b32_e32 v209, 0xffff0000, v140
	v_fma_f32 v208, v208, v160, v200
	v_fma_f32 v209, v209, v160, v201
	v_cvt_pk_bf16_f32 v210, v208, v209
	v_lshlrev_b32_e32 v24, 16, v210
	v_and_b32_e32 v25, 0xffff0000, v210
	v_lshlrev_b32_e32 v208, 16, v141
	v_and_b32_e32 v209, 0xffff0000, v141
	v_fma_f32 v208, v208, v160, v202
	v_fma_f32 v209, v209, v160, v203
	v_cvt_pk_bf16_f32 v210, v208, v209
	v_lshlrev_b32_e32 v26, 16, v210
	v_and_b32_e32 v27, 0xffff0000, v210
	v_lshlrev_b32_e32 v208, 16, v142
	v_and_b32_e32 v209, 0xffff0000, v142
	v_fma_f32 v208, v208, v160, v204
	v_fma_f32 v209, v209, v160, v205
	v_cvt_pk_bf16_f32 v210, v208, v209
	v_lshlrev_b32_e32 v28, 16, v210
	v_and_b32_e32 v29, 0xffff0000, v210
	v_lshlrev_b32_e32 v208, 16, v143
	v_and_b32_e32 v209, 0xffff0000, v143
	v_fma_f32 v208, v208, v160, v206
	v_fma_f32 v209, v209, v160, v207
	v_cvt_pk_bf16_f32 v210, v208, v209
	v_lshlrev_b32_e32 v30, 16, v210
	v_and_b32_e32 v31, 0xffff0000, v210
	s_nop 0
	s_add_i32 s0, s77, 4
	s_lshl_b32 s1, s0, 11
	s_add_u32 s78, s12, s1
	s_addc_u32 s79, s13, 0
	global_load_dwordx4 v[128:131], v245, s[78:79]
	global_load_dwordx4 v[132:135], v245, s[78:79] offset:16
	global_load_dwordx4 v[136:139], v245, s[78:79] offset:2048
	global_load_dwordx4 v[140:143], v245, s[78:79] offset:2064
	s_lshl_b32 s1, s0, 6
	s_add_u32 s78, s14, s1
	s_addc_u32 s79, s15, 0
	global_load_dwordx4 v[144:147], v244, s[78:79] offset:0
	global_load_dwordx4 v[148:151], v244, s[78:79] offset:16
	global_load_dwordx4 v[152:155], v244, s[78:79] offset:32
	global_load_dwordx4 v[156:159], v244, s[78:79] offset:48
	global_load_dwordx4 v[160:163], v244, s[78:79] offset:64
	global_load_dwordx4 v[164:167], v244, s[78:79] offset:80
	global_load_dwordx4 v[168:171], v244, s[78:79] offset:96
	global_load_dwordx4 v[172:175], v244, s[78:79] offset:112
	s_waitcnt vmcnt(12)
	v_pk_add_f32 v[216:217], v[216:217], v[220:221]
	v_pk_add_f32 v[218:219], v[218:219], v[222:223]
	v_pk_add_f32 v[224:225], v[224:225], v[228:229]
	v_pk_add_f32 v[226:227], v[226:227], v[230:231]
	v_pk_add_f32 v[216:217], v[216:217], v[224:225]
	v_pk_add_f32 v[218:219], v[218:219], v[226:227]
	v_add_f32_e32 v216, v216, v217
	v_add_f32_e32 v218, v218, v219
	v_add_f32_e32 v216, v216, v218
	v_fmamk_f32 v216, v216, 0x3a800000, v243
	v_rsq_f32_e32 v216, v216
	v_pk_add_f32 v[232:233], v[232:233], v[236:237]
	v_pk_add_f32 v[234:235], v[234:235], v[238:239]
	v_pk_add_f32 v[248:249], v[248:249], v[252:253]
	v_pk_add_f32 v[250:251], v[250:251], v[254:255]
	v_pk_add_f32 v[232:233], v[232:233], v[248:249]
	v_pk_add_f32 v[234:235], v[234:235], v[250:251]
	v_add_f32_e32 v232, v232, v233
	v_add_f32_e32 v234, v234, v235
	v_add_f32_e32 v232, v232, v234
	v_fmamk_f32 v232, v232, 0x3a800000, v243
	v_rsq_f32_e32 v232, v232
	v_lshlrev_b32_e32 v208, 16, v176
	v_and_b32_e32 v209, 0xffff0000, v176
	v_fma_f32 v208, v208, v216, v192
	v_fma_f32 v209, v209, v216, v193
	v_cvt_pk_bf16_f32 v210, v208, v209
	v_lshlrev_b32_e32 v32, 16, v210
	v_and_b32_e32 v33, 0xffff0000, v210
	v_lshlrev_b32_e32 v208, 16, v177
	v_and_b32_e32 v209, 0xffff0000, v177
	v_fma_f32 v208, v208, v216, v194
	v_fma_f32 v209, v209, v216, v195
	v_cvt_pk_bf16_f32 v210, v208, v209
	v_lshlrev_b32_e32 v34, 16, v210
	v_and_b32_e32 v35, 0xffff0000, v210
	v_lshlrev_b32_e32 v208, 16, v178
	v_and_b32_e32 v209, 0xffff0000, v178
	v_fma_f32 v208, v208, v216, v196
	v_fma_f32 v209, v209, v216, v197
	v_cvt_pk_bf16_f32 v210, v208, v209
	v_lshlrev_b32_e32 v36, 16, v210
	v_and_b32_e32 v37, 0xffff0000, v210
	v_lshlrev_b32_e32 v208, 16, v179
	v_and_b32_e32 v209, 0xffff0000, v179
	v_fma_f32 v208, v208, v216, v198
	v_fma_f32 v209, v209, v216, v199
	v_cvt_pk_bf16_f32 v210, v208, v209
	v_lshlrev_b32_e32 v38, 16, v210
	v_and_b32_e32 v39, 0xffff0000, v210
	v_lshlrev_b32_e32 v208, 16, v180
	v_and_b32_e32 v209, 0xffff0000, v180
	v_fma_f32 v208, v208, v216, v200
	v_fma_f32 v209, v209, v216, v201
	v_cvt_pk_bf16_f32 v210, v208, v209
	v_lshlrev_b32_e32 v40, 16, v210
	v_and_b32_e32 v41, 0xffff0000, v210
	v_lshlrev_b32_e32 v208, 16, v181
	v_and_b32_e32 v209, 0xffff0000, v181
; __device__ __forceinline__ unsigned pk2(float lo, float hi) { const f32x2 v = {lo, hi}; const bf16x2_t b = __builtin_convertvector(v, bf16x2_t); return __builtin_bit_cast(unsigned, b); }
; __device__ __forceinline__ float bflo(unsigned u) { return __uint_as_float(u << 16); }
; __device__ __forceinline__ float bfhi(unsigned u) { return __uint_as_float(u & 0xffff0000u); }
; __device__ __forceinline__ void peer_tile(const Args& A, LAS unsigned char* lds, int tile) {
;     ...
;         for (int tk = 0; tk < 4; ++tk) { const size_t m = (size_t)tile * 64 + tb + tk;
;             { const u32x4 ra = *(const u32x4*)(A3 + m * 1024 + 16 * lane), rb = *(const u32x4*)(A3 + m * 1024 + 16 * lane + 8);
;               float xr_; { const f32x4 p0 = *(const f32x4*)(RSq + m * 16), p1 = *(const f32x4*)(RSq + m * 16 + 4), p2 = *(const f32x4*)(RSq + m * 16 + 8), p3 = *(const f32x4*)(RSq + m * 16 + 12);
;                 const f32x4 ps = (p0 + p1) + (p2 + p3); xr_ = rsqrtf(((ps[0] + ps[1]) + (ps[2] + ps[3])) * (1.f / 1024.f) + 1e-6f); }
;               const unsigned rr[8] = {ra.x, ra.y, ra.z, ra.w, rb.x, rb.y, rb.z, rb.w}; unsigned hh[8];
;               const float* sp = MOD + (int)(m >> 11) * 6144 + 3072 + 16 * lane;
; #pragma unroll
;               for (int q = 0; q < 8; ++q) { const f32x2 sh = *(const f32x2*)(sp + 2 * q); hh[q] = pk2(bflo(rr[q]) * xr_ + sh[0], bfhi(rr[q]) * xr_ + sh[1]); }
;               xpa[tk] = (u32x4){hh[0], hh[1], hh[2], hh[3]}; xpb[tk] = (u32x4){hh[4], hh[5], hh[6], hh[7]}; }
;     ...
;                 { const unsigned xx[8] = {xpa[tk].x, xpa[tk].y, xpa[tk].z, xpa[tk].w, xpb[tk].x, xpb[tk].y, xpb[tk].z, xpb[tk].w};
; #pragma unroll
;                   for (int q = 0; q < 8; ++q) xf[q] = (f32x2){bflo(xx[q]), bfhi(xx[q])}; }
	v_fma_f32 v208, v208, v216, v202
	v_fma_f32 v209, v209, v216, v203
	v_cvt_pk_bf16_f32 v210, v208, v209
	v_lshlrev_b32_e32 v42, 16, v210
	v_and_b32_e32 v43, 0xffff0000, v210
	v_lshlrev_b32_e32 v208, 16, v182
	v_and_b32_e32 v209, 0xffff0000, v182
	v_fma_f32 v208, v208, v216, v204
	v_fma_f32 v209, v209, v216, v205
	v_cvt_pk_bf16_f32 v210, v208, v209
	v_lshlrev_b32_e32 v44, 16, v210
	v_and_b32_e32 v45, 0xffff0000, v210
	v_lshlrev_b32_e32 v208, 16, v183
	v_and_b32_e32 v209, 0xffff0000, v183
	v_fma_f32 v208, v208, v216, v206
	v_fma_f32 v209, v209, v216, v207
	v_cvt_pk_bf16_f32 v210, v208, v209
	v_lshlrev_b32_e32 v46, 16, v210
	v_and_b32_e32 v47, 0xffff0000, v210
	v_lshlrev_b32_e32 v208, 16, v184
	v_and_b32_e32 v209, 0xffff0000, v184
	v_fma_f32 v208, v208, v232, v192
	v_fma_f32 v209, v209, v232, v193
	v_cvt_pk_bf16_f32 v210, v208, v209
	v_lshlrev_b32_e32 v48, 16, v210
	v_and_b32_e32 v49, 0xffff0000, v210
	v_lshlrev_b32_e32 v208, 16, v185
	v_and_b32_e32 v209, 0xffff0000, v185
	v_fma_f32 v208, v208, v232, v194
	v_fma_f32 v209, v209, v232, v195
	v_cvt_pk_bf16_f32 v210, v208, v209
	v_lshlrev_b32_e32 v50, 16, v210
	v_and_b32_e32 v51, 0xffff0000, v210
	v_lshlrev_b32_e32 v208, 16, v186
	v_and_b32_e32 v209, 0xffff0000, v186
	v_fma_f32 v208, v208, v232, v196
	v_fma_f32 v209, v209, v232, v197
	v_cvt_pk_bf16_f32 v210, v208, v209
	v_lshlrev_b32_e32 v52, 16, v210
	v_and_b32_e32 v53, 0xffff0000, v210
	v_lshlrev_b32_e32 v208, 16, v187
	v_and_b32_e32 v209, 0xffff0000, v187
	v_fma_f32 v208, v208, v232, v198
	v_fma_f32 v209, v209, v232, v199
	v_cvt_pk_bf16_f32 v210, v208, v209
	v_lshlrev_b32_e32 v54, 16, v210
	v_and_b32_e32 v55, 0xffff0000, v210
	v_lshlrev_b32_e32 v208, 16, v188
	v_and_b32_e32 v209, 0xffff0000, v188
	v_fma_f32 v208, v208, v232, v200
	v_fma_f32 v209, v209, v232, v201
	v_cvt_pk_bf16_f32 v210, v208, v209
	v_lshlrev_b32_e32 v56, 16, v210
	v_and_b32_e32 v57, 0xffff0000, v210
	v_lshlrev_b32_e32 v208, 16, v189
	v_and_b32_e32 v209, 0xffff0000, v189
	v_fma_f32 v208, v208, v232, v202
	v_fma_f32 v209, v209, v232, v203
	v_cvt_pk_bf16_f32 v210, v208, v209
	v_lshlrev_b32_e32 v58, 16, v210
	v_and_b32_e32 v59, 0xffff0000, v210
	v_lshlrev_b32_e32 v208, 16, v190
	v_and_b32_e32 v209, 0xffff0000, v190
	v_fma_f32 v208, v208, v232, v204
	v_fma_f32 v209, v209, v232, v205
	v_cvt_pk_bf16_f32 v210, v208, v209
	v_lshlrev_b32_e32 v60, 16, v210
	v_and_b32_e32 v61, 0xffff0000, v210
	v_lshlrev_b32_e32 v208, 16, v191
	v_and_b32_e32 v209, 0xffff0000, v191
	v_fma_f32 v208, v208, v232, v206
	v_fma_f32 v209, v209, v232, v207
	v_cvt_pk_bf16_f32 v210, v208, v209
	v_lshlrev_b32_e32 v62, 16, v210
	v_and_b32_e32 v63, 0xffff0000, v210
	s_nop 0
	s_add_i32 s0, s77, 6
	s_lshl_b32 s1, s0, 11
	s_add_u32 s78, s12, s1
	s_addc_u32 s79, s13, 0
	global_load_dwordx4 v[176:179], v245, s[78:79]
	global_load_dwordx4 v[180:183], v245, s[78:79] offset:16
	global_load_dwordx4 v[184:187], v245, s[78:79] offset:2048
	global_load_dwordx4 v[188:191], v245, s[78:79] offset:2064
	s_lshl_b32 s1, s0, 6
	s_add_u32 s78, s14, s1
	s_addc_u32 s79, s15, 0
	global_load_dwordx4 v[216:219], v244, s[78:79] offset:0
	global_load_dwordx4 v[220:223], v244, s[78:79] offset:16
	global_load_dwordx4 v[224:227], v244, s[78:79] offset:32
	global_load_dwordx4 v[228:231], v244, s[78:79] offset:48
	global_load_dwordx4 v[232:235], v244, s[78:79] offset:64
	global_load_dwordx4 v[236:239], v244, s[78:79] offset:80
	global_load_dwordx4 v[248:251], v244, s[78:79] offset:96
	global_load_dwordx4 v[252:255], v244, s[78:79] offset:112
	s_waitcnt vmcnt(12)
	v_pk_add_f32 v[144:145], v[144:145], v[148:149]
	v_pk_add_f32 v[146:147], v[146:147], v[150:151]
	v_pk_add_f32 v[152:153], v[152:153], v[156:157]
	v_pk_add_f32 v[154:155], v[154:155], v[158:159]
	v_pk_add_f32 v[144:145], v[144:145], v[152:153]
	v_pk_add_f32 v[146:147], v[146:147], v[154:155]
	v_add_f32_e32 v144, v144, v145
	v_add_f32_e32 v146, v146, v147
	v_add_f32_e32 v144, v144, v146
	v_fmamk_f32 v144, v144, 0x3a800000, v243
	v_rsq_f32_e32 v144, v144
	v_pk_add_f32 v[160:161], v[160:161], v[164:165]
	v_pk_add_f32 v[162:163], v[162:163], v[166:167]
	v_pk_add_f32 v[168:169], v[168:169], v[172:173]
	v_pk_add_f32 v[170:171], v[170:171], v[174:175]
	v_pk_add_f32 v[160:161], v[160:161], v[168:169]
	v_pk_add_f32 v[162:163], v[162:163], v[170:171]
	v_add_f32_e32 v160, v160, v161
	v_add_f32_e32 v162, v162, v163
	v_add_f32_e32 v160, v160, v162
	v_fmamk_f32 v160, v160, 0x3a800000, v243
	v_rsq_f32_e32 v160, v160
	v_lshlrev_b32_e32 v208, 16, v128
	v_and_b32_e32 v209, 0xffff0000, v128
	v_fma_f32 v208, v208, v144, v192
	v_fma_f32 v209, v209, v144, v193
	v_cvt_pk_bf16_f32 v210, v208, v209
	v_lshlrev_b32_e32 v64, 16, v210
	v_and_b32_e32 v65, 0xffff0000, v210
	v_lshlrev_b32_e32 v208, 16, v129
	v_and_b32_e32 v209, 0xffff0000, v129
	v_fma_f32 v208, v208, v144, v194
	v_fma_f32 v209, v209, v144, v195
	v_cvt_pk_bf16_f32 v210, v208, v209
	v_lshlrev_b32_e32 v66, 16, v210
	v_and_b32_e32 v67, 0xffff0000, v210
	v_lshlrev_b32_e32 v208, 16, v130
	v_and_b32_e32 v209, 0xffff0000, v130
	v_fma_f32 v208, v208, v144, v196
	v_fma_f32 v209, v209, v144, v197
	v_cvt_pk_bf16_f32 v210, v208, v209
	v_lshlrev_b32_e32 v68, 16, v210
	v_and_b32_e32 v69, 0xffff0000, v210
	v_lshlrev_b32_e32 v208, 16, v131
	v_and_b32_e32 v209, 0xffff0000, v131
	v_fma_f32 v208, v208, v144, v198
	v_fma_f32 v209, v209, v144, v199
	v_cvt_pk_bf16_f32 v210, v208, v209
	v_lshlrev_b32_e32 v70, 16, v210
	v_and_b32_e32 v71, 0xffff0000, v210
	v_lshlrev_b32_e32 v208, 16, v132
	v_and_b32_e32 v209, 0xffff0000, v132
	v_fma_f32 v208, v208, v144, v200
	v_fma_f32 v209, v209, v144, v201
	v_cvt_pk_bf16_f32 v210, v208, v209
	v_lshlrev_b32_e32 v72, 16, v210
; __device__ __forceinline__ unsigned pk2(float lo, float hi) { const f32x2 v = {lo, hi}; const bf16x2_t b = __builtin_convertvector(v, bf16x2_t); return __builtin_bit_cast(unsigned, b); }
; __device__ __forceinline__ float bflo(unsigned u) { return __uint_as_float(u << 16); }
; __device__ __forceinline__ float bfhi(unsigned u) { return __uint_as_float(u & 0xffff0000u); }
; __device__ __forceinline__ void peer_tile(const Args& A, LAS unsigned char* lds, int tile) {
;     ...
;         for (int tk = 0; tk < 4; ++tk) { const size_t m = (size_t)tile * 64 + tb + tk;
;             { const u32x4 ra = *(const u32x4*)(A3 + m * 1024 + 16 * lane), rb = *(const u32x4*)(A3 + m * 1024 + 16 * lane + 8);
;               float xr_; { const f32x4 p0 = *(const f32x4*)(RSq + m * 16), p1 = *(const f32x4*)(RSq + m * 16 + 4), p2 = *(const f32x4*)(RSq + m * 16 + 8), p3 = *(const f32x4*)(RSq + m * 16 + 12);
;                 const f32x4 ps = (p0 + p1) + (p2 + p3); xr_ = rsqrtf(((ps[0] + ps[1]) + (ps[2] + ps[3])) * (1.f / 1024.f) + 1e-6f); }
;               const unsigned rr[8] = {ra.x, ra.y, ra.z, ra.w, rb.x, rb.y, rb.z, rb.w}; unsigned hh[8];
;               const float* sp = MOD + (int)(m >> 11) * 6144 + 3072 + 16 * lane;
; #pragma unroll
;               for (int q = 0; q < 8; ++q) { const f32x2 sh = *(const f32x2*)(sp + 2 * q); hh[q] = pk2(bflo(rr[q]) * xr_ + sh[0], bfhi(rr[q]) * xr_ + sh[1]); }
;               xpa[tk] = (u32x4){hh[0], hh[1], hh[2], hh[3]}; xpb[tk] = (u32x4){hh[4], hh[5], hh[6], hh[7]}; }
;     ...
;                 { const unsigned xx[8] = {xpa[tk].x, xpa[tk].y, xpa[tk].z, xpa[tk].w, xpb[tk].x, xpb[tk].y, xpb[tk].z, xpb[tk].w};
; #pragma unroll
;                   for (int q = 0; q < 8; ++q) xf[q] = (f32x2){bflo(xx[q]), bfhi(xx[q])}; }
	v_and_b32_e32 v73, 0xffff0000, v210
	v_lshlrev_b32_e32 v208, 16, v133
	v_and_b32_e32 v209, 0xffff0000, v133
	v_fma_f32 v208, v208, v144, v202
	v_fma_f32 v209, v209, v144, v203
	v_cvt_pk_bf16_f32 v210, v208, v209
	v_lshlrev_b32_e32 v74, 16, v210
	v_and_b32_e32 v75, 0xffff0000, v210
	v_lshlrev_b32_e32 v208, 16, v134
	v_and_b32_e32 v209, 0xffff0000, v134
	v_fma_f32 v208, v208, v144, v204
	v_fma_f32 v209, v209, v144, v205
	v_cvt_pk_bf16_f32 v210, v208, v209
	v_lshlrev_b32_e32 v76, 16, v210
	v_and_b32_e32 v77, 0xffff0000, v210
	v_lshlrev_b32_e32 v208, 16, v135
	v_and_b32_e32 v209, 0xffff0000, v135
	v_fma_f32 v208, v208, v144, v206
	v_fma_f32 v209, v209, v144, v207
	v_cvt_pk_bf16_f32 v210, v208, v209
	v_lshlrev_b32_e32 v78, 16, v210
	v_and_b32_e32 v79, 0xffff0000, v210
	v_lshlrev_b32_e32 v208, 16, v136
	v_and_b32_e32 v209, 0xffff0000, v136
	v_fma_f32 v208, v208, v160, v192
	v_fma_f32 v209, v209, v160, v193
	v_cvt_pk_bf16_f32 v210, v208, v209
	v_lshlrev_b32_e32 v80, 16, v210
	v_and_b32_e32 v81, 0xffff0000, v210
	v_lshlrev_b32_e32 v208, 16, v137
	v_and_b32_e32 v209, 0xffff0000, v137
	v_fma_f32 v208, v208, v160, v194
	v_fma_f32 v209, v209, v160, v195
	v_cvt_pk_bf16_f32 v210, v208, v209
	v_lshlrev_b32_e32 v82, 16, v210
	v_and_b32_e32 v83, 0xffff0000, v210
	v_lshlrev_b32_e32 v208, 16, v138
	v_and_b32_e32 v209, 0xffff0000, v138
	v_fma_f32 v208, v208, v160, v196
	v_fma_f32 v209, v209, v160, v197
	v_cvt_pk_bf16_f32 v210, v208, v209
	v_lshlrev_b32_e32 v84, 16, v210
	v_and_b32_e32 v85, 0xffff0000, v210
	v_lshlrev_b32_e32 v208, 16, v139
	v_and_b32_e32 v209, 0xffff0000, v139
	v_fma_f32 v208, v208, v160, v198
	v_fma_f32 v209, v209, v160, v199
	v_cvt_pk_bf16_f32 v210, v208, v209
	v_lshlrev_b32_e32 v86, 16, v210
	v_and_b32_e32 v87, 0xffff0000, v210
	v_lshlrev_b32_e32 v208, 16, v140
	v_and_b32_e32 v209, 0xffff0000, v140
	v_fma_f32 v208, v208, v160, v200
	v_fma_f32 v209, v209, v160, v201
	v_cvt_pk_bf16_f32 v210, v208, v209
	v_lshlrev_b32_e32 v88, 16, v210
	v_and_b32_e32 v89, 0xffff0000, v210
	v_lshlrev_b32_e32 v208, 16, v141
	v_and_b32_e32 v209, 0xffff0000, v141
	v_fma_f32 v208, v208, v160, v202
	v_fma_f32 v209, v209, v160, v203
	v_cvt_pk_bf16_f32 v210, v208, v209
	v_lshlrev_b32_e32 v90, 16, v210
	v_and_b32_e32 v91, 0xffff0000, v210
	v_lshlrev_b32_e32 v208, 16, v142
	v_and_b32_e32 v209, 0xffff0000, v142
	v_fma_f32 v208, v208, v160, v204
	v_fma_f32 v209, v209, v160, v205
	v_cvt_pk_bf16_f32 v210, v208, v209
	v_lshlrev_b32_e32 v92, 16, v210
	v_and_b32_e32 v93, 0xffff0000, v210
	v_lshlrev_b32_e32 v208, 16, v143
	v_and_b32_e32 v209, 0xffff0000, v143
	v_fma_f32 v208, v208, v160, v206
	v_fma_f32 v209, v209, v160, v207
	v_cvt_pk_bf16_f32 v210, v208, v209
	v_lshlrev_b32_e32 v94, 16, v210
	v_and_b32_e32 v95, 0xffff0000, v210
	s_nop 0
	s_waitcnt vmcnt(0)
	v_pk_add_f32 v[216:217], v[216:217], v[220:221]
	v_pk_add_f32 v[218:219], v[218:219], v[222:223]
	v_pk_add_f32 v[224:225], v[224:225], v[228:229]
	v_pk_add_f32 v[226:227], v[226:227], v[230:231]
	v_pk_add_f32 v[216:217], v[216:217], v[224:225]
	v_pk_add_f32 v[218:219], v[218:219], v[226:227]
	v_add_f32_e32 v216, v216, v217
	v_add_f32_e32 v218, v218, v219
	v_add_f32_e32 v216, v216, v218
	v_fmamk_f32 v216, v216, 0x3a800000, v243
	v_rsq_f32_e32 v216, v216
	v_pk_add_f32 v[232:233], v[232:233], v[236:237]
	v_pk_add_f32 v[234:235], v[234:235], v[238:239]
	v_pk_add_f32 v[248:249], v[248:249], v[252:253]
	v_pk_add_f32 v[250:251], v[250:251], v[254:255]
	v_pk_add_f32 v[232:233], v[232:233], v[248:249]
	v_pk_add_f32 v[234:235], v[234:235], v[250:251]
	v_add_f32_e32 v232, v232, v233
	v_add_f32_e32 v234, v234, v235
	v_add_f32_e32 v232, v232, v234
	v_fmamk_f32 v232, v232, 0x3a800000, v243
	v_rsq_f32_e32 v232, v232
	v_lshlrev_b32_e32 v208, 16, v176
	v_and_b32_e32 v209, 0xffff0000, v176
	v_fma_f32 v208, v208, v216, v192
	v_fma_f32 v209, v209, v216, v193
	v_cvt_pk_bf16_f32 v210, v208, v209
	v_lshlrev_b32_e32 v96, 16, v210
	v_and_b32_e32 v97, 0xffff0000, v210
	v_lshlrev_b32_e32 v208, 16, v177
	v_and_b32_e32 v209, 0xffff0000, v177
	v_fma_f32 v208, v208, v216, v194
	v_fma_f32 v209, v209, v216, v195
	v_cvt_pk_bf16_f32 v210, v208, v209
	v_lshlrev_b32_e32 v98, 16, v210
	v_and_b32_e32 v99, 0xffff0000, v210
	v_lshlrev_b32_e32 v208, 16, v178
	v_and_b32_e32 v209, 0xffff0000, v178
	v_fma_f32 v208, v208, v216, v196
	v_fma_f32 v209, v209, v216, v197
	v_cvt_pk_bf16_f32 v210, v208, v209
	v_lshlrev_b32_e32 v100, 16, v210
	v_and_b32_e32 v101, 0xffff0000, v210
	v_lshlrev_b32_e32 v208, 16, v179
	v_and_b32_e32 v209, 0xffff0000, v179
	v_fma_f32 v208, v208, v216, v198
	v_fma_f32 v209, v209, v216, v199
	v_cvt_pk_bf16_f32 v210, v208, v209
	v_lshlrev_b32_e32 v102, 16, v210
	v_and_b32_e32 v103, 0xffff0000, v210
	v_lshlrev_b32_e32 v208, 16, v180
	v_and_b32_e32 v209, 0xffff0000, v180
	v_fma_f32 v208, v208, v216, v200
	v_fma_f32 v209, v209, v216, v201
	v_cvt_pk_bf16_f32 v210, v208, v209
	v_lshlrev_b32_e32 v104, 16, v210
	v_and_b32_e32 v105, 0xffff0000, v210
	v_lshlrev_b32_e32 v208, 16, v181
	v_and_b32_e32 v209, 0xffff0000, v181
	v_fma_f32 v208, v208, v216, v202
	v_fma_f32 v209, v209, v216, v203
	v_cvt_pk_bf16_f32 v210, v208, v209
	v_lshlrev_b32_e32 v106, 16, v210
	v_and_b32_e32 v107, 0xffff0000, v210
	v_lshlrev_b32_e32 v208, 16, v182
	v_and_b32_e32 v209, 0xffff0000, v182
	v_fma_f32 v208, v208, v216, v204
	v_fma_f32 v209, v209, v216, v205
	v_cvt_pk_bf16_f32 v210, v208, v209
	v_lshlrev_b32_e32 v108, 16, v210
	v_and_b32_e32 v109, 0xffff0000, v210
	v_lshlrev_b32_e32 v208, 16, v183
	v_and_b32_e32 v209, 0xffff0000, v183
	v_fma_f32 v208, v208, v216, v206
	v_fma_f32 v209, v209, v216, v207
	v_cvt_pk_bf16_f32 v210, v208, v209
	v_lshlrev_b32_e32 v110, 16, v210
; #define LAS __attribute__((address_space(3)))
; __device__ __forceinline__ float bflo(unsigned u) { return __uint_as_float(u << 16); }
; __device__ __forceinline__ float bfhi(unsigned u) { return __uint_as_float(u & 0xffff0000u); }
; __device__ __forceinline__ void peer_tile(const Args& A, LAS unsigned char* lds, int tile) {
;     ...
;     const unsigned char* T8 = A.ws + WS_T8; const float* SC = (const float*)(A.ws + WS_SC);
;     LAS u32x2* SORT = (LAS u32x2*)(lds + PE_IDX);
;     LAS int* OFFS = (LAS int*)(lds + PE_SEL + 65536);
;     for (int ti = 0; ti < 8; ++ti) {
;         const int tl = 8 * w + ti;
;         const u32x2 e0 = SEL[tl * 128 + lane], e1 = SEL[tl * 128 + 64 + lane];
;         const int p0 = (int)(e0.x >> 10), p1 = (int)(e1.x >> 10);
;         int off = 0;
;         for (int p = 0; p < 16; ++p) {
;             const unsigned long long m0 = __ballot(p0 == p), m1 = __ballot(p1 == p);
;             const int c0 = __popcll(m0), c1 = __popcll(m1);
;             const int r0 = __builtin_amdgcn_mbcnt_hi((unsigned)(m0 >> 32), __builtin_amdgcn_mbcnt_lo((unsigned)m0, 0u));
;             const int r1 = __builtin_amdgcn_mbcnt_hi((unsigned)(m1 >> 32), __builtin_amdgcn_mbcnt_lo((unsigned)m1, 0u));
;             if (p0 == p) SORT[tl * 128 + off + r0] = e0;
;             if (p1 == p) SORT[tl * 128 + off + c0 + r1] = e1;
;             if (lane == 0) OFFS[tl * 17 + p] = off;
;             off += c0 + c1;
;         }
;         if (lane == 0) OFFS[tl * 17 + 16] = off;
;     }
;     ...
;                 { const unsigned xx[8] = {xpa[tk].x, xpa[tk].y, xpa[tk].z, xpa[tk].w, xpb[tk].x, xpb[tk].y, xpb[tk].z, xpb[tk].w};
; #pragma unroll
;                   for (int q = 0; q < 8; ++q) xf[q] = (f32x2){bflo(xx[q]), bfhi(xx[q])}; }
	v_and_b32_e32 v111, 0xffff0000, v210
	v_lshlrev_b32_e32 v208, 16, v184
	v_and_b32_e32 v209, 0xffff0000, v184
	v_fma_f32 v208, v208, v232, v192
	v_fma_f32 v209, v209, v232, v193
	v_cvt_pk_bf16_f32 v210, v208, v209
	v_lshlrev_b32_e32 v112, 16, v210
	v_and_b32_e32 v113, 0xffff0000, v210
	v_lshlrev_b32_e32 v208, 16, v185
	v_and_b32_e32 v209, 0xffff0000, v185
	v_fma_f32 v208, v208, v232, v194
	v_fma_f32 v209, v209, v232, v195
	v_cvt_pk_bf16_f32 v210, v208, v209
	v_lshlrev_b32_e32 v114, 16, v210
	v_and_b32_e32 v115, 0xffff0000, v210
	v_lshlrev_b32_e32 v208, 16, v186
	v_and_b32_e32 v209, 0xffff0000, v186
	v_fma_f32 v208, v208, v232, v196
	v_fma_f32 v209, v209, v232, v197
	v_cvt_pk_bf16_f32 v210, v208, v209
	v_lshlrev_b32_e32 v116, 16, v210
	v_and_b32_e32 v117, 0xffff0000, v210
	v_lshlrev_b32_e32 v208, 16, v187
	v_and_b32_e32 v209, 0xffff0000, v187
	v_fma_f32 v208, v208, v232, v198
	v_fma_f32 v209, v209, v232, v199
	v_cvt_pk_bf16_f32 v210, v208, v209
	v_lshlrev_b32_e32 v118, 16, v210
	v_and_b32_e32 v119, 0xffff0000, v210
	v_lshlrev_b32_e32 v208, 16, v188
	v_and_b32_e32 v209, 0xffff0000, v188
	v_fma_f32 v208, v208, v232, v200
	v_fma_f32 v209, v209, v232, v201
	v_cvt_pk_bf16_f32 v210, v208, v209
	v_lshlrev_b32_e32 v120, 16, v210
	v_and_b32_e32 v121, 0xffff0000, v210
	v_lshlrev_b32_e32 v208, 16, v189
	v_and_b32_e32 v209, 0xffff0000, v189
	v_fma_f32 v208, v208, v232, v202
	v_fma_f32 v209, v209, v232, v203
	v_cvt_pk_bf16_f32 v210, v208, v209
	v_lshlrev_b32_e32 v122, 16, v210
	v_and_b32_e32 v123, 0xffff0000, v210
	v_lshlrev_b32_e32 v208, 16, v190
	v_and_b32_e32 v209, 0xffff0000, v190
	v_fma_f32 v208, v208, v232, v204
	v_fma_f32 v209, v209, v232, v205
	v_cvt_pk_bf16_f32 v210, v208, v209
	v_lshlrev_b32_e32 v124, 16, v210
	v_and_b32_e32 v125, 0xffff0000, v210
	v_lshlrev_b32_e32 v208, 16, v191
	v_and_b32_e32 v209, 0xffff0000, v191
	v_fma_f32 v208, v208, v232, v206
	v_fma_f32 v209, v209, v232, v207
	v_cvt_pk_bf16_f32 v210, v208, v209
	v_lshlrev_b32_e32 v126, 16, v210
	v_and_b32_e32 v127, 0xffff0000, v210
	s_nop 0
	s_mov_b32 s24, s8
	s_and_b32 s25, s9, 0xffff
	s_mov_b32 s26, 0x20000
	s_mov_b32 s27, 0x00027000
	s_lshl_b32 s0, s76, 10
	s_add_i32 s0, s0, 0x11000
	s_sub_i32 s85, s0, s22
	v_mov_b32_e32 v224, 0x7fffffff
	v_mov_b32_e32 v225, 0x7fffffff
	v_mov_b32_e32 v226, 0x7fffffff
	v_mov_b32_e32 v227, 0x7fffffff
	v_mov_b32_e32 v228, 0
	v_mov_b32_e32 v229, 0
	v_mov_b32_e32 v230, 0
	v_mov_b32_e32 v231, 0
	v_add_u32_e32 v232, s22, v240
	ds_write_b128 v232, v[224:227] offset:0
	ds_write_b128 v232, v[228:231] offset:4992
	ds_write_b128 v232, v[224:227] offset:1024
	ds_write_b128 v232, v[228:231] offset:6016
	ds_write_b128 v232, v[224:227] offset:2048
	ds_write_b128 v232, v[228:231] offset:7040
	ds_write_b128 v232, v[224:227] offset:3072
	ds_write_b128 v232, v[228:231] offset:8064
	s_mov_b32 exec_hi, 0x00ffffff
	ds_write_b128 v232, v[224:227] offset:4096
	s_mov_b32 exec_hi, 0x000fffff
	ds_write_b128 v232, v[228:231] offset:9088
	s_mov_b64 exec, -1
	v_lshrrev_b32_e32 v221, 2, v240
	v_add_u32_e32 v221, s22, v221
	ds_write_b32 v221, v228 offset:4224
	v_lshrrev_b32_e32 v233, 1, v240
	s_lshl_b32 s0, s76, 10
	s_add_i32 s0, s0, 0x11000
	v_add_u32_e32 v233, s0, v233
	ds_read_b64 v[128:129], v233 offset:0
	ds_read_b64 v[130:131], v233 offset:512
	ds_read_b64 v[132:133], v233 offset:1024
	ds_read_b64 v[134:135], v233 offset:1536
	ds_read_b64 v[136:137], v233 offset:2048
	ds_read_b64 v[138:139], v233 offset:2560
	ds_read_b64 v[140:141], v233 offset:3072
	ds_read_b64 v[142:143], v233 offset:3584
	ds_read_b64 v[144:145], v233 offset:4096
	ds_read_b64 v[146:147], v233 offset:4608
	ds_read_b64 v[148:149], v233 offset:5120
	ds_read_b64 v[150:151], v233 offset:5632
	ds_read_b64 v[152:153], v233 offset:6144
	ds_read_b64 v[154:155], v233 offset:6656
	ds_read_b64 v[156:157], v233 offset:7168
	ds_read_b64 v[158:159], v233 offset:7680
	v_mov_b32_e32 v220, 1
	v_lshrrev_b32_e32 v200, 4, v240
	v_lshrrev_b32_e32 v201, 3, v200
	v_and_b32_e32 v200, 7, v200
	s_add_i32 s3, s22, 4224
	s_and_b32 s1, s32, 7
	s_waitcnt lgkmcnt(0)
	v_lshrrev_b32_e32 v160, 11, v128
	v_subrev_u32_e32 v160, s1, v160
	v_and_b32_e32 v160, 7, v160
	v_lshl_add_u32 v176, v160, 2, s3
	v_lshrrev_b32_e32 v161, 11, v130
	v_subrev_u32_e32 v161, s1, v161
	v_and_b32_e32 v161, 7, v161
	v_lshl_add_u32 v177, v161, 2, s3
	v_lshrrev_b32_e32 v162, 11, v132
	v_subrev_u32_e32 v162, s1, v162
	v_and_b32_e32 v162, 7, v162
	v_lshl_add_u32 v178, v162, 2, s3
	v_lshrrev_b32_e32 v163, 11, v134
	v_subrev_u32_e32 v163, s1, v163
	v_and_b32_e32 v163, 7, v163
	v_lshl_add_u32 v179, v163, 2, s3
	v_lshrrev_b32_e32 v164, 11, v136
	v_subrev_u32_e32 v164, s1, v164
	v_and_b32_e32 v164, 7, v164
	v_lshl_add_u32 v180, v164, 2, s3
	v_lshrrev_b32_e32 v165, 11, v138
	v_subrev_u32_e32 v165, s1, v165
	v_and_b32_e32 v165, 7, v165
	v_lshl_add_u32 v181, v165, 2, s3
	v_lshrrev_b32_e32 v166, 11, v140
	v_subrev_u32_e32 v166, s1, v166
	v_and_b32_e32 v166, 7, v166
	v_lshl_add_u32 v182, v166, 2, s3
	v_lshrrev_b32_e32 v167, 11, v142
	v_subrev_u32_e32 v167, s1, v167
	v_and_b32_e32 v167, 7, v167
	v_lshl_add_u32 v183, v167, 2, s3
	v_lshrrev_b32_e32 v168, 11, v144
	v_subrev_u32_e32 v168, s1, v168
	v_and_b32_e32 v168, 7, v168
	v_lshl_add_u32 v184, v168, 2, s3
	v_lshrrev_b32_e32 v169, 11, v146
	v_subrev_u32_e32 v169, s1, v169
	v_and_b32_e32 v169, 7, v169
	v_lshl_add_u32 v185, v169, 2, s3
	v_lshrrev_b32_e32 v170, 11, v148
	v_subrev_u32_e32 v170, s1, v170
	v_and_b32_e32 v170, 7, v170
	v_lshl_add_u32 v186, v170, 2, s3
	v_lshrrev_b32_e32 v171, 11, v150
	v_subrev_u32_e32 v171, s1, v171
	v_and_b32_e32 v171, 7, v171
	v_lshl_add_u32 v187, v171, 2, s3
	v_lshrrev_b32_e32 v172, 11, v152
; __device__ __forceinline__ void peer_tile(const Args& A, LAS unsigned char* lds, int tile) {
;     ...
;     for (int ti = 0; ti < 8; ++ti) {
;         const int tl = 8 * w + ti;
;         const u32x2 e0 = SEL[tl * 128 + lane], e1 = SEL[tl * 128 + 64 + lane];
;         const int p0 = (int)(e0.x >> 10), p1 = (int)(e1.x >> 10);
;         int off = 0;
;         for (int p = 0; p < 16; ++p) {
;             const unsigned long long m0 = __ballot(p0 == p), m1 = __ballot(p1 == p);
;             const int c0 = __popcll(m0), c1 = __popcll(m1);
;             const int r0 = __builtin_amdgcn_mbcnt_hi((unsigned)(m0 >> 32), __builtin_amdgcn_mbcnt_lo((unsigned)m0, 0u));
;             const int r1 = __builtin_amdgcn_mbcnt_hi((unsigned)(m1 >> 32), __builtin_amdgcn_mbcnt_lo((unsigned)m1, 0u));
;             if (p0 == p) SORT[tl * 128 + off + r0] = e0;
;             if (p1 == p) SORT[tl * 128 + off + c0 + r1] = e1;
;             if (lane == 0) OFFS[tl * 17 + p] = off;
;             off += c0 + c1;
;         }
;         if (lane == 0) OFFS[tl * 17 + 16] = off;
;     }
	v_subrev_u32_e32 v172, s1, v172
	v_and_b32_e32 v172, 7, v172
	v_lshl_add_u32 v188, v172, 2, s3
	v_lshrrev_b32_e32 v173, 11, v154
	v_subrev_u32_e32 v173, s1, v173
	v_and_b32_e32 v173, 7, v173
	v_lshl_add_u32 v189, v173, 2, s3
	v_lshrrev_b32_e32 v174, 11, v156
	v_subrev_u32_e32 v174, s1, v174
	v_and_b32_e32 v174, 7, v174
	v_lshl_add_u32 v190, v174, 2, s3
	v_lshrrev_b32_e32 v175, 11, v158
	v_subrev_u32_e32 v175, s1, v175
	v_and_b32_e32 v175, 7, v175
	v_lshl_add_u32 v191, v175, 2, s3
	v_lshlrev_b32_e32 v206, 3, v128
	buffer_load_dwordx2 v[224:225], v206, s[24:27], 0 offen
	v_lshlrev_b32_e32 v206, 3, v130
	buffer_load_dwordx2 v[226:227], v206, s[24:27], 0 offen
	v_lshlrev_b32_e32 v206, 3, v132
	buffer_load_dwordx2 v[228:229], v206, s[24:27], 0 offen
	v_lshlrev_b32_e32 v206, 3, v134
	buffer_load_dwordx2 v[230:231], v206, s[24:27], 0 offen
	v_lshlrev_b32_e32 v206, 3, v136
	buffer_load_dwordx2 v[232:233], v206, s[24:27], 0 offen
	v_lshlrev_b32_e32 v206, 3, v138
	buffer_load_dwordx2 v[234:235], v206, s[24:27], 0 offen
	v_lshlrev_b32_e32 v206, 3, v140
	buffer_load_dwordx2 v[236:237], v206, s[24:27], 0 offen
	v_lshlrev_b32_e32 v206, 3, v142
	buffer_load_dwordx2 v[238:239], v206, s[24:27], 0 offen
	v_lshlrev_b32_e32 v206, 3, v144
	buffer_load_dwordx2 v[248:249], v206, s[24:27], 0 offen
	v_lshlrev_b32_e32 v206, 3, v146
	buffer_load_dwordx2 v[250:251], v206, s[24:27], 0 offen
	v_lshlrev_b32_e32 v206, 3, v148
	buffer_load_dwordx2 v[252:253], v206, s[24:27], 0 offen
	v_lshlrev_b32_e32 v206, 3, v150
	buffer_load_dwordx2 v[254:255], v206, s[24:27], 0 offen
	ds_add_rtn_u32 v176, v176, v220 offset:0
	ds_add_rtn_u32 v177, v177, v220 offset:0
	ds_add_rtn_u32 v178, v178, v220 offset:32
	ds_add_rtn_u32 v179, v179, v220 offset:32
	ds_add_rtn_u32 v180, v180, v220 offset:64
	ds_add_rtn_u32 v181, v181, v220 offset:64
	ds_add_rtn_u32 v182, v182, v220 offset:96
	ds_add_rtn_u32 v183, v183, v220 offset:96
	ds_add_rtn_u32 v184, v184, v220 offset:128
	ds_add_rtn_u32 v185, v185, v220 offset:128
	ds_add_rtn_u32 v186, v186, v220 offset:160
	ds_add_rtn_u32 v187, v187, v220 offset:160
	ds_add_rtn_u32 v188, v188, v220 offset:192
	ds_add_rtn_u32 v189, v189, v220 offset:192
	ds_add_rtn_u32 v190, v190, v220 offset:224
	ds_add_rtn_u32 v191, v191, v220 offset:224
	v_lshl_add_u32 v207, v201, 5, s3
	ds_read_b32 v203, v221 offset:4224
	ds_read_b128 v[192:195], v207
	ds_read_b128 v[196:199], v207 offset:16
	v_mov_b32_e32 v202, 0
	s_waitcnt lgkmcnt(0)
	v_cmp_lt_u32_e64 s[38:39], 0, v200
	v_cmp_lt_u32_e64 s[40:41], 1, v200
	v_cmp_lt_u32_e64 s[42:43], 2, v200
	v_cmp_lt_u32_e64 s[44:45], 3, v200
	v_cmp_lt_u32_e64 s[64:65], 4, v200
	v_cmp_lt_u32_e64 s[66:67], 5, v200
	v_cmp_lt_u32_e64 s[94:95], 6, v200
	v_cndmask_b32_e64 v206, 0, v192, s[38:39]
	v_add_u32_e32 v202, v202, v206
	v_cndmask_b32_e64 v206, 0, v193, s[40:41]
	v_add_u32_e32 v202, v202, v206
	v_cndmask_b32_e64 v206, 0, v194, s[42:43]
	v_add_u32_e32 v202, v202, v206
	v_cndmask_b32_e64 v206, 0, v195, s[44:45]
	v_add_u32_e32 v202, v202, v206
	v_cndmask_b32_e64 v206, 0, v196, s[64:65]
	v_add_u32_e32 v202, v202, v206
	v_cndmask_b32_e64 v206, 0, v197, s[66:67]
	v_add_u32_e32 v202, v202, v206
	v_cndmask_b32_e64 v206, 0, v198, s[94:95]
	v_add_u32_e32 v202, v202, v206
	v_add_u32_e32 v204, 3, v202
	v_add3_u32 v212, v202, v203, 3
	v_lshrrev_b32_e32 v204, 2, v204
	v_lshrrev_b32_e32 v212, 2, v212
	v_sub_u32_e32 v212, v212, v204
	v_lshl_add_u32 v207, v200, 3, v201
	v_lshl_add_u32 v207, v207, 2, s3
	ds_write_b32 v207, v212 offset:256
	v_lshl_add_u32 v208, v200, 5, s3
	ds_read_b128 v[192:195], v208 offset:256
	ds_read_b128 v[196:199], v208 offset:272
	v_mov_b32_e32 v205, 0
	s_waitcnt lgkmcnt(0)
	v_cmp_lt_u32_e64 s[38:39], 0, v201
	v_cmp_lt_u32_e64 s[40:41], 1, v201
	v_cmp_lt_u32_e64 s[42:43], 2, v201
	v_cmp_lt_u32_e64 s[44:45], 3, v201
	v_cmp_lt_u32_e64 s[64:65], 4, v201
	v_cmp_lt_u32_e64 s[66:67], 5, v201
	v_cmp_lt_u32_e64 s[94:95], 6, v201
	v_cndmask_b32_e64 v206, 0, v192, s[38:39]
	v_add_u32_e32 v205, v205, v206
	v_cndmask_b32_e64 v206, 0, v193, s[40:41]
	v_add_u32_e32 v205, v205, v206
	v_cndmask_b32_e64 v206, 0, v194, s[42:43]
	v_add_u32_e32 v205, v205, v206
	v_cndmask_b32_e64 v206, 0, v195, s[44:45]
	v_add_u32_e32 v205, v205, v206
	v_cndmask_b32_e64 v206, 0, v196, s[64:65]
	v_add_u32_e32 v205, v205, v206
	v_cndmask_b32_e64 v206, 0, v197, s[66:67]
	v_add_u32_e32 v205, v205, v206
	v_cndmask_b32_e64 v206, 0, v198, s[94:95]
	v_add_u32_e32 v205, v205, v206
	v_add_u32_e32 v206, v192, v193
	v_add_u32_e32 v206, v206, v194
	v_add_u32_e32 v206, v206, v195
	v_add_u32_e32 v206, v206, v196
	v_add_u32_e32 v206, v206, v197
	v_add_u32_e32 v206, v206, v198
	v_add_u32_e32 v206, v206, v199
	v_lshl_add_u32 v207, v200, 2, s3
	ds_write_b32 v207, v206 offset:512
	v_mov_b32_e32 v207, s3
	ds_read_b128 v[192:195], v207 offset:512
	ds_read_b128 v[196:199], v207 offset:528
	ds_write_b32 v221, v202 offset:4224
	s_waitcnt lgkmcnt(0)
	v_cmp_lt_u32_e64 s[38:39], 0, v200
	v_cmp_lt_u32_e64 s[40:41], 1, v200
	v_cmp_lt_u32_e64 s[42:43], 2, v200
	v_cmp_lt_u32_e64 s[44:45], 3, v200
	v_cmp_lt_u32_e64 s[64:65], 4, v200
	v_cmp_lt_u32_e64 s[66:67], 5, v200
	v_cmp_lt_u32_e64 s[94:95], 6, v200
	v_cndmask_b32_e64 v206, 0, v192, s[38:39]
	v_add_u32_e32 v205, v205, v206
	v_cndmask_b32_e64 v206, 0, v193, s[40:41]
	v_add_u32_e32 v205, v205, v206
	v_cndmask_b32_e64 v206, 0, v194, s[42:43]
	v_add_u32_e32 v205, v205, v206
	v_cndmask_b32_e64 v206, 0, v195, s[44:45]
	v_add_u32_e32 v205, v205, v206
	v_cndmask_b32_e64 v206, 0, v196, s[64:65]
	v_add_u32_e32 v205, v205, v206
	v_cndmask_b32_e64 v206, 0, v197, s[66:67]
	v_add_u32_e32 v205, v205, v206
	v_cndmask_b32_e64 v206, 0, v198, s[94:95]
	v_add_u32_e32 v205, v205, v206
	v_sub_u32_e32 v205, v205, v204
	v_lshrrev_b32_e32 v208, 4, v240
	v_and_b32_e32 v222, 31, v208
	v_lshrrev_b32_e32 v208, 5, v208
	v_add_u32_e32 v207, 0, v208
	v_lshl_add_u32 v206, v207, 5, s3
	ds_read_b128 v[192:195], v206
	ds_read_b128 v[196:199], v206 offset:16
	v_lshlrev_b32_e32 v206, 2, v222
	v_lshlrev_b32_e32 v223, 3, v207
	s_waitcnt lgkmcnt(0)
; __device__ __forceinline__ void peer_tile(const Args& A, LAS unsigned char* lds, int tile) {
;     ...
;     for (int ti = 0; ti < 8; ++ti) {
;         const int tl = 8 * w + ti;
;         const u32x2 e0 = SEL[tl * 128 + lane], e1 = SEL[tl * 128 + 64 + lane];
;         const int p0 = (int)(e0.x >> 10), p1 = (int)(e1.x >> 10);
;         int off = 0;
;         for (int p = 0; p < 16; ++p) {
;             const unsigned long long m0 = __ballot(p0 == p), m1 = __ballot(p1 == p);
;             const int c0 = __popcll(m0), c1 = __popcll(m1);
;             const int r0 = __builtin_amdgcn_mbcnt_hi((unsigned)(m0 >> 32), __builtin_amdgcn_mbcnt_lo((unsigned)m0, 0u));
;             const int r1 = __builtin_amdgcn_mbcnt_hi((unsigned)(m1 >> 32), __builtin_amdgcn_mbcnt_lo((unsigned)m1, 0u));
;             if (p0 == p) SORT[tl * 128 + off + r0] = e0;
;             if (p1 == p) SORT[tl * 128 + off + c0 + r1] = e1;
;             if (lane == 0) OFFS[tl * 17 + p] = off;
;             off += c0 + c1;
;         }
;         if (lane == 0) OFFS[tl * 17 + 16] = off;
;     }
	v_cmp_le_u32_e64 s[38:39], v193, v206
	v_cmp_le_u32_e64 s[40:41], v194, v206
	v_cmp_le_u32_e64 s[42:43], v195, v206
	v_cmp_le_u32_e64 s[44:45], v196, v206
	v_cmp_le_u32_e64 s[64:65], v197, v206
	v_cmp_le_u32_e64 s[66:67], v198, v206
	v_cmp_le_u32_e64 s[94:95], v199, v206
	v_addc_co_u32_e64 v223, s[92:93], 0, v223, s[38:39]
	v_addc_co_u32_e64 v223, s[92:93], 0, v223, s[40:41]
	v_addc_co_u32_e64 v223, s[92:93], 0, v223, s[42:43]
	v_addc_co_u32_e64 v223, s[92:93], 0, v223, s[44:45]
	v_addc_co_u32_e64 v223, s[92:93], 0, v223, s[64:65]
	v_addc_co_u32_e64 v223, s[92:93], 0, v223, s[66:67]
	v_addc_co_u32_e64 v223, s[92:93], 0, v223, s[94:95]
	v_lshlrev_b32_e32 v223, 2, v223
	ds_bpermute_b32 v216, v223, v205
	v_add_u32_e32 v207, 2, v208
	v_lshl_add_u32 v206, v207, 5, s3
	ds_read_b128 v[192:195], v206
	ds_read_b128 v[196:199], v206 offset:16
	v_lshlrev_b32_e32 v206, 2, v222
	v_lshlrev_b32_e32 v223, 3, v207
	s_waitcnt lgkmcnt(0)
	v_cmp_le_u32_e64 s[38:39], v193, v206
	v_cmp_le_u32_e64 s[40:41], v194, v206
	v_cmp_le_u32_e64 s[42:43], v195, v206
	v_cmp_le_u32_e64 s[44:45], v196, v206
	v_cmp_le_u32_e64 s[64:65], v197, v206
	v_cmp_le_u32_e64 s[66:67], v198, v206
	v_cmp_le_u32_e64 s[94:95], v199, v206
	v_addc_co_u32_e64 v223, s[92:93], 0, v223, s[38:39]
	v_addc_co_u32_e64 v223, s[92:93], 0, v223, s[40:41]
	v_addc_co_u32_e64 v223, s[92:93], 0, v223, s[42:43]
	v_addc_co_u32_e64 v223, s[92:93], 0, v223, s[44:45]
	v_addc_co_u32_e64 v223, s[92:93], 0, v223, s[64:65]
	v_addc_co_u32_e64 v223, s[92:93], 0, v223, s[66:67]
	v_addc_co_u32_e64 v223, s[92:93], 0, v223, s[94:95]
	v_lshlrev_b32_e32 v223, 2, v223
	ds_bpermute_b32 v217, v223, v205
	v_add_u32_e32 v207, 4, v208
	v_lshl_add_u32 v206, v207, 5, s3
	ds_read_b128 v[192:195], v206
	ds_read_b128 v[196:199], v206 offset:16
	v_lshlrev_b32_e32 v206, 2, v222
	v_lshlrev_b32_e32 v223, 3, v207
	s_waitcnt lgkmcnt(0)
	v_cmp_le_u32_e64 s[38:39], v193, v206
	v_cmp_le_u32_e64 s[40:41], v194, v206
	v_cmp_le_u32_e64 s[42:43], v195, v206
	v_cmp_le_u32_e64 s[44:45], v196, v206
	v_cmp_le_u32_e64 s[64:65], v197, v206
	v_cmp_le_u32_e64 s[66:67], v198, v206
	v_cmp_le_u32_e64 s[94:95], v199, v206
	v_addc_co_u32_e64 v223, s[92:93], 0, v223, s[38:39]
	v_addc_co_u32_e64 v223, s[92:93], 0, v223, s[40:41]
	v_addc_co_u32_e64 v223, s[92:93], 0, v223, s[42:43]
	v_addc_co_u32_e64 v223, s[92:93], 0, v223, s[44:45]
	v_addc_co_u32_e64 v223, s[92:93], 0, v223, s[64:65]
	v_addc_co_u32_e64 v223, s[92:93], 0, v223, s[66:67]
	v_addc_co_u32_e64 v223, s[92:93], 0, v223, s[94:95]
	v_lshlrev_b32_e32 v223, 2, v223
	ds_bpermute_b32 v218, v223, v205
	v_add_u32_e32 v207, 6, v208
	v_lshl_add_u32 v206, v207, 5, s3
	ds_read_b128 v[192:195], v206
	ds_read_b128 v[196:199], v206 offset:16
	v_lshlrev_b32_e32 v206, 2, v222
	v_lshlrev_b32_e32 v223, 3, v207
	s_waitcnt lgkmcnt(0)
	v_cmp_le_u32_e64 s[38:39], v193, v206
	v_cmp_le_u32_e64 s[40:41], v194, v206
	v_cmp_le_u32_e64 s[42:43], v195, v206
	v_cmp_le_u32_e64 s[44:45], v196, v206
	v_cmp_le_u32_e64 s[64:65], v197, v206
	v_cmp_le_u32_e64 s[66:67], v198, v206
	v_cmp_le_u32_e64 s[94:95], v199, v206
	v_addc_co_u32_e64 v223, s[92:93], 0, v223, s[38:39]
	v_addc_co_u32_e64 v223, s[92:93], 0, v223, s[40:41]
	v_addc_co_u32_e64 v223, s[92:93], 0, v223, s[42:43]
	v_addc_co_u32_e64 v223, s[92:93], 0, v223, s[44:45]
	v_addc_co_u32_e64 v223, s[92:93], 0, v223, s[64:65]
	v_addc_co_u32_e64 v223, s[92:93], 0, v223, s[66:67]
	v_addc_co_u32_e64 v223, s[92:93], 0, v223, s[94:95]
	v_lshlrev_b32_e32 v223, 2, v223
	ds_bpermute_b32 v219, v223, v205
	s_waitcnt lgkmcnt(0)
	v_add_u32_e32 v216, v216, v222
	v_add_u32_e32 v217, v217, v222
	v_add_u32_e32 v218, v218, v222
	v_add_u32_e32 v219, v219, v222
	v_lshlrev_b32_e32 v206, 3, v152
	buffer_load_dwordx2 v[192:193], v206, s[24:27], 0 offen
	v_lshlrev_b32_e32 v206, 3, v154
	buffer_load_dwordx2 v[194:195], v206, s[24:27], 0 offen
	v_lshlrev_b32_e32 v206, 3, v156
	buffer_load_dwordx2 v[196:197], v206, s[24:27], 0 offen
	v_lshlrev_b32_e32 v206, 3, v158
	buffer_load_dwordx2 v[198:199], v206, s[24:27], 0 offen
	v_lshlrev_b32_e32 v160, 2, v160
	ds_bpermute_b32 v160, v160, v202
	v_lshlrev_b32_e32 v161, 2, v161
	ds_bpermute_b32 v161, v161, v202
	v_lshlrev_b32_e32 v162, 2, v162
	v_add_u32_e32 v162, 32, v162
	ds_bpermute_b32 v162, v162, v202
	v_lshlrev_b32_e32 v163, 2, v163
	v_add_u32_e32 v163, 32, v163
	ds_bpermute_b32 v163, v163, v202
	v_lshlrev_b32_e32 v164, 2, v164
	v_add_u32_e32 v164, 64, v164
	ds_bpermute_b32 v164, v164, v202
	v_lshlrev_b32_e32 v165, 2, v165
	v_add_u32_e32 v165, 64, v165
	ds_bpermute_b32 v165, v165, v202
	v_lshlrev_b32_e32 v166, 2, v166
	v_add_u32_e32 v166, 96, v166
	ds_bpermute_b32 v166, v166, v202
	v_lshlrev_b32_e32 v167, 2, v167
	v_add_u32_e32 v167, 96, v167
	ds_bpermute_b32 v167, v167, v202
	v_lshlrev_b32_e32 v168, 2, v168
	v_add_u32_e32 v168, 128, v168
	ds_bpermute_b32 v168, v168, v202
	v_lshlrev_b32_e32 v169, 2, v169
	v_add_u32_e32 v169, 128, v169
	ds_bpermute_b32 v169, v169, v202
	v_lshlrev_b32_e32 v170, 2, v170
	v_add_u32_e32 v170, 160, v170
	ds_bpermute_b32 v170, v170, v202
	v_lshlrev_b32_e32 v171, 2, v171
	v_add_u32_e32 v171, 160, v171
	ds_bpermute_b32 v171, v171, v202
	v_lshlrev_b32_e32 v172, 2, v172
	v_add_u32_e32 v172, 192, v172
	ds_bpermute_b32 v172, v172, v202
	v_lshlrev_b32_e32 v173, 2, v173
	v_add_u32_e32 v173, 192, v173
	ds_bpermute_b32 v173, v173, v202
	v_lshlrev_b32_e32 v174, 2, v174
	v_add_u32_e32 v174, 224, v174
	ds_bpermute_b32 v174, v174, v202
	v_lshlrev_b32_e32 v175, 2, v175
	v_add_u32_e32 v175, 224, v175
	ds_bpermute_b32 v175, v175, v202
	s_waitcnt lgkmcnt(0)
; __device__ __forceinline__ void peer_tile(const Args& A, LAS unsigned char* lds, int tile) {
;     ...
;     for (int ti = 0; ti < 8; ++ti) {
;         const int tl = 8 * w + ti;
;         const u32x2 e0 = SEL[tl * 128 + lane], e1 = SEL[tl * 128 + 64 + lane];
;         const int p0 = (int)(e0.x >> 10), p1 = (int)(e1.x >> 10);
;         int off = 0;
;         for (int p = 0; p < 16; ++p) {
;             const unsigned long long m0 = __ballot(p0 == p), m1 = __ballot(p1 == p);
;             const int c0 = __popcll(m0), c1 = __popcll(m1);
;             const int r0 = __builtin_amdgcn_mbcnt_hi((unsigned)(m0 >> 32), __builtin_amdgcn_mbcnt_lo((unsigned)m0, 0u));
;             const int r1 = __builtin_amdgcn_mbcnt_hi((unsigned)(m1 >> 32), __builtin_amdgcn_mbcnt_lo((unsigned)m1, 0u));
;             if (p0 == p) SORT[tl * 128 + off + r0] = e0;
;             if (p1 == p) SORT[tl * 128 + off + c0 + r1] = e1;
;             if (lane == 0) OFFS[tl * 17 + p] = off;
;             off += c0 + c1;
;         }
;         if (lane == 0) OFFS[tl * 17 + 16] = off;
;     }
	v_add_u32_e32 v176, v176, v160
	v_lshrrev_b32_e32 v160, 2, v176
	v_and_b32_e32 v176, 3, v176
	v_lshlrev_b32_e32 v160, 2, v160
	ds_bpermute_b32 v160, v160, v216
	v_add_u32_e32 v177, v177, v161
	v_lshrrev_b32_e32 v161, 2, v177
	v_and_b32_e32 v177, 3, v177
	v_lshlrev_b32_e32 v161, 2, v161
	ds_bpermute_b32 v161, v161, v216
	v_add_u32_e32 v178, v178, v162
	v_lshrrev_b32_e32 v162, 2, v178
	v_and_b32_e32 v178, 3, v178
	v_lshlrev_b32_e32 v162, 2, v162
	v_add_u32_e32 v162, 128, v162
	ds_bpermute_b32 v162, v162, v216
	v_add_u32_e32 v179, v179, v163
	v_lshrrev_b32_e32 v163, 2, v179
	v_and_b32_e32 v179, 3, v179
	v_lshlrev_b32_e32 v163, 2, v163
	v_add_u32_e32 v163, 128, v163
	ds_bpermute_b32 v163, v163, v216
	v_add_u32_e32 v180, v180, v164
	v_lshrrev_b32_e32 v164, 2, v180
	v_and_b32_e32 v180, 3, v180
	v_lshlrev_b32_e32 v164, 2, v164
	ds_bpermute_b32 v164, v164, v217
	v_add_u32_e32 v181, v181, v165
	v_lshrrev_b32_e32 v165, 2, v181
	v_and_b32_e32 v181, 3, v181
	v_lshlrev_b32_e32 v165, 2, v165
	ds_bpermute_b32 v165, v165, v217
	v_add_u32_e32 v182, v182, v166
	v_lshrrev_b32_e32 v166, 2, v182
	v_and_b32_e32 v182, 3, v182
	v_lshlrev_b32_e32 v166, 2, v166
	v_add_u32_e32 v166, 128, v166
	ds_bpermute_b32 v166, v166, v217
	v_add_u32_e32 v183, v183, v167
	v_lshrrev_b32_e32 v167, 2, v183
	v_and_b32_e32 v183, 3, v183
	v_lshlrev_b32_e32 v167, 2, v167
	v_add_u32_e32 v167, 128, v167
	ds_bpermute_b32 v167, v167, v217
	v_add_u32_e32 v184, v184, v168
	v_lshrrev_b32_e32 v168, 2, v184
	v_and_b32_e32 v184, 3, v184
	v_lshlrev_b32_e32 v168, 2, v168
	ds_bpermute_b32 v168, v168, v218
	v_add_u32_e32 v185, v185, v169
	v_lshrrev_b32_e32 v169, 2, v185
	v_and_b32_e32 v185, 3, v185
	v_lshlrev_b32_e32 v169, 2, v169
	ds_bpermute_b32 v169, v169, v218
	v_add_u32_e32 v186, v186, v170
	v_lshrrev_b32_e32 v170, 2, v186
	v_and_b32_e32 v186, 3, v186
	v_lshlrev_b32_e32 v170, 2, v170
	v_add_u32_e32 v170, 128, v170
	ds_bpermute_b32 v170, v170, v218
	v_add_u32_e32 v187, v187, v171
	v_lshrrev_b32_e32 v171, 2, v187
	v_and_b32_e32 v187, 3, v187
	v_lshlrev_b32_e32 v171, 2, v171
	v_add_u32_e32 v171, 128, v171
	ds_bpermute_b32 v171, v171, v218
	v_add_u32_e32 v188, v188, v172
	v_lshrrev_b32_e32 v172, 2, v188
	v_and_b32_e32 v188, 3, v188
	v_lshlrev_b32_e32 v172, 2, v172
	ds_bpermute_b32 v172, v172, v219
	v_add_u32_e32 v189, v189, v173
	v_lshrrev_b32_e32 v173, 2, v189
	v_and_b32_e32 v189, 3, v189
	v_lshlrev_b32_e32 v173, 2, v173
	ds_bpermute_b32 v173, v173, v219
	v_add_u32_e32 v190, v190, v174
	v_lshrrev_b32_e32 v174, 2, v190
	v_and_b32_e32 v190, 3, v190
	v_lshlrev_b32_e32 v174, 2, v174
	v_add_u32_e32 v174, 128, v174
	ds_bpermute_b32 v174, v174, v219
	v_add_u32_e32 v191, v191, v175
	v_lshrrev_b32_e32 v175, 2, v191
	v_and_b32_e32 v191, 3, v191
	v_lshlrev_b32_e32 v175, 2, v175
	v_add_u32_e32 v175, 128, v175
	ds_bpermute_b32 v175, v175, v219
	s_waitcnt lgkmcnt(0)
	v_lshl_add_u32 v160, v160, 4, s22
	v_lshl_add_u32 v160, v176, 2, v160
	ds_write_b32 v160, v128
	ds_write_b32 v160, v129 offset:4992
	v_lshl_add_u32 v161, v161, 4, s22
	v_lshl_add_u32 v161, v177, 2, v161
	ds_write_b32 v161, v130
	ds_write_b32 v161, v131 offset:4992
	v_lshl_add_u32 v162, v162, 4, s22
	v_lshl_add_u32 v162, v178, 2, v162
	ds_write_b32 v162, v132
	ds_write_b32 v162, v133 offset:4992
	v_lshl_add_u32 v163, v163, 4, s22
	v_lshl_add_u32 v163, v179, 2, v163
	ds_write_b32 v163, v134
	ds_write_b32 v163, v135 offset:4992
	v_lshl_add_u32 v164, v164, 4, s22
	v_lshl_add_u32 v164, v180, 2, v164
	ds_write_b32 v164, v136
	ds_write_b32 v164, v137 offset:4992
	v_lshl_add_u32 v165, v165, 4, s22
	v_lshl_add_u32 v165, v181, 2, v165
	ds_write_b32 v165, v138
	ds_write_b32 v165, v139 offset:4992
	v_lshl_add_u32 v166, v166, 4, s22
	v_lshl_add_u32 v166, v182, 2, v166
	ds_write_b32 v166, v140
	ds_write_b32 v166, v141 offset:4992
	v_lshl_add_u32 v167, v167, 4, s22
	v_lshl_add_u32 v167, v183, 2, v167
	ds_write_b32 v167, v142
	ds_write_b32 v167, v143 offset:4992
	v_lshl_add_u32 v168, v168, 4, s22
	v_lshl_add_u32 v168, v184, 2, v168
	ds_write_b32 v168, v144
	ds_write_b32 v168, v145 offset:4992
	v_lshl_add_u32 v169, v169, 4, s22
	v_lshl_add_u32 v169, v185, 2, v169
	ds_write_b32 v169, v146
	ds_write_b32 v169, v147 offset:4992
	v_lshl_add_u32 v170, v170, 4, s22
	v_lshl_add_u32 v170, v186, 2, v170
	ds_write_b32 v170, v148
	ds_write_b32 v170, v149 offset:4992
	v_lshl_add_u32 v171, v171, 4, s22
	v_lshl_add_u32 v171, v187, 2, v171
	ds_write_b32 v171, v150
	ds_write_b32 v171, v151 offset:4992
	v_lshl_add_u32 v172, v172, 4, s22
	v_lshl_add_u32 v172, v188, 2, v172
	ds_write_b32 v172, v152
	ds_write_b32 v172, v153 offset:4992
	v_lshl_add_u32 v173, v173, 4, s22
	v_lshl_add_u32 v173, v189, 2, v173
	ds_write_b32 v173, v154
	ds_write_b32 v173, v155 offset:4992
	v_lshl_add_u32 v174, v174, 4, s22
	v_lshl_add_u32 v174, v190, 2, v174
	ds_write_b32 v174, v156
	ds_write_b32 v174, v157 offset:4992
	v_lshl_add_u32 v175, v175, 4, s22
	v_lshl_add_u32 v175, v191, 2, v175
	ds_write_b32 v175, v158
	ds_write_b32 v175, v159 offset:4992
	s_waitcnt vmcnt(0)
; #define IT_ADVANCE() do { it_j += 4; while (it_j >= it_end) { if (it_done) break; ++it_tk; if (it_tk == 4) { it_tk = 0; ++it_p; if (it_p == 16) { it_done = true; it_p = 15; it_j = 0; it_end = 1; break; } } \
;             it_j = __builtin_amdgcn_readfirstlane(OFFS[(tb + it_tk) * 17 + it_p]); it_end = __builtin_amdgcn_readfirstlane(OFFS[(tb + it_tk) * 17 + it_p + 1]); } } while (0)
; __device__ __forceinline__ void peer_tile(const Args& A, LAS unsigned char* lds, int tile) {
;     ...
;         int it_p = 0, it_tk = -1, it_j = 0, it_end = 0; bool it_done = false;
;     ...
;         u32x4 uA[4], vA[4], uB[4], vB[4]; float cgA = 0.f, suA = 0.f, svA = 0.f, cgB = 0.f, suB = 0.f, svB = 0.f;
; #pragma unroll
;         for (int k = 0; k < 4; ++k) { uA[k] = (u32x4){0u, 0u, 0u, 0u}; vA[k] = uA[k]; uB[k] = uA[k]; vB[k] = uA[k]; }
;         IT_ADVANCE();
;         LOAD_SET(uA, vA, cgA, suA, svA);
	v_add_u32_e32 v160, s85, v160
	ds_write_b32 v160, v224
	ds_write_b32 v160, v225 offset:4096
	v_add_u32_e32 v161, s85, v161
	ds_write_b32 v161, v226
	ds_write_b32 v161, v227 offset:4096
	v_add_u32_e32 v162, s85, v162
	ds_write_b32 v162, v228
	ds_write_b32 v162, v229 offset:4096
	v_add_u32_e32 v163, s85, v163
	ds_write_b32 v163, v230
	ds_write_b32 v163, v231 offset:4096
	v_add_u32_e32 v164, s85, v164
	ds_write_b32 v164, v232
	ds_write_b32 v164, v233 offset:4096
	v_add_u32_e32 v165, s85, v165
	ds_write_b32 v165, v234
	ds_write_b32 v165, v235 offset:4096
	v_add_u32_e32 v166, s85, v166
	ds_write_b32 v166, v236
	ds_write_b32 v166, v237 offset:4096
	v_add_u32_e32 v167, s85, v167
	ds_write_b32 v167, v238
	ds_write_b32 v167, v239 offset:4096
	v_add_u32_e32 v168, s85, v168
	ds_write_b32 v168, v248
	ds_write_b32 v168, v249 offset:4096
	v_add_u32_e32 v169, s85, v169
	ds_write_b32 v169, v250
	ds_write_b32 v169, v251 offset:4096
	v_add_u32_e32 v170, s85, v170
	ds_write_b32 v170, v252
	ds_write_b32 v170, v253 offset:4096
	v_add_u32_e32 v171, s85, v171
	ds_write_b32 v171, v254
	ds_write_b32 v171, v255 offset:4096
	v_add_u32_e32 v172, s85, v172
	ds_write_b32 v172, v192
	ds_write_b32 v172, v193 offset:4096
	v_add_u32_e32 v173, s85, v173
	ds_write_b32 v173, v194
	ds_write_b32 v173, v195 offset:4096
	v_add_u32_e32 v174, s85, v174
	ds_write_b32 v174, v196
	ds_write_b32 v174, v197 offset:4096
	v_add_u32_e32 v175, s85, v175
	ds_write_b32 v175, v198
	ds_write_b32 v175, v199 offset:4096
	v_mov_b32_e32 v206, 0x7fffffff
	ds_write_b32 v221, v206 offset:4224
	ds_write_b32 v221, v206 offset:4480
	ds_write_b32 v221, v206 offset:4736
	s_mov_b32 s91, 256
	s_add_i32 s20, s91, 3
	s_and_b32 s20, s20, -4
	s_mov_b32 s24, s8
	s_and_b32 s25, s9, 0xffff
	s_mov_b32 s26, 0x20000
	s_mov_b32 s27, 0x00027000
	s_mov_b32 s28, s52
	s_and_b32 s29, s53, 0xffff
	s_mov_b32 s30, 0x20000
	s_mov_b32 s31, 0x00027000
	s_waitcnt vmcnt(0) lgkmcnt(0)
	v_mov_b32_e32 v213, s22
	v_mov_b32_e32 v233, v240
	v_mov_b32_e32 v235, v240
	v_mov_b32_e32 v237, v240
	v_mov_b32_e32 v239, v240
	ds_read_b32 v232, v213 offset:0
	ds_read_b32 v234, v213 offset:4
	ds_read_b32 v236, v213 offset:8
	ds_read_b32 v238, v213 offset:12
	s_waitcnt lgkmcnt(0)
	buffer_load_dwordx4 v[128:131], v[232:233], s[56:59], 0 idxen offen
	buffer_load_dwordx4 v[132:135], v[234:235], s[56:59], 0 idxen offen
	buffer_load_dwordx4 v[136:139], v[236:237], s[56:59], 0 idxen offen
	buffer_load_dwordx4 v[140:143], v[238:239], s[56:59], 0 idxen offen
	ds_read_b32 v232, v213 offset:16
	ds_read_b32 v234, v213 offset:20
	ds_read_b32 v236, v213 offset:24
	ds_read_b32 v238, v213 offset:28
	s_waitcnt lgkmcnt(0)
	buffer_load_dwordx4 v[144:147], v[232:233], s[56:59], 0 idxen offen
	buffer_load_dwordx4 v[148:151], v[234:235], s[56:59], 0 idxen offen
	buffer_load_dwordx4 v[152:155], v[236:237], s[56:59], 0 idxen offen
	buffer_load_dwordx4 v[156:159], v[238:239], s[56:59], 0 idxen offen
	ds_read_b32 v232, v213 offset:32
	ds_read_b32 v234, v213 offset:36
	ds_read_b32 v236, v213 offset:40
	ds_read_b32 v238, v213 offset:44
	s_waitcnt lgkmcnt(0)
	buffer_load_dwordx4 v[160:163], v[232:233], s[56:59], 0 idxen offen
	buffer_load_dwordx4 v[164:167], v[234:235], s[56:59], 0 idxen offen
	buffer_load_dwordx4 v[168:171], v[236:237], s[56:59], 0 idxen offen
	buffer_load_dwordx4 v[172:175], v[238:239], s[56:59], 0 idxen offen
	ds_read_b32 v232, v213 offset:48
	ds_read_b32 v234, v213 offset:52
	ds_read_b32 v236, v213 offset:56
	ds_read_b32 v238, v213 offset:60
	s_mov_b32 s21, 0
	s_mov_b32 s89, -1
	s_mov_b32 s86, 0
	v_lshrrev_b32_e32 v208, 6, v240
	v_and_b32_e32 v208, 3, v208
	v_lshrrev_b32_e32 v209, 1, v208
	v_lshlrev_b32_e32 v208, 1, v208
	v_and_b32_e32 v208, 2, v208
	v_or_b32_e32 v208, v208, v209
	v_lshlrev_b32_e32 v208, 2, v208
	v_add3_u32 v211, v208, v247, s22
	v_add_u32_e32 v250, s85, v211
	ds_read_b32 v252, v250
	ds_read_b32 v253, v250 offset:4096
	ds_read_b32 v249, v211 offset:4992
	s_branch .LU_sw0
